# E25hi: strategy 4 static s_setprio 1 for waves 4-7 at entry, all per-segment flips removed; on E23
# baseline (speedup 1.0000x reference)
_Z6mk_fwd4Args:
	v_readfirstlane_b32 s3, v0
	s_nop 3
	s_lshr_b32 s3, s3, 6
	s_and_b32 s3, s3, 15
	s_cmp_ge_u32 s3, 4
	s_cbranch_scc0 .Lgk_prio_done
	s_setprio 1
.Lgk_prio_done:
	s_load_dword s3, s[0:1], 0xd8
	s_add_u32 s4, s0, 0xd8
	v_writelane_b32 v252, s0, 0
	s_addc_u32 s5, s1, 0
	s_mov_b32 s97, s2
	v_writelane_b32 v252, s1, 1
	v_writelane_b32 v252, s4, 2
	s_waitcnt lgkmcnt(0)
	s_and_b32 s0, s3, 7
	s_cmp_lg_u32 s0, 0
	v_writelane_b32 v252, s5, 3
	s_mov_b32 s12, s2
	s_cbranch_scc1 .LBB0_2
	s_ashr_i32 s1, s97, 31
	s_lshr_b32 s1, s1, 29
	s_add_i32 s1, s97, s1
	s_and_b32 s2, s1, -8
	s_ashr_i32 s0, s3, 3
	s_sub_i32 s2, s97, s2
	s_mul_i32 s0, s0, s2
	s_ashr_i32 s1, s1, 3
	s_add_i32 s12, s0, s1

.LBB0_303:
	s_lshl_b32 s18, s91, 20
	s_and_b64 s[8:9], s[34:35], exec
	s_cselect_b32 s8, s18, s94
	s_lshl_b32 s19, s90, 20
	s_and_b64 s[42:43], s[34:35], exec
	s_cselect_b32 s9, s19, s95
	s_add_i32 s94, s94, 0x80080
	s_addk_i32 s95, 0x100
	s_mov_b32 vcc_lo, -2
	ds_read_b128 v[142:145], v136
	ds_read_b128 v[170:173], v136 offset:1024
	ds_read_b128 v[174:177], v136 offset:2048
	ds_read_b128 v[178:181], v136 offset:3072
	ds_read_b128 v[182:185], v137
	ds_read_b128 v[186:189], v137 offset:1024
	ds_read_b128 v[190:193], v137 offset:2048
	ds_read_b128 v[194:197], v137 offset:3072
	s_add_i32 s42, s94, 0xfff80080
	s_cmp_eq_u32 vcc_lo, 28
	s_cselect_b32 s97, s8, s42
	s_cselect_b32 s52, s9, s95
	s_or_b32 vcc_hi, s97, 0x80
	s_mov_b32 m0, s72
	ds_read_b128 v[198:201], v138
	ds_read_b128 v[202:205], v138 offset:1024
	ds_read_b128 v[228:231], v138 offset:2048
	ds_read_b128 v[232:235], v138 offset:3072
	ds_read_b128 v[236:239], v138 offset:4096
	ds_read_b128 v[240:243], v138 offset:5120
	ds_read_b128 v[244:247], v138 offset:6144
	ds_read_b128 v[248:251], v138 offset:7168
	buffer_load_dwordx4 v132, s[60:63], s94 offen lds
	s_mov_b32 m0, s47
	s_nop 0
	buffer_load_dwordx4 v134, s[60:63], s94 offen lds
	s_waitcnt vmcnt(8)
	s_waitcnt lgkmcnt(0)
	s_barrier
	v_mfma_f32_16x16x32_bf16 v[114:117], v[142:145], v[198:201], 0
	v_mfma_f32_16x16x32_bf16 v[114:117], v[170:173], v[202:205], v[114:117]
	v_mfma_f32_16x16x32_bf16 v[110:113], v[174:177], v[198:201], 0
	v_mfma_f32_16x16x32_bf16 v[110:113], v[178:181], v[202:205], v[110:113]
	v_mfma_f32_16x16x32_bf16 v[122:125], v[190:193], v[198:201], 0
	v_mfma_f32_16x16x32_bf16 v[122:125], v[194:197], v[202:205], v[122:125]
	v_mfma_f32_16x16x32_bf16 v[126:129], v[182:185], v[198:201], 0
	v_mfma_f32_16x16x32_bf16 v[126:129], v[186:189], v[202:205], v[126:129]
	v_mfma_f32_16x16x32_bf16 v[118:121], v[182:185], v[228:231], 0
	v_mfma_f32_16x16x32_bf16 v[118:121], v[186:189], v[232:235], v[118:121]
	v_mfma_f32_16x16x32_bf16 v[98:101], v[190:193], v[228:231], 0
	v_mfma_f32_16x16x32_bf16 v[98:101], v[194:197], v[232:235], v[98:101]
	v_mfma_f32_16x16x32_bf16 v[102:105], v[174:177], v[228:231], 0
	v_mfma_f32_16x16x32_bf16 v[102:105], v[178:181], v[232:235], v[102:105]
	v_mfma_f32_16x16x32_bf16 v[106:109], v[142:145], v[228:231], 0
	v_mfma_f32_16x16x32_bf16 v[106:109], v[170:173], v[232:235], v[106:109]
	v_mfma_f32_16x16x32_bf16 v[94:97], v[142:145], v[236:239], 0
	v_mfma_f32_16x16x32_bf16 v[94:97], v[170:173], v[240:243], v[94:97]
	v_mfma_f32_16x16x32_bf16 v[86:89], v[174:177], v[236:239], 0
	v_mfma_f32_16x16x32_bf16 v[86:89], v[178:181], v[240:243], v[86:89]
	v_mfma_f32_16x16x32_bf16 v[82:85], v[190:193], v[236:239], 0
	v_mfma_f32_16x16x32_bf16 v[82:85], v[194:197], v[240:243], v[82:85]
	v_mfma_f32_16x16x32_bf16 v[90:93], v[182:185], v[236:239], 0
	v_mfma_f32_16x16x32_bf16 v[90:93], v[186:189], v[240:243], v[90:93]
	v_mfma_f32_16x16x32_bf16 v[74:77], v[182:185], v[244:247], 0
	v_mfma_f32_16x16x32_bf16 v[74:77], v[186:189], v[248:251], v[74:77]
	v_mfma_f32_16x16x32_bf16 v[66:69], v[190:193], v[244:247], 0
	v_mfma_f32_16x16x32_bf16 v[66:69], v[194:197], v[248:251], v[66:69]
	v_mfma_f32_16x16x32_bf16 v[70:73], v[174:177], v[244:247], 0
	v_mfma_f32_16x16x32_bf16 v[70:73], v[178:181], v[248:251], v[70:73]
	v_mfma_f32_16x16x32_bf16 v[78:81], v[142:145], v[244:247], 0
	v_mfma_f32_16x16x32_bf16 v[78:81], v[170:173], v[248:251], v[78:81]
	s_barrier
	s_mov_b32 s42, s62
	s_mov_b32 s43, s63
	s_mov_b32 m0, s13
	ds_read_b128 v[198:201], v138 offset:16384
	buffer_load_dwordx4 v133, s[40:43], s52 offen lds
	s_add_i32 s96, s52, 0x80000
	s_mov_b32 m0, s14
	ds_read_b128 v[202:205], v138 offset:17408
	buffer_load_dwordx4 v135, s[40:43], s52 offen lds
	s_mov_b32 m0, s15
	ds_read_b128 v[228:231], v138 offset:18432
	buffer_load_dwordx4 v133, s[40:43], s96 offen lds
	s_mov_b32 m0, s16
	ds_read_b128 v[232:235], v138 offset:19456
	buffer_load_dwordx4 v135, s[40:43], s96 offen lds
	s_mov_b32 m0, s2
	ds_read_b128 v[236:239], v138 offset:20480
	buffer_load_dwordx4 v132, s[60:63], s97 offen lds
	s_mov_b32 m0, s21
	ds_read_b128 v[240:243], v138 offset:21504
	buffer_load_dwordx4 v134, s[60:63], s97 offen lds
	ds_read_b128 v[244:247], v138 offset:22528
	ds_read_b128 v[248:251], v138 offset:23552
	s_waitcnt vmcnt(8)
	s_waitcnt lgkmcnt(0)
	s_barrier
	v_mfma_f32_16x16x32_bf16 v[62:65], v[142:145], v[198:201], 0
	v_mfma_f32_16x16x32_bf16 v[62:65], v[170:173], v[202:205], v[62:65]
	v_mfma_f32_16x16x32_bf16 v[54:57], v[174:177], v[198:201], 0
	v_mfma_f32_16x16x32_bf16 v[54:57], v[178:181], v[202:205], v[54:57]
	v_mfma_f32_16x16x32_bf16 v[50:53], v[190:193], v[198:201], 0
	v_mfma_f32_16x16x32_bf16 v[50:53], v[194:197], v[202:205], v[50:53]
	v_mfma_f32_16x16x32_bf16 v[58:61], v[182:185], v[198:201], 0
	v_mfma_f32_16x16x32_bf16 v[58:61], v[186:189], v[202:205], v[58:61]
	v_mfma_f32_16x16x32_bf16 v[42:45], v[182:185], v[228:231], 0
	v_mfma_f32_16x16x32_bf16 v[42:45], v[186:189], v[232:235], v[42:45]
	v_mfma_f32_16x16x32_bf16 v[34:37], v[190:193], v[228:231], 0
	v_mfma_f32_16x16x32_bf16 v[34:37], v[194:197], v[232:235], v[34:37]
	v_mfma_f32_16x16x32_bf16 v[38:41], v[174:177], v[228:231], 0
	v_mfma_f32_16x16x32_bf16 v[38:41], v[178:181], v[232:235], v[38:41]
	v_mfma_f32_16x16x32_bf16 v[46:49], v[142:145], v[228:231], 0
	v_mfma_f32_16x16x32_bf16 v[46:49], v[170:173], v[232:235], v[46:49]
	v_mfma_f32_16x16x32_bf16 v[30:33], v[142:145], v[236:239], 0
	v_mfma_f32_16x16x32_bf16 v[30:33], v[170:173], v[240:243], v[30:33]
	v_mfma_f32_16x16x32_bf16 v[22:25], v[174:177], v[236:239], 0
	v_mfma_f32_16x16x32_bf16 v[22:25], v[178:181], v[240:243], v[22:25]
	v_mfma_f32_16x16x32_bf16 v[18:21], v[190:193], v[236:239], 0
	v_mfma_f32_16x16x32_bf16 v[18:21], v[194:197], v[240:243], v[18:21]
	v_mfma_f32_16x16x32_bf16 v[26:29], v[182:185], v[236:239], 0
	v_mfma_f32_16x16x32_bf16 v[26:29], v[186:189], v[240:243], v[26:29]
	v_mfma_f32_16x16x32_bf16 v[10:13], v[182:185], v[244:247], 0
	v_mfma_f32_16x16x32_bf16 v[10:13], v[186:189], v[248:251], v[10:13]
	v_mfma_f32_16x16x32_bf16 v[2:5], v[190:193], v[244:247], 0
	v_mfma_f32_16x16x32_bf16 v[2:5], v[194:197], v[248:251], v[2:5]
	v_mfma_f32_16x16x32_bf16 v[6:9], v[174:177], v[244:247], 0
	v_mfma_f32_16x16x32_bf16 v[6:9], v[178:181], v[248:251], v[6:9]
	v_mfma_f32_16x16x32_bf16 v[14:17], v[142:145], v[244:247], 0
	v_mfma_f32_16x16x32_bf16 v[14:17], v[170:173], v[248:251], v[14:17]
	s_barrier
	ds_read_b128 v[142:145], v139
	ds_read_b128 v[170:173], v139 offset:1024
	ds_read_b128 v[174:177], v139 offset:2048
	ds_read_b128 v[178:181], v139 offset:3072
	ds_read_b128 v[182:185], v140
	ds_read_b128 v[186:189], v140 offset:1024
	ds_read_b128 v[190:193], v140 offset:2048
	ds_read_b128 v[194:197], v140 offset:3072
	s_add_i32 s97, s97, 0x80000
	s_mov_b32 m0, s23
	ds_read_b128 v[198:201], v138 offset:32768
	ds_read_b128 v[202:205], v138 offset:33792
	ds_read_b128 v[228:231], v138 offset:34816
	ds_read_b128 v[232:235], v138 offset:35840
	ds_read_b128 v[236:239], v138 offset:36864
	ds_read_b128 v[240:243], v138 offset:37888
	ds_read_b128 v[244:247], v138 offset:38912
	ds_read_b128 v[248:251], v138 offset:39936
	buffer_load_dwordx4 v132, s[60:63], s97 offen lds
	s_mov_b32 m0, s24
	s_nop 0
	buffer_load_dwordx4 v134, s[60:63], s97 offen lds
	s_waitcnt vmcnt(8)
	s_waitcnt lgkmcnt(0)
	s_barrier
	v_mfma_f32_16x16x32_bf16 v[114:117], v[142:145], v[198:201], v[114:117]
	v_mfma_f32_16x16x32_bf16 v[114:117], v[170:173], v[202:205], v[114:117]
	v_mfma_f32_16x16x32_bf16 v[110:113], v[174:177], v[198:201], v[110:113]
	v_mfma_f32_16x16x32_bf16 v[110:113], v[178:181], v[202:205], v[110:113]
	v_mfma_f32_16x16x32_bf16 v[122:125], v[190:193], v[198:201], v[122:125]
	v_mfma_f32_16x16x32_bf16 v[122:125], v[194:197], v[202:205], v[122:125]
	v_mfma_f32_16x16x32_bf16 v[126:129], v[182:185], v[198:201], v[126:129]
	v_mfma_f32_16x16x32_bf16 v[126:129], v[186:189], v[202:205], v[126:129]
	v_mfma_f32_16x16x32_bf16 v[118:121], v[182:185], v[228:231], v[118:121]
	v_mfma_f32_16x16x32_bf16 v[118:121], v[186:189], v[232:235], v[118:121]
	v_mfma_f32_16x16x32_bf16 v[98:101], v[190:193], v[228:231], v[98:101]
	v_mfma_f32_16x16x32_bf16 v[98:101], v[194:197], v[232:235], v[98:101]
	v_mfma_f32_16x16x32_bf16 v[102:105], v[174:177], v[228:231], v[102:105]
	v_mfma_f32_16x16x32_bf16 v[102:105], v[178:181], v[232:235], v[102:105]
	v_mfma_f32_16x16x32_bf16 v[106:109], v[142:145], v[228:231], v[106:109]
	v_mfma_f32_16x16x32_bf16 v[106:109], v[170:173], v[232:235], v[106:109]
	v_mfma_f32_16x16x32_bf16 v[94:97], v[142:145], v[236:239], v[94:97]
	v_mfma_f32_16x16x32_bf16 v[94:97], v[170:173], v[240:243], v[94:97]
	v_mfma_f32_16x16x32_bf16 v[86:89], v[174:177], v[236:239], v[86:89]
	v_mfma_f32_16x16x32_bf16 v[86:89], v[178:181], v[240:243], v[86:89]
	v_mfma_f32_16x16x32_bf16 v[82:85], v[190:193], v[236:239], v[82:85]
	v_mfma_f32_16x16x32_bf16 v[82:85], v[194:197], v[240:243], v[82:85]
	v_mfma_f32_16x16x32_bf16 v[90:93], v[182:185], v[236:239], v[90:93]
	v_mfma_f32_16x16x32_bf16 v[90:93], v[186:189], v[240:243], v[90:93]
	v_mfma_f32_16x16x32_bf16 v[74:77], v[182:185], v[244:247], v[74:77]
	v_mfma_f32_16x16x32_bf16 v[74:77], v[186:189], v[248:251], v[74:77]
	v_mfma_f32_16x16x32_bf16 v[66:69], v[190:193], v[244:247], v[66:69]
	v_mfma_f32_16x16x32_bf16 v[66:69], v[194:197], v[248:251], v[66:69]
	v_mfma_f32_16x16x32_bf16 v[70:73], v[174:177], v[244:247], v[70:73]
	v_mfma_f32_16x16x32_bf16 v[70:73], v[178:181], v[248:251], v[70:73]
	v_mfma_f32_16x16x32_bf16 v[78:81], v[142:145], v[244:247], v[78:81]
	v_mfma_f32_16x16x32_bf16 v[78:81], v[170:173], v[248:251], v[78:81]
	s_barrier
	s_or_b32 s53, s52, 0x80
	s_mov_b32 m0, s31
	ds_read_b128 v[198:201], v138 offset:49152
	buffer_load_dwordx4 v133, s[40:43], s53 offen lds
	s_add_i32 s52, s52, 0x80080
	s_mov_b32 m0, s33
	ds_read_b128 v[202:205], v138 offset:50176
	buffer_load_dwordx4 v135, s[40:43], s53 offen lds
	s_mov_b32 m0, s68
	ds_read_b128 v[228:231], v138 offset:51200
	buffer_load_dwordx4 v133, s[40:43], s52 offen lds
	s_mov_b32 m0, s69
	ds_read_b128 v[232:235], v138 offset:52224
	buffer_load_dwordx4 v135, s[40:43], s52 offen lds
	s_mov_b32 m0, s36
	ds_read_b128 v[236:239], v138 offset:53248
	buffer_load_dwordx4 v132, s[60:63], vcc_hi offen lds
	s_mov_b32 m0, s37
	ds_read_b128 v[240:243], v138 offset:54272
	buffer_load_dwordx4 v134, s[60:63], vcc_hi offen lds
	ds_read_b128 v[244:247], v138 offset:55296
	ds_read_b128 v[248:251], v138 offset:56320
	s_waitcnt vmcnt(8)
	s_waitcnt lgkmcnt(0)
	s_barrier
	v_mfma_f32_16x16x32_bf16 v[62:65], v[142:145], v[198:201], v[62:65]
	v_mfma_f32_16x16x32_bf16 v[62:65], v[170:173], v[202:205], v[62:65]
	v_mfma_f32_16x16x32_bf16 v[54:57], v[174:177], v[198:201], v[54:57]
	v_mfma_f32_16x16x32_bf16 v[54:57], v[178:181], v[202:205], v[54:57]
	v_mfma_f32_16x16x32_bf16 v[50:53], v[190:193], v[198:201], v[50:53]
	v_mfma_f32_16x16x32_bf16 v[50:53], v[194:197], v[202:205], v[50:53]
	v_mfma_f32_16x16x32_bf16 v[58:61], v[182:185], v[198:201], v[58:61]
	v_mfma_f32_16x16x32_bf16 v[58:61], v[186:189], v[202:205], v[58:61]
	v_mfma_f32_16x16x32_bf16 v[42:45], v[182:185], v[228:231], v[42:45]
	v_mfma_f32_16x16x32_bf16 v[42:45], v[186:189], v[232:235], v[42:45]
	v_mfma_f32_16x16x32_bf16 v[34:37], v[190:193], v[228:231], v[34:37]
	v_mfma_f32_16x16x32_bf16 v[34:37], v[194:197], v[232:235], v[34:37]
	v_mfma_f32_16x16x32_bf16 v[38:41], v[174:177], v[228:231], v[38:41]
	v_mfma_f32_16x16x32_bf16 v[38:41], v[178:181], v[232:235], v[38:41]
	v_mfma_f32_16x16x32_bf16 v[46:49], v[142:145], v[228:231], v[46:49]
	v_mfma_f32_16x16x32_bf16 v[46:49], v[170:173], v[232:235], v[46:49]
	v_mfma_f32_16x16x32_bf16 v[30:33], v[142:145], v[236:239], v[30:33]
	v_mfma_f32_16x16x32_bf16 v[30:33], v[170:173], v[240:243], v[30:33]
	v_mfma_f32_16x16x32_bf16 v[22:25], v[174:177], v[236:239], v[22:25]
	v_mfma_f32_16x16x32_bf16 v[22:25], v[178:181], v[240:243], v[22:25]
	v_mfma_f32_16x16x32_bf16 v[18:21], v[190:193], v[236:239], v[18:21]
	v_mfma_f32_16x16x32_bf16 v[18:21], v[194:197], v[240:243], v[18:21]
	v_mfma_f32_16x16x32_bf16 v[26:29], v[182:185], v[236:239], v[26:29]
	v_mfma_f32_16x16x32_bf16 v[26:29], v[186:189], v[240:243], v[26:29]
	v_mfma_f32_16x16x32_bf16 v[10:13], v[182:185], v[244:247], v[10:13]
	v_mfma_f32_16x16x32_bf16 v[10:13], v[186:189], v[248:251], v[10:13]
	v_mfma_f32_16x16x32_bf16 v[2:5], v[190:193], v[244:247], v[2:5]
	v_mfma_f32_16x16x32_bf16 v[2:5], v[194:197], v[248:251], v[2:5]
	v_mfma_f32_16x16x32_bf16 v[6:9], v[174:177], v[244:247], v[6:9]
	v_mfma_f32_16x16x32_bf16 v[6:9], v[178:181], v[248:251], v[6:9]
	v_mfma_f32_16x16x32_bf16 v[14:17], v[142:145], v[244:247], v[14:17]
	v_mfma_f32_16x16x32_bf16 v[14:17], v[170:173], v[248:251], v[14:17]
	s_barrier
	s_add_i32 vcc_lo, vcc_lo, 2
	s_addk_i32 s94, 0x100
	s_addk_i32 s95, 0x100
	s_cmp_gt_u32 vcc_lo, 29
.LBB0_304:
	ds_read_b128 v[142:145], v136
	ds_read_b128 v[170:173], v136 offset:1024
	ds_read_b128 v[174:177], v136 offset:2048
	ds_read_b128 v[178:181], v136 offset:3072
	ds_read_b128 v[182:185], v137
	ds_read_b128 v[186:189], v137 offset:1024
	ds_read_b128 v[190:193], v137 offset:2048
	ds_read_b128 v[194:197], v137 offset:3072
	s_add_i32 s42, s94, 0xfff80080
	s_cmp_eq_u32 vcc_lo, 28
	s_cselect_b32 s97, s8, s42
	s_cselect_b32 s52, s9, s95
	s_or_b32 vcc_hi, s97, 0x80
	s_mov_b32 m0, s72
	ds_read_b128 v[198:201], v138
	ds_read_b128 v[202:205], v138 offset:1024
	ds_read_b128 v[228:231], v138 offset:2048
	ds_read_b128 v[232:235], v138 offset:3072
	ds_read_b128 v[236:239], v138 offset:4096
	ds_read_b128 v[240:243], v138 offset:5120
	ds_read_b128 v[244:247], v138 offset:6144
	ds_read_b128 v[248:251], v138 offset:7168
	buffer_load_dwordx4 v132, s[60:63], s94 offen lds
	s_mov_b32 m0, s47
	s_nop 0
	buffer_load_dwordx4 v134, s[60:63], s94 offen lds
	s_waitcnt vmcnt(8)
	s_waitcnt lgkmcnt(0)
	s_barrier
	v_mfma_f32_16x16x32_bf16 v[114:117], v[142:145], v[198:201], v[114:117]
	v_mfma_f32_16x16x32_bf16 v[114:117], v[170:173], v[202:205], v[114:117]
	v_mfma_f32_16x16x32_bf16 v[110:113], v[174:177], v[198:201], v[110:113]
	v_mfma_f32_16x16x32_bf16 v[110:113], v[178:181], v[202:205], v[110:113]
	v_mfma_f32_16x16x32_bf16 v[122:125], v[190:193], v[198:201], v[122:125]
	v_mfma_f32_16x16x32_bf16 v[122:125], v[194:197], v[202:205], v[122:125]
	v_mfma_f32_16x16x32_bf16 v[126:129], v[182:185], v[198:201], v[126:129]
	v_mfma_f32_16x16x32_bf16 v[126:129], v[186:189], v[202:205], v[126:129]
	v_mfma_f32_16x16x32_bf16 v[118:121], v[182:185], v[228:231], v[118:121]
	v_mfma_f32_16x16x32_bf16 v[118:121], v[186:189], v[232:235], v[118:121]
	v_mfma_f32_16x16x32_bf16 v[98:101], v[190:193], v[228:231], v[98:101]
	v_mfma_f32_16x16x32_bf16 v[98:101], v[194:197], v[232:235], v[98:101]
	v_mfma_f32_16x16x32_bf16 v[102:105], v[174:177], v[228:231], v[102:105]
	v_mfma_f32_16x16x32_bf16 v[102:105], v[178:181], v[232:235], v[102:105]
	v_mfma_f32_16x16x32_bf16 v[106:109], v[142:145], v[228:231], v[106:109]
	v_mfma_f32_16x16x32_bf16 v[106:109], v[170:173], v[232:235], v[106:109]
	v_mfma_f32_16x16x32_bf16 v[94:97], v[142:145], v[236:239], v[94:97]
	v_mfma_f32_16x16x32_bf16 v[94:97], v[170:173], v[240:243], v[94:97]
	v_mfma_f32_16x16x32_bf16 v[86:89], v[174:177], v[236:239], v[86:89]
	v_mfma_f32_16x16x32_bf16 v[86:89], v[178:181], v[240:243], v[86:89]
	v_mfma_f32_16x16x32_bf16 v[82:85], v[190:193], v[236:239], v[82:85]
	v_mfma_f32_16x16x32_bf16 v[82:85], v[194:197], v[240:243], v[82:85]
	v_mfma_f32_16x16x32_bf16 v[90:93], v[182:185], v[236:239], v[90:93]
	v_mfma_f32_16x16x32_bf16 v[90:93], v[186:189], v[240:243], v[90:93]
	v_mfma_f32_16x16x32_bf16 v[74:77], v[182:185], v[244:247], v[74:77]
	v_mfma_f32_16x16x32_bf16 v[74:77], v[186:189], v[248:251], v[74:77]
	v_mfma_f32_16x16x32_bf16 v[66:69], v[190:193], v[244:247], v[66:69]
	v_mfma_f32_16x16x32_bf16 v[66:69], v[194:197], v[248:251], v[66:69]
	v_mfma_f32_16x16x32_bf16 v[70:73], v[174:177], v[244:247], v[70:73]
	v_mfma_f32_16x16x32_bf16 v[70:73], v[178:181], v[248:251], v[70:73]
	v_mfma_f32_16x16x32_bf16 v[78:81], v[142:145], v[244:247], v[78:81]
	v_mfma_f32_16x16x32_bf16 v[78:81], v[170:173], v[248:251], v[78:81]
	s_barrier
	s_mov_b32 s42, s62
	s_mov_b32 s43, s63
	s_mov_b32 m0, s13
	ds_read_b128 v[198:201], v138 offset:16384
	buffer_load_dwordx4 v133, s[40:43], s52 offen lds
	s_add_i32 s96, s52, 0x80000
	s_mov_b32 m0, s14
	ds_read_b128 v[202:205], v138 offset:17408
	buffer_load_dwordx4 v135, s[40:43], s52 offen lds
	s_mov_b32 m0, s15
	ds_read_b128 v[228:231], v138 offset:18432
	buffer_load_dwordx4 v133, s[40:43], s96 offen lds
	s_mov_b32 m0, s16
	ds_read_b128 v[232:235], v138 offset:19456
	buffer_load_dwordx4 v135, s[40:43], s96 offen lds
	s_mov_b32 m0, s2
	ds_read_b128 v[236:239], v138 offset:20480
	buffer_load_dwordx4 v132, s[60:63], s97 offen lds
	s_mov_b32 m0, s21
	ds_read_b128 v[240:243], v138 offset:21504
	buffer_load_dwordx4 v134, s[60:63], s97 offen lds
	ds_read_b128 v[244:247], v138 offset:22528
	ds_read_b128 v[248:251], v138 offset:23552
	s_waitcnt vmcnt(8)
	s_waitcnt lgkmcnt(0)
	s_barrier
	v_mfma_f32_16x16x32_bf16 v[62:65], v[142:145], v[198:201], v[62:65]
	v_mfma_f32_16x16x32_bf16 v[62:65], v[170:173], v[202:205], v[62:65]
	v_mfma_f32_16x16x32_bf16 v[54:57], v[174:177], v[198:201], v[54:57]
	v_mfma_f32_16x16x32_bf16 v[54:57], v[178:181], v[202:205], v[54:57]
	v_mfma_f32_16x16x32_bf16 v[50:53], v[190:193], v[198:201], v[50:53]
	v_mfma_f32_16x16x32_bf16 v[50:53], v[194:197], v[202:205], v[50:53]
	v_mfma_f32_16x16x32_bf16 v[58:61], v[182:185], v[198:201], v[58:61]
	v_mfma_f32_16x16x32_bf16 v[58:61], v[186:189], v[202:205], v[58:61]
	v_mfma_f32_16x16x32_bf16 v[42:45], v[182:185], v[228:231], v[42:45]
	v_mfma_f32_16x16x32_bf16 v[42:45], v[186:189], v[232:235], v[42:45]
	v_mfma_f32_16x16x32_bf16 v[34:37], v[190:193], v[228:231], v[34:37]
	v_mfma_f32_16x16x32_bf16 v[34:37], v[194:197], v[232:235], v[34:37]
	v_mfma_f32_16x16x32_bf16 v[38:41], v[174:177], v[228:231], v[38:41]
	v_mfma_f32_16x16x32_bf16 v[38:41], v[178:181], v[232:235], v[38:41]
	v_mfma_f32_16x16x32_bf16 v[46:49], v[142:145], v[228:231], v[46:49]
	v_mfma_f32_16x16x32_bf16 v[46:49], v[170:173], v[232:235], v[46:49]
	v_mfma_f32_16x16x32_bf16 v[30:33], v[142:145], v[236:239], v[30:33]
	v_mfma_f32_16x16x32_bf16 v[30:33], v[170:173], v[240:243], v[30:33]
	v_mfma_f32_16x16x32_bf16 v[22:25], v[174:177], v[236:239], v[22:25]
	v_mfma_f32_16x16x32_bf16 v[22:25], v[178:181], v[240:243], v[22:25]
	v_mfma_f32_16x16x32_bf16 v[18:21], v[190:193], v[236:239], v[18:21]
	v_mfma_f32_16x16x32_bf16 v[18:21], v[194:197], v[240:243], v[18:21]
	v_mfma_f32_16x16x32_bf16 v[26:29], v[182:185], v[236:239], v[26:29]
	v_mfma_f32_16x16x32_bf16 v[26:29], v[186:189], v[240:243], v[26:29]
	v_mfma_f32_16x16x32_bf16 v[10:13], v[182:185], v[244:247], v[10:13]
	v_mfma_f32_16x16x32_bf16 v[10:13], v[186:189], v[248:251], v[10:13]
	v_mfma_f32_16x16x32_bf16 v[2:5], v[190:193], v[244:247], v[2:5]
	v_mfma_f32_16x16x32_bf16 v[2:5], v[194:197], v[248:251], v[2:5]
	v_mfma_f32_16x16x32_bf16 v[6:9], v[174:177], v[244:247], v[6:9]
	v_mfma_f32_16x16x32_bf16 v[6:9], v[178:181], v[248:251], v[6:9]
	v_mfma_f32_16x16x32_bf16 v[14:17], v[142:145], v[244:247], v[14:17]
	v_mfma_f32_16x16x32_bf16 v[14:17], v[170:173], v[248:251], v[14:17]
	s_barrier
	ds_read_b128 v[142:145], v139
	ds_read_b128 v[170:173], v139 offset:1024
	ds_read_b128 v[174:177], v139 offset:2048
	ds_read_b128 v[178:181], v139 offset:3072
	ds_read_b128 v[182:185], v140
	ds_read_b128 v[186:189], v140 offset:1024
	ds_read_b128 v[190:193], v140 offset:2048
	ds_read_b128 v[194:197], v140 offset:3072
	s_add_i32 s97, s97, 0x80000
	s_mov_b32 m0, s23
	ds_read_b128 v[198:201], v138 offset:32768
	ds_read_b128 v[202:205], v138 offset:33792
	ds_read_b128 v[228:231], v138 offset:34816
	ds_read_b128 v[232:235], v138 offset:35840
	ds_read_b128 v[236:239], v138 offset:36864
	ds_read_b128 v[240:243], v138 offset:37888
	ds_read_b128 v[244:247], v138 offset:38912
	ds_read_b128 v[248:251], v138 offset:39936
	buffer_load_dwordx4 v132, s[60:63], s97 offen lds
	s_mov_b32 m0, s24
	s_nop 0
	buffer_load_dwordx4 v134, s[60:63], s97 offen lds
	s_waitcnt vmcnt(8)
	s_waitcnt lgkmcnt(0)
	s_barrier
	v_mfma_f32_16x16x32_bf16 v[114:117], v[142:145], v[198:201], v[114:117]
	v_mfma_f32_16x16x32_bf16 v[114:117], v[170:173], v[202:205], v[114:117]
	v_mfma_f32_16x16x32_bf16 v[110:113], v[174:177], v[198:201], v[110:113]
	v_mfma_f32_16x16x32_bf16 v[110:113], v[178:181], v[202:205], v[110:113]
	v_mfma_f32_16x16x32_bf16 v[122:125], v[190:193], v[198:201], v[122:125]
	v_mfma_f32_16x16x32_bf16 v[122:125], v[194:197], v[202:205], v[122:125]
	v_mfma_f32_16x16x32_bf16 v[126:129], v[182:185], v[198:201], v[126:129]
	v_mfma_f32_16x16x32_bf16 v[126:129], v[186:189], v[202:205], v[126:129]
	v_mfma_f32_16x16x32_bf16 v[118:121], v[182:185], v[228:231], v[118:121]
	v_mfma_f32_16x16x32_bf16 v[118:121], v[186:189], v[232:235], v[118:121]
	v_mfma_f32_16x16x32_bf16 v[98:101], v[190:193], v[228:231], v[98:101]
	v_mfma_f32_16x16x32_bf16 v[98:101], v[194:197], v[232:235], v[98:101]
	v_mfma_f32_16x16x32_bf16 v[102:105], v[174:177], v[228:231], v[102:105]
	v_mfma_f32_16x16x32_bf16 v[102:105], v[178:181], v[232:235], v[102:105]
	v_mfma_f32_16x16x32_bf16 v[106:109], v[142:145], v[228:231], v[106:109]
	v_mfma_f32_16x16x32_bf16 v[106:109], v[170:173], v[232:235], v[106:109]
	v_mfma_f32_16x16x32_bf16 v[94:97], v[142:145], v[236:239], v[94:97]
	v_mfma_f32_16x16x32_bf16 v[94:97], v[170:173], v[240:243], v[94:97]
	v_mfma_f32_16x16x32_bf16 v[86:89], v[174:177], v[236:239], v[86:89]
	v_mfma_f32_16x16x32_bf16 v[86:89], v[178:181], v[240:243], v[86:89]
	v_mfma_f32_16x16x32_bf16 v[82:85], v[190:193], v[236:239], v[82:85]
	v_mfma_f32_16x16x32_bf16 v[82:85], v[194:197], v[240:243], v[82:85]
	v_mfma_f32_16x16x32_bf16 v[90:93], v[182:185], v[236:239], v[90:93]
	v_mfma_f32_16x16x32_bf16 v[90:93], v[186:189], v[240:243], v[90:93]
	v_mfma_f32_16x16x32_bf16 v[74:77], v[182:185], v[244:247], v[74:77]
	v_mfma_f32_16x16x32_bf16 v[74:77], v[186:189], v[248:251], v[74:77]
	v_mfma_f32_16x16x32_bf16 v[66:69], v[190:193], v[244:247], v[66:69]
	v_mfma_f32_16x16x32_bf16 v[66:69], v[194:197], v[248:251], v[66:69]
	v_mfma_f32_16x16x32_bf16 v[70:73], v[174:177], v[244:247], v[70:73]
	v_mfma_f32_16x16x32_bf16 v[70:73], v[178:181], v[248:251], v[70:73]
	v_mfma_f32_16x16x32_bf16 v[78:81], v[142:145], v[244:247], v[78:81]
	v_mfma_f32_16x16x32_bf16 v[78:81], v[170:173], v[248:251], v[78:81]
	s_barrier
	s_or_b32 s53, s52, 0x80
	s_mov_b32 m0, s31
	ds_read_b128 v[198:201], v138 offset:49152
	buffer_load_dwordx4 v133, s[40:43], s53 offen lds
	s_add_i32 s52, s52, 0x80080
	s_mov_b32 m0, s33
	ds_read_b128 v[202:205], v138 offset:50176
	buffer_load_dwordx4 v135, s[40:43], s53 offen lds
	s_mov_b32 m0, s68
	ds_read_b128 v[228:231], v138 offset:51200
	buffer_load_dwordx4 v133, s[40:43], s52 offen lds
	s_mov_b32 m0, s69
	ds_read_b128 v[232:235], v138 offset:52224
	buffer_load_dwordx4 v135, s[40:43], s52 offen lds
	s_mov_b32 m0, s36
	ds_read_b128 v[236:239], v138 offset:53248
	buffer_load_dwordx4 v132, s[60:63], vcc_hi offen lds
	s_mov_b32 m0, s37
	ds_read_b128 v[240:243], v138 offset:54272
	buffer_load_dwordx4 v134, s[60:63], vcc_hi offen lds
	ds_read_b128 v[244:247], v138 offset:55296
	ds_read_b128 v[248:251], v138 offset:56320
	s_waitcnt vmcnt(8)
	s_waitcnt lgkmcnt(0)
	s_barrier
	v_mfma_f32_16x16x32_bf16 v[62:65], v[142:145], v[198:201], v[62:65]
	v_mfma_f32_16x16x32_bf16 v[62:65], v[170:173], v[202:205], v[62:65]
	v_mfma_f32_16x16x32_bf16 v[54:57], v[174:177], v[198:201], v[54:57]
	v_mfma_f32_16x16x32_bf16 v[54:57], v[178:181], v[202:205], v[54:57]
	v_mfma_f32_16x16x32_bf16 v[50:53], v[190:193], v[198:201], v[50:53]
	v_mfma_f32_16x16x32_bf16 v[50:53], v[194:197], v[202:205], v[50:53]
	v_mfma_f32_16x16x32_bf16 v[58:61], v[182:185], v[198:201], v[58:61]
	v_mfma_f32_16x16x32_bf16 v[58:61], v[186:189], v[202:205], v[58:61]
	v_mfma_f32_16x16x32_bf16 v[42:45], v[182:185], v[228:231], v[42:45]
	v_mfma_f32_16x16x32_bf16 v[42:45], v[186:189], v[232:235], v[42:45]
	v_mfma_f32_16x16x32_bf16 v[34:37], v[190:193], v[228:231], v[34:37]
	v_mfma_f32_16x16x32_bf16 v[34:37], v[194:197], v[232:235], v[34:37]
	v_mfma_f32_16x16x32_bf16 v[38:41], v[174:177], v[228:231], v[38:41]
	v_mfma_f32_16x16x32_bf16 v[38:41], v[178:181], v[232:235], v[38:41]
	v_mfma_f32_16x16x32_bf16 v[46:49], v[142:145], v[228:231], v[46:49]
	v_mfma_f32_16x16x32_bf16 v[46:49], v[170:173], v[232:235], v[46:49]
	v_mfma_f32_16x16x32_bf16 v[30:33], v[142:145], v[236:239], v[30:33]
	v_mfma_f32_16x16x32_bf16 v[30:33], v[170:173], v[240:243], v[30:33]
	v_mfma_f32_16x16x32_bf16 v[22:25], v[174:177], v[236:239], v[22:25]
	v_mfma_f32_16x16x32_bf16 v[22:25], v[178:181], v[240:243], v[22:25]
	v_mfma_f32_16x16x32_bf16 v[18:21], v[190:193], v[236:239], v[18:21]
	v_mfma_f32_16x16x32_bf16 v[18:21], v[194:197], v[240:243], v[18:21]
	v_mfma_f32_16x16x32_bf16 v[26:29], v[182:185], v[236:239], v[26:29]
	v_mfma_f32_16x16x32_bf16 v[26:29], v[186:189], v[240:243], v[26:29]
	v_mfma_f32_16x16x32_bf16 v[10:13], v[182:185], v[244:247], v[10:13]
	v_mfma_f32_16x16x32_bf16 v[10:13], v[186:189], v[248:251], v[10:13]
	v_mfma_f32_16x16x32_bf16 v[2:5], v[190:193], v[244:247], v[2:5]
	v_mfma_f32_16x16x32_bf16 v[2:5], v[194:197], v[248:251], v[2:5]
	v_mfma_f32_16x16x32_bf16 v[6:9], v[174:177], v[244:247], v[6:9]
	v_mfma_f32_16x16x32_bf16 v[6:9], v[178:181], v[248:251], v[6:9]
	v_mfma_f32_16x16x32_bf16 v[14:17], v[142:145], v[244:247], v[14:17]
	v_mfma_f32_16x16x32_bf16 v[14:17], v[170:173], v[248:251], v[14:17]
	s_barrier
	s_add_i32 vcc_lo, vcc_lo, 2
	s_addk_i32 s94, 0x100
	s_addk_i32 s95, 0x100
	s_cmp_gt_u32 vcc_lo, 29
	s_cbranch_scc0 .LBB0_304
	s_and_b64 vcc, exec, s[48:49]
	s_cbranch_vccz .LBB0_307
	s_barrier

.LBB0_579:
	s_mul_i32 s73, s72, 0x2c0000
	s_and_b64 s[8:9], s[42:43], exec
	s_mul_i32 s84, s71, 0x2c0000
	s_cselect_b32 s8, s73, s21
	s_cselect_b32 s9, s84, s13
	s_addk_i32 s13, 0x100
	s_add_i32 s21, s21, 0xc000
	s_mov_b32 s22, -2
	s_waitcnt lgkmcnt(0)
	v_add_u32_e32 v154, 0x10000, v140
	ds_read_b128 v[132:135], v154
	ds_read_b128 v[142:145], v154 offset:1024
	ds_read_b128 v[170:173], v154 offset:2048
	ds_read_b128 v[174:177], v154 offset:3072
	v_add_u32_e32 v154, 0x14000, v140
	ds_read_b128 v[178:181], v154
	ds_read_b128 v[182:185], v154 offset:1024
	ds_read_b128 v[186:189], v154 offset:2048
	ds_read_b128 v[190:193], v154 offset:3072
	s_add_i32 s23, s21, 0x4000
	s_cmpk_eq_i32 s22, 0x54
	s_cselect_b32 s27, s8, s23
	s_cselect_b32 s26, s9, s13
	s_or_b32 s23, s27, 0x8000
	s_mov_b32 m0, s68
	ds_read_b128 v[194:197], v141
	ds_read_b128 v[198:201], v141 offset:1024
	ds_read_b128 v[202:205], v141 offset:2048
	ds_read_b128 v[228:231], v141 offset:3072
	ds_read_b128 v[232:235], v141 offset:4096
	ds_read_b128 v[236:239], v141 offset:5120
	ds_read_b128 v[240:243], v141 offset:6144
	ds_read_b128 v[244:247], v141 offset:7168
	buffer_load_dwordx4 v136, s[60:63], s21 offen lds
	s_mov_b32 m0, s70
	s_nop 0
	buffer_load_dwordx4 v138, s[60:63], s21 offen lds
	s_waitcnt vmcnt(8)
	s_waitcnt lgkmcnt(0)
	s_barrier
	v_mfma_f32_16x16x32_bf16 v[126:129], v[132:135], v[194:197], 0
	v_mfma_f32_16x16x32_bf16 v[126:129], v[142:145], v[198:201], v[126:129]
	v_mfma_f32_16x16x32_bf16 v[106:109], v[170:173], v[194:197], 0
	v_mfma_f32_16x16x32_bf16 v[106:109], v[174:177], v[198:201], v[106:109]
	v_mfma_f32_16x16x32_bf16 v[110:113], v[186:189], v[194:197], 0
	v_mfma_f32_16x16x32_bf16 v[110:113], v[190:193], v[198:201], v[110:113]
	v_mfma_f32_16x16x32_bf16 v[122:125], v[178:181], v[194:197], 0
	v_mfma_f32_16x16x32_bf16 v[122:125], v[182:185], v[198:201], v[122:125]
	v_mfma_f32_16x16x32_bf16 v[102:105], v[178:181], v[202:205], 0
	v_mfma_f32_16x16x32_bf16 v[102:105], v[182:185], v[228:231], v[102:105]
	v_mfma_f32_16x16x32_bf16 v[98:101], v[186:189], v[202:205], 0
	v_mfma_f32_16x16x32_bf16 v[98:101], v[190:193], v[228:231], v[98:101]
	v_mfma_f32_16x16x32_bf16 v[114:117], v[170:173], v[202:205], 0
	v_mfma_f32_16x16x32_bf16 v[114:117], v[174:177], v[228:231], v[114:117]
	v_mfma_f32_16x16x32_bf16 v[118:121], v[132:135], v[202:205], 0
	v_mfma_f32_16x16x32_bf16 v[118:121], v[142:145], v[228:231], v[118:121]
	v_mfma_f32_16x16x32_bf16 v[94:97], v[132:135], v[232:235], 0
	v_mfma_f32_16x16x32_bf16 v[94:97], v[142:145], v[236:239], v[94:97]
	v_mfma_f32_16x16x32_bf16 v[90:93], v[170:173], v[232:235], 0
	v_mfma_f32_16x16x32_bf16 v[90:93], v[174:177], v[236:239], v[90:93]
	v_mfma_f32_16x16x32_bf16 v[82:85], v[186:189], v[232:235], 0
	v_mfma_f32_16x16x32_bf16 v[82:85], v[190:193], v[236:239], v[82:85]
	v_mfma_f32_16x16x32_bf16 v[86:89], v[178:181], v[232:235], 0
	v_mfma_f32_16x16x32_bf16 v[86:89], v[182:185], v[236:239], v[86:89]
	v_mfma_f32_16x16x32_bf16 v[70:73], v[178:181], v[240:243], 0
	v_mfma_f32_16x16x32_bf16 v[70:73], v[182:185], v[244:247], v[70:73]
	v_mfma_f32_16x16x32_bf16 v[66:69], v[186:189], v[240:243], 0
	v_mfma_f32_16x16x32_bf16 v[66:69], v[190:193], v[244:247], v[66:69]
	v_mfma_f32_16x16x32_bf16 v[74:77], v[170:173], v[240:243], 0
	v_mfma_f32_16x16x32_bf16 v[74:77], v[174:177], v[244:247], v[74:77]
	v_mfma_f32_16x16x32_bf16 v[78:81], v[132:135], v[240:243], 0
	v_mfma_f32_16x16x32_bf16 v[78:81], v[142:145], v[244:247], v[78:81]
	s_barrier
	s_mov_b32 s46, s62
	s_mov_b32 s47, s63
	s_mov_b32 m0, s15
	ds_read_b128 v[194:197], v141 offset:16384
	buffer_load_dwordx4 v137, s[44:47], s26 offen lds
	s_add_i32 s52, s26, 0x160000
	s_mov_b32 m0, s16
	ds_read_b128 v[198:201], v141 offset:17408
	buffer_load_dwordx4 v139, s[44:47], s26 offen lds
	s_mov_b32 m0, s18
	ds_read_b128 v[202:205], v141 offset:18432
	buffer_load_dwordx4 v137, s[44:47], s52 offen lds
	s_mov_b32 m0, s19
	ds_read_b128 v[228:231], v141 offset:19456
	buffer_load_dwordx4 v139, s[44:47], s52 offen lds
	s_mov_b32 m0, s14
	ds_read_b128 v[232:235], v141 offset:20480
	buffer_load_dwordx4 v136, s[60:63], s27 offen lds
	s_mov_b32 m0, s24
	ds_read_b128 v[236:239], v141 offset:21504
	buffer_load_dwordx4 v138, s[60:63], s27 offen lds
	ds_read_b128 v[240:243], v141 offset:22528
	ds_read_b128 v[244:247], v141 offset:23552
	s_waitcnt vmcnt(8)
	s_waitcnt lgkmcnt(0)
	s_barrier
	v_mfma_f32_16x16x32_bf16 v[62:65], v[132:135], v[194:197], 0
	v_mfma_f32_16x16x32_bf16 v[62:65], v[142:145], v[198:201], v[62:65]
	v_mfma_f32_16x16x32_bf16 v[58:61], v[170:173], v[194:197], 0
	v_mfma_f32_16x16x32_bf16 v[58:61], v[174:177], v[198:201], v[58:61]
	v_mfma_f32_16x16x32_bf16 v[50:53], v[186:189], v[194:197], 0
	v_mfma_f32_16x16x32_bf16 v[50:53], v[190:193], v[198:201], v[50:53]
	v_mfma_f32_16x16x32_bf16 v[54:57], v[178:181], v[194:197], 0
	v_mfma_f32_16x16x32_bf16 v[54:57], v[182:185], v[198:201], v[54:57]
	v_mfma_f32_16x16x32_bf16 v[38:41], v[178:181], v[202:205], 0
	v_mfma_f32_16x16x32_bf16 v[38:41], v[182:185], v[228:231], v[38:41]
	v_mfma_f32_16x16x32_bf16 v[34:37], v[186:189], v[202:205], 0
	v_mfma_f32_16x16x32_bf16 v[34:37], v[190:193], v[228:231], v[34:37]
	v_mfma_f32_16x16x32_bf16 v[42:45], v[170:173], v[202:205], 0
	v_mfma_f32_16x16x32_bf16 v[42:45], v[174:177], v[228:231], v[42:45]
	v_mfma_f32_16x16x32_bf16 v[46:49], v[132:135], v[202:205], 0
	v_mfma_f32_16x16x32_bf16 v[46:49], v[142:145], v[228:231], v[46:49]
	v_mfma_f32_16x16x32_bf16 v[30:33], v[132:135], v[232:235], 0
	v_mfma_f32_16x16x32_bf16 v[30:33], v[142:145], v[236:239], v[30:33]
	v_mfma_f32_16x16x32_bf16 v[26:29], v[170:173], v[232:235], 0
	v_mfma_f32_16x16x32_bf16 v[26:29], v[174:177], v[236:239], v[26:29]
	v_mfma_f32_16x16x32_bf16 v[18:21], v[186:189], v[232:235], 0
	v_mfma_f32_16x16x32_bf16 v[18:21], v[190:193], v[236:239], v[18:21]
	v_mfma_f32_16x16x32_bf16 v[22:25], v[178:181], v[232:235], 0
	v_mfma_f32_16x16x32_bf16 v[22:25], v[182:185], v[236:239], v[22:25]
	v_mfma_f32_16x16x32_bf16 v[6:9], v[178:181], v[240:243], 0
	v_mfma_f32_16x16x32_bf16 v[6:9], v[182:185], v[244:247], v[6:9]
	v_mfma_f32_16x16x32_bf16 v[2:5], v[186:189], v[240:243], 0
	v_mfma_f32_16x16x32_bf16 v[2:5], v[190:193], v[244:247], v[2:5]
	v_mfma_f32_16x16x32_bf16 v[10:13], v[170:173], v[240:243], 0
	v_mfma_f32_16x16x32_bf16 v[10:13], v[174:177], v[244:247], v[10:13]
	v_mfma_f32_16x16x32_bf16 v[14:17], v[132:135], v[240:243], 0
	v_mfma_f32_16x16x32_bf16 v[14:17], v[142:145], v[244:247], v[14:17]
	s_barrier
	v_add_u32_e32 v154, 0x18000, v140
	ds_read_b128 v[132:135], v154
	ds_read_b128 v[142:145], v154 offset:1024
	ds_read_b128 v[170:173], v154 offset:2048
	ds_read_b128 v[174:177], v154 offset:3072
	v_add_u32_e32 v154, 0x1c000, v140
	ds_read_b128 v[178:181], v154
	ds_read_b128 v[182:185], v154 offset:1024
	ds_read_b128 v[186:189], v154 offset:2048
	ds_read_b128 v[190:193], v154 offset:3072
	s_bitset1_b32 s27, 14
	s_mov_b32 m0, s25
	ds_read_b128 v[194:197], v141 offset:32768
	ds_read_b128 v[198:201], v141 offset:33792
	ds_read_b128 v[202:205], v141 offset:34816
	ds_read_b128 v[228:231], v141 offset:35840
	ds_read_b128 v[232:235], v141 offset:36864
	ds_read_b128 v[236:239], v141 offset:37888
	ds_read_b128 v[240:243], v141 offset:38912
	ds_read_b128 v[244:247], v141 offset:39936
	buffer_load_dwordx4 v136, s[60:63], s27 offen lds
	s_mov_b32 m0, s30
	s_nop 0
	buffer_load_dwordx4 v138, s[60:63], s27 offen lds
	s_waitcnt vmcnt(8)
	s_waitcnt lgkmcnt(0)
	s_barrier
	v_mfma_f32_16x16x32_bf16 v[126:129], v[132:135], v[194:197], v[126:129]
	v_mfma_f32_16x16x32_bf16 v[126:129], v[142:145], v[198:201], v[126:129]
	v_mfma_f32_16x16x32_bf16 v[106:109], v[170:173], v[194:197], v[106:109]
	v_mfma_f32_16x16x32_bf16 v[106:109], v[174:177], v[198:201], v[106:109]
	v_mfma_f32_16x16x32_bf16 v[110:113], v[186:189], v[194:197], v[110:113]
	v_mfma_f32_16x16x32_bf16 v[110:113], v[190:193], v[198:201], v[110:113]
	v_mfma_f32_16x16x32_bf16 v[122:125], v[178:181], v[194:197], v[122:125]
	v_mfma_f32_16x16x32_bf16 v[122:125], v[182:185], v[198:201], v[122:125]
	v_mfma_f32_16x16x32_bf16 v[102:105], v[178:181], v[202:205], v[102:105]
	v_mfma_f32_16x16x32_bf16 v[102:105], v[182:185], v[228:231], v[102:105]
	v_mfma_f32_16x16x32_bf16 v[98:101], v[186:189], v[202:205], v[98:101]
	v_mfma_f32_16x16x32_bf16 v[98:101], v[190:193], v[228:231], v[98:101]
	v_mfma_f32_16x16x32_bf16 v[114:117], v[170:173], v[202:205], v[114:117]
	v_mfma_f32_16x16x32_bf16 v[114:117], v[174:177], v[228:231], v[114:117]
	v_mfma_f32_16x16x32_bf16 v[118:121], v[132:135], v[202:205], v[118:121]
	v_mfma_f32_16x16x32_bf16 v[118:121], v[142:145], v[228:231], v[118:121]
	v_mfma_f32_16x16x32_bf16 v[94:97], v[132:135], v[232:235], v[94:97]
	v_mfma_f32_16x16x32_bf16 v[94:97], v[142:145], v[236:239], v[94:97]
	v_mfma_f32_16x16x32_bf16 v[90:93], v[170:173], v[232:235], v[90:93]
	v_mfma_f32_16x16x32_bf16 v[90:93], v[174:177], v[236:239], v[90:93]
	v_mfma_f32_16x16x32_bf16 v[82:85], v[186:189], v[232:235], v[82:85]
	v_mfma_f32_16x16x32_bf16 v[82:85], v[190:193], v[236:239], v[82:85]
	v_mfma_f32_16x16x32_bf16 v[86:89], v[178:181], v[232:235], v[86:89]
	v_mfma_f32_16x16x32_bf16 v[86:89], v[182:185], v[236:239], v[86:89]
	v_mfma_f32_16x16x32_bf16 v[70:73], v[178:181], v[240:243], v[70:73]
	v_mfma_f32_16x16x32_bf16 v[70:73], v[182:185], v[244:247], v[70:73]
	v_mfma_f32_16x16x32_bf16 v[66:69], v[186:189], v[240:243], v[66:69]
	v_mfma_f32_16x16x32_bf16 v[66:69], v[190:193], v[244:247], v[66:69]
	v_mfma_f32_16x16x32_bf16 v[74:77], v[170:173], v[240:243], v[74:77]
	v_mfma_f32_16x16x32_bf16 v[74:77], v[174:177], v[244:247], v[74:77]
	v_mfma_f32_16x16x32_bf16 v[78:81], v[132:135], v[240:243], v[78:81]
	v_mfma_f32_16x16x32_bf16 v[78:81], v[142:145], v[244:247], v[78:81]
	s_barrier
	s_or_b32 s27, s26, 0x80
	s_mov_b32 m0, s36
	ds_read_b128 v[194:197], v141 offset:49152
	buffer_load_dwordx4 v137, s[44:47], s27 offen lds
	s_add_i32 s26, s26, 0x160080
	s_mov_b32 m0, s37
	ds_read_b128 v[198:201], v141 offset:50176
	buffer_load_dwordx4 v139, s[44:47], s27 offen lds
	s_mov_b32 m0, s66
	ds_read_b128 v[202:205], v141 offset:51200
	buffer_load_dwordx4 v137, s[44:47], s26 offen lds
	s_mov_b32 m0, s67
	ds_read_b128 v[228:231], v141 offset:52224
	buffer_load_dwordx4 v139, s[44:47], s26 offen lds
	s_mov_b32 m0, s48
	ds_read_b128 v[232:235], v141 offset:53248
	buffer_load_dwordx4 v136, s[60:63], s23 offen lds
	s_mov_b32 m0, s49
	ds_read_b128 v[236:239], v141 offset:54272
	buffer_load_dwordx4 v138, s[60:63], s23 offen lds
	ds_read_b128 v[240:243], v141 offset:55296
	ds_read_b128 v[244:247], v141 offset:56320
	s_waitcnt vmcnt(8)
	s_waitcnt lgkmcnt(0)
	s_barrier
	v_mfma_f32_16x16x32_bf16 v[62:65], v[132:135], v[194:197], v[62:65]
	v_mfma_f32_16x16x32_bf16 v[62:65], v[142:145], v[198:201], v[62:65]
	v_mfma_f32_16x16x32_bf16 v[58:61], v[170:173], v[194:197], v[58:61]
	v_mfma_f32_16x16x32_bf16 v[58:61], v[174:177], v[198:201], v[58:61]
	v_mfma_f32_16x16x32_bf16 v[50:53], v[186:189], v[194:197], v[50:53]
	v_mfma_f32_16x16x32_bf16 v[50:53], v[190:193], v[198:201], v[50:53]
	v_mfma_f32_16x16x32_bf16 v[54:57], v[178:181], v[194:197], v[54:57]
	v_mfma_f32_16x16x32_bf16 v[54:57], v[182:185], v[198:201], v[54:57]
	v_mfma_f32_16x16x32_bf16 v[38:41], v[178:181], v[202:205], v[38:41]
	v_mfma_f32_16x16x32_bf16 v[38:41], v[182:185], v[228:231], v[38:41]
	v_mfma_f32_16x16x32_bf16 v[34:37], v[186:189], v[202:205], v[34:37]
	v_mfma_f32_16x16x32_bf16 v[34:37], v[190:193], v[228:231], v[34:37]
	v_mfma_f32_16x16x32_bf16 v[42:45], v[170:173], v[202:205], v[42:45]
	v_mfma_f32_16x16x32_bf16 v[42:45], v[174:177], v[228:231], v[42:45]
	v_mfma_f32_16x16x32_bf16 v[46:49], v[132:135], v[202:205], v[46:49]
	v_mfma_f32_16x16x32_bf16 v[46:49], v[142:145], v[228:231], v[46:49]
	v_mfma_f32_16x16x32_bf16 v[30:33], v[132:135], v[232:235], v[30:33]
	v_mfma_f32_16x16x32_bf16 v[30:33], v[142:145], v[236:239], v[30:33]
	v_mfma_f32_16x16x32_bf16 v[26:29], v[170:173], v[232:235], v[26:29]
	v_mfma_f32_16x16x32_bf16 v[26:29], v[174:177], v[236:239], v[26:29]
	v_mfma_f32_16x16x32_bf16 v[18:21], v[186:189], v[232:235], v[18:21]
	v_mfma_f32_16x16x32_bf16 v[18:21], v[190:193], v[236:239], v[18:21]
	v_mfma_f32_16x16x32_bf16 v[22:25], v[178:181], v[232:235], v[22:25]
	v_mfma_f32_16x16x32_bf16 v[22:25], v[182:185], v[236:239], v[22:25]
	v_mfma_f32_16x16x32_bf16 v[6:9], v[178:181], v[240:243], v[6:9]
	v_mfma_f32_16x16x32_bf16 v[6:9], v[182:185], v[244:247], v[6:9]
	v_mfma_f32_16x16x32_bf16 v[2:5], v[186:189], v[240:243], v[2:5]
	v_mfma_f32_16x16x32_bf16 v[2:5], v[190:193], v[244:247], v[2:5]
	v_mfma_f32_16x16x32_bf16 v[10:13], v[170:173], v[240:243], v[10:13]
	v_mfma_f32_16x16x32_bf16 v[10:13], v[174:177], v[244:247], v[10:13]
	v_mfma_f32_16x16x32_bf16 v[14:17], v[132:135], v[240:243], v[14:17]
	v_mfma_f32_16x16x32_bf16 v[14:17], v[142:145], v[244:247], v[14:17]
	s_barrier
	s_addk_i32 s13, 0x100
	s_add_i32 s22, s22, 2
	s_add_i32 s21, s21, 0x10000
	s_cmpk_gt_u32 s22, 0x55
.LBB0_580:
	v_add_u32_e32 v154, 0x10000, v140
	ds_read_b128 v[132:135], v154
	ds_read_b128 v[142:145], v154 offset:1024
	ds_read_b128 v[170:173], v154 offset:2048
	ds_read_b128 v[174:177], v154 offset:3072
	v_add_u32_e32 v154, 0x14000, v140
	ds_read_b128 v[178:181], v154
	ds_read_b128 v[182:185], v154 offset:1024
	ds_read_b128 v[186:189], v154 offset:2048
	ds_read_b128 v[190:193], v154 offset:3072
	s_add_i32 s23, s21, 0x4000
	s_cmpk_eq_i32 s22, 0x54
	s_cselect_b32 s27, s8, s23
	s_cselect_b32 s26, s9, s13
	s_or_b32 s23, s27, 0x8000
	s_mov_b32 m0, s68
	ds_read_b128 v[194:197], v141
	ds_read_b128 v[198:201], v141 offset:1024
	ds_read_b128 v[202:205], v141 offset:2048
	ds_read_b128 v[228:231], v141 offset:3072
	ds_read_b128 v[232:235], v141 offset:4096
	ds_read_b128 v[236:239], v141 offset:5120
	ds_read_b128 v[240:243], v141 offset:6144
	ds_read_b128 v[244:247], v141 offset:7168
	buffer_load_dwordx4 v136, s[60:63], s21 offen lds
	s_mov_b32 m0, s70
	s_nop 0
	buffer_load_dwordx4 v138, s[60:63], s21 offen lds
	s_waitcnt vmcnt(8)
	s_waitcnt lgkmcnt(0)
	s_barrier
	v_mfma_f32_16x16x32_bf16 v[126:129], v[132:135], v[194:197], v[126:129]
	v_mfma_f32_16x16x32_bf16 v[126:129], v[142:145], v[198:201], v[126:129]
	v_mfma_f32_16x16x32_bf16 v[106:109], v[170:173], v[194:197], v[106:109]
	v_mfma_f32_16x16x32_bf16 v[106:109], v[174:177], v[198:201], v[106:109]
	v_mfma_f32_16x16x32_bf16 v[110:113], v[186:189], v[194:197], v[110:113]
	v_mfma_f32_16x16x32_bf16 v[110:113], v[190:193], v[198:201], v[110:113]
	v_mfma_f32_16x16x32_bf16 v[122:125], v[178:181], v[194:197], v[122:125]
	v_mfma_f32_16x16x32_bf16 v[122:125], v[182:185], v[198:201], v[122:125]
	v_mfma_f32_16x16x32_bf16 v[102:105], v[178:181], v[202:205], v[102:105]
	v_mfma_f32_16x16x32_bf16 v[102:105], v[182:185], v[228:231], v[102:105]
	v_mfma_f32_16x16x32_bf16 v[98:101], v[186:189], v[202:205], v[98:101]
	v_mfma_f32_16x16x32_bf16 v[98:101], v[190:193], v[228:231], v[98:101]
	v_mfma_f32_16x16x32_bf16 v[114:117], v[170:173], v[202:205], v[114:117]
	v_mfma_f32_16x16x32_bf16 v[114:117], v[174:177], v[228:231], v[114:117]
	v_mfma_f32_16x16x32_bf16 v[118:121], v[132:135], v[202:205], v[118:121]
	v_mfma_f32_16x16x32_bf16 v[118:121], v[142:145], v[228:231], v[118:121]
	v_mfma_f32_16x16x32_bf16 v[94:97], v[132:135], v[232:235], v[94:97]
	v_mfma_f32_16x16x32_bf16 v[94:97], v[142:145], v[236:239], v[94:97]
	v_mfma_f32_16x16x32_bf16 v[90:93], v[170:173], v[232:235], v[90:93]
	v_mfma_f32_16x16x32_bf16 v[90:93], v[174:177], v[236:239], v[90:93]
	v_mfma_f32_16x16x32_bf16 v[82:85], v[186:189], v[232:235], v[82:85]
	v_mfma_f32_16x16x32_bf16 v[82:85], v[190:193], v[236:239], v[82:85]
	v_mfma_f32_16x16x32_bf16 v[86:89], v[178:181], v[232:235], v[86:89]
	v_mfma_f32_16x16x32_bf16 v[86:89], v[182:185], v[236:239], v[86:89]
	v_mfma_f32_16x16x32_bf16 v[70:73], v[178:181], v[240:243], v[70:73]
	v_mfma_f32_16x16x32_bf16 v[70:73], v[182:185], v[244:247], v[70:73]
	v_mfma_f32_16x16x32_bf16 v[66:69], v[186:189], v[240:243], v[66:69]
	v_mfma_f32_16x16x32_bf16 v[66:69], v[190:193], v[244:247], v[66:69]
	v_mfma_f32_16x16x32_bf16 v[74:77], v[170:173], v[240:243], v[74:77]
	v_mfma_f32_16x16x32_bf16 v[74:77], v[174:177], v[244:247], v[74:77]
	v_mfma_f32_16x16x32_bf16 v[78:81], v[132:135], v[240:243], v[78:81]
	v_mfma_f32_16x16x32_bf16 v[78:81], v[142:145], v[244:247], v[78:81]
	s_barrier
	s_mov_b32 s46, s62
	s_mov_b32 s47, s63
	s_mov_b32 m0, s15
	ds_read_b128 v[194:197], v141 offset:16384
	buffer_load_dwordx4 v137, s[44:47], s26 offen lds
	s_add_i32 s52, s26, 0x160000
	s_mov_b32 m0, s16
	ds_read_b128 v[198:201], v141 offset:17408
	buffer_load_dwordx4 v139, s[44:47], s26 offen lds
	s_mov_b32 m0, s18
	ds_read_b128 v[202:205], v141 offset:18432
	buffer_load_dwordx4 v137, s[44:47], s52 offen lds
	s_mov_b32 m0, s19
	ds_read_b128 v[228:231], v141 offset:19456
	buffer_load_dwordx4 v139, s[44:47], s52 offen lds
	s_mov_b32 m0, s14
	ds_read_b128 v[232:235], v141 offset:20480
	buffer_load_dwordx4 v136, s[60:63], s27 offen lds
	s_mov_b32 m0, s24
	ds_read_b128 v[236:239], v141 offset:21504
	buffer_load_dwordx4 v138, s[60:63], s27 offen lds
	ds_read_b128 v[240:243], v141 offset:22528
	ds_read_b128 v[244:247], v141 offset:23552
	s_waitcnt vmcnt(8)
	s_waitcnt lgkmcnt(0)
	s_barrier
	v_mfma_f32_16x16x32_bf16 v[62:65], v[132:135], v[194:197], v[62:65]
	v_mfma_f32_16x16x32_bf16 v[62:65], v[142:145], v[198:201], v[62:65]
	v_mfma_f32_16x16x32_bf16 v[58:61], v[170:173], v[194:197], v[58:61]
	v_mfma_f32_16x16x32_bf16 v[58:61], v[174:177], v[198:201], v[58:61]
	v_mfma_f32_16x16x32_bf16 v[50:53], v[186:189], v[194:197], v[50:53]
	v_mfma_f32_16x16x32_bf16 v[50:53], v[190:193], v[198:201], v[50:53]
	v_mfma_f32_16x16x32_bf16 v[54:57], v[178:181], v[194:197], v[54:57]
	v_mfma_f32_16x16x32_bf16 v[54:57], v[182:185], v[198:201], v[54:57]
	v_mfma_f32_16x16x32_bf16 v[38:41], v[178:181], v[202:205], v[38:41]
	v_mfma_f32_16x16x32_bf16 v[38:41], v[182:185], v[228:231], v[38:41]
	v_mfma_f32_16x16x32_bf16 v[34:37], v[186:189], v[202:205], v[34:37]
	v_mfma_f32_16x16x32_bf16 v[34:37], v[190:193], v[228:231], v[34:37]
	v_mfma_f32_16x16x32_bf16 v[42:45], v[170:173], v[202:205], v[42:45]
	v_mfma_f32_16x16x32_bf16 v[42:45], v[174:177], v[228:231], v[42:45]
	v_mfma_f32_16x16x32_bf16 v[46:49], v[132:135], v[202:205], v[46:49]
	v_mfma_f32_16x16x32_bf16 v[46:49], v[142:145], v[228:231], v[46:49]
	v_mfma_f32_16x16x32_bf16 v[30:33], v[132:135], v[232:235], v[30:33]
	v_mfma_f32_16x16x32_bf16 v[30:33], v[142:145], v[236:239], v[30:33]
	v_mfma_f32_16x16x32_bf16 v[26:29], v[170:173], v[232:235], v[26:29]
	v_mfma_f32_16x16x32_bf16 v[26:29], v[174:177], v[236:239], v[26:29]
	v_mfma_f32_16x16x32_bf16 v[18:21], v[186:189], v[232:235], v[18:21]
	v_mfma_f32_16x16x32_bf16 v[18:21], v[190:193], v[236:239], v[18:21]
	v_mfma_f32_16x16x32_bf16 v[22:25], v[178:181], v[232:235], v[22:25]
	v_mfma_f32_16x16x32_bf16 v[22:25], v[182:185], v[236:239], v[22:25]
	v_mfma_f32_16x16x32_bf16 v[6:9], v[178:181], v[240:243], v[6:9]
	v_mfma_f32_16x16x32_bf16 v[6:9], v[182:185], v[244:247], v[6:9]
	v_mfma_f32_16x16x32_bf16 v[2:5], v[186:189], v[240:243], v[2:5]
	v_mfma_f32_16x16x32_bf16 v[2:5], v[190:193], v[244:247], v[2:5]
	v_mfma_f32_16x16x32_bf16 v[10:13], v[170:173], v[240:243], v[10:13]
	v_mfma_f32_16x16x32_bf16 v[10:13], v[174:177], v[244:247], v[10:13]
	v_mfma_f32_16x16x32_bf16 v[14:17], v[132:135], v[240:243], v[14:17]
	v_mfma_f32_16x16x32_bf16 v[14:17], v[142:145], v[244:247], v[14:17]
	s_barrier
	v_add_u32_e32 v154, 0x18000, v140
	ds_read_b128 v[132:135], v154
	ds_read_b128 v[142:145], v154 offset:1024
	ds_read_b128 v[170:173], v154 offset:2048
	ds_read_b128 v[174:177], v154 offset:3072
	v_add_u32_e32 v154, 0x1c000, v140
	ds_read_b128 v[178:181], v154
	ds_read_b128 v[182:185], v154 offset:1024
	ds_read_b128 v[186:189], v154 offset:2048
	ds_read_b128 v[190:193], v154 offset:3072
	s_bitset1_b32 s27, 14
	s_mov_b32 m0, s25
	ds_read_b128 v[194:197], v141 offset:32768
	ds_read_b128 v[198:201], v141 offset:33792
	ds_read_b128 v[202:205], v141 offset:34816
	ds_read_b128 v[228:231], v141 offset:35840
	ds_read_b128 v[232:235], v141 offset:36864
	ds_read_b128 v[236:239], v141 offset:37888
	ds_read_b128 v[240:243], v141 offset:38912
	ds_read_b128 v[244:247], v141 offset:39936
	buffer_load_dwordx4 v136, s[60:63], s27 offen lds
	s_mov_b32 m0, s30
	s_nop 0
	buffer_load_dwordx4 v138, s[60:63], s27 offen lds
	s_waitcnt vmcnt(8)
	s_waitcnt lgkmcnt(0)
	s_barrier
	v_mfma_f32_16x16x32_bf16 v[126:129], v[132:135], v[194:197], v[126:129]
	v_mfma_f32_16x16x32_bf16 v[126:129], v[142:145], v[198:201], v[126:129]
	v_mfma_f32_16x16x32_bf16 v[106:109], v[170:173], v[194:197], v[106:109]
	v_mfma_f32_16x16x32_bf16 v[106:109], v[174:177], v[198:201], v[106:109]
	v_mfma_f32_16x16x32_bf16 v[110:113], v[186:189], v[194:197], v[110:113]
	v_mfma_f32_16x16x32_bf16 v[110:113], v[190:193], v[198:201], v[110:113]
	v_mfma_f32_16x16x32_bf16 v[122:125], v[178:181], v[194:197], v[122:125]
	v_mfma_f32_16x16x32_bf16 v[122:125], v[182:185], v[198:201], v[122:125]
	v_mfma_f32_16x16x32_bf16 v[102:105], v[178:181], v[202:205], v[102:105]
	v_mfma_f32_16x16x32_bf16 v[102:105], v[182:185], v[228:231], v[102:105]
	v_mfma_f32_16x16x32_bf16 v[98:101], v[186:189], v[202:205], v[98:101]
	v_mfma_f32_16x16x32_bf16 v[98:101], v[190:193], v[228:231], v[98:101]
	v_mfma_f32_16x16x32_bf16 v[114:117], v[170:173], v[202:205], v[114:117]
	v_mfma_f32_16x16x32_bf16 v[114:117], v[174:177], v[228:231], v[114:117]
	v_mfma_f32_16x16x32_bf16 v[118:121], v[132:135], v[202:205], v[118:121]
	v_mfma_f32_16x16x32_bf16 v[118:121], v[142:145], v[228:231], v[118:121]
	v_mfma_f32_16x16x32_bf16 v[94:97], v[132:135], v[232:235], v[94:97]
	v_mfma_f32_16x16x32_bf16 v[94:97], v[142:145], v[236:239], v[94:97]
	v_mfma_f32_16x16x32_bf16 v[90:93], v[170:173], v[232:235], v[90:93]
	v_mfma_f32_16x16x32_bf16 v[90:93], v[174:177], v[236:239], v[90:93]
	v_mfma_f32_16x16x32_bf16 v[82:85], v[186:189], v[232:235], v[82:85]
	v_mfma_f32_16x16x32_bf16 v[82:85], v[190:193], v[236:239], v[82:85]
	v_mfma_f32_16x16x32_bf16 v[86:89], v[178:181], v[232:235], v[86:89]
	v_mfma_f32_16x16x32_bf16 v[86:89], v[182:185], v[236:239], v[86:89]
	v_mfma_f32_16x16x32_bf16 v[70:73], v[178:181], v[240:243], v[70:73]
	v_mfma_f32_16x16x32_bf16 v[70:73], v[182:185], v[244:247], v[70:73]
	v_mfma_f32_16x16x32_bf16 v[66:69], v[186:189], v[240:243], v[66:69]
	v_mfma_f32_16x16x32_bf16 v[66:69], v[190:193], v[244:247], v[66:69]
	v_mfma_f32_16x16x32_bf16 v[74:77], v[170:173], v[240:243], v[74:77]
	v_mfma_f32_16x16x32_bf16 v[74:77], v[174:177], v[244:247], v[74:77]
	v_mfma_f32_16x16x32_bf16 v[78:81], v[132:135], v[240:243], v[78:81]
	v_mfma_f32_16x16x32_bf16 v[78:81], v[142:145], v[244:247], v[78:81]
	s_barrier
	s_or_b32 s27, s26, 0x80
	s_mov_b32 m0, s36
	ds_read_b128 v[194:197], v141 offset:49152
	buffer_load_dwordx4 v137, s[44:47], s27 offen lds
	s_add_i32 s26, s26, 0x160080
	s_mov_b32 m0, s37
	ds_read_b128 v[198:201], v141 offset:50176
	buffer_load_dwordx4 v139, s[44:47], s27 offen lds
	s_mov_b32 m0, s66
	ds_read_b128 v[202:205], v141 offset:51200
	buffer_load_dwordx4 v137, s[44:47], s26 offen lds
	s_mov_b32 m0, s67
	ds_read_b128 v[228:231], v141 offset:52224
	buffer_load_dwordx4 v139, s[44:47], s26 offen lds
	s_mov_b32 m0, s48
	ds_read_b128 v[232:235], v141 offset:53248
	buffer_load_dwordx4 v136, s[60:63], s23 offen lds
	s_mov_b32 m0, s49
	ds_read_b128 v[236:239], v141 offset:54272
	buffer_load_dwordx4 v138, s[60:63], s23 offen lds
	ds_read_b128 v[240:243], v141 offset:55296
	ds_read_b128 v[244:247], v141 offset:56320
	s_waitcnt vmcnt(8)
	s_waitcnt lgkmcnt(0)
	s_barrier
	v_mfma_f32_16x16x32_bf16 v[62:65], v[132:135], v[194:197], v[62:65]
	v_mfma_f32_16x16x32_bf16 v[62:65], v[142:145], v[198:201], v[62:65]
	v_mfma_f32_16x16x32_bf16 v[58:61], v[170:173], v[194:197], v[58:61]
	v_mfma_f32_16x16x32_bf16 v[58:61], v[174:177], v[198:201], v[58:61]
	v_mfma_f32_16x16x32_bf16 v[50:53], v[186:189], v[194:197], v[50:53]
	v_mfma_f32_16x16x32_bf16 v[50:53], v[190:193], v[198:201], v[50:53]
	v_mfma_f32_16x16x32_bf16 v[54:57], v[178:181], v[194:197], v[54:57]
	v_mfma_f32_16x16x32_bf16 v[54:57], v[182:185], v[198:201], v[54:57]
	v_mfma_f32_16x16x32_bf16 v[38:41], v[178:181], v[202:205], v[38:41]
	v_mfma_f32_16x16x32_bf16 v[38:41], v[182:185], v[228:231], v[38:41]
	v_mfma_f32_16x16x32_bf16 v[34:37], v[186:189], v[202:205], v[34:37]
	v_mfma_f32_16x16x32_bf16 v[34:37], v[190:193], v[228:231], v[34:37]
	v_mfma_f32_16x16x32_bf16 v[42:45], v[170:173], v[202:205], v[42:45]
	v_mfma_f32_16x16x32_bf16 v[42:45], v[174:177], v[228:231], v[42:45]
	v_mfma_f32_16x16x32_bf16 v[46:49], v[132:135], v[202:205], v[46:49]
	v_mfma_f32_16x16x32_bf16 v[46:49], v[142:145], v[228:231], v[46:49]
	v_mfma_f32_16x16x32_bf16 v[30:33], v[132:135], v[232:235], v[30:33]
	v_mfma_f32_16x16x32_bf16 v[30:33], v[142:145], v[236:239], v[30:33]
	v_mfma_f32_16x16x32_bf16 v[26:29], v[170:173], v[232:235], v[26:29]
	v_mfma_f32_16x16x32_bf16 v[26:29], v[174:177], v[236:239], v[26:29]
	v_mfma_f32_16x16x32_bf16 v[18:21], v[186:189], v[232:235], v[18:21]
	v_mfma_f32_16x16x32_bf16 v[18:21], v[190:193], v[236:239], v[18:21]
	v_mfma_f32_16x16x32_bf16 v[22:25], v[178:181], v[232:235], v[22:25]
	v_mfma_f32_16x16x32_bf16 v[22:25], v[182:185], v[236:239], v[22:25]
	v_mfma_f32_16x16x32_bf16 v[6:9], v[178:181], v[240:243], v[6:9]
	v_mfma_f32_16x16x32_bf16 v[6:9], v[182:185], v[244:247], v[6:9]
	v_mfma_f32_16x16x32_bf16 v[2:5], v[186:189], v[240:243], v[2:5]
	v_mfma_f32_16x16x32_bf16 v[2:5], v[190:193], v[244:247], v[2:5]
	v_mfma_f32_16x16x32_bf16 v[10:13], v[170:173], v[240:243], v[10:13]
	v_mfma_f32_16x16x32_bf16 v[10:13], v[174:177], v[244:247], v[10:13]
	v_mfma_f32_16x16x32_bf16 v[14:17], v[132:135], v[240:243], v[14:17]
	v_mfma_f32_16x16x32_bf16 v[14:17], v[142:145], v[244:247], v[14:17]
	s_barrier
	s_addk_i32 s13, 0x100
	s_add_i32 s22, s22, 2
	s_add_i32 s21, s21, 0x10000
	s_cmpk_gt_u32 s22, 0x55
	s_cbranch_scc0 .LBB0_580
	s_and_b64 vcc, exec, s[64:65]
	s_cbranch_vccz .LBB0_583
	s_barrier

.LBB0_858:
	s_lshl_b32 s2, s21, 20
	s_and_b64 s[8:9], s[42:43], exec
	s_cselect_b32 s8, s2, s18
	s_lshl_b32 s82, s71, 20
	s_and_b64 s[26:27], s[42:43], exec
	s_cselect_b32 s9, s82, s19
	s_add_i32 s18, s18, 0x80080
	s_addk_i32 s19, 0x100
	s_mov_b32 s22, -2
	v_add_u32_e32 v146, 0x10000, v195
	ds_read_b128 v[130:133], v146
	ds_read_b128 v[138:141], v146 offset:1024
	ds_read_b128 v[142:145], v146 offset:2048
	ds_read_b128 v[154:157], v146 offset:3072
	v_add_u32_e32 v146, 0x14000, v195
	ds_read_b128 v[170:173], v146
	ds_read_b128 v[174:177], v146 offset:1024
	ds_read_b128 v[178:181], v146 offset:2048
	ds_read_b128 v[182:185], v146 offset:3072
	s_add_i32 s26, s18, 0xfff80080
	s_cmp_eq_u32 s22, 28
	s_cselect_b32 s52, s8, s26
	s_cselect_b32 s27, s9, s19
	s_or_b32 s26, s52, 0x80
	s_mov_b32 m0, s85
	ds_read_b128 v[186:189], v196
	ds_read_b128 v[198:201], v196 offset:1024
	ds_read_b128 v[202:205], v196 offset:2048
	ds_read_b128 v[228:231], v196 offset:3072
	ds_read_b128 v[232:235], v196 offset:4096
	ds_read_b128 v[236:239], v196 offset:5120
	ds_read_b128 v[240:243], v196 offset:6144
	ds_read_b128 v[244:247], v196 offset:7168
	buffer_load_dwordx4 v135, s[44:47], s18 offen lds
	s_mov_b32 m0, s15
	s_nop 0
	buffer_load_dwordx4 v193, s[44:47], s18 offen lds
	s_waitcnt vmcnt(8)
	s_waitcnt lgkmcnt(0)
	s_barrier
	v_mfma_f32_16x16x32_bf16 v[126:129], v[130:133], v[186:189], 0
	v_mfma_f32_16x16x32_bf16 v[126:129], v[138:141], v[198:201], v[126:129]
	v_mfma_f32_16x16x32_bf16 v[122:125], v[142:145], v[186:189], 0
	v_mfma_f32_16x16x32_bf16 v[122:125], v[154:157], v[198:201], v[122:125]
	v_mfma_f32_16x16x32_bf16 v[114:117], v[178:181], v[186:189], 0
	v_mfma_f32_16x16x32_bf16 v[114:117], v[182:185], v[198:201], v[114:117]
	v_mfma_f32_16x16x32_bf16 v[118:121], v[170:173], v[186:189], 0
	v_mfma_f32_16x16x32_bf16 v[118:121], v[174:177], v[198:201], v[118:121]
	v_mfma_f32_16x16x32_bf16 v[102:105], v[170:173], v[202:205], 0
	v_mfma_f32_16x16x32_bf16 v[102:105], v[174:177], v[228:231], v[102:105]
	v_mfma_f32_16x16x32_bf16 v[98:101], v[178:181], v[202:205], 0
	v_mfma_f32_16x16x32_bf16 v[98:101], v[182:185], v[228:231], v[98:101]
	v_mfma_f32_16x16x32_bf16 v[106:109], v[142:145], v[202:205], 0
	v_mfma_f32_16x16x32_bf16 v[106:109], v[154:157], v[228:231], v[106:109]
	v_mfma_f32_16x16x32_bf16 v[110:113], v[130:133], v[202:205], 0
	v_mfma_f32_16x16x32_bf16 v[110:113], v[138:141], v[228:231], v[110:113]
	v_mfma_f32_16x16x32_bf16 v[94:97], v[130:133], v[232:235], 0
	v_mfma_f32_16x16x32_bf16 v[94:97], v[138:141], v[236:239], v[94:97]
	v_mfma_f32_16x16x32_bf16 v[90:93], v[142:145], v[232:235], 0
	v_mfma_f32_16x16x32_bf16 v[90:93], v[154:157], v[236:239], v[90:93]
	v_mfma_f32_16x16x32_bf16 v[82:85], v[178:181], v[232:235], 0
	v_mfma_f32_16x16x32_bf16 v[82:85], v[182:185], v[236:239], v[82:85]
	v_mfma_f32_16x16x32_bf16 v[86:89], v[170:173], v[232:235], 0
	v_mfma_f32_16x16x32_bf16 v[86:89], v[174:177], v[236:239], v[86:89]
	v_mfma_f32_16x16x32_bf16 v[70:73], v[170:173], v[240:243], 0
	v_mfma_f32_16x16x32_bf16 v[70:73], v[174:177], v[244:247], v[70:73]
	v_mfma_f32_16x16x32_bf16 v[66:69], v[178:181], v[240:243], 0
	v_mfma_f32_16x16x32_bf16 v[66:69], v[182:185], v[244:247], v[66:69]
	v_mfma_f32_16x16x32_bf16 v[74:77], v[142:145], v[240:243], 0
	v_mfma_f32_16x16x32_bf16 v[74:77], v[154:157], v[244:247], v[74:77]
	v_mfma_f32_16x16x32_bf16 v[78:81], v[130:133], v[240:243], 0
	v_mfma_f32_16x16x32_bf16 v[78:81], v[138:141], v[244:247], v[78:81]
	s_barrier
	s_mov_b32 s66, s46
	s_mov_b32 s67, s47
	s_mov_b32 m0, s23
	ds_read_b128 v[186:189], v196 offset:16384
	buffer_load_dwordx4 v192, s[64:67], s27 offen lds
	s_add_i32 s53, s27, 0x80000
	s_mov_b32 m0, s24
	ds_read_b128 v[198:201], v196 offset:17408
	buffer_load_dwordx4 v194, s[64:67], s27 offen lds
	s_mov_b32 m0, s25
	ds_read_b128 v[202:205], v196 offset:18432
	buffer_load_dwordx4 v192, s[64:67], s53 offen lds
	s_mov_b32 m0, s33
	ds_read_b128 v[228:231], v196 offset:19456
	buffer_load_dwordx4 v194, s[64:67], s53 offen lds
	s_mov_b32 m0, s13
	ds_read_b128 v[232:235], v196 offset:20480
	buffer_load_dwordx4 v135, s[44:47], s52 offen lds
	s_mov_b32 m0, s34
	ds_read_b128 v[236:239], v196 offset:21504
	buffer_load_dwordx4 v193, s[44:47], s52 offen lds
	ds_read_b128 v[240:243], v196 offset:22528
	ds_read_b128 v[244:247], v196 offset:23552
	s_waitcnt vmcnt(8)
	s_waitcnt lgkmcnt(0)
	s_barrier
	v_mfma_f32_16x16x32_bf16 v[62:65], v[130:133], v[186:189], 0
	v_mfma_f32_16x16x32_bf16 v[62:65], v[138:141], v[198:201], v[62:65]
	v_mfma_f32_16x16x32_bf16 v[58:61], v[142:145], v[186:189], 0
	v_mfma_f32_16x16x32_bf16 v[58:61], v[154:157], v[198:201], v[58:61]
	v_mfma_f32_16x16x32_bf16 v[50:53], v[178:181], v[186:189], 0
	v_mfma_f32_16x16x32_bf16 v[50:53], v[182:185], v[198:201], v[50:53]
	v_mfma_f32_16x16x32_bf16 v[54:57], v[170:173], v[186:189], 0
	v_mfma_f32_16x16x32_bf16 v[54:57], v[174:177], v[198:201], v[54:57]
	v_mfma_f32_16x16x32_bf16 v[38:41], v[170:173], v[202:205], 0
	v_mfma_f32_16x16x32_bf16 v[38:41], v[174:177], v[228:231], v[38:41]
	v_mfma_f32_16x16x32_bf16 v[34:37], v[178:181], v[202:205], 0
	v_mfma_f32_16x16x32_bf16 v[34:37], v[182:185], v[228:231], v[34:37]
	v_mfma_f32_16x16x32_bf16 v[42:45], v[142:145], v[202:205], 0
	v_mfma_f32_16x16x32_bf16 v[42:45], v[154:157], v[228:231], v[42:45]
	v_mfma_f32_16x16x32_bf16 v[46:49], v[130:133], v[202:205], 0
	v_mfma_f32_16x16x32_bf16 v[46:49], v[138:141], v[228:231], v[46:49]
	v_mfma_f32_16x16x32_bf16 v[30:33], v[130:133], v[232:235], 0
	v_mfma_f32_16x16x32_bf16 v[30:33], v[138:141], v[236:239], v[30:33]
	v_mfma_f32_16x16x32_bf16 v[26:29], v[142:145], v[232:235], 0
	v_mfma_f32_16x16x32_bf16 v[26:29], v[154:157], v[236:239], v[26:29]
	v_mfma_f32_16x16x32_bf16 v[18:21], v[178:181], v[232:235], 0
	v_mfma_f32_16x16x32_bf16 v[18:21], v[182:185], v[236:239], v[18:21]
	v_mfma_f32_16x16x32_bf16 v[22:25], v[170:173], v[232:235], 0
	v_mfma_f32_16x16x32_bf16 v[22:25], v[174:177], v[236:239], v[22:25]
	v_mfma_f32_16x16x32_bf16 v[6:9], v[170:173], v[240:243], 0
	v_mfma_f32_16x16x32_bf16 v[6:9], v[174:177], v[244:247], v[6:9]
	v_mfma_f32_16x16x32_bf16 v[2:5], v[178:181], v[240:243], 0
	v_mfma_f32_16x16x32_bf16 v[2:5], v[182:185], v[244:247], v[2:5]
	v_mfma_f32_16x16x32_bf16 v[10:13], v[142:145], v[240:243], 0
	v_mfma_f32_16x16x32_bf16 v[10:13], v[154:157], v[244:247], v[10:13]
	v_mfma_f32_16x16x32_bf16 v[14:17], v[130:133], v[240:243], 0
	v_mfma_f32_16x16x32_bf16 v[14:17], v[138:141], v[244:247], v[14:17]
	s_barrier
	v_add_u32_e32 v146, 0x18000, v195
	ds_read_b128 v[130:133], v146
	ds_read_b128 v[138:141], v146 offset:1024
	ds_read_b128 v[142:145], v146 offset:2048
	ds_read_b128 v[154:157], v146 offset:3072
	v_add_u32_e32 v146, 0x1c000, v195
	ds_read_b128 v[170:173], v146
	ds_read_b128 v[174:177], v146 offset:1024
	ds_read_b128 v[178:181], v146 offset:2048
	ds_read_b128 v[182:185], v146 offset:3072
	s_add_i32 s52, s52, 0x80000
	s_mov_b32 m0, s35
	ds_read_b128 v[186:189], v196 offset:32768
	ds_read_b128 v[198:201], v196 offset:33792
	ds_read_b128 v[202:205], v196 offset:34816
	ds_read_b128 v[228:231], v196 offset:35840
	ds_read_b128 v[232:235], v196 offset:36864
	ds_read_b128 v[236:239], v196 offset:37888
	ds_read_b128 v[240:243], v196 offset:38912
	ds_read_b128 v[244:247], v196 offset:39936
	buffer_load_dwordx4 v135, s[44:47], s52 offen lds
	s_mov_b32 m0, s36
	s_nop 0
	buffer_load_dwordx4 v193, s[44:47], s52 offen lds
	s_waitcnt vmcnt(8)
	s_waitcnt lgkmcnt(0)
	s_barrier
	v_mfma_f32_16x16x32_bf16 v[126:129], v[130:133], v[186:189], v[126:129]
	v_mfma_f32_16x16x32_bf16 v[126:129], v[138:141], v[198:201], v[126:129]
	v_mfma_f32_16x16x32_bf16 v[122:125], v[142:145], v[186:189], v[122:125]
	v_mfma_f32_16x16x32_bf16 v[122:125], v[154:157], v[198:201], v[122:125]
	v_mfma_f32_16x16x32_bf16 v[114:117], v[178:181], v[186:189], v[114:117]
	v_mfma_f32_16x16x32_bf16 v[114:117], v[182:185], v[198:201], v[114:117]
	v_mfma_f32_16x16x32_bf16 v[118:121], v[170:173], v[186:189], v[118:121]
	v_mfma_f32_16x16x32_bf16 v[118:121], v[174:177], v[198:201], v[118:121]
	v_mfma_f32_16x16x32_bf16 v[102:105], v[170:173], v[202:205], v[102:105]
	v_mfma_f32_16x16x32_bf16 v[102:105], v[174:177], v[228:231], v[102:105]
	v_mfma_f32_16x16x32_bf16 v[98:101], v[178:181], v[202:205], v[98:101]
	v_mfma_f32_16x16x32_bf16 v[98:101], v[182:185], v[228:231], v[98:101]
	v_mfma_f32_16x16x32_bf16 v[106:109], v[142:145], v[202:205], v[106:109]
	v_mfma_f32_16x16x32_bf16 v[106:109], v[154:157], v[228:231], v[106:109]
	v_mfma_f32_16x16x32_bf16 v[110:113], v[130:133], v[202:205], v[110:113]
	v_mfma_f32_16x16x32_bf16 v[110:113], v[138:141], v[228:231], v[110:113]
	v_mfma_f32_16x16x32_bf16 v[94:97], v[130:133], v[232:235], v[94:97]
	v_mfma_f32_16x16x32_bf16 v[94:97], v[138:141], v[236:239], v[94:97]
	v_mfma_f32_16x16x32_bf16 v[90:93], v[142:145], v[232:235], v[90:93]
	v_mfma_f32_16x16x32_bf16 v[90:93], v[154:157], v[236:239], v[90:93]
	v_mfma_f32_16x16x32_bf16 v[82:85], v[178:181], v[232:235], v[82:85]
	v_mfma_f32_16x16x32_bf16 v[82:85], v[182:185], v[236:239], v[82:85]
	v_mfma_f32_16x16x32_bf16 v[86:89], v[170:173], v[232:235], v[86:89]
	v_mfma_f32_16x16x32_bf16 v[86:89], v[174:177], v[236:239], v[86:89]
	v_mfma_f32_16x16x32_bf16 v[70:73], v[170:173], v[240:243], v[70:73]
	v_mfma_f32_16x16x32_bf16 v[70:73], v[174:177], v[244:247], v[70:73]
	v_mfma_f32_16x16x32_bf16 v[66:69], v[178:181], v[240:243], v[66:69]
	v_mfma_f32_16x16x32_bf16 v[66:69], v[182:185], v[244:247], v[66:69]
	v_mfma_f32_16x16x32_bf16 v[74:77], v[142:145], v[240:243], v[74:77]
	v_mfma_f32_16x16x32_bf16 v[74:77], v[154:157], v[244:247], v[74:77]
	v_mfma_f32_16x16x32_bf16 v[78:81], v[130:133], v[240:243], v[78:81]
	v_mfma_f32_16x16x32_bf16 v[78:81], v[138:141], v[244:247], v[78:81]
	s_barrier
	s_or_b32 s52, s27, 0x80
	s_mov_b32 m0, s41
	ds_read_b128 v[186:189], v196 offset:49152
	buffer_load_dwordx4 v192, s[64:67], s52 offen lds
	s_add_i32 s27, s27, 0x80080
	s_mov_b32 m0, s48
	ds_read_b128 v[198:201], v196 offset:50176
	buffer_load_dwordx4 v194, s[64:67], s52 offen lds
	s_mov_b32 m0, s69
	ds_read_b128 v[202:205], v196 offset:51200
	buffer_load_dwordx4 v192, s[64:67], s27 offen lds
	s_mov_b32 m0, s72
	ds_read_b128 v[228:231], v196 offset:52224
	buffer_load_dwordx4 v194, s[64:67], s27 offen lds
	s_mov_b32 m0, s49
	ds_read_b128 v[232:235], v196 offset:53248
	buffer_load_dwordx4 v135, s[44:47], s26 offen lds
	s_mov_b32 m0, s68
	ds_read_b128 v[236:239], v196 offset:54272
	buffer_load_dwordx4 v193, s[44:47], s26 offen lds
	ds_read_b128 v[240:243], v196 offset:55296
	ds_read_b128 v[244:247], v196 offset:56320
	s_waitcnt vmcnt(8)
	s_waitcnt lgkmcnt(0)
	s_barrier
	v_mfma_f32_16x16x32_bf16 v[62:65], v[130:133], v[186:189], v[62:65]
	v_mfma_f32_16x16x32_bf16 v[62:65], v[138:141], v[198:201], v[62:65]
	v_mfma_f32_16x16x32_bf16 v[58:61], v[142:145], v[186:189], v[58:61]
	v_mfma_f32_16x16x32_bf16 v[58:61], v[154:157], v[198:201], v[58:61]
	v_mfma_f32_16x16x32_bf16 v[50:53], v[178:181], v[186:189], v[50:53]
	v_mfma_f32_16x16x32_bf16 v[50:53], v[182:185], v[198:201], v[50:53]
	v_mfma_f32_16x16x32_bf16 v[54:57], v[170:173], v[186:189], v[54:57]
	v_mfma_f32_16x16x32_bf16 v[54:57], v[174:177], v[198:201], v[54:57]
	v_mfma_f32_16x16x32_bf16 v[38:41], v[170:173], v[202:205], v[38:41]
	v_mfma_f32_16x16x32_bf16 v[38:41], v[174:177], v[228:231], v[38:41]
	v_mfma_f32_16x16x32_bf16 v[34:37], v[178:181], v[202:205], v[34:37]
	v_mfma_f32_16x16x32_bf16 v[34:37], v[182:185], v[228:231], v[34:37]
	v_mfma_f32_16x16x32_bf16 v[42:45], v[142:145], v[202:205], v[42:45]
	v_mfma_f32_16x16x32_bf16 v[42:45], v[154:157], v[228:231], v[42:45]
	v_mfma_f32_16x16x32_bf16 v[46:49], v[130:133], v[202:205], v[46:49]
	v_mfma_f32_16x16x32_bf16 v[46:49], v[138:141], v[228:231], v[46:49]
	v_mfma_f32_16x16x32_bf16 v[30:33], v[130:133], v[232:235], v[30:33]
	v_mfma_f32_16x16x32_bf16 v[30:33], v[138:141], v[236:239], v[30:33]
	v_mfma_f32_16x16x32_bf16 v[26:29], v[142:145], v[232:235], v[26:29]
	v_mfma_f32_16x16x32_bf16 v[26:29], v[154:157], v[236:239], v[26:29]
	v_mfma_f32_16x16x32_bf16 v[18:21], v[178:181], v[232:235], v[18:21]
	v_mfma_f32_16x16x32_bf16 v[18:21], v[182:185], v[236:239], v[18:21]
	v_mfma_f32_16x16x32_bf16 v[22:25], v[170:173], v[232:235], v[22:25]
	v_mfma_f32_16x16x32_bf16 v[22:25], v[174:177], v[236:239], v[22:25]
	v_mfma_f32_16x16x32_bf16 v[6:9], v[170:173], v[240:243], v[6:9]
	v_mfma_f32_16x16x32_bf16 v[6:9], v[174:177], v[244:247], v[6:9]
	v_mfma_f32_16x16x32_bf16 v[2:5], v[178:181], v[240:243], v[2:5]
	v_mfma_f32_16x16x32_bf16 v[2:5], v[182:185], v[244:247], v[2:5]
	v_mfma_f32_16x16x32_bf16 v[10:13], v[142:145], v[240:243], v[10:13]
	v_mfma_f32_16x16x32_bf16 v[10:13], v[154:157], v[244:247], v[10:13]
	v_mfma_f32_16x16x32_bf16 v[14:17], v[130:133], v[240:243], v[14:17]
	v_mfma_f32_16x16x32_bf16 v[14:17], v[138:141], v[244:247], v[14:17]
	s_barrier
	s_add_i32 s22, s22, 2
	s_addk_i32 s18, 0x100
	s_addk_i32 s19, 0x100
	s_cmp_gt_u32 s22, 29
.LBB0_859:
	v_add_u32_e32 v146, 0x10000, v195
	ds_read_b128 v[130:133], v146
	ds_read_b128 v[138:141], v146 offset:1024
	ds_read_b128 v[142:145], v146 offset:2048
	ds_read_b128 v[154:157], v146 offset:3072
	v_add_u32_e32 v146, 0x14000, v195
	ds_read_b128 v[170:173], v146
	ds_read_b128 v[174:177], v146 offset:1024
	ds_read_b128 v[178:181], v146 offset:2048
	ds_read_b128 v[182:185], v146 offset:3072
	s_add_i32 s26, s18, 0xfff80080
	s_cmp_eq_u32 s22, 28
	s_cselect_b32 s52, s8, s26
	s_cselect_b32 s27, s9, s19
	s_or_b32 s26, s52, 0x80
	s_mov_b32 m0, s85
	ds_read_b128 v[186:189], v196
	ds_read_b128 v[198:201], v196 offset:1024
	ds_read_b128 v[202:205], v196 offset:2048
	ds_read_b128 v[228:231], v196 offset:3072
	ds_read_b128 v[232:235], v196 offset:4096
	ds_read_b128 v[236:239], v196 offset:5120
	ds_read_b128 v[240:243], v196 offset:6144
	ds_read_b128 v[244:247], v196 offset:7168
	buffer_load_dwordx4 v135, s[44:47], s18 offen lds
	s_mov_b32 m0, s15
	s_nop 0
	buffer_load_dwordx4 v193, s[44:47], s18 offen lds
	s_waitcnt vmcnt(8)
	s_waitcnt lgkmcnt(0)
	s_barrier
	v_mfma_f32_16x16x32_bf16 v[126:129], v[130:133], v[186:189], v[126:129]
	v_mfma_f32_16x16x32_bf16 v[126:129], v[138:141], v[198:201], v[126:129]
	v_mfma_f32_16x16x32_bf16 v[122:125], v[142:145], v[186:189], v[122:125]
	v_mfma_f32_16x16x32_bf16 v[122:125], v[154:157], v[198:201], v[122:125]
	v_mfma_f32_16x16x32_bf16 v[114:117], v[178:181], v[186:189], v[114:117]
	v_mfma_f32_16x16x32_bf16 v[114:117], v[182:185], v[198:201], v[114:117]
	v_mfma_f32_16x16x32_bf16 v[118:121], v[170:173], v[186:189], v[118:121]
	v_mfma_f32_16x16x32_bf16 v[118:121], v[174:177], v[198:201], v[118:121]
	v_mfma_f32_16x16x32_bf16 v[102:105], v[170:173], v[202:205], v[102:105]
	v_mfma_f32_16x16x32_bf16 v[102:105], v[174:177], v[228:231], v[102:105]
	v_mfma_f32_16x16x32_bf16 v[98:101], v[178:181], v[202:205], v[98:101]
	v_mfma_f32_16x16x32_bf16 v[98:101], v[182:185], v[228:231], v[98:101]
	v_mfma_f32_16x16x32_bf16 v[106:109], v[142:145], v[202:205], v[106:109]
	v_mfma_f32_16x16x32_bf16 v[106:109], v[154:157], v[228:231], v[106:109]
	v_mfma_f32_16x16x32_bf16 v[110:113], v[130:133], v[202:205], v[110:113]
	v_mfma_f32_16x16x32_bf16 v[110:113], v[138:141], v[228:231], v[110:113]
	v_mfma_f32_16x16x32_bf16 v[94:97], v[130:133], v[232:235], v[94:97]
	v_mfma_f32_16x16x32_bf16 v[94:97], v[138:141], v[236:239], v[94:97]
	v_mfma_f32_16x16x32_bf16 v[90:93], v[142:145], v[232:235], v[90:93]
	v_mfma_f32_16x16x32_bf16 v[90:93], v[154:157], v[236:239], v[90:93]
	v_mfma_f32_16x16x32_bf16 v[82:85], v[178:181], v[232:235], v[82:85]
	v_mfma_f32_16x16x32_bf16 v[82:85], v[182:185], v[236:239], v[82:85]
	v_mfma_f32_16x16x32_bf16 v[86:89], v[170:173], v[232:235], v[86:89]
	v_mfma_f32_16x16x32_bf16 v[86:89], v[174:177], v[236:239], v[86:89]
	v_mfma_f32_16x16x32_bf16 v[70:73], v[170:173], v[240:243], v[70:73]
	v_mfma_f32_16x16x32_bf16 v[70:73], v[174:177], v[244:247], v[70:73]
	v_mfma_f32_16x16x32_bf16 v[66:69], v[178:181], v[240:243], v[66:69]
	v_mfma_f32_16x16x32_bf16 v[66:69], v[182:185], v[244:247], v[66:69]
	v_mfma_f32_16x16x32_bf16 v[74:77], v[142:145], v[240:243], v[74:77]
	v_mfma_f32_16x16x32_bf16 v[74:77], v[154:157], v[244:247], v[74:77]
	v_mfma_f32_16x16x32_bf16 v[78:81], v[130:133], v[240:243], v[78:81]
	v_mfma_f32_16x16x32_bf16 v[78:81], v[138:141], v[244:247], v[78:81]
	s_barrier
	s_mov_b32 s66, s46
	s_mov_b32 s67, s47
	s_mov_b32 m0, s23
	ds_read_b128 v[186:189], v196 offset:16384
	buffer_load_dwordx4 v192, s[64:67], s27 offen lds
	s_add_i32 s53, s27, 0x80000
	s_mov_b32 m0, s24
	ds_read_b128 v[198:201], v196 offset:17408
	buffer_load_dwordx4 v194, s[64:67], s27 offen lds
	s_mov_b32 m0, s25
	ds_read_b128 v[202:205], v196 offset:18432
	buffer_load_dwordx4 v192, s[64:67], s53 offen lds
	s_mov_b32 m0, s33
	ds_read_b128 v[228:231], v196 offset:19456
	buffer_load_dwordx4 v194, s[64:67], s53 offen lds
	s_mov_b32 m0, s13
	ds_read_b128 v[232:235], v196 offset:20480
	buffer_load_dwordx4 v135, s[44:47], s52 offen lds
	s_mov_b32 m0, s34
	ds_read_b128 v[236:239], v196 offset:21504
	buffer_load_dwordx4 v193, s[44:47], s52 offen lds
	ds_read_b128 v[240:243], v196 offset:22528
	ds_read_b128 v[244:247], v196 offset:23552
	s_waitcnt vmcnt(8)
	s_waitcnt lgkmcnt(0)
	s_barrier
	v_mfma_f32_16x16x32_bf16 v[62:65], v[130:133], v[186:189], v[62:65]
	v_mfma_f32_16x16x32_bf16 v[62:65], v[138:141], v[198:201], v[62:65]
	v_mfma_f32_16x16x32_bf16 v[58:61], v[142:145], v[186:189], v[58:61]
	v_mfma_f32_16x16x32_bf16 v[58:61], v[154:157], v[198:201], v[58:61]
	v_mfma_f32_16x16x32_bf16 v[50:53], v[178:181], v[186:189], v[50:53]
	v_mfma_f32_16x16x32_bf16 v[50:53], v[182:185], v[198:201], v[50:53]
	v_mfma_f32_16x16x32_bf16 v[54:57], v[170:173], v[186:189], v[54:57]
	v_mfma_f32_16x16x32_bf16 v[54:57], v[174:177], v[198:201], v[54:57]
	v_mfma_f32_16x16x32_bf16 v[38:41], v[170:173], v[202:205], v[38:41]
	v_mfma_f32_16x16x32_bf16 v[38:41], v[174:177], v[228:231], v[38:41]
	v_mfma_f32_16x16x32_bf16 v[34:37], v[178:181], v[202:205], v[34:37]
	v_mfma_f32_16x16x32_bf16 v[34:37], v[182:185], v[228:231], v[34:37]
	v_mfma_f32_16x16x32_bf16 v[42:45], v[142:145], v[202:205], v[42:45]
	v_mfma_f32_16x16x32_bf16 v[42:45], v[154:157], v[228:231], v[42:45]
	v_mfma_f32_16x16x32_bf16 v[46:49], v[130:133], v[202:205], v[46:49]
	v_mfma_f32_16x16x32_bf16 v[46:49], v[138:141], v[228:231], v[46:49]
	v_mfma_f32_16x16x32_bf16 v[30:33], v[130:133], v[232:235], v[30:33]
	v_mfma_f32_16x16x32_bf16 v[30:33], v[138:141], v[236:239], v[30:33]
	v_mfma_f32_16x16x32_bf16 v[26:29], v[142:145], v[232:235], v[26:29]
	v_mfma_f32_16x16x32_bf16 v[26:29], v[154:157], v[236:239], v[26:29]
	v_mfma_f32_16x16x32_bf16 v[18:21], v[178:181], v[232:235], v[18:21]
	v_mfma_f32_16x16x32_bf16 v[18:21], v[182:185], v[236:239], v[18:21]
	v_mfma_f32_16x16x32_bf16 v[22:25], v[170:173], v[232:235], v[22:25]
	v_mfma_f32_16x16x32_bf16 v[22:25], v[174:177], v[236:239], v[22:25]
	v_mfma_f32_16x16x32_bf16 v[6:9], v[170:173], v[240:243], v[6:9]
	v_mfma_f32_16x16x32_bf16 v[6:9], v[174:177], v[244:247], v[6:9]
	v_mfma_f32_16x16x32_bf16 v[2:5], v[178:181], v[240:243], v[2:5]
	v_mfma_f32_16x16x32_bf16 v[2:5], v[182:185], v[244:247], v[2:5]
	v_mfma_f32_16x16x32_bf16 v[10:13], v[142:145], v[240:243], v[10:13]
	v_mfma_f32_16x16x32_bf16 v[10:13], v[154:157], v[244:247], v[10:13]
	v_mfma_f32_16x16x32_bf16 v[14:17], v[130:133], v[240:243], v[14:17]
	v_mfma_f32_16x16x32_bf16 v[14:17], v[138:141], v[244:247], v[14:17]
	s_barrier
	v_add_u32_e32 v146, 0x18000, v195
	ds_read_b128 v[130:133], v146
	ds_read_b128 v[138:141], v146 offset:1024
	ds_read_b128 v[142:145], v146 offset:2048
	ds_read_b128 v[154:157], v146 offset:3072
	v_add_u32_e32 v146, 0x1c000, v195
	ds_read_b128 v[170:173], v146
	ds_read_b128 v[174:177], v146 offset:1024
	ds_read_b128 v[178:181], v146 offset:2048
	ds_read_b128 v[182:185], v146 offset:3072
	s_add_i32 s52, s52, 0x80000
	s_mov_b32 m0, s35
	ds_read_b128 v[186:189], v196 offset:32768
	ds_read_b128 v[198:201], v196 offset:33792
	ds_read_b128 v[202:205], v196 offset:34816
	ds_read_b128 v[228:231], v196 offset:35840
	ds_read_b128 v[232:235], v196 offset:36864
	ds_read_b128 v[236:239], v196 offset:37888
	ds_read_b128 v[240:243], v196 offset:38912
	ds_read_b128 v[244:247], v196 offset:39936
	buffer_load_dwordx4 v135, s[44:47], s52 offen lds
	s_mov_b32 m0, s36
	s_nop 0
	buffer_load_dwordx4 v193, s[44:47], s52 offen lds
	s_waitcnt vmcnt(8)
	s_waitcnt lgkmcnt(0)
	s_barrier
	v_mfma_f32_16x16x32_bf16 v[126:129], v[130:133], v[186:189], v[126:129]
	v_mfma_f32_16x16x32_bf16 v[126:129], v[138:141], v[198:201], v[126:129]
	v_mfma_f32_16x16x32_bf16 v[122:125], v[142:145], v[186:189], v[122:125]
	v_mfma_f32_16x16x32_bf16 v[122:125], v[154:157], v[198:201], v[122:125]
	v_mfma_f32_16x16x32_bf16 v[114:117], v[178:181], v[186:189], v[114:117]
	v_mfma_f32_16x16x32_bf16 v[114:117], v[182:185], v[198:201], v[114:117]
	v_mfma_f32_16x16x32_bf16 v[118:121], v[170:173], v[186:189], v[118:121]
	v_mfma_f32_16x16x32_bf16 v[118:121], v[174:177], v[198:201], v[118:121]
	v_mfma_f32_16x16x32_bf16 v[102:105], v[170:173], v[202:205], v[102:105]
	v_mfma_f32_16x16x32_bf16 v[102:105], v[174:177], v[228:231], v[102:105]
	v_mfma_f32_16x16x32_bf16 v[98:101], v[178:181], v[202:205], v[98:101]
	v_mfma_f32_16x16x32_bf16 v[98:101], v[182:185], v[228:231], v[98:101]
	v_mfma_f32_16x16x32_bf16 v[106:109], v[142:145], v[202:205], v[106:109]
	v_mfma_f32_16x16x32_bf16 v[106:109], v[154:157], v[228:231], v[106:109]
	v_mfma_f32_16x16x32_bf16 v[110:113], v[130:133], v[202:205], v[110:113]
	v_mfma_f32_16x16x32_bf16 v[110:113], v[138:141], v[228:231], v[110:113]
	v_mfma_f32_16x16x32_bf16 v[94:97], v[130:133], v[232:235], v[94:97]
	v_mfma_f32_16x16x32_bf16 v[94:97], v[138:141], v[236:239], v[94:97]
	v_mfma_f32_16x16x32_bf16 v[90:93], v[142:145], v[232:235], v[90:93]
	v_mfma_f32_16x16x32_bf16 v[90:93], v[154:157], v[236:239], v[90:93]
	v_mfma_f32_16x16x32_bf16 v[82:85], v[178:181], v[232:235], v[82:85]
	v_mfma_f32_16x16x32_bf16 v[82:85], v[182:185], v[236:239], v[82:85]
	v_mfma_f32_16x16x32_bf16 v[86:89], v[170:173], v[232:235], v[86:89]
	v_mfma_f32_16x16x32_bf16 v[86:89], v[174:177], v[236:239], v[86:89]
	v_mfma_f32_16x16x32_bf16 v[70:73], v[170:173], v[240:243], v[70:73]
	v_mfma_f32_16x16x32_bf16 v[70:73], v[174:177], v[244:247], v[70:73]
	v_mfma_f32_16x16x32_bf16 v[66:69], v[178:181], v[240:243], v[66:69]
	v_mfma_f32_16x16x32_bf16 v[66:69], v[182:185], v[244:247], v[66:69]
	v_mfma_f32_16x16x32_bf16 v[74:77], v[142:145], v[240:243], v[74:77]
	v_mfma_f32_16x16x32_bf16 v[74:77], v[154:157], v[244:247], v[74:77]
	v_mfma_f32_16x16x32_bf16 v[78:81], v[130:133], v[240:243], v[78:81]
	v_mfma_f32_16x16x32_bf16 v[78:81], v[138:141], v[244:247], v[78:81]
	s_barrier
	s_or_b32 s52, s27, 0x80
	s_mov_b32 m0, s41
	ds_read_b128 v[186:189], v196 offset:49152
	buffer_load_dwordx4 v192, s[64:67], s52 offen lds
	s_add_i32 s27, s27, 0x80080
	s_mov_b32 m0, s48
	ds_read_b128 v[198:201], v196 offset:50176
	buffer_load_dwordx4 v194, s[64:67], s52 offen lds
	s_mov_b32 m0, s69
	ds_read_b128 v[202:205], v196 offset:51200
	buffer_load_dwordx4 v192, s[64:67], s27 offen lds
	s_mov_b32 m0, s72
	ds_read_b128 v[228:231], v196 offset:52224
	buffer_load_dwordx4 v194, s[64:67], s27 offen lds
	s_mov_b32 m0, s49
	ds_read_b128 v[232:235], v196 offset:53248
	buffer_load_dwordx4 v135, s[44:47], s26 offen lds
	s_mov_b32 m0, s68
	ds_read_b128 v[236:239], v196 offset:54272
	buffer_load_dwordx4 v193, s[44:47], s26 offen lds
	ds_read_b128 v[240:243], v196 offset:55296
	ds_read_b128 v[244:247], v196 offset:56320
	s_waitcnt vmcnt(8)
	s_waitcnt lgkmcnt(0)
	s_barrier
	v_mfma_f32_16x16x32_bf16 v[62:65], v[130:133], v[186:189], v[62:65]
	v_mfma_f32_16x16x32_bf16 v[62:65], v[138:141], v[198:201], v[62:65]
	v_mfma_f32_16x16x32_bf16 v[58:61], v[142:145], v[186:189], v[58:61]
	v_mfma_f32_16x16x32_bf16 v[58:61], v[154:157], v[198:201], v[58:61]
	v_mfma_f32_16x16x32_bf16 v[50:53], v[178:181], v[186:189], v[50:53]
	v_mfma_f32_16x16x32_bf16 v[50:53], v[182:185], v[198:201], v[50:53]
	v_mfma_f32_16x16x32_bf16 v[54:57], v[170:173], v[186:189], v[54:57]
	v_mfma_f32_16x16x32_bf16 v[54:57], v[174:177], v[198:201], v[54:57]
	v_mfma_f32_16x16x32_bf16 v[38:41], v[170:173], v[202:205], v[38:41]
	v_mfma_f32_16x16x32_bf16 v[38:41], v[174:177], v[228:231], v[38:41]
	v_mfma_f32_16x16x32_bf16 v[34:37], v[178:181], v[202:205], v[34:37]
	v_mfma_f32_16x16x32_bf16 v[34:37], v[182:185], v[228:231], v[34:37]
	v_mfma_f32_16x16x32_bf16 v[42:45], v[142:145], v[202:205], v[42:45]
	v_mfma_f32_16x16x32_bf16 v[42:45], v[154:157], v[228:231], v[42:45]
	v_mfma_f32_16x16x32_bf16 v[46:49], v[130:133], v[202:205], v[46:49]
	v_mfma_f32_16x16x32_bf16 v[46:49], v[138:141], v[228:231], v[46:49]
	v_mfma_f32_16x16x32_bf16 v[30:33], v[130:133], v[232:235], v[30:33]
	v_mfma_f32_16x16x32_bf16 v[30:33], v[138:141], v[236:239], v[30:33]
	v_mfma_f32_16x16x32_bf16 v[26:29], v[142:145], v[232:235], v[26:29]
	v_mfma_f32_16x16x32_bf16 v[26:29], v[154:157], v[236:239], v[26:29]
	v_mfma_f32_16x16x32_bf16 v[18:21], v[178:181], v[232:235], v[18:21]
	v_mfma_f32_16x16x32_bf16 v[18:21], v[182:185], v[236:239], v[18:21]
	v_mfma_f32_16x16x32_bf16 v[22:25], v[170:173], v[232:235], v[22:25]
	v_mfma_f32_16x16x32_bf16 v[22:25], v[174:177], v[236:239], v[22:25]
	v_mfma_f32_16x16x32_bf16 v[6:9], v[170:173], v[240:243], v[6:9]
	v_mfma_f32_16x16x32_bf16 v[6:9], v[174:177], v[244:247], v[6:9]
	v_mfma_f32_16x16x32_bf16 v[2:5], v[178:181], v[240:243], v[2:5]
	v_mfma_f32_16x16x32_bf16 v[2:5], v[182:185], v[244:247], v[2:5]
	v_mfma_f32_16x16x32_bf16 v[10:13], v[142:145], v[240:243], v[10:13]
	v_mfma_f32_16x16x32_bf16 v[10:13], v[154:157], v[244:247], v[10:13]
	v_mfma_f32_16x16x32_bf16 v[14:17], v[130:133], v[240:243], v[14:17]
	v_mfma_f32_16x16x32_bf16 v[14:17], v[138:141], v[244:247], v[14:17]
	s_barrier
	s_add_i32 s22, s22, 2
	s_addk_i32 s18, 0x100
	s_addk_i32 s19, 0x100
	s_cmp_gt_u32 s22, 29
	s_cbranch_scc0 .LBB0_859
	s_and_b64 vcc, exec, s[60:61]
	s_cbranch_vccz .LBB0_862
	s_barrier

.LBB0_880:
	s_lshl_b32 s14, s85, 20
	s_and_b64 s[8:9], s[42:43], exec
	s_cselect_b32 s8, s14, s12
	s_lshl_b32 s15, s66, 20
	s_and_b64 s[22:23], s[42:43], exec
	s_cselect_b32 s9, s15, s13
	s_add_i32 s12, s12, 0x80080
	s_addk_i32 s13, 0x100
	s_mov_b32 s16, -2
	v_add_u32_e32 v139, 0x10000, v234
	ds_read_b128 v[130:133], v139
	ds_read_b128 v[140:143], v139 offset:1024
	ds_read_b128 v[170:173], v139 offset:2048
	ds_read_b128 v[174:177], v139 offset:3072
	v_add_u32_e32 v139, 0x14000, v234
	ds_read_b128 v[178:181], v139
	ds_read_b128 v[182:185], v139 offset:1024
	ds_read_b128 v[186:189], v139 offset:2048
	ds_read_b128 v[190:193], v139 offset:3072
	s_add_i32 s21, s12, 0xfff80080
	s_cmp_eq_u32 s16, 28
	s_cselect_b32 s23, s8, s21
	s_cselect_b32 s22, s9, s13
	s_or_b32 s21, s23, 0x80
	s_mov_b32 m0, s72
	ds_read_b128 v[194:197], v235
	ds_read_b128 v[198:201], v235 offset:1024
	ds_read_b128 v[202:205], v235 offset:2048
	ds_read_b128 v[236:239], v235 offset:3072
	ds_read_b128 v[240:243], v235 offset:4096
	ds_read_b128 v[244:247], v235 offset:5120
	ds_read_b128 v[248:251], v235 offset:6144
	ds_read_b128 v[154:157], v235 offset:7168
	buffer_load_dwordx4 v228, s[60:63], s12 offen lds
	s_mov_b32 m0, s73
	s_nop 0
	buffer_load_dwordx4 v230, s[60:63], s12 offen lds
	s_waitcnt vmcnt(8)
	s_waitcnt lgkmcnt(0)
	s_barrier
	v_mfma_f32_16x16x32_bf16 v[126:129], v[130:133], v[194:197], 0
	v_mfma_f32_16x16x32_bf16 v[126:129], v[140:143], v[198:201], v[126:129]
	v_mfma_f32_16x16x32_bf16 v[122:125], v[170:173], v[194:197], 0
	v_mfma_f32_16x16x32_bf16 v[122:125], v[174:177], v[198:201], v[122:125]
	v_mfma_f32_16x16x32_bf16 v[110:113], v[186:189], v[194:197], 0
	v_mfma_f32_16x16x32_bf16 v[110:113], v[190:193], v[198:201], v[110:113]
	v_mfma_f32_16x16x32_bf16 v[118:121], v[178:181], v[194:197], 0
	v_mfma_f32_16x16x32_bf16 v[118:121], v[182:185], v[198:201], v[118:121]
	v_mfma_f32_16x16x32_bf16 v[102:105], v[178:181], v[202:205], 0
	v_mfma_f32_16x16x32_bf16 v[102:105], v[182:185], v[236:239], v[102:105]
	v_mfma_f32_16x16x32_bf16 v[94:97], v[186:189], v[202:205], 0
	v_mfma_f32_16x16x32_bf16 v[94:97], v[190:193], v[236:239], v[94:97]
	v_mfma_f32_16x16x32_bf16 v[106:109], v[170:173], v[202:205], 0
	v_mfma_f32_16x16x32_bf16 v[106:109], v[174:177], v[236:239], v[106:109]
	v_mfma_f32_16x16x32_bf16 v[114:117], v[130:133], v[202:205], 0
	v_mfma_f32_16x16x32_bf16 v[114:117], v[140:143], v[236:239], v[114:117]
	v_mfma_f32_16x16x32_bf16 v[98:101], v[130:133], v[240:243], 0
	v_mfma_f32_16x16x32_bf16 v[98:101], v[140:143], v[244:247], v[98:101]
	v_mfma_f32_16x16x32_bf16 v[90:93], v[170:173], v[240:243], 0
	v_mfma_f32_16x16x32_bf16 v[90:93], v[174:177], v[244:247], v[90:93]
	v_mfma_f32_16x16x32_bf16 v[78:81], v[186:189], v[240:243], 0
	v_mfma_f32_16x16x32_bf16 v[78:81], v[190:193], v[244:247], v[78:81]
	v_mfma_f32_16x16x32_bf16 v[86:89], v[178:181], v[240:243], 0
	v_mfma_f32_16x16x32_bf16 v[86:89], v[182:185], v[244:247], v[86:89]
	v_mfma_f32_16x16x32_bf16 v[70:73], v[178:181], v[248:251], 0
	v_mfma_f32_16x16x32_bf16 v[70:73], v[182:185], v[154:157], v[70:73]
	v_mfma_f32_16x16x32_bf16 v[66:69], v[186:189], v[248:251], 0
	v_mfma_f32_16x16x32_bf16 v[66:69], v[190:193], v[154:157], v[66:69]
	v_mfma_f32_16x16x32_bf16 v[74:77], v[170:173], v[248:251], 0
	v_mfma_f32_16x16x32_bf16 v[74:77], v[174:177], v[154:157], v[74:77]
	v_mfma_f32_16x16x32_bf16 v[82:85], v[130:133], v[248:251], 0
	v_mfma_f32_16x16x32_bf16 v[82:85], v[140:143], v[154:157], v[82:85]
	s_barrier
	s_mov_b32 s46, s62
	s_mov_b32 s47, s63
	s_mov_b32 m0, s26
	ds_read_b128 v[154:157], v235 offset:16384
	buffer_load_dwordx4 v229, s[44:47], s22 offen lds
	s_add_i32 s38, s22, 0x80000
	s_mov_b32 m0, s27
	ds_read_b128 v[194:197], v235 offset:17408
	buffer_load_dwordx4 v231, s[44:47], s22 offen lds
	s_mov_b32 m0, s34
	ds_read_b128 v[198:201], v235 offset:18432
	buffer_load_dwordx4 v229, s[44:47], s38 offen lds
	s_mov_b32 m0, s35
	ds_read_b128 v[202:205], v235 offset:19456
	buffer_load_dwordx4 v231, s[44:47], s38 offen lds
	s_mov_b32 m0, s19
	ds_read_b128 v[236:239], v235 offset:20480
	buffer_load_dwordx4 v228, s[60:63], s23 offen lds
	s_mov_b32 m0, s36
	ds_read_b128 v[240:243], v235 offset:21504
	buffer_load_dwordx4 v230, s[60:63], s23 offen lds
	ds_read_b128 v[244:247], v235 offset:22528
	ds_read_b128 v[248:251], v235 offset:23552
	s_waitcnt vmcnt(8)
	s_waitcnt lgkmcnt(0)
	s_barrier
	v_mfma_f32_16x16x32_bf16 v[62:65], v[130:133], v[154:157], 0
	v_mfma_f32_16x16x32_bf16 v[62:65], v[140:143], v[194:197], v[62:65]
	v_mfma_f32_16x16x32_bf16 v[58:61], v[170:173], v[154:157], 0
	v_mfma_f32_16x16x32_bf16 v[58:61], v[174:177], v[194:197], v[58:61]
	v_mfma_f32_16x16x32_bf16 v[46:49], v[186:189], v[154:157], 0
	v_mfma_f32_16x16x32_bf16 v[46:49], v[190:193], v[194:197], v[46:49]
	v_mfma_f32_16x16x32_bf16 v[54:57], v[178:181], v[154:157], 0
	v_mfma_f32_16x16x32_bf16 v[54:57], v[182:185], v[194:197], v[54:57]
	v_mfma_f32_16x16x32_bf16 v[38:41], v[178:181], v[198:201], 0
	v_mfma_f32_16x16x32_bf16 v[38:41], v[182:185], v[202:205], v[38:41]
	v_mfma_f32_16x16x32_bf16 v[30:33], v[186:189], v[198:201], 0
	v_mfma_f32_16x16x32_bf16 v[30:33], v[190:193], v[202:205], v[30:33]
	v_mfma_f32_16x16x32_bf16 v[42:45], v[170:173], v[198:201], 0
	v_mfma_f32_16x16x32_bf16 v[42:45], v[174:177], v[202:205], v[42:45]
	v_mfma_f32_16x16x32_bf16 v[50:53], v[130:133], v[198:201], 0
	v_mfma_f32_16x16x32_bf16 v[50:53], v[140:143], v[202:205], v[50:53]
	v_mfma_f32_16x16x32_bf16 v[34:37], v[130:133], v[236:239], 0
	v_mfma_f32_16x16x32_bf16 v[34:37], v[140:143], v[240:243], v[34:37]
	v_mfma_f32_16x16x32_bf16 v[26:29], v[170:173], v[236:239], 0
	v_mfma_f32_16x16x32_bf16 v[26:29], v[174:177], v[240:243], v[26:29]
	v_mfma_f32_16x16x32_bf16 v[14:17], v[186:189], v[236:239], 0
	v_mfma_f32_16x16x32_bf16 v[14:17], v[190:193], v[240:243], v[14:17]
	v_mfma_f32_16x16x32_bf16 v[22:25], v[178:181], v[236:239], 0
	v_mfma_f32_16x16x32_bf16 v[22:25], v[182:185], v[240:243], v[22:25]
	v_mfma_f32_16x16x32_bf16 v[6:9], v[178:181], v[244:247], 0
	v_mfma_f32_16x16x32_bf16 v[6:9], v[182:185], v[248:251], v[6:9]
	v_mfma_f32_16x16x32_bf16 v[2:5], v[186:189], v[244:247], 0
	v_mfma_f32_16x16x32_bf16 v[2:5], v[190:193], v[248:251], v[2:5]
	v_mfma_f32_16x16x32_bf16 v[10:13], v[170:173], v[244:247], 0
	v_mfma_f32_16x16x32_bf16 v[10:13], v[174:177], v[248:251], v[10:13]
	v_mfma_f32_16x16x32_bf16 v[18:21], v[130:133], v[244:247], 0
	v_mfma_f32_16x16x32_bf16 v[18:21], v[140:143], v[248:251], v[18:21]
	s_barrier
	v_add_u32_e32 v139, 0x18000, v234
	ds_read_b128 v[130:133], v139
	ds_read_b128 v[140:143], v139 offset:1024
	ds_read_b128 v[154:157], v139 offset:2048
	ds_read_b128 v[170:173], v139 offset:3072
	v_add_u32_e32 v139, 0x1c000, v234
	ds_read_b128 v[174:177], v139
	ds_read_b128 v[178:181], v139 offset:1024
	ds_read_b128 v[182:185], v139 offset:2048
	ds_read_b128 v[186:189], v139 offset:3072
	s_add_i32 s23, s23, 0x80000
	s_mov_b32 m0, s37
	ds_read_b128 v[190:193], v235 offset:32768
	ds_read_b128 v[194:197], v235 offset:33792
	ds_read_b128 v[198:201], v235 offset:34816
	ds_read_b128 v[202:205], v235 offset:35840
	ds_read_b128 v[236:239], v235 offset:36864
	ds_read_b128 v[240:243], v235 offset:37888
	ds_read_b128 v[244:247], v235 offset:38912
	ds_read_b128 v[248:251], v235 offset:39936
	buffer_load_dwordx4 v228, s[60:63], s23 offen lds
	s_mov_b32 m0, s18
	s_nop 0
	buffer_load_dwordx4 v230, s[60:63], s23 offen lds
	s_waitcnt vmcnt(8)
	s_waitcnt lgkmcnt(0)
	s_barrier
	v_mfma_f32_16x16x32_bf16 v[126:129], v[130:133], v[190:193], v[126:129]
	v_mfma_f32_16x16x32_bf16 v[126:129], v[140:143], v[194:197], v[126:129]
	v_mfma_f32_16x16x32_bf16 v[122:125], v[154:157], v[190:193], v[122:125]
	v_mfma_f32_16x16x32_bf16 v[122:125], v[170:173], v[194:197], v[122:125]
	v_mfma_f32_16x16x32_bf16 v[110:113], v[182:185], v[190:193], v[110:113]
	v_mfma_f32_16x16x32_bf16 v[110:113], v[186:189], v[194:197], v[110:113]
	v_mfma_f32_16x16x32_bf16 v[118:121], v[174:177], v[190:193], v[118:121]
	v_mfma_f32_16x16x32_bf16 v[118:121], v[178:181], v[194:197], v[118:121]
	v_mfma_f32_16x16x32_bf16 v[102:105], v[174:177], v[198:201], v[102:105]
	v_mfma_f32_16x16x32_bf16 v[102:105], v[178:181], v[202:205], v[102:105]
	v_mfma_f32_16x16x32_bf16 v[94:97], v[182:185], v[198:201], v[94:97]
	v_mfma_f32_16x16x32_bf16 v[94:97], v[186:189], v[202:205], v[94:97]
	v_mfma_f32_16x16x32_bf16 v[106:109], v[154:157], v[198:201], v[106:109]
	v_mfma_f32_16x16x32_bf16 v[106:109], v[170:173], v[202:205], v[106:109]
	v_mfma_f32_16x16x32_bf16 v[114:117], v[130:133], v[198:201], v[114:117]
	v_mfma_f32_16x16x32_bf16 v[114:117], v[140:143], v[202:205], v[114:117]
	v_mfma_f32_16x16x32_bf16 v[98:101], v[130:133], v[236:239], v[98:101]
	v_mfma_f32_16x16x32_bf16 v[98:101], v[140:143], v[240:243], v[98:101]
	v_mfma_f32_16x16x32_bf16 v[90:93], v[154:157], v[236:239], v[90:93]
	v_mfma_f32_16x16x32_bf16 v[90:93], v[170:173], v[240:243], v[90:93]
	v_mfma_f32_16x16x32_bf16 v[78:81], v[182:185], v[236:239], v[78:81]
	v_mfma_f32_16x16x32_bf16 v[78:81], v[186:189], v[240:243], v[78:81]
	v_mfma_f32_16x16x32_bf16 v[86:89], v[174:177], v[236:239], v[86:89]
	v_mfma_f32_16x16x32_bf16 v[86:89], v[178:181], v[240:243], v[86:89]
	v_mfma_f32_16x16x32_bf16 v[70:73], v[174:177], v[244:247], v[70:73]
	v_mfma_f32_16x16x32_bf16 v[70:73], v[178:181], v[248:251], v[70:73]
	v_mfma_f32_16x16x32_bf16 v[66:69], v[182:185], v[244:247], v[66:69]
	v_mfma_f32_16x16x32_bf16 v[66:69], v[186:189], v[248:251], v[66:69]
	v_mfma_f32_16x16x32_bf16 v[74:77], v[154:157], v[244:247], v[74:77]
	v_mfma_f32_16x16x32_bf16 v[74:77], v[170:173], v[248:251], v[74:77]
	v_mfma_f32_16x16x32_bf16 v[82:85], v[130:133], v[244:247], v[82:85]
	v_mfma_f32_16x16x32_bf16 v[82:85], v[140:143], v[248:251], v[82:85]
	s_barrier
	s_or_b32 s23, s22, 0x80
	s_mov_b32 m0, s24
	ds_read_b128 v[190:193], v235 offset:49152
	buffer_load_dwordx4 v229, s[44:47], s23 offen lds
	s_add_i32 s22, s22, 0x80080
	s_mov_b32 m0, s25
	ds_read_b128 v[194:197], v235 offset:50176
	buffer_load_dwordx4 v231, s[44:47], s23 offen lds
	s_mov_b32 m0, s64
	ds_read_b128 v[198:201], v235 offset:51200
	buffer_load_dwordx4 v229, s[44:47], s22 offen lds
	s_mov_b32 m0, s65
	ds_read_b128 v[202:205], v235 offset:52224
	buffer_load_dwordx4 v231, s[44:47], s22 offen lds
	s_mov_b32 m0, s48
	ds_read_b128 v[236:239], v235 offset:53248
	buffer_load_dwordx4 v228, s[60:63], s21 offen lds
	s_mov_b32 m0, s49
	ds_read_b128 v[240:243], v235 offset:54272
	buffer_load_dwordx4 v230, s[60:63], s21 offen lds
	ds_read_b128 v[244:247], v235 offset:55296
	ds_read_b128 v[248:251], v235 offset:56320
	s_waitcnt vmcnt(8)
	s_waitcnt lgkmcnt(0)
	s_barrier
	v_mfma_f32_16x16x32_bf16 v[62:65], v[130:133], v[190:193], v[62:65]
	v_mfma_f32_16x16x32_bf16 v[62:65], v[140:143], v[194:197], v[62:65]
	v_mfma_f32_16x16x32_bf16 v[58:61], v[154:157], v[190:193], v[58:61]
	v_mfma_f32_16x16x32_bf16 v[58:61], v[170:173], v[194:197], v[58:61]
	v_mfma_f32_16x16x32_bf16 v[46:49], v[182:185], v[190:193], v[46:49]
	v_mfma_f32_16x16x32_bf16 v[46:49], v[186:189], v[194:197], v[46:49]
	v_mfma_f32_16x16x32_bf16 v[54:57], v[174:177], v[190:193], v[54:57]
	v_mfma_f32_16x16x32_bf16 v[54:57], v[178:181], v[194:197], v[54:57]
	v_mfma_f32_16x16x32_bf16 v[38:41], v[174:177], v[198:201], v[38:41]
	v_mfma_f32_16x16x32_bf16 v[38:41], v[178:181], v[202:205], v[38:41]
	v_mfma_f32_16x16x32_bf16 v[30:33], v[182:185], v[198:201], v[30:33]
	v_mfma_f32_16x16x32_bf16 v[30:33], v[186:189], v[202:205], v[30:33]
	v_mfma_f32_16x16x32_bf16 v[42:45], v[154:157], v[198:201], v[42:45]
	v_mfma_f32_16x16x32_bf16 v[42:45], v[170:173], v[202:205], v[42:45]
	v_mfma_f32_16x16x32_bf16 v[50:53], v[130:133], v[198:201], v[50:53]
	v_mfma_f32_16x16x32_bf16 v[50:53], v[140:143], v[202:205], v[50:53]
	v_mfma_f32_16x16x32_bf16 v[34:37], v[130:133], v[236:239], v[34:37]
	v_mfma_f32_16x16x32_bf16 v[34:37], v[140:143], v[240:243], v[34:37]
	v_mfma_f32_16x16x32_bf16 v[26:29], v[154:157], v[236:239], v[26:29]
	v_mfma_f32_16x16x32_bf16 v[26:29], v[170:173], v[240:243], v[26:29]
	v_mfma_f32_16x16x32_bf16 v[14:17], v[182:185], v[236:239], v[14:17]
	v_mfma_f32_16x16x32_bf16 v[14:17], v[186:189], v[240:243], v[14:17]
	v_mfma_f32_16x16x32_bf16 v[22:25], v[174:177], v[236:239], v[22:25]
	v_mfma_f32_16x16x32_bf16 v[22:25], v[178:181], v[240:243], v[22:25]
	v_mfma_f32_16x16x32_bf16 v[6:9], v[174:177], v[244:247], v[6:9]
	v_mfma_f32_16x16x32_bf16 v[6:9], v[178:181], v[248:251], v[6:9]
	v_mfma_f32_16x16x32_bf16 v[2:5], v[182:185], v[244:247], v[2:5]
	v_mfma_f32_16x16x32_bf16 v[2:5], v[186:189], v[248:251], v[2:5]
	v_mfma_f32_16x16x32_bf16 v[10:13], v[154:157], v[244:247], v[10:13]
	v_mfma_f32_16x16x32_bf16 v[10:13], v[170:173], v[248:251], v[10:13]
	v_mfma_f32_16x16x32_bf16 v[18:21], v[130:133], v[244:247], v[18:21]
	v_mfma_f32_16x16x32_bf16 v[18:21], v[140:143], v[248:251], v[18:21]
	s_barrier
	s_add_i32 s16, s16, 2
	s_addk_i32 s12, 0x100
	s_addk_i32 s13, 0x100
	s_cmp_gt_u32 s16, 29
.LBB0_881:
	v_add_u32_e32 v139, 0x10000, v234
	ds_read_b128 v[130:133], v139
	ds_read_b128 v[140:143], v139 offset:1024
	ds_read_b128 v[170:173], v139 offset:2048
	ds_read_b128 v[174:177], v139 offset:3072
	v_add_u32_e32 v139, 0x14000, v234
	ds_read_b128 v[178:181], v139
	ds_read_b128 v[182:185], v139 offset:1024
	ds_read_b128 v[186:189], v139 offset:2048
	ds_read_b128 v[190:193], v139 offset:3072
	s_add_i32 s21, s12, 0xfff80080
	s_cmp_eq_u32 s16, 28
	s_cselect_b32 s23, s8, s21
	s_cselect_b32 s22, s9, s13
	s_or_b32 s21, s23, 0x80
	s_mov_b32 m0, s72
	ds_read_b128 v[194:197], v235
	ds_read_b128 v[198:201], v235 offset:1024
	ds_read_b128 v[202:205], v235 offset:2048
	ds_read_b128 v[236:239], v235 offset:3072
	ds_read_b128 v[240:243], v235 offset:4096
	ds_read_b128 v[244:247], v235 offset:5120
	ds_read_b128 v[248:251], v235 offset:6144
	ds_read_b128 v[154:157], v235 offset:7168
	buffer_load_dwordx4 v228, s[60:63], s12 offen lds
	s_mov_b32 m0, s73
	s_nop 0
	buffer_load_dwordx4 v230, s[60:63], s12 offen lds
	s_waitcnt vmcnt(8)
	s_waitcnt lgkmcnt(0)
	s_barrier
	v_mfma_f32_16x16x32_bf16 v[126:129], v[130:133], v[194:197], v[126:129]
	v_mfma_f32_16x16x32_bf16 v[126:129], v[140:143], v[198:201], v[126:129]
	v_mfma_f32_16x16x32_bf16 v[122:125], v[170:173], v[194:197], v[122:125]
	v_mfma_f32_16x16x32_bf16 v[122:125], v[174:177], v[198:201], v[122:125]
	v_mfma_f32_16x16x32_bf16 v[110:113], v[186:189], v[194:197], v[110:113]
	v_mfma_f32_16x16x32_bf16 v[110:113], v[190:193], v[198:201], v[110:113]
	v_mfma_f32_16x16x32_bf16 v[118:121], v[178:181], v[194:197], v[118:121]
	v_mfma_f32_16x16x32_bf16 v[118:121], v[182:185], v[198:201], v[118:121]
	v_mfma_f32_16x16x32_bf16 v[102:105], v[178:181], v[202:205], v[102:105]
	v_mfma_f32_16x16x32_bf16 v[102:105], v[182:185], v[236:239], v[102:105]
	v_mfma_f32_16x16x32_bf16 v[94:97], v[186:189], v[202:205], v[94:97]
	v_mfma_f32_16x16x32_bf16 v[94:97], v[190:193], v[236:239], v[94:97]
	v_mfma_f32_16x16x32_bf16 v[106:109], v[170:173], v[202:205], v[106:109]
	v_mfma_f32_16x16x32_bf16 v[106:109], v[174:177], v[236:239], v[106:109]
	v_mfma_f32_16x16x32_bf16 v[114:117], v[130:133], v[202:205], v[114:117]
	v_mfma_f32_16x16x32_bf16 v[114:117], v[140:143], v[236:239], v[114:117]
	v_mfma_f32_16x16x32_bf16 v[98:101], v[130:133], v[240:243], v[98:101]
	v_mfma_f32_16x16x32_bf16 v[98:101], v[140:143], v[244:247], v[98:101]
	v_mfma_f32_16x16x32_bf16 v[90:93], v[170:173], v[240:243], v[90:93]
	v_mfma_f32_16x16x32_bf16 v[90:93], v[174:177], v[244:247], v[90:93]
	v_mfma_f32_16x16x32_bf16 v[78:81], v[186:189], v[240:243], v[78:81]
	v_mfma_f32_16x16x32_bf16 v[78:81], v[190:193], v[244:247], v[78:81]
	v_mfma_f32_16x16x32_bf16 v[86:89], v[178:181], v[240:243], v[86:89]
	v_mfma_f32_16x16x32_bf16 v[86:89], v[182:185], v[244:247], v[86:89]
	v_mfma_f32_16x16x32_bf16 v[70:73], v[178:181], v[248:251], v[70:73]
	v_mfma_f32_16x16x32_bf16 v[70:73], v[182:185], v[154:157], v[70:73]
	v_mfma_f32_16x16x32_bf16 v[66:69], v[186:189], v[248:251], v[66:69]
	v_mfma_f32_16x16x32_bf16 v[66:69], v[190:193], v[154:157], v[66:69]
	v_mfma_f32_16x16x32_bf16 v[74:77], v[170:173], v[248:251], v[74:77]
	v_mfma_f32_16x16x32_bf16 v[74:77], v[174:177], v[154:157], v[74:77]
	v_mfma_f32_16x16x32_bf16 v[82:85], v[130:133], v[248:251], v[82:85]
	v_mfma_f32_16x16x32_bf16 v[82:85], v[140:143], v[154:157], v[82:85]
	s_barrier
	s_mov_b32 s46, s62
	s_mov_b32 s47, s63
	s_mov_b32 m0, s26
	ds_read_b128 v[154:157], v235 offset:16384
	buffer_load_dwordx4 v229, s[44:47], s22 offen lds
	s_add_i32 s38, s22, 0x80000
	s_mov_b32 m0, s27
	ds_read_b128 v[194:197], v235 offset:17408
	buffer_load_dwordx4 v231, s[44:47], s22 offen lds
	s_mov_b32 m0, s34
	ds_read_b128 v[198:201], v235 offset:18432
	buffer_load_dwordx4 v229, s[44:47], s38 offen lds
	s_mov_b32 m0, s35
	ds_read_b128 v[202:205], v235 offset:19456
	buffer_load_dwordx4 v231, s[44:47], s38 offen lds
	s_mov_b32 m0, s19
	ds_read_b128 v[236:239], v235 offset:20480
	buffer_load_dwordx4 v228, s[60:63], s23 offen lds
	s_mov_b32 m0, s36
	ds_read_b128 v[240:243], v235 offset:21504
	buffer_load_dwordx4 v230, s[60:63], s23 offen lds
	ds_read_b128 v[244:247], v235 offset:22528
	ds_read_b128 v[248:251], v235 offset:23552
	s_waitcnt vmcnt(8)
	s_waitcnt lgkmcnt(0)
	s_barrier
	v_mfma_f32_16x16x32_bf16 v[62:65], v[130:133], v[154:157], v[62:65]
	v_mfma_f32_16x16x32_bf16 v[62:65], v[140:143], v[194:197], v[62:65]
	v_mfma_f32_16x16x32_bf16 v[58:61], v[170:173], v[154:157], v[58:61]
	v_mfma_f32_16x16x32_bf16 v[58:61], v[174:177], v[194:197], v[58:61]
	v_mfma_f32_16x16x32_bf16 v[46:49], v[186:189], v[154:157], v[46:49]
	v_mfma_f32_16x16x32_bf16 v[46:49], v[190:193], v[194:197], v[46:49]
	v_mfma_f32_16x16x32_bf16 v[54:57], v[178:181], v[154:157], v[54:57]
	v_mfma_f32_16x16x32_bf16 v[54:57], v[182:185], v[194:197], v[54:57]
	v_mfma_f32_16x16x32_bf16 v[38:41], v[178:181], v[198:201], v[38:41]
	v_mfma_f32_16x16x32_bf16 v[38:41], v[182:185], v[202:205], v[38:41]
	v_mfma_f32_16x16x32_bf16 v[30:33], v[186:189], v[198:201], v[30:33]
	v_mfma_f32_16x16x32_bf16 v[30:33], v[190:193], v[202:205], v[30:33]
	v_mfma_f32_16x16x32_bf16 v[42:45], v[170:173], v[198:201], v[42:45]
	v_mfma_f32_16x16x32_bf16 v[42:45], v[174:177], v[202:205], v[42:45]
	v_mfma_f32_16x16x32_bf16 v[50:53], v[130:133], v[198:201], v[50:53]
	v_mfma_f32_16x16x32_bf16 v[50:53], v[140:143], v[202:205], v[50:53]
	v_mfma_f32_16x16x32_bf16 v[34:37], v[130:133], v[236:239], v[34:37]
	v_mfma_f32_16x16x32_bf16 v[34:37], v[140:143], v[240:243], v[34:37]
	v_mfma_f32_16x16x32_bf16 v[26:29], v[170:173], v[236:239], v[26:29]
	v_mfma_f32_16x16x32_bf16 v[26:29], v[174:177], v[240:243], v[26:29]
	v_mfma_f32_16x16x32_bf16 v[14:17], v[186:189], v[236:239], v[14:17]
	v_mfma_f32_16x16x32_bf16 v[14:17], v[190:193], v[240:243], v[14:17]
	v_mfma_f32_16x16x32_bf16 v[22:25], v[178:181], v[236:239], v[22:25]
	v_mfma_f32_16x16x32_bf16 v[22:25], v[182:185], v[240:243], v[22:25]
	v_mfma_f32_16x16x32_bf16 v[6:9], v[178:181], v[244:247], v[6:9]
	v_mfma_f32_16x16x32_bf16 v[6:9], v[182:185], v[248:251], v[6:9]
	v_mfma_f32_16x16x32_bf16 v[2:5], v[186:189], v[244:247], v[2:5]
	v_mfma_f32_16x16x32_bf16 v[2:5], v[190:193], v[248:251], v[2:5]
	v_mfma_f32_16x16x32_bf16 v[10:13], v[170:173], v[244:247], v[10:13]
	v_mfma_f32_16x16x32_bf16 v[10:13], v[174:177], v[248:251], v[10:13]
	v_mfma_f32_16x16x32_bf16 v[18:21], v[130:133], v[244:247], v[18:21]
	v_mfma_f32_16x16x32_bf16 v[18:21], v[140:143], v[248:251], v[18:21]
	s_barrier
	v_add_u32_e32 v139, 0x18000, v234
	ds_read_b128 v[130:133], v139
	ds_read_b128 v[140:143], v139 offset:1024
	ds_read_b128 v[154:157], v139 offset:2048
	ds_read_b128 v[170:173], v139 offset:3072
	v_add_u32_e32 v139, 0x1c000, v234
	ds_read_b128 v[174:177], v139
	ds_read_b128 v[178:181], v139 offset:1024
	ds_read_b128 v[182:185], v139 offset:2048
	ds_read_b128 v[186:189], v139 offset:3072
	s_add_i32 s23, s23, 0x80000
	s_mov_b32 m0, s37
	ds_read_b128 v[190:193], v235 offset:32768
	ds_read_b128 v[194:197], v235 offset:33792
	ds_read_b128 v[198:201], v235 offset:34816
	ds_read_b128 v[202:205], v235 offset:35840
	ds_read_b128 v[236:239], v235 offset:36864
	ds_read_b128 v[240:243], v235 offset:37888
	ds_read_b128 v[244:247], v235 offset:38912
	ds_read_b128 v[248:251], v235 offset:39936
	buffer_load_dwordx4 v228, s[60:63], s23 offen lds
	s_mov_b32 m0, s18
	s_nop 0
	buffer_load_dwordx4 v230, s[60:63], s23 offen lds
	s_waitcnt vmcnt(8)
	s_waitcnt lgkmcnt(0)
	s_barrier
	v_mfma_f32_16x16x32_bf16 v[126:129], v[130:133], v[190:193], v[126:129]
	v_mfma_f32_16x16x32_bf16 v[126:129], v[140:143], v[194:197], v[126:129]
	v_mfma_f32_16x16x32_bf16 v[122:125], v[154:157], v[190:193], v[122:125]
	v_mfma_f32_16x16x32_bf16 v[122:125], v[170:173], v[194:197], v[122:125]
	v_mfma_f32_16x16x32_bf16 v[110:113], v[182:185], v[190:193], v[110:113]
	v_mfma_f32_16x16x32_bf16 v[110:113], v[186:189], v[194:197], v[110:113]
	v_mfma_f32_16x16x32_bf16 v[118:121], v[174:177], v[190:193], v[118:121]
	v_mfma_f32_16x16x32_bf16 v[118:121], v[178:181], v[194:197], v[118:121]
	v_mfma_f32_16x16x32_bf16 v[102:105], v[174:177], v[198:201], v[102:105]
	v_mfma_f32_16x16x32_bf16 v[102:105], v[178:181], v[202:205], v[102:105]
	v_mfma_f32_16x16x32_bf16 v[94:97], v[182:185], v[198:201], v[94:97]
	v_mfma_f32_16x16x32_bf16 v[94:97], v[186:189], v[202:205], v[94:97]
	v_mfma_f32_16x16x32_bf16 v[106:109], v[154:157], v[198:201], v[106:109]
	v_mfma_f32_16x16x32_bf16 v[106:109], v[170:173], v[202:205], v[106:109]
	v_mfma_f32_16x16x32_bf16 v[114:117], v[130:133], v[198:201], v[114:117]
	v_mfma_f32_16x16x32_bf16 v[114:117], v[140:143], v[202:205], v[114:117]
	v_mfma_f32_16x16x32_bf16 v[98:101], v[130:133], v[236:239], v[98:101]
	v_mfma_f32_16x16x32_bf16 v[98:101], v[140:143], v[240:243], v[98:101]
	v_mfma_f32_16x16x32_bf16 v[90:93], v[154:157], v[236:239], v[90:93]
	v_mfma_f32_16x16x32_bf16 v[90:93], v[170:173], v[240:243], v[90:93]
	v_mfma_f32_16x16x32_bf16 v[78:81], v[182:185], v[236:239], v[78:81]
	v_mfma_f32_16x16x32_bf16 v[78:81], v[186:189], v[240:243], v[78:81]
	v_mfma_f32_16x16x32_bf16 v[86:89], v[174:177], v[236:239], v[86:89]
	v_mfma_f32_16x16x32_bf16 v[86:89], v[178:181], v[240:243], v[86:89]
	v_mfma_f32_16x16x32_bf16 v[70:73], v[174:177], v[244:247], v[70:73]
	v_mfma_f32_16x16x32_bf16 v[70:73], v[178:181], v[248:251], v[70:73]
	v_mfma_f32_16x16x32_bf16 v[66:69], v[182:185], v[244:247], v[66:69]
	v_mfma_f32_16x16x32_bf16 v[66:69], v[186:189], v[248:251], v[66:69]
	v_mfma_f32_16x16x32_bf16 v[74:77], v[154:157], v[244:247], v[74:77]
	v_mfma_f32_16x16x32_bf16 v[74:77], v[170:173], v[248:251], v[74:77]
	v_mfma_f32_16x16x32_bf16 v[82:85], v[130:133], v[244:247], v[82:85]
	v_mfma_f32_16x16x32_bf16 v[82:85], v[140:143], v[248:251], v[82:85]
	s_barrier
	s_or_b32 s23, s22, 0x80
	s_mov_b32 m0, s24
	ds_read_b128 v[190:193], v235 offset:49152
	buffer_load_dwordx4 v229, s[44:47], s23 offen lds
	s_add_i32 s22, s22, 0x80080
	s_mov_b32 m0, s25
	ds_read_b128 v[194:197], v235 offset:50176
	buffer_load_dwordx4 v231, s[44:47], s23 offen lds
	s_mov_b32 m0, s64
	ds_read_b128 v[198:201], v235 offset:51200
	buffer_load_dwordx4 v229, s[44:47], s22 offen lds
	s_mov_b32 m0, s65
	ds_read_b128 v[202:205], v235 offset:52224
	buffer_load_dwordx4 v231, s[44:47], s22 offen lds
	s_mov_b32 m0, s48
	ds_read_b128 v[236:239], v235 offset:53248
	buffer_load_dwordx4 v228, s[60:63], s21 offen lds
	s_mov_b32 m0, s49
	ds_read_b128 v[240:243], v235 offset:54272
	buffer_load_dwordx4 v230, s[60:63], s21 offen lds
	ds_read_b128 v[244:247], v235 offset:55296
	ds_read_b128 v[248:251], v235 offset:56320
	s_waitcnt vmcnt(8)
	s_waitcnt lgkmcnt(0)
	s_barrier
	v_mfma_f32_16x16x32_bf16 v[62:65], v[130:133], v[190:193], v[62:65]
	v_mfma_f32_16x16x32_bf16 v[62:65], v[140:143], v[194:197], v[62:65]
	v_mfma_f32_16x16x32_bf16 v[58:61], v[154:157], v[190:193], v[58:61]
	v_mfma_f32_16x16x32_bf16 v[58:61], v[170:173], v[194:197], v[58:61]
	v_mfma_f32_16x16x32_bf16 v[46:49], v[182:185], v[190:193], v[46:49]
	v_mfma_f32_16x16x32_bf16 v[46:49], v[186:189], v[194:197], v[46:49]
	v_mfma_f32_16x16x32_bf16 v[54:57], v[174:177], v[190:193], v[54:57]
	v_mfma_f32_16x16x32_bf16 v[54:57], v[178:181], v[194:197], v[54:57]
	v_mfma_f32_16x16x32_bf16 v[38:41], v[174:177], v[198:201], v[38:41]
	v_mfma_f32_16x16x32_bf16 v[38:41], v[178:181], v[202:205], v[38:41]
	v_mfma_f32_16x16x32_bf16 v[30:33], v[182:185], v[198:201], v[30:33]
	v_mfma_f32_16x16x32_bf16 v[30:33], v[186:189], v[202:205], v[30:33]
	v_mfma_f32_16x16x32_bf16 v[42:45], v[154:157], v[198:201], v[42:45]
	v_mfma_f32_16x16x32_bf16 v[42:45], v[170:173], v[202:205], v[42:45]
	v_mfma_f32_16x16x32_bf16 v[50:53], v[130:133], v[198:201], v[50:53]
	v_mfma_f32_16x16x32_bf16 v[50:53], v[140:143], v[202:205], v[50:53]
	v_mfma_f32_16x16x32_bf16 v[34:37], v[130:133], v[236:239], v[34:37]
	v_mfma_f32_16x16x32_bf16 v[34:37], v[140:143], v[240:243], v[34:37]
	v_mfma_f32_16x16x32_bf16 v[26:29], v[154:157], v[236:239], v[26:29]
	v_mfma_f32_16x16x32_bf16 v[26:29], v[170:173], v[240:243], v[26:29]
	v_mfma_f32_16x16x32_bf16 v[14:17], v[182:185], v[236:239], v[14:17]
	v_mfma_f32_16x16x32_bf16 v[14:17], v[186:189], v[240:243], v[14:17]
	v_mfma_f32_16x16x32_bf16 v[22:25], v[174:177], v[236:239], v[22:25]
	v_mfma_f32_16x16x32_bf16 v[22:25], v[178:181], v[240:243], v[22:25]
	v_mfma_f32_16x16x32_bf16 v[6:9], v[174:177], v[244:247], v[6:9]
	v_mfma_f32_16x16x32_bf16 v[6:9], v[178:181], v[248:251], v[6:9]
	v_mfma_f32_16x16x32_bf16 v[2:5], v[182:185], v[244:247], v[2:5]
	v_mfma_f32_16x16x32_bf16 v[2:5], v[186:189], v[248:251], v[2:5]
	v_mfma_f32_16x16x32_bf16 v[10:13], v[154:157], v[244:247], v[10:13]
	v_mfma_f32_16x16x32_bf16 v[10:13], v[170:173], v[248:251], v[10:13]
	v_mfma_f32_16x16x32_bf16 v[18:21], v[130:133], v[244:247], v[18:21]
	v_mfma_f32_16x16x32_bf16 v[18:21], v[140:143], v[248:251], v[18:21]
	s_barrier
	s_add_i32 s16, s16, 2
	s_addk_i32 s12, 0x100
	s_addk_i32 s13, 0x100
	s_cmp_gt_u32 s16, 29
	s_cbranch_scc0 .LBB0_881
	v_readlane_b32 s8, v255, 44
	v_readlane_b32 s9, v255, 45
	s_and_b64 vcc, exec, s[8:9]
	s_cbranch_vccz .LBB0_884
	s_barrier

.LBB0_904:
	s_lshl_b32 s73, s72, 20
	s_and_b64 s[8:9], s[42:43], exec
	s_cselect_b32 s8, s73, s13
	s_lshl_b32 s84, s71, 20
	s_and_b64 s[22:23], s[42:43], exec
	s_cselect_b32 s9, s84, s21
	s_add_i32 s13, s13, 0x80080
	s_addk_i32 s21, 0x100
	s_mov_b32 s22, -2
	v_add_u32_e32 v133, 0x10000, v178
	ds_read_b128 v[134:137], v133
	ds_read_b128 v[138:141], v133 offset:1024
	ds_read_b128 v[142:145], v133 offset:2048
	ds_read_b128 v[154:157], v133 offset:3072
	v_add_u32_e32 v133, 0x14000, v178
	ds_read_b128 v[170:173], v133
	ds_read_b128 v[180:183], v133 offset:1024
	ds_read_b128 v[184:187], v133 offset:2048
	ds_read_b128 v[188:191], v133 offset:3072
	s_add_i32 s23, s13, 0xfff80080
	s_cmp_eq_u32 s22, 28
	s_cselect_b32 s27, s8, s23
	s_cselect_b32 s26, s9, s21
	s_or_b32 s23, s27, 0x80
	s_mov_b32 s46, s62
	s_mov_b32 s47, s63
	s_mov_b32 m0, s68
	ds_read_b128 v[192:195], v179
	ds_read_b128 v[196:199], v179 offset:1024
	ds_read_b128 v[200:203], v179 offset:2048
	ds_read_b128 v[204:207], v179 offset:3072
	ds_read_b128 v[228:231], v179 offset:4096
	ds_read_b128 v[232:235], v179 offset:5120
	ds_read_b128 v[236:239], v179 offset:6144
	ds_read_b128 v[240:243], v179 offset:7168
	buffer_load_dwordx4 v174, s[44:47], s13 offen lds
	s_mov_b32 m0, s69
	s_nop 0
	buffer_load_dwordx4 v176, s[44:47], s13 offen lds
	s_waitcnt vmcnt(8)
	s_waitcnt lgkmcnt(0)
	s_barrier
	v_mfma_f32_16x16x32_bf16 v[126:129], v[134:137], v[192:195], 0
	v_mfma_f32_16x16x32_bf16 v[126:129], v[138:141], v[196:199], v[126:129]
	v_mfma_f32_16x16x32_bf16 v[122:125], v[142:145], v[192:195], 0
	v_mfma_f32_16x16x32_bf16 v[122:125], v[154:157], v[196:199], v[122:125]
	v_mfma_f32_16x16x32_bf16 v[114:117], v[184:187], v[192:195], 0
	v_mfma_f32_16x16x32_bf16 v[114:117], v[188:191], v[196:199], v[114:117]
	v_mfma_f32_16x16x32_bf16 v[118:121], v[170:173], v[192:195], 0
	v_mfma_f32_16x16x32_bf16 v[118:121], v[180:183], v[196:199], v[118:121]
	v_mfma_f32_16x16x32_bf16 v[102:105], v[170:173], v[200:203], 0
	v_mfma_f32_16x16x32_bf16 v[102:105], v[180:183], v[204:207], v[102:105]
	v_mfma_f32_16x16x32_bf16 v[98:101], v[184:187], v[200:203], 0
	v_mfma_f32_16x16x32_bf16 v[98:101], v[188:191], v[204:207], v[98:101]
	v_mfma_f32_16x16x32_bf16 v[106:109], v[142:145], v[200:203], 0
	v_mfma_f32_16x16x32_bf16 v[106:109], v[154:157], v[204:207], v[106:109]
	v_mfma_f32_16x16x32_bf16 v[110:113], v[134:137], v[200:203], 0
	v_mfma_f32_16x16x32_bf16 v[110:113], v[138:141], v[204:207], v[110:113]
	v_mfma_f32_16x16x32_bf16 v[94:97], v[134:137], v[228:231], 0
	v_mfma_f32_16x16x32_bf16 v[94:97], v[138:141], v[232:235], v[94:97]
	v_mfma_f32_16x16x32_bf16 v[90:93], v[142:145], v[228:231], 0
	v_mfma_f32_16x16x32_bf16 v[90:93], v[154:157], v[232:235], v[90:93]
	v_mfma_f32_16x16x32_bf16 v[82:85], v[184:187], v[228:231], 0
	v_mfma_f32_16x16x32_bf16 v[82:85], v[188:191], v[232:235], v[82:85]
	v_mfma_f32_16x16x32_bf16 v[86:89], v[170:173], v[228:231], 0
	v_mfma_f32_16x16x32_bf16 v[86:89], v[180:183], v[232:235], v[86:89]
	v_mfma_f32_16x16x32_bf16 v[70:73], v[170:173], v[236:239], 0
	v_mfma_f32_16x16x32_bf16 v[70:73], v[180:183], v[240:243], v[70:73]
	v_mfma_f32_16x16x32_bf16 v[66:69], v[184:187], v[236:239], 0
	v_mfma_f32_16x16x32_bf16 v[66:69], v[188:191], v[240:243], v[66:69]
	v_mfma_f32_16x16x32_bf16 v[74:77], v[142:145], v[236:239], 0
	v_mfma_f32_16x16x32_bf16 v[74:77], v[154:157], v[240:243], v[74:77]
	v_mfma_f32_16x16x32_bf16 v[78:81], v[134:137], v[236:239], 0
	v_mfma_f32_16x16x32_bf16 v[78:81], v[138:141], v[240:243], v[78:81]
	s_barrier
	s_mov_b32 m0, s15
	ds_read_b128 v[192:195], v179 offset:16384
	buffer_load_dwordx4 v175, s[60:63], s26 offen lds
	s_add_i32 s34, s26, 0x80000
	s_mov_b32 m0, s16
	ds_read_b128 v[196:199], v179 offset:17408
	buffer_load_dwordx4 v177, s[60:63], s26 offen lds
	s_mov_b32 m0, s18
	ds_read_b128 v[200:203], v179 offset:18432
	buffer_load_dwordx4 v175, s[60:63], s34 offen lds
	s_mov_b32 m0, s19
	ds_read_b128 v[204:207], v179 offset:19456
	buffer_load_dwordx4 v177, s[60:63], s34 offen lds
	s_mov_b32 m0, s14
	ds_read_b128 v[228:231], v179 offset:20480
	buffer_load_dwordx4 v174, s[44:47], s27 offen lds
	s_mov_b32 m0, s24
	ds_read_b128 v[232:235], v179 offset:21504
	buffer_load_dwordx4 v176, s[44:47], s27 offen lds
	ds_read_b128 v[236:239], v179 offset:22528
	ds_read_b128 v[240:243], v179 offset:23552
	s_waitcnt vmcnt(8)
	s_waitcnt lgkmcnt(0)
	s_barrier
	v_mfma_f32_16x16x32_bf16 v[62:65], v[134:137], v[192:195], 0
	v_mfma_f32_16x16x32_bf16 v[62:65], v[138:141], v[196:199], v[62:65]
	v_mfma_f32_16x16x32_bf16 v[58:61], v[142:145], v[192:195], 0
	v_mfma_f32_16x16x32_bf16 v[58:61], v[154:157], v[196:199], v[58:61]
	v_mfma_f32_16x16x32_bf16 v[50:53], v[184:187], v[192:195], 0
	v_mfma_f32_16x16x32_bf16 v[50:53], v[188:191], v[196:199], v[50:53]
	v_mfma_f32_16x16x32_bf16 v[54:57], v[170:173], v[192:195], 0
	v_mfma_f32_16x16x32_bf16 v[54:57], v[180:183], v[196:199], v[54:57]
	v_mfma_f32_16x16x32_bf16 v[38:41], v[170:173], v[200:203], 0
	v_mfma_f32_16x16x32_bf16 v[38:41], v[180:183], v[204:207], v[38:41]
	v_mfma_f32_16x16x32_bf16 v[34:37], v[184:187], v[200:203], 0
	v_mfma_f32_16x16x32_bf16 v[34:37], v[188:191], v[204:207], v[34:37]
	v_mfma_f32_16x16x32_bf16 v[42:45], v[142:145], v[200:203], 0
	v_mfma_f32_16x16x32_bf16 v[42:45], v[154:157], v[204:207], v[42:45]
	v_mfma_f32_16x16x32_bf16 v[46:49], v[134:137], v[200:203], 0
	v_mfma_f32_16x16x32_bf16 v[46:49], v[138:141], v[204:207], v[46:49]
	v_mfma_f32_16x16x32_bf16 v[30:33], v[134:137], v[228:231], 0
	v_mfma_f32_16x16x32_bf16 v[30:33], v[138:141], v[232:235], v[30:33]
	v_mfma_f32_16x16x32_bf16 v[26:29], v[142:145], v[228:231], 0
	v_mfma_f32_16x16x32_bf16 v[26:29], v[154:157], v[232:235], v[26:29]
	v_mfma_f32_16x16x32_bf16 v[18:21], v[184:187], v[228:231], 0
	v_mfma_f32_16x16x32_bf16 v[18:21], v[188:191], v[232:235], v[18:21]
	v_mfma_f32_16x16x32_bf16 v[22:25], v[170:173], v[228:231], 0
	v_mfma_f32_16x16x32_bf16 v[22:25], v[180:183], v[232:235], v[22:25]
	v_mfma_f32_16x16x32_bf16 v[6:9], v[170:173], v[236:239], 0
	v_mfma_f32_16x16x32_bf16 v[6:9], v[180:183], v[240:243], v[6:9]
	v_mfma_f32_16x16x32_bf16 v[2:5], v[184:187], v[236:239], 0
	v_mfma_f32_16x16x32_bf16 v[2:5], v[188:191], v[240:243], v[2:5]
	v_mfma_f32_16x16x32_bf16 v[10:13], v[142:145], v[236:239], 0
	v_mfma_f32_16x16x32_bf16 v[10:13], v[154:157], v[240:243], v[10:13]
	v_mfma_f32_16x16x32_bf16 v[14:17], v[134:137], v[236:239], 0
	v_mfma_f32_16x16x32_bf16 v[14:17], v[138:141], v[240:243], v[14:17]
	s_barrier
	v_add_u32_e32 v133, 0x18000, v178
	ds_read_b128 v[134:137], v133
	ds_read_b128 v[138:141], v133 offset:1024
	ds_read_b128 v[142:145], v133 offset:2048
	ds_read_b128 v[154:157], v133 offset:3072
	v_add_u32_e32 v133, 0x1c000, v178
	ds_read_b128 v[170:173], v133
	ds_read_b128 v[180:183], v133 offset:1024
	ds_read_b128 v[184:187], v133 offset:2048
	ds_read_b128 v[188:191], v133 offset:3072
	s_add_i32 s27, s27, 0x80000
	s_mov_b32 m0, s25
	ds_read_b128 v[192:195], v179 offset:32768
	ds_read_b128 v[196:199], v179 offset:33792
	ds_read_b128 v[200:203], v179 offset:34816
	ds_read_b128 v[204:207], v179 offset:35840
	ds_read_b128 v[228:231], v179 offset:36864
	ds_read_b128 v[232:235], v179 offset:37888
	ds_read_b128 v[236:239], v179 offset:38912
	ds_read_b128 v[240:243], v179 offset:39936
	buffer_load_dwordx4 v174, s[44:47], s27 offen lds
	s_mov_b32 m0, s30
	s_nop 0
	buffer_load_dwordx4 v176, s[44:47], s27 offen lds
	s_waitcnt vmcnt(8)
	s_waitcnt lgkmcnt(0)
	s_barrier
	v_mfma_f32_16x16x32_bf16 v[126:129], v[134:137], v[192:195], v[126:129]
	v_mfma_f32_16x16x32_bf16 v[126:129], v[138:141], v[196:199], v[126:129]
	v_mfma_f32_16x16x32_bf16 v[122:125], v[142:145], v[192:195], v[122:125]
	v_mfma_f32_16x16x32_bf16 v[122:125], v[154:157], v[196:199], v[122:125]
	v_mfma_f32_16x16x32_bf16 v[114:117], v[184:187], v[192:195], v[114:117]
	v_mfma_f32_16x16x32_bf16 v[114:117], v[188:191], v[196:199], v[114:117]
	v_mfma_f32_16x16x32_bf16 v[118:121], v[170:173], v[192:195], v[118:121]
	v_mfma_f32_16x16x32_bf16 v[118:121], v[180:183], v[196:199], v[118:121]
	v_mfma_f32_16x16x32_bf16 v[102:105], v[170:173], v[200:203], v[102:105]
	v_mfma_f32_16x16x32_bf16 v[102:105], v[180:183], v[204:207], v[102:105]
	v_mfma_f32_16x16x32_bf16 v[98:101], v[184:187], v[200:203], v[98:101]
	v_mfma_f32_16x16x32_bf16 v[98:101], v[188:191], v[204:207], v[98:101]
	v_mfma_f32_16x16x32_bf16 v[106:109], v[142:145], v[200:203], v[106:109]
	v_mfma_f32_16x16x32_bf16 v[106:109], v[154:157], v[204:207], v[106:109]
	v_mfma_f32_16x16x32_bf16 v[110:113], v[134:137], v[200:203], v[110:113]
	v_mfma_f32_16x16x32_bf16 v[110:113], v[138:141], v[204:207], v[110:113]
	v_mfma_f32_16x16x32_bf16 v[94:97], v[134:137], v[228:231], v[94:97]
	v_mfma_f32_16x16x32_bf16 v[94:97], v[138:141], v[232:235], v[94:97]
	v_mfma_f32_16x16x32_bf16 v[90:93], v[142:145], v[228:231], v[90:93]
	v_mfma_f32_16x16x32_bf16 v[90:93], v[154:157], v[232:235], v[90:93]
	v_mfma_f32_16x16x32_bf16 v[82:85], v[184:187], v[228:231], v[82:85]
	v_mfma_f32_16x16x32_bf16 v[82:85], v[188:191], v[232:235], v[82:85]
	v_mfma_f32_16x16x32_bf16 v[86:89], v[170:173], v[228:231], v[86:89]
	v_mfma_f32_16x16x32_bf16 v[86:89], v[180:183], v[232:235], v[86:89]
	v_mfma_f32_16x16x32_bf16 v[70:73], v[170:173], v[236:239], v[70:73]
	v_mfma_f32_16x16x32_bf16 v[70:73], v[180:183], v[240:243], v[70:73]
	v_mfma_f32_16x16x32_bf16 v[66:69], v[184:187], v[236:239], v[66:69]
	v_mfma_f32_16x16x32_bf16 v[66:69], v[188:191], v[240:243], v[66:69]
	v_mfma_f32_16x16x32_bf16 v[74:77], v[142:145], v[236:239], v[74:77]
	v_mfma_f32_16x16x32_bf16 v[74:77], v[154:157], v[240:243], v[74:77]
	v_mfma_f32_16x16x32_bf16 v[78:81], v[134:137], v[236:239], v[78:81]
	v_mfma_f32_16x16x32_bf16 v[78:81], v[138:141], v[240:243], v[78:81]
	s_barrier
	s_or_b32 s27, s26, 0x80
	s_mov_b32 m0, s36
	ds_read_b128 v[192:195], v179 offset:49152
	buffer_load_dwordx4 v175, s[60:63], s27 offen lds
	s_add_i32 s26, s26, 0x80080
	s_mov_b32 m0, s37
	ds_read_b128 v[196:199], v179 offset:50176
	buffer_load_dwordx4 v177, s[60:63], s27 offen lds
	s_mov_b32 m0, s48
	ds_read_b128 v[200:203], v179 offset:51200
	buffer_load_dwordx4 v175, s[60:63], s26 offen lds
	s_mov_b32 m0, s49
	ds_read_b128 v[204:207], v179 offset:52224
	buffer_load_dwordx4 v177, s[60:63], s26 offen lds
	s_mov_b32 m0, s40
	ds_read_b128 v[228:231], v179 offset:53248
	buffer_load_dwordx4 v174, s[44:47], s23 offen lds
	s_mov_b32 m0, s41
	ds_read_b128 v[232:235], v179 offset:54272
	buffer_load_dwordx4 v176, s[44:47], s23 offen lds
	ds_read_b128 v[236:239], v179 offset:55296
	ds_read_b128 v[240:243], v179 offset:56320
	s_waitcnt vmcnt(8)
	s_waitcnt lgkmcnt(0)
	s_barrier
	v_mfma_f32_16x16x32_bf16 v[62:65], v[134:137], v[192:195], v[62:65]
	v_mfma_f32_16x16x32_bf16 v[62:65], v[138:141], v[196:199], v[62:65]
	v_mfma_f32_16x16x32_bf16 v[58:61], v[142:145], v[192:195], v[58:61]
	v_mfma_f32_16x16x32_bf16 v[58:61], v[154:157], v[196:199], v[58:61]
	v_mfma_f32_16x16x32_bf16 v[50:53], v[184:187], v[192:195], v[50:53]
	v_mfma_f32_16x16x32_bf16 v[50:53], v[188:191], v[196:199], v[50:53]
	v_mfma_f32_16x16x32_bf16 v[54:57], v[170:173], v[192:195], v[54:57]
	v_mfma_f32_16x16x32_bf16 v[54:57], v[180:183], v[196:199], v[54:57]
	v_mfma_f32_16x16x32_bf16 v[38:41], v[170:173], v[200:203], v[38:41]
	v_mfma_f32_16x16x32_bf16 v[38:41], v[180:183], v[204:207], v[38:41]
	v_mfma_f32_16x16x32_bf16 v[34:37], v[184:187], v[200:203], v[34:37]
	v_mfma_f32_16x16x32_bf16 v[34:37], v[188:191], v[204:207], v[34:37]
	v_mfma_f32_16x16x32_bf16 v[42:45], v[142:145], v[200:203], v[42:45]
	v_mfma_f32_16x16x32_bf16 v[42:45], v[154:157], v[204:207], v[42:45]
	v_mfma_f32_16x16x32_bf16 v[46:49], v[134:137], v[200:203], v[46:49]
	v_mfma_f32_16x16x32_bf16 v[46:49], v[138:141], v[204:207], v[46:49]
	v_mfma_f32_16x16x32_bf16 v[30:33], v[134:137], v[228:231], v[30:33]
	v_mfma_f32_16x16x32_bf16 v[30:33], v[138:141], v[232:235], v[30:33]
	v_mfma_f32_16x16x32_bf16 v[26:29], v[142:145], v[228:231], v[26:29]
	v_mfma_f32_16x16x32_bf16 v[26:29], v[154:157], v[232:235], v[26:29]
	v_mfma_f32_16x16x32_bf16 v[18:21], v[184:187], v[228:231], v[18:21]
	v_mfma_f32_16x16x32_bf16 v[18:21], v[188:191], v[232:235], v[18:21]
	v_mfma_f32_16x16x32_bf16 v[22:25], v[170:173], v[228:231], v[22:25]
	v_mfma_f32_16x16x32_bf16 v[22:25], v[180:183], v[232:235], v[22:25]
	v_mfma_f32_16x16x32_bf16 v[6:9], v[170:173], v[236:239], v[6:9]
	v_mfma_f32_16x16x32_bf16 v[6:9], v[180:183], v[240:243], v[6:9]
	v_mfma_f32_16x16x32_bf16 v[2:5], v[184:187], v[236:239], v[2:5]
	v_mfma_f32_16x16x32_bf16 v[2:5], v[188:191], v[240:243], v[2:5]
	v_mfma_f32_16x16x32_bf16 v[10:13], v[142:145], v[236:239], v[10:13]
	v_mfma_f32_16x16x32_bf16 v[10:13], v[154:157], v[240:243], v[10:13]
	v_mfma_f32_16x16x32_bf16 v[14:17], v[134:137], v[236:239], v[14:17]
	v_mfma_f32_16x16x32_bf16 v[14:17], v[138:141], v[240:243], v[14:17]
	s_barrier
	s_add_i32 s22, s22, 2
	s_addk_i32 s13, 0x100
	s_addk_i32 s21, 0x100
	s_cmp_gt_u32 s22, 29
.LBB0_905:
	v_add_u32_e32 v133, 0x10000, v178
	ds_read_b128 v[134:137], v133
	ds_read_b128 v[138:141], v133 offset:1024
	ds_read_b128 v[142:145], v133 offset:2048
	ds_read_b128 v[154:157], v133 offset:3072
	v_add_u32_e32 v133, 0x14000, v178
	ds_read_b128 v[170:173], v133
	ds_read_b128 v[180:183], v133 offset:1024
	ds_read_b128 v[184:187], v133 offset:2048
	ds_read_b128 v[188:191], v133 offset:3072
	s_add_i32 s23, s13, 0xfff80080
	s_cmp_eq_u32 s22, 28
	s_cselect_b32 s27, s8, s23
	s_cselect_b32 s26, s9, s21
	s_or_b32 s23, s27, 0x80
	s_mov_b32 s46, s62
	s_mov_b32 s47, s63
	s_mov_b32 m0, s68
	ds_read_b128 v[192:195], v179
	ds_read_b128 v[196:199], v179 offset:1024
	ds_read_b128 v[200:203], v179 offset:2048
	ds_read_b128 v[204:207], v179 offset:3072
	ds_read_b128 v[228:231], v179 offset:4096
	ds_read_b128 v[232:235], v179 offset:5120
	ds_read_b128 v[236:239], v179 offset:6144
	ds_read_b128 v[240:243], v179 offset:7168
	buffer_load_dwordx4 v174, s[44:47], s13 offen lds
	s_mov_b32 m0, s69
	s_nop 0
	buffer_load_dwordx4 v176, s[44:47], s13 offen lds
	s_waitcnt vmcnt(8)
	s_waitcnt lgkmcnt(0)
	s_barrier
	v_mfma_f32_16x16x32_bf16 v[126:129], v[134:137], v[192:195], v[126:129]
	v_mfma_f32_16x16x32_bf16 v[126:129], v[138:141], v[196:199], v[126:129]
	v_mfma_f32_16x16x32_bf16 v[122:125], v[142:145], v[192:195], v[122:125]
	v_mfma_f32_16x16x32_bf16 v[122:125], v[154:157], v[196:199], v[122:125]
	v_mfma_f32_16x16x32_bf16 v[114:117], v[184:187], v[192:195], v[114:117]
	v_mfma_f32_16x16x32_bf16 v[114:117], v[188:191], v[196:199], v[114:117]
	v_mfma_f32_16x16x32_bf16 v[118:121], v[170:173], v[192:195], v[118:121]
	v_mfma_f32_16x16x32_bf16 v[118:121], v[180:183], v[196:199], v[118:121]
	v_mfma_f32_16x16x32_bf16 v[102:105], v[170:173], v[200:203], v[102:105]
	v_mfma_f32_16x16x32_bf16 v[102:105], v[180:183], v[204:207], v[102:105]
	v_mfma_f32_16x16x32_bf16 v[98:101], v[184:187], v[200:203], v[98:101]
	v_mfma_f32_16x16x32_bf16 v[98:101], v[188:191], v[204:207], v[98:101]
	v_mfma_f32_16x16x32_bf16 v[106:109], v[142:145], v[200:203], v[106:109]
	v_mfma_f32_16x16x32_bf16 v[106:109], v[154:157], v[204:207], v[106:109]
	v_mfma_f32_16x16x32_bf16 v[110:113], v[134:137], v[200:203], v[110:113]
	v_mfma_f32_16x16x32_bf16 v[110:113], v[138:141], v[204:207], v[110:113]
	v_mfma_f32_16x16x32_bf16 v[94:97], v[134:137], v[228:231], v[94:97]
	v_mfma_f32_16x16x32_bf16 v[94:97], v[138:141], v[232:235], v[94:97]
	v_mfma_f32_16x16x32_bf16 v[90:93], v[142:145], v[228:231], v[90:93]
	v_mfma_f32_16x16x32_bf16 v[90:93], v[154:157], v[232:235], v[90:93]
	v_mfma_f32_16x16x32_bf16 v[82:85], v[184:187], v[228:231], v[82:85]
	v_mfma_f32_16x16x32_bf16 v[82:85], v[188:191], v[232:235], v[82:85]
	v_mfma_f32_16x16x32_bf16 v[86:89], v[170:173], v[228:231], v[86:89]
	v_mfma_f32_16x16x32_bf16 v[86:89], v[180:183], v[232:235], v[86:89]
	v_mfma_f32_16x16x32_bf16 v[70:73], v[170:173], v[236:239], v[70:73]
	v_mfma_f32_16x16x32_bf16 v[70:73], v[180:183], v[240:243], v[70:73]
	v_mfma_f32_16x16x32_bf16 v[66:69], v[184:187], v[236:239], v[66:69]
	v_mfma_f32_16x16x32_bf16 v[66:69], v[188:191], v[240:243], v[66:69]
	v_mfma_f32_16x16x32_bf16 v[74:77], v[142:145], v[236:239], v[74:77]
	v_mfma_f32_16x16x32_bf16 v[74:77], v[154:157], v[240:243], v[74:77]
	v_mfma_f32_16x16x32_bf16 v[78:81], v[134:137], v[236:239], v[78:81]
	v_mfma_f32_16x16x32_bf16 v[78:81], v[138:141], v[240:243], v[78:81]
	s_barrier
	s_mov_b32 m0, s15
	ds_read_b128 v[192:195], v179 offset:16384
	buffer_load_dwordx4 v175, s[60:63], s26 offen lds
	s_add_i32 s34, s26, 0x80000
	s_mov_b32 m0, s16
	ds_read_b128 v[196:199], v179 offset:17408
	buffer_load_dwordx4 v177, s[60:63], s26 offen lds
	s_mov_b32 m0, s18
	ds_read_b128 v[200:203], v179 offset:18432
	buffer_load_dwordx4 v175, s[60:63], s34 offen lds
	s_mov_b32 m0, s19
	ds_read_b128 v[204:207], v179 offset:19456
	buffer_load_dwordx4 v177, s[60:63], s34 offen lds
	s_mov_b32 m0, s14
	ds_read_b128 v[228:231], v179 offset:20480
	buffer_load_dwordx4 v174, s[44:47], s27 offen lds
	s_mov_b32 m0, s24
	ds_read_b128 v[232:235], v179 offset:21504
	buffer_load_dwordx4 v176, s[44:47], s27 offen lds
	ds_read_b128 v[236:239], v179 offset:22528
	ds_read_b128 v[240:243], v179 offset:23552
	s_waitcnt vmcnt(8)
	s_waitcnt lgkmcnt(0)
	s_barrier
	v_mfma_f32_16x16x32_bf16 v[62:65], v[134:137], v[192:195], v[62:65]
	v_mfma_f32_16x16x32_bf16 v[62:65], v[138:141], v[196:199], v[62:65]
	v_mfma_f32_16x16x32_bf16 v[58:61], v[142:145], v[192:195], v[58:61]
	v_mfma_f32_16x16x32_bf16 v[58:61], v[154:157], v[196:199], v[58:61]
	v_mfma_f32_16x16x32_bf16 v[50:53], v[184:187], v[192:195], v[50:53]
	v_mfma_f32_16x16x32_bf16 v[50:53], v[188:191], v[196:199], v[50:53]
	v_mfma_f32_16x16x32_bf16 v[54:57], v[170:173], v[192:195], v[54:57]
	v_mfma_f32_16x16x32_bf16 v[54:57], v[180:183], v[196:199], v[54:57]
	v_mfma_f32_16x16x32_bf16 v[38:41], v[170:173], v[200:203], v[38:41]
	v_mfma_f32_16x16x32_bf16 v[38:41], v[180:183], v[204:207], v[38:41]
	v_mfma_f32_16x16x32_bf16 v[34:37], v[184:187], v[200:203], v[34:37]
	v_mfma_f32_16x16x32_bf16 v[34:37], v[188:191], v[204:207], v[34:37]
	v_mfma_f32_16x16x32_bf16 v[42:45], v[142:145], v[200:203], v[42:45]
	v_mfma_f32_16x16x32_bf16 v[42:45], v[154:157], v[204:207], v[42:45]
	v_mfma_f32_16x16x32_bf16 v[46:49], v[134:137], v[200:203], v[46:49]
	v_mfma_f32_16x16x32_bf16 v[46:49], v[138:141], v[204:207], v[46:49]
	v_mfma_f32_16x16x32_bf16 v[30:33], v[134:137], v[228:231], v[30:33]
	v_mfma_f32_16x16x32_bf16 v[30:33], v[138:141], v[232:235], v[30:33]
	v_mfma_f32_16x16x32_bf16 v[26:29], v[142:145], v[228:231], v[26:29]
	v_mfma_f32_16x16x32_bf16 v[26:29], v[154:157], v[232:235], v[26:29]
	v_mfma_f32_16x16x32_bf16 v[18:21], v[184:187], v[228:231], v[18:21]
	v_mfma_f32_16x16x32_bf16 v[18:21], v[188:191], v[232:235], v[18:21]
	v_mfma_f32_16x16x32_bf16 v[22:25], v[170:173], v[228:231], v[22:25]
	v_mfma_f32_16x16x32_bf16 v[22:25], v[180:183], v[232:235], v[22:25]
	v_mfma_f32_16x16x32_bf16 v[6:9], v[170:173], v[236:239], v[6:9]
	v_mfma_f32_16x16x32_bf16 v[6:9], v[180:183], v[240:243], v[6:9]
	v_mfma_f32_16x16x32_bf16 v[2:5], v[184:187], v[236:239], v[2:5]
	v_mfma_f32_16x16x32_bf16 v[2:5], v[188:191], v[240:243], v[2:5]
	v_mfma_f32_16x16x32_bf16 v[10:13], v[142:145], v[236:239], v[10:13]
	v_mfma_f32_16x16x32_bf16 v[10:13], v[154:157], v[240:243], v[10:13]
	v_mfma_f32_16x16x32_bf16 v[14:17], v[134:137], v[236:239], v[14:17]
	v_mfma_f32_16x16x32_bf16 v[14:17], v[138:141], v[240:243], v[14:17]
	s_barrier
	v_add_u32_e32 v133, 0x18000, v178
	ds_read_b128 v[134:137], v133
	ds_read_b128 v[138:141], v133 offset:1024
	ds_read_b128 v[142:145], v133 offset:2048
	ds_read_b128 v[154:157], v133 offset:3072
	v_add_u32_e32 v133, 0x1c000, v178
	ds_read_b128 v[170:173], v133
	ds_read_b128 v[180:183], v133 offset:1024
	ds_read_b128 v[184:187], v133 offset:2048
	ds_read_b128 v[188:191], v133 offset:3072
	s_add_i32 s27, s27, 0x80000
	s_mov_b32 m0, s25
	ds_read_b128 v[192:195], v179 offset:32768
	ds_read_b128 v[196:199], v179 offset:33792
	ds_read_b128 v[200:203], v179 offset:34816
	ds_read_b128 v[204:207], v179 offset:35840
	ds_read_b128 v[228:231], v179 offset:36864
	ds_read_b128 v[232:235], v179 offset:37888
	ds_read_b128 v[236:239], v179 offset:38912
	ds_read_b128 v[240:243], v179 offset:39936
	buffer_load_dwordx4 v174, s[44:47], s27 offen lds
	s_mov_b32 m0, s30
	s_nop 0
	buffer_load_dwordx4 v176, s[44:47], s27 offen lds
	s_waitcnt vmcnt(8)
	s_waitcnt lgkmcnt(0)
	s_barrier
	v_mfma_f32_16x16x32_bf16 v[126:129], v[134:137], v[192:195], v[126:129]
	v_mfma_f32_16x16x32_bf16 v[126:129], v[138:141], v[196:199], v[126:129]
	v_mfma_f32_16x16x32_bf16 v[122:125], v[142:145], v[192:195], v[122:125]
	v_mfma_f32_16x16x32_bf16 v[122:125], v[154:157], v[196:199], v[122:125]
	v_mfma_f32_16x16x32_bf16 v[114:117], v[184:187], v[192:195], v[114:117]
	v_mfma_f32_16x16x32_bf16 v[114:117], v[188:191], v[196:199], v[114:117]
	v_mfma_f32_16x16x32_bf16 v[118:121], v[170:173], v[192:195], v[118:121]
	v_mfma_f32_16x16x32_bf16 v[118:121], v[180:183], v[196:199], v[118:121]
	v_mfma_f32_16x16x32_bf16 v[102:105], v[170:173], v[200:203], v[102:105]
	v_mfma_f32_16x16x32_bf16 v[102:105], v[180:183], v[204:207], v[102:105]
	v_mfma_f32_16x16x32_bf16 v[98:101], v[184:187], v[200:203], v[98:101]
	v_mfma_f32_16x16x32_bf16 v[98:101], v[188:191], v[204:207], v[98:101]
	v_mfma_f32_16x16x32_bf16 v[106:109], v[142:145], v[200:203], v[106:109]
	v_mfma_f32_16x16x32_bf16 v[106:109], v[154:157], v[204:207], v[106:109]
	v_mfma_f32_16x16x32_bf16 v[110:113], v[134:137], v[200:203], v[110:113]
	v_mfma_f32_16x16x32_bf16 v[110:113], v[138:141], v[204:207], v[110:113]
	v_mfma_f32_16x16x32_bf16 v[94:97], v[134:137], v[228:231], v[94:97]
	v_mfma_f32_16x16x32_bf16 v[94:97], v[138:141], v[232:235], v[94:97]
	v_mfma_f32_16x16x32_bf16 v[90:93], v[142:145], v[228:231], v[90:93]
	v_mfma_f32_16x16x32_bf16 v[90:93], v[154:157], v[232:235], v[90:93]
	v_mfma_f32_16x16x32_bf16 v[82:85], v[184:187], v[228:231], v[82:85]
	v_mfma_f32_16x16x32_bf16 v[82:85], v[188:191], v[232:235], v[82:85]
	v_mfma_f32_16x16x32_bf16 v[86:89], v[170:173], v[228:231], v[86:89]
	v_mfma_f32_16x16x32_bf16 v[86:89], v[180:183], v[232:235], v[86:89]
	v_mfma_f32_16x16x32_bf16 v[70:73], v[170:173], v[236:239], v[70:73]
	v_mfma_f32_16x16x32_bf16 v[70:73], v[180:183], v[240:243], v[70:73]
	v_mfma_f32_16x16x32_bf16 v[66:69], v[184:187], v[236:239], v[66:69]
	v_mfma_f32_16x16x32_bf16 v[66:69], v[188:191], v[240:243], v[66:69]
	v_mfma_f32_16x16x32_bf16 v[74:77], v[142:145], v[236:239], v[74:77]
	v_mfma_f32_16x16x32_bf16 v[74:77], v[154:157], v[240:243], v[74:77]
	v_mfma_f32_16x16x32_bf16 v[78:81], v[134:137], v[236:239], v[78:81]
	v_mfma_f32_16x16x32_bf16 v[78:81], v[138:141], v[240:243], v[78:81]
	s_barrier
	s_or_b32 s27, s26, 0x80
	s_mov_b32 m0, s36
	ds_read_b128 v[192:195], v179 offset:49152
	buffer_load_dwordx4 v175, s[60:63], s27 offen lds
	s_add_i32 s26, s26, 0x80080
	s_mov_b32 m0, s37
	ds_read_b128 v[196:199], v179 offset:50176
	buffer_load_dwordx4 v177, s[60:63], s27 offen lds
	s_mov_b32 m0, s48
	ds_read_b128 v[200:203], v179 offset:51200
	buffer_load_dwordx4 v175, s[60:63], s26 offen lds
	s_mov_b32 m0, s49
	ds_read_b128 v[204:207], v179 offset:52224
	buffer_load_dwordx4 v177, s[60:63], s26 offen lds
	s_mov_b32 m0, s40
	ds_read_b128 v[228:231], v179 offset:53248
	buffer_load_dwordx4 v174, s[44:47], s23 offen lds
	s_mov_b32 m0, s41
	ds_read_b128 v[232:235], v179 offset:54272
	buffer_load_dwordx4 v176, s[44:47], s23 offen lds
	ds_read_b128 v[236:239], v179 offset:55296
	ds_read_b128 v[240:243], v179 offset:56320
	s_waitcnt vmcnt(8)
	s_waitcnt lgkmcnt(0)
	s_barrier
	v_mfma_f32_16x16x32_bf16 v[62:65], v[134:137], v[192:195], v[62:65]
	v_mfma_f32_16x16x32_bf16 v[62:65], v[138:141], v[196:199], v[62:65]
	v_mfma_f32_16x16x32_bf16 v[58:61], v[142:145], v[192:195], v[58:61]
	v_mfma_f32_16x16x32_bf16 v[58:61], v[154:157], v[196:199], v[58:61]
	v_mfma_f32_16x16x32_bf16 v[50:53], v[184:187], v[192:195], v[50:53]
	v_mfma_f32_16x16x32_bf16 v[50:53], v[188:191], v[196:199], v[50:53]
	v_mfma_f32_16x16x32_bf16 v[54:57], v[170:173], v[192:195], v[54:57]
	v_mfma_f32_16x16x32_bf16 v[54:57], v[180:183], v[196:199], v[54:57]
	v_mfma_f32_16x16x32_bf16 v[38:41], v[170:173], v[200:203], v[38:41]
	v_mfma_f32_16x16x32_bf16 v[38:41], v[180:183], v[204:207], v[38:41]
	v_mfma_f32_16x16x32_bf16 v[34:37], v[184:187], v[200:203], v[34:37]
	v_mfma_f32_16x16x32_bf16 v[34:37], v[188:191], v[204:207], v[34:37]
	v_mfma_f32_16x16x32_bf16 v[42:45], v[142:145], v[200:203], v[42:45]
	v_mfma_f32_16x16x32_bf16 v[42:45], v[154:157], v[204:207], v[42:45]
	v_mfma_f32_16x16x32_bf16 v[46:49], v[134:137], v[200:203], v[46:49]
	v_mfma_f32_16x16x32_bf16 v[46:49], v[138:141], v[204:207], v[46:49]
	v_mfma_f32_16x16x32_bf16 v[30:33], v[134:137], v[228:231], v[30:33]
	v_mfma_f32_16x16x32_bf16 v[30:33], v[138:141], v[232:235], v[30:33]
	v_mfma_f32_16x16x32_bf16 v[26:29], v[142:145], v[228:231], v[26:29]
	v_mfma_f32_16x16x32_bf16 v[26:29], v[154:157], v[232:235], v[26:29]
	v_mfma_f32_16x16x32_bf16 v[18:21], v[184:187], v[228:231], v[18:21]
	v_mfma_f32_16x16x32_bf16 v[18:21], v[188:191], v[232:235], v[18:21]
	v_mfma_f32_16x16x32_bf16 v[22:25], v[170:173], v[228:231], v[22:25]
	v_mfma_f32_16x16x32_bf16 v[22:25], v[180:183], v[232:235], v[22:25]
	v_mfma_f32_16x16x32_bf16 v[6:9], v[170:173], v[236:239], v[6:9]
	v_mfma_f32_16x16x32_bf16 v[6:9], v[180:183], v[240:243], v[6:9]
	v_mfma_f32_16x16x32_bf16 v[2:5], v[184:187], v[236:239], v[2:5]
	v_mfma_f32_16x16x32_bf16 v[2:5], v[188:191], v[240:243], v[2:5]
	v_mfma_f32_16x16x32_bf16 v[10:13], v[142:145], v[236:239], v[10:13]
	v_mfma_f32_16x16x32_bf16 v[10:13], v[154:157], v[240:243], v[10:13]
	v_mfma_f32_16x16x32_bf16 v[14:17], v[134:137], v[236:239], v[14:17]
	v_mfma_f32_16x16x32_bf16 v[14:17], v[138:141], v[240:243], v[14:17]
	s_barrier
	s_add_i32 s22, s22, 2
	s_addk_i32 s13, 0x100
	s_addk_i32 s21, 0x100
	s_cmp_gt_u32 s22, 29
	s_cbranch_scc0 .LBB0_905
	s_and_b64 vcc, exec, s[64:65]
	s_cbranch_vccz .LBB0_908
	s_barrier

.LBB0_1192:
	s_lshl_b32 s12, s70, 22
	s_and_b64 s[8:9], s[26:27], exec
	s_cselect_b32 s8, s12, s30
	s_lshl_b32 s22, s71, 22
	s_and_b64 s[66:67], s[26:27], exec
	s_cselect_b32 s9, s22, s31
	s_add_i32 s30, s30, 0x200080
	s_addk_i32 s31, 0x100
	s_mov_b32 s72, -2
	v_add_u32_e32 v141, 0x10000, v139
	ds_read_b128 v[142:145], v141
	ds_read_b128 v[154:157], v141 offset:1024
	ds_read_b128 v[170:173], v141 offset:2048
	ds_read_b128 v[174:177], v141 offset:3072
	v_add_u32_e32 v141, 0x14000, v139
	ds_read_b128 v[178:181], v141
	ds_read_b128 v[182:185], v141 offset:1024
	ds_read_b128 v[186:189], v141 offset:2048
	ds_read_b128 v[190:193], v141 offset:3072
	s_add_i32 s52, s30, 0xffe00080
	s_cmpk_eq_i32 s72, 0x7c
	s_cselect_b32 s52, s8, s52
	s_cselect_b32 s82, s9, s31
	s_or_b32 s73, s52, 0x80
	s_mov_b32 m0, s69
	ds_read_b128 v[194:197], v140
	ds_read_b128 v[198:201], v140 offset:1024
	ds_read_b128 v[202:205], v140 offset:2048
	ds_read_b128 v[228:231], v140 offset:3072
	ds_read_b128 v[232:235], v140 offset:4096
	ds_read_b128 v[236:239], v140 offset:5120
	ds_read_b128 v[240:243], v140 offset:6144
	ds_read_b128 v[244:247], v140 offset:7168
	buffer_load_dwordx4 v131, s[60:63], s30 offen lds
	s_mov_b32 m0, s46
	s_nop 0
	buffer_load_dwordx4 v135, s[60:63], s30 offen lds
	s_waitcnt vmcnt(8)
	s_waitcnt lgkmcnt(0)
	s_barrier
	v_mfma_f32_16x16x32_bf16 v[126:129], v[142:145], v[194:197], 0
	v_mfma_f32_16x16x32_bf16 v[126:129], v[154:157], v[198:201], v[126:129]
	v_mfma_f32_16x16x32_bf16 v[122:125], v[170:173], v[194:197], 0
	v_mfma_f32_16x16x32_bf16 v[122:125], v[174:177], v[198:201], v[122:125]
	v_mfma_f32_16x16x32_bf16 v[58:61], v[186:189], v[194:197], 0
	v_mfma_f32_16x16x32_bf16 v[58:61], v[190:193], v[198:201], v[58:61]
	v_mfma_f32_16x16x32_bf16 v[62:65], v[178:181], v[194:197], 0
	v_mfma_f32_16x16x32_bf16 v[62:65], v[182:185], v[198:201], v[62:65]
	v_mfma_f32_16x16x32_bf16 v[54:57], v[178:181], v[202:205], 0
	v_mfma_f32_16x16x32_bf16 v[54:57], v[182:185], v[228:231], v[54:57]
	v_mfma_f32_16x16x32_bf16 v[50:53], v[186:189], v[202:205], 0
	v_mfma_f32_16x16x32_bf16 v[50:53], v[190:193], v[228:231], v[50:53]
	v_mfma_f32_16x16x32_bf16 v[114:117], v[170:173], v[202:205], 0
	v_mfma_f32_16x16x32_bf16 v[114:117], v[174:177], v[228:231], v[114:117]
	v_mfma_f32_16x16x32_bf16 v[118:121], v[142:145], v[202:205], 0
	v_mfma_f32_16x16x32_bf16 v[118:121], v[154:157], v[228:231], v[118:121]
	v_mfma_f32_16x16x32_bf16 v[110:113], v[142:145], v[232:235], 0
	v_mfma_f32_16x16x32_bf16 v[110:113], v[154:157], v[236:239], v[110:113]
	v_mfma_f32_16x16x32_bf16 v[106:109], v[170:173], v[232:235], 0
	v_mfma_f32_16x16x32_bf16 v[106:109], v[174:177], v[236:239], v[106:109]
	v_mfma_f32_16x16x32_bf16 v[42:45], v[186:189], v[232:235], 0
	v_mfma_f32_16x16x32_bf16 v[42:45], v[190:193], v[236:239], v[42:45]
	v_mfma_f32_16x16x32_bf16 v[46:49], v[178:181], v[232:235], 0
	v_mfma_f32_16x16x32_bf16 v[46:49], v[182:185], v[236:239], v[46:49]
	v_mfma_f32_16x16x32_bf16 v[38:41], v[178:181], v[240:243], 0
	v_mfma_f32_16x16x32_bf16 v[38:41], v[182:185], v[244:247], v[38:41]
	v_mfma_f32_16x16x32_bf16 v[34:37], v[186:189], v[240:243], 0
	v_mfma_f32_16x16x32_bf16 v[34:37], v[190:193], v[244:247], v[34:37]
	v_mfma_f32_16x16x32_bf16 v[98:101], v[170:173], v[240:243], 0
	v_mfma_f32_16x16x32_bf16 v[98:101], v[174:177], v[244:247], v[98:101]
	v_mfma_f32_16x16x32_bf16 v[102:105], v[142:145], v[240:243], 0
	v_mfma_f32_16x16x32_bf16 v[102:105], v[154:157], v[244:247], v[102:105]
	s_barrier
	s_mov_b32 s66, s62
	s_mov_b32 s67, s63
	s_mov_b32 m0, s15
	ds_read_b128 v[194:197], v140 offset:16384
	buffer_load_dwordx4 v134, s[64:67], s82 offen lds
	s_add_i32 s53, s82, 0x200000
	s_mov_b32 m0, s16
	ds_read_b128 v[198:201], v140 offset:17408
	buffer_load_dwordx4 v136, s[64:67], s82 offen lds
	s_mov_b32 m0, s21
	ds_read_b128 v[202:205], v140 offset:18432
	buffer_load_dwordx4 v134, s[64:67], s53 offen lds
	s_mov_b32 m0, s23
	ds_read_b128 v[228:231], v140 offset:19456
	buffer_load_dwordx4 v136, s[64:67], s53 offen lds
	s_mov_b32 m0, s2
	ds_read_b128 v[232:235], v140 offset:20480
	buffer_load_dwordx4 v131, s[60:63], s52 offen lds
	s_mov_b32 m0, s24
	ds_read_b128 v[236:239], v140 offset:21504
	buffer_load_dwordx4 v135, s[60:63], s52 offen lds
	ds_read_b128 v[240:243], v140 offset:22528
	ds_read_b128 v[244:247], v140 offset:23552
	s_waitcnt vmcnt(8)
	s_waitcnt lgkmcnt(0)
	s_barrier
	v_mfma_f32_16x16x32_bf16 v[94:97], v[142:145], v[194:197], 0
	v_mfma_f32_16x16x32_bf16 v[94:97], v[154:157], v[198:201], v[94:97]
	v_mfma_f32_16x16x32_bf16 v[90:93], v[170:173], v[194:197], 0
	v_mfma_f32_16x16x32_bf16 v[90:93], v[174:177], v[198:201], v[90:93]
	v_mfma_f32_16x16x32_bf16 v[26:29], v[186:189], v[194:197], 0
	v_mfma_f32_16x16x32_bf16 v[26:29], v[190:193], v[198:201], v[26:29]
	v_mfma_f32_16x16x32_bf16 v[30:33], v[178:181], v[194:197], 0
	v_mfma_f32_16x16x32_bf16 v[30:33], v[182:185], v[198:201], v[30:33]
	v_mfma_f32_16x16x32_bf16 v[22:25], v[178:181], v[202:205], 0
	v_mfma_f32_16x16x32_bf16 v[22:25], v[182:185], v[228:231], v[22:25]
	v_mfma_f32_16x16x32_bf16 v[18:21], v[186:189], v[202:205], 0
	v_mfma_f32_16x16x32_bf16 v[18:21], v[190:193], v[228:231], v[18:21]
	v_mfma_f32_16x16x32_bf16 v[82:85], v[170:173], v[202:205], 0
	v_mfma_f32_16x16x32_bf16 v[82:85], v[174:177], v[228:231], v[82:85]
	v_mfma_f32_16x16x32_bf16 v[86:89], v[142:145], v[202:205], 0
	v_mfma_f32_16x16x32_bf16 v[86:89], v[154:157], v[228:231], v[86:89]
	v_mfma_f32_16x16x32_bf16 v[78:81], v[142:145], v[232:235], 0
	v_mfma_f32_16x16x32_bf16 v[78:81], v[154:157], v[236:239], v[78:81]
	v_mfma_f32_16x16x32_bf16 v[74:77], v[170:173], v[232:235], 0
	v_mfma_f32_16x16x32_bf16 v[74:77], v[174:177], v[236:239], v[74:77]
	v_mfma_f32_16x16x32_bf16 v[10:13], v[186:189], v[232:235], 0
	v_mfma_f32_16x16x32_bf16 v[10:13], v[190:193], v[236:239], v[10:13]
	v_mfma_f32_16x16x32_bf16 v[14:17], v[178:181], v[232:235], 0
	v_mfma_f32_16x16x32_bf16 v[14:17], v[182:185], v[236:239], v[14:17]
	v_mfma_f32_16x16x32_bf16 v[6:9], v[178:181], v[240:243], 0
	v_mfma_f32_16x16x32_bf16 v[6:9], v[182:185], v[244:247], v[6:9]
	v_mfma_f32_16x16x32_bf16 v[2:5], v[186:189], v[240:243], 0
	v_mfma_f32_16x16x32_bf16 v[2:5], v[190:193], v[244:247], v[2:5]
	v_mfma_f32_16x16x32_bf16 v[66:69], v[170:173], v[240:243], 0
	v_mfma_f32_16x16x32_bf16 v[66:69], v[174:177], v[244:247], v[66:69]
	v_mfma_f32_16x16x32_bf16 v[70:73], v[142:145], v[240:243], 0
	v_mfma_f32_16x16x32_bf16 v[70:73], v[154:157], v[244:247], v[70:73]
	s_barrier
	v_add_u32_e32 v141, 0x18000, v139
	ds_read_b128 v[142:145], v141
	ds_read_b128 v[154:157], v141 offset:1024
	ds_read_b128 v[170:173], v141 offset:2048
	ds_read_b128 v[174:177], v141 offset:3072
	v_add_u32_e32 v141, 0x1c000, v139
	ds_read_b128 v[178:181], v141
	ds_read_b128 v[182:185], v141 offset:1024
	ds_read_b128 v[186:189], v141 offset:2048
	ds_read_b128 v[190:193], v141 offset:3072
	s_add_i32 s52, s52, 0x200000
	s_mov_b32 m0, s25
	ds_read_b128 v[194:197], v140 offset:32768
	ds_read_b128 v[198:201], v140 offset:33792
	ds_read_b128 v[202:205], v140 offset:34816
	ds_read_b128 v[228:231], v140 offset:35840
	ds_read_b128 v[232:235], v140 offset:36864
	ds_read_b128 v[236:239], v140 offset:37888
	ds_read_b128 v[240:243], v140 offset:38912
	ds_read_b128 v[244:247], v140 offset:39936
	buffer_load_dwordx4 v131, s[60:63], s52 offen lds
	s_mov_b32 m0, s33
	s_nop 0
	buffer_load_dwordx4 v135, s[60:63], s52 offen lds
	s_waitcnt vmcnt(8)
	s_waitcnt lgkmcnt(0)
	s_barrier
	v_mfma_f32_16x16x32_bf16 v[126:129], v[142:145], v[194:197], v[126:129]
	v_mfma_f32_16x16x32_bf16 v[126:129], v[154:157], v[198:201], v[126:129]
	v_mfma_f32_16x16x32_bf16 v[122:125], v[170:173], v[194:197], v[122:125]
	v_mfma_f32_16x16x32_bf16 v[122:125], v[174:177], v[198:201], v[122:125]
	v_mfma_f32_16x16x32_bf16 v[58:61], v[186:189], v[194:197], v[58:61]
	v_mfma_f32_16x16x32_bf16 v[58:61], v[190:193], v[198:201], v[58:61]
	v_mfma_f32_16x16x32_bf16 v[62:65], v[178:181], v[194:197], v[62:65]
	v_mfma_f32_16x16x32_bf16 v[62:65], v[182:185], v[198:201], v[62:65]
	v_mfma_f32_16x16x32_bf16 v[54:57], v[178:181], v[202:205], v[54:57]
	v_mfma_f32_16x16x32_bf16 v[54:57], v[182:185], v[228:231], v[54:57]
	v_mfma_f32_16x16x32_bf16 v[50:53], v[186:189], v[202:205], v[50:53]
	v_mfma_f32_16x16x32_bf16 v[50:53], v[190:193], v[228:231], v[50:53]
	v_mfma_f32_16x16x32_bf16 v[114:117], v[170:173], v[202:205], v[114:117]
	v_mfma_f32_16x16x32_bf16 v[114:117], v[174:177], v[228:231], v[114:117]
	v_mfma_f32_16x16x32_bf16 v[118:121], v[142:145], v[202:205], v[118:121]
	v_mfma_f32_16x16x32_bf16 v[118:121], v[154:157], v[228:231], v[118:121]
	v_mfma_f32_16x16x32_bf16 v[110:113], v[142:145], v[232:235], v[110:113]
	v_mfma_f32_16x16x32_bf16 v[110:113], v[154:157], v[236:239], v[110:113]
	v_mfma_f32_16x16x32_bf16 v[106:109], v[170:173], v[232:235], v[106:109]
	v_mfma_f32_16x16x32_bf16 v[106:109], v[174:177], v[236:239], v[106:109]
	v_mfma_f32_16x16x32_bf16 v[42:45], v[186:189], v[232:235], v[42:45]
	v_mfma_f32_16x16x32_bf16 v[42:45], v[190:193], v[236:239], v[42:45]
	v_mfma_f32_16x16x32_bf16 v[46:49], v[178:181], v[232:235], v[46:49]
	v_mfma_f32_16x16x32_bf16 v[46:49], v[182:185], v[236:239], v[46:49]
	v_mfma_f32_16x16x32_bf16 v[38:41], v[178:181], v[240:243], v[38:41]
	v_mfma_f32_16x16x32_bf16 v[38:41], v[182:185], v[244:247], v[38:41]
	v_mfma_f32_16x16x32_bf16 v[34:37], v[186:189], v[240:243], v[34:37]
	v_mfma_f32_16x16x32_bf16 v[34:37], v[190:193], v[244:247], v[34:37]
	v_mfma_f32_16x16x32_bf16 v[98:101], v[170:173], v[240:243], v[98:101]
	v_mfma_f32_16x16x32_bf16 v[98:101], v[174:177], v[244:247], v[98:101]
	v_mfma_f32_16x16x32_bf16 v[102:105], v[142:145], v[240:243], v[102:105]
	v_mfma_f32_16x16x32_bf16 v[102:105], v[154:157], v[244:247], v[102:105]
	s_barrier
	s_or_b32 s52, s82, 0x80
	s_mov_b32 m0, s34
	ds_read_b128 v[194:197], v140 offset:49152
	buffer_load_dwordx4 v134, s[64:67], s52 offen lds
	s_add_i32 s82, s82, 0x200080
	s_mov_b32 m0, s35
	ds_read_b128 v[198:201], v140 offset:50176
	buffer_load_dwordx4 v136, s[64:67], s52 offen lds
	s_mov_b32 m0, s37
	ds_read_b128 v[202:205], v140 offset:51200
	buffer_load_dwordx4 v134, s[64:67], s82 offen lds
	s_mov_b32 m0, s44
	ds_read_b128 v[228:231], v140 offset:52224
	buffer_load_dwordx4 v136, s[64:67], s82 offen lds
	s_mov_b32 m0, s14
	ds_read_b128 v[232:235], v140 offset:53248
	buffer_load_dwordx4 v131, s[60:63], s73 offen lds
	s_mov_b32 m0, s36
	ds_read_b128 v[236:239], v140 offset:54272
	buffer_load_dwordx4 v135, s[60:63], s73 offen lds
	ds_read_b128 v[240:243], v140 offset:55296
	ds_read_b128 v[244:247], v140 offset:56320
	s_waitcnt vmcnt(8)
	s_waitcnt lgkmcnt(0)
	s_barrier
	v_mfma_f32_16x16x32_bf16 v[94:97], v[142:145], v[194:197], v[94:97]
	v_mfma_f32_16x16x32_bf16 v[94:97], v[154:157], v[198:201], v[94:97]
	v_mfma_f32_16x16x32_bf16 v[90:93], v[170:173], v[194:197], v[90:93]
	v_mfma_f32_16x16x32_bf16 v[90:93], v[174:177], v[198:201], v[90:93]
	v_mfma_f32_16x16x32_bf16 v[26:29], v[186:189], v[194:197], v[26:29]
	v_mfma_f32_16x16x32_bf16 v[26:29], v[190:193], v[198:201], v[26:29]
	v_mfma_f32_16x16x32_bf16 v[30:33], v[178:181], v[194:197], v[30:33]
	v_mfma_f32_16x16x32_bf16 v[30:33], v[182:185], v[198:201], v[30:33]
	v_mfma_f32_16x16x32_bf16 v[22:25], v[178:181], v[202:205], v[22:25]
	v_mfma_f32_16x16x32_bf16 v[22:25], v[182:185], v[228:231], v[22:25]
	v_mfma_f32_16x16x32_bf16 v[18:21], v[186:189], v[202:205], v[18:21]
	v_mfma_f32_16x16x32_bf16 v[18:21], v[190:193], v[228:231], v[18:21]
	v_mfma_f32_16x16x32_bf16 v[82:85], v[170:173], v[202:205], v[82:85]
	v_mfma_f32_16x16x32_bf16 v[82:85], v[174:177], v[228:231], v[82:85]
	v_mfma_f32_16x16x32_bf16 v[86:89], v[142:145], v[202:205], v[86:89]
	v_mfma_f32_16x16x32_bf16 v[86:89], v[154:157], v[228:231], v[86:89]
	v_mfma_f32_16x16x32_bf16 v[78:81], v[142:145], v[232:235], v[78:81]
	v_mfma_f32_16x16x32_bf16 v[78:81], v[154:157], v[236:239], v[78:81]
	v_mfma_f32_16x16x32_bf16 v[74:77], v[170:173], v[232:235], v[74:77]
	v_mfma_f32_16x16x32_bf16 v[74:77], v[174:177], v[236:239], v[74:77]
	v_mfma_f32_16x16x32_bf16 v[10:13], v[186:189], v[232:235], v[10:13]
	v_mfma_f32_16x16x32_bf16 v[10:13], v[190:193], v[236:239], v[10:13]
	v_mfma_f32_16x16x32_bf16 v[14:17], v[178:181], v[232:235], v[14:17]
	v_mfma_f32_16x16x32_bf16 v[14:17], v[182:185], v[236:239], v[14:17]
	v_mfma_f32_16x16x32_bf16 v[6:9], v[178:181], v[240:243], v[6:9]
	v_mfma_f32_16x16x32_bf16 v[6:9], v[182:185], v[244:247], v[6:9]
	v_mfma_f32_16x16x32_bf16 v[2:5], v[186:189], v[240:243], v[2:5]
	v_mfma_f32_16x16x32_bf16 v[2:5], v[190:193], v[244:247], v[2:5]
	v_mfma_f32_16x16x32_bf16 v[66:69], v[170:173], v[240:243], v[66:69]
	v_mfma_f32_16x16x32_bf16 v[66:69], v[174:177], v[244:247], v[66:69]
	v_mfma_f32_16x16x32_bf16 v[70:73], v[142:145], v[240:243], v[70:73]
	v_mfma_f32_16x16x32_bf16 v[70:73], v[154:157], v[244:247], v[70:73]
	s_barrier
	s_add_i32 s72, s72, 2
	s_addk_i32 s30, 0x100
	s_addk_i32 s31, 0x100
	s_cmpk_gt_u32 s72, 0x7d
.LBB0_1193:
	v_add_u32_e32 v141, 0x10000, v139
	ds_read_b128 v[142:145], v141
	ds_read_b128 v[154:157], v141 offset:1024
	ds_read_b128 v[170:173], v141 offset:2048
	ds_read_b128 v[174:177], v141 offset:3072
	v_add_u32_e32 v141, 0x14000, v139
	ds_read_b128 v[178:181], v141
	ds_read_b128 v[182:185], v141 offset:1024
	ds_read_b128 v[186:189], v141 offset:2048
	ds_read_b128 v[190:193], v141 offset:3072
	s_add_i32 s52, s30, 0xffe00080
	s_cmpk_eq_i32 s72, 0x7c
	s_cselect_b32 s52, s8, s52
	s_cselect_b32 s82, s9, s31
	s_or_b32 s73, s52, 0x80
	s_mov_b32 m0, s69
	ds_read_b128 v[194:197], v140
	ds_read_b128 v[198:201], v140 offset:1024
	ds_read_b128 v[202:205], v140 offset:2048
	ds_read_b128 v[228:231], v140 offset:3072
	ds_read_b128 v[232:235], v140 offset:4096
	ds_read_b128 v[236:239], v140 offset:5120
	ds_read_b128 v[240:243], v140 offset:6144
	ds_read_b128 v[244:247], v140 offset:7168
	buffer_load_dwordx4 v131, s[60:63], s30 offen lds
	s_mov_b32 m0, s46
	s_nop 0
	buffer_load_dwordx4 v135, s[60:63], s30 offen lds
	s_waitcnt vmcnt(8)
	s_waitcnt lgkmcnt(0)
	s_barrier
	v_mfma_f32_16x16x32_bf16 v[126:129], v[142:145], v[194:197], v[126:129]
	v_mfma_f32_16x16x32_bf16 v[126:129], v[154:157], v[198:201], v[126:129]
	v_mfma_f32_16x16x32_bf16 v[122:125], v[170:173], v[194:197], v[122:125]
	v_mfma_f32_16x16x32_bf16 v[122:125], v[174:177], v[198:201], v[122:125]
	v_mfma_f32_16x16x32_bf16 v[58:61], v[186:189], v[194:197], v[58:61]
	v_mfma_f32_16x16x32_bf16 v[58:61], v[190:193], v[198:201], v[58:61]
	v_mfma_f32_16x16x32_bf16 v[62:65], v[178:181], v[194:197], v[62:65]
	v_mfma_f32_16x16x32_bf16 v[62:65], v[182:185], v[198:201], v[62:65]
	v_mfma_f32_16x16x32_bf16 v[54:57], v[178:181], v[202:205], v[54:57]
	v_mfma_f32_16x16x32_bf16 v[54:57], v[182:185], v[228:231], v[54:57]
	v_mfma_f32_16x16x32_bf16 v[50:53], v[186:189], v[202:205], v[50:53]
	v_mfma_f32_16x16x32_bf16 v[50:53], v[190:193], v[228:231], v[50:53]
	v_mfma_f32_16x16x32_bf16 v[114:117], v[170:173], v[202:205], v[114:117]
	v_mfma_f32_16x16x32_bf16 v[114:117], v[174:177], v[228:231], v[114:117]
	v_mfma_f32_16x16x32_bf16 v[118:121], v[142:145], v[202:205], v[118:121]
	v_mfma_f32_16x16x32_bf16 v[118:121], v[154:157], v[228:231], v[118:121]
	v_mfma_f32_16x16x32_bf16 v[110:113], v[142:145], v[232:235], v[110:113]
	v_mfma_f32_16x16x32_bf16 v[110:113], v[154:157], v[236:239], v[110:113]
	v_mfma_f32_16x16x32_bf16 v[106:109], v[170:173], v[232:235], v[106:109]
	v_mfma_f32_16x16x32_bf16 v[106:109], v[174:177], v[236:239], v[106:109]
	v_mfma_f32_16x16x32_bf16 v[42:45], v[186:189], v[232:235], v[42:45]
	v_mfma_f32_16x16x32_bf16 v[42:45], v[190:193], v[236:239], v[42:45]
	v_mfma_f32_16x16x32_bf16 v[46:49], v[178:181], v[232:235], v[46:49]
	v_mfma_f32_16x16x32_bf16 v[46:49], v[182:185], v[236:239], v[46:49]
	v_mfma_f32_16x16x32_bf16 v[38:41], v[178:181], v[240:243], v[38:41]
	v_mfma_f32_16x16x32_bf16 v[38:41], v[182:185], v[244:247], v[38:41]
	v_mfma_f32_16x16x32_bf16 v[34:37], v[186:189], v[240:243], v[34:37]
	v_mfma_f32_16x16x32_bf16 v[34:37], v[190:193], v[244:247], v[34:37]
	v_mfma_f32_16x16x32_bf16 v[98:101], v[170:173], v[240:243], v[98:101]
	v_mfma_f32_16x16x32_bf16 v[98:101], v[174:177], v[244:247], v[98:101]
	v_mfma_f32_16x16x32_bf16 v[102:105], v[142:145], v[240:243], v[102:105]
	v_mfma_f32_16x16x32_bf16 v[102:105], v[154:157], v[244:247], v[102:105]
	s_barrier
	s_mov_b32 s66, s62
	s_mov_b32 s67, s63
	s_mov_b32 m0, s15
	ds_read_b128 v[194:197], v140 offset:16384
	buffer_load_dwordx4 v134, s[64:67], s82 offen lds
	s_add_i32 s53, s82, 0x200000
	s_mov_b32 m0, s16
	ds_read_b128 v[198:201], v140 offset:17408
	buffer_load_dwordx4 v136, s[64:67], s82 offen lds
	s_mov_b32 m0, s21
	ds_read_b128 v[202:205], v140 offset:18432
	buffer_load_dwordx4 v134, s[64:67], s53 offen lds
	s_mov_b32 m0, s23
	ds_read_b128 v[228:231], v140 offset:19456
	buffer_load_dwordx4 v136, s[64:67], s53 offen lds
	s_mov_b32 m0, s2
	ds_read_b128 v[232:235], v140 offset:20480
	buffer_load_dwordx4 v131, s[60:63], s52 offen lds
	s_mov_b32 m0, s24
	ds_read_b128 v[236:239], v140 offset:21504
	buffer_load_dwordx4 v135, s[60:63], s52 offen lds
	ds_read_b128 v[240:243], v140 offset:22528
	ds_read_b128 v[244:247], v140 offset:23552
	s_waitcnt vmcnt(8)
	s_waitcnt lgkmcnt(0)
	s_barrier
	v_mfma_f32_16x16x32_bf16 v[94:97], v[142:145], v[194:197], v[94:97]
	v_mfma_f32_16x16x32_bf16 v[94:97], v[154:157], v[198:201], v[94:97]
	v_mfma_f32_16x16x32_bf16 v[90:93], v[170:173], v[194:197], v[90:93]
	v_mfma_f32_16x16x32_bf16 v[90:93], v[174:177], v[198:201], v[90:93]
	v_mfma_f32_16x16x32_bf16 v[26:29], v[186:189], v[194:197], v[26:29]
	v_mfma_f32_16x16x32_bf16 v[26:29], v[190:193], v[198:201], v[26:29]
	v_mfma_f32_16x16x32_bf16 v[30:33], v[178:181], v[194:197], v[30:33]
	v_mfma_f32_16x16x32_bf16 v[30:33], v[182:185], v[198:201], v[30:33]
	v_mfma_f32_16x16x32_bf16 v[22:25], v[178:181], v[202:205], v[22:25]
	v_mfma_f32_16x16x32_bf16 v[22:25], v[182:185], v[228:231], v[22:25]
	v_mfma_f32_16x16x32_bf16 v[18:21], v[186:189], v[202:205], v[18:21]
	v_mfma_f32_16x16x32_bf16 v[18:21], v[190:193], v[228:231], v[18:21]
	v_mfma_f32_16x16x32_bf16 v[82:85], v[170:173], v[202:205], v[82:85]
	v_mfma_f32_16x16x32_bf16 v[82:85], v[174:177], v[228:231], v[82:85]
	v_mfma_f32_16x16x32_bf16 v[86:89], v[142:145], v[202:205], v[86:89]
	v_mfma_f32_16x16x32_bf16 v[86:89], v[154:157], v[228:231], v[86:89]
	v_mfma_f32_16x16x32_bf16 v[78:81], v[142:145], v[232:235], v[78:81]
	v_mfma_f32_16x16x32_bf16 v[78:81], v[154:157], v[236:239], v[78:81]
	v_mfma_f32_16x16x32_bf16 v[74:77], v[170:173], v[232:235], v[74:77]
	v_mfma_f32_16x16x32_bf16 v[74:77], v[174:177], v[236:239], v[74:77]
	v_mfma_f32_16x16x32_bf16 v[10:13], v[186:189], v[232:235], v[10:13]
	v_mfma_f32_16x16x32_bf16 v[10:13], v[190:193], v[236:239], v[10:13]
	v_mfma_f32_16x16x32_bf16 v[14:17], v[178:181], v[232:235], v[14:17]
	v_mfma_f32_16x16x32_bf16 v[14:17], v[182:185], v[236:239], v[14:17]
	v_mfma_f32_16x16x32_bf16 v[6:9], v[178:181], v[240:243], v[6:9]
	v_mfma_f32_16x16x32_bf16 v[6:9], v[182:185], v[244:247], v[6:9]
	v_mfma_f32_16x16x32_bf16 v[2:5], v[186:189], v[240:243], v[2:5]
	v_mfma_f32_16x16x32_bf16 v[2:5], v[190:193], v[244:247], v[2:5]
	v_mfma_f32_16x16x32_bf16 v[66:69], v[170:173], v[240:243], v[66:69]
	v_mfma_f32_16x16x32_bf16 v[66:69], v[174:177], v[244:247], v[66:69]
	v_mfma_f32_16x16x32_bf16 v[70:73], v[142:145], v[240:243], v[70:73]
	v_mfma_f32_16x16x32_bf16 v[70:73], v[154:157], v[244:247], v[70:73]
	s_barrier
	v_add_u32_e32 v141, 0x18000, v139
	ds_read_b128 v[142:145], v141
	ds_read_b128 v[154:157], v141 offset:1024
	ds_read_b128 v[170:173], v141 offset:2048
	ds_read_b128 v[174:177], v141 offset:3072
	v_add_u32_e32 v141, 0x1c000, v139
	ds_read_b128 v[178:181], v141
	ds_read_b128 v[182:185], v141 offset:1024
	ds_read_b128 v[186:189], v141 offset:2048
	ds_read_b128 v[190:193], v141 offset:3072
	s_add_i32 s52, s52, 0x200000
	s_mov_b32 m0, s25
	ds_read_b128 v[194:197], v140 offset:32768
	ds_read_b128 v[198:201], v140 offset:33792
	ds_read_b128 v[202:205], v140 offset:34816
	ds_read_b128 v[228:231], v140 offset:35840
	ds_read_b128 v[232:235], v140 offset:36864
	ds_read_b128 v[236:239], v140 offset:37888
	ds_read_b128 v[240:243], v140 offset:38912
	ds_read_b128 v[244:247], v140 offset:39936
	buffer_load_dwordx4 v131, s[60:63], s52 offen lds
	s_mov_b32 m0, s33
	s_nop 0
	buffer_load_dwordx4 v135, s[60:63], s52 offen lds
	s_waitcnt vmcnt(8)
	s_waitcnt lgkmcnt(0)
	s_barrier
	v_mfma_f32_16x16x32_bf16 v[126:129], v[142:145], v[194:197], v[126:129]
	v_mfma_f32_16x16x32_bf16 v[126:129], v[154:157], v[198:201], v[126:129]
	v_mfma_f32_16x16x32_bf16 v[122:125], v[170:173], v[194:197], v[122:125]
	v_mfma_f32_16x16x32_bf16 v[122:125], v[174:177], v[198:201], v[122:125]
	v_mfma_f32_16x16x32_bf16 v[58:61], v[186:189], v[194:197], v[58:61]
	v_mfma_f32_16x16x32_bf16 v[58:61], v[190:193], v[198:201], v[58:61]
	v_mfma_f32_16x16x32_bf16 v[62:65], v[178:181], v[194:197], v[62:65]
	v_mfma_f32_16x16x32_bf16 v[62:65], v[182:185], v[198:201], v[62:65]
	v_mfma_f32_16x16x32_bf16 v[54:57], v[178:181], v[202:205], v[54:57]
	v_mfma_f32_16x16x32_bf16 v[54:57], v[182:185], v[228:231], v[54:57]
	v_mfma_f32_16x16x32_bf16 v[50:53], v[186:189], v[202:205], v[50:53]
	v_mfma_f32_16x16x32_bf16 v[50:53], v[190:193], v[228:231], v[50:53]
	v_mfma_f32_16x16x32_bf16 v[114:117], v[170:173], v[202:205], v[114:117]
	v_mfma_f32_16x16x32_bf16 v[114:117], v[174:177], v[228:231], v[114:117]
	v_mfma_f32_16x16x32_bf16 v[118:121], v[142:145], v[202:205], v[118:121]
	v_mfma_f32_16x16x32_bf16 v[118:121], v[154:157], v[228:231], v[118:121]
	v_mfma_f32_16x16x32_bf16 v[110:113], v[142:145], v[232:235], v[110:113]
	v_mfma_f32_16x16x32_bf16 v[110:113], v[154:157], v[236:239], v[110:113]
	v_mfma_f32_16x16x32_bf16 v[106:109], v[170:173], v[232:235], v[106:109]
	v_mfma_f32_16x16x32_bf16 v[106:109], v[174:177], v[236:239], v[106:109]
	v_mfma_f32_16x16x32_bf16 v[42:45], v[186:189], v[232:235], v[42:45]
	v_mfma_f32_16x16x32_bf16 v[42:45], v[190:193], v[236:239], v[42:45]
	v_mfma_f32_16x16x32_bf16 v[46:49], v[178:181], v[232:235], v[46:49]
	v_mfma_f32_16x16x32_bf16 v[46:49], v[182:185], v[236:239], v[46:49]
	v_mfma_f32_16x16x32_bf16 v[38:41], v[178:181], v[240:243], v[38:41]
	v_mfma_f32_16x16x32_bf16 v[38:41], v[182:185], v[244:247], v[38:41]
	v_mfma_f32_16x16x32_bf16 v[34:37], v[186:189], v[240:243], v[34:37]
	v_mfma_f32_16x16x32_bf16 v[34:37], v[190:193], v[244:247], v[34:37]
	v_mfma_f32_16x16x32_bf16 v[98:101], v[170:173], v[240:243], v[98:101]
	v_mfma_f32_16x16x32_bf16 v[98:101], v[174:177], v[244:247], v[98:101]
	v_mfma_f32_16x16x32_bf16 v[102:105], v[142:145], v[240:243], v[102:105]
	v_mfma_f32_16x16x32_bf16 v[102:105], v[154:157], v[244:247], v[102:105]
	s_barrier
	s_or_b32 s52, s82, 0x80
	s_mov_b32 m0, s34
	ds_read_b128 v[194:197], v140 offset:49152
	buffer_load_dwordx4 v134, s[64:67], s52 offen lds
	s_add_i32 s82, s82, 0x200080
	s_mov_b32 m0, s35
	ds_read_b128 v[198:201], v140 offset:50176
	buffer_load_dwordx4 v136, s[64:67], s52 offen lds
	s_mov_b32 m0, s37
	ds_read_b128 v[202:205], v140 offset:51200
	buffer_load_dwordx4 v134, s[64:67], s82 offen lds
	s_mov_b32 m0, s44
	ds_read_b128 v[228:231], v140 offset:52224
	buffer_load_dwordx4 v136, s[64:67], s82 offen lds
	s_mov_b32 m0, s14
	ds_read_b128 v[232:235], v140 offset:53248
	buffer_load_dwordx4 v131, s[60:63], s73 offen lds
	s_mov_b32 m0, s36
	ds_read_b128 v[236:239], v140 offset:54272
	buffer_load_dwordx4 v135, s[60:63], s73 offen lds
	ds_read_b128 v[240:243], v140 offset:55296
	ds_read_b128 v[244:247], v140 offset:56320
	s_waitcnt vmcnt(8)
	s_waitcnt lgkmcnt(0)
	s_barrier
	v_mfma_f32_16x16x32_bf16 v[94:97], v[142:145], v[194:197], v[94:97]
	v_mfma_f32_16x16x32_bf16 v[94:97], v[154:157], v[198:201], v[94:97]
	v_mfma_f32_16x16x32_bf16 v[90:93], v[170:173], v[194:197], v[90:93]
	v_mfma_f32_16x16x32_bf16 v[90:93], v[174:177], v[198:201], v[90:93]
	v_mfma_f32_16x16x32_bf16 v[26:29], v[186:189], v[194:197], v[26:29]
	v_mfma_f32_16x16x32_bf16 v[26:29], v[190:193], v[198:201], v[26:29]
	v_mfma_f32_16x16x32_bf16 v[30:33], v[178:181], v[194:197], v[30:33]
	v_mfma_f32_16x16x32_bf16 v[30:33], v[182:185], v[198:201], v[30:33]
	v_mfma_f32_16x16x32_bf16 v[22:25], v[178:181], v[202:205], v[22:25]
	v_mfma_f32_16x16x32_bf16 v[22:25], v[182:185], v[228:231], v[22:25]
	v_mfma_f32_16x16x32_bf16 v[18:21], v[186:189], v[202:205], v[18:21]
	v_mfma_f32_16x16x32_bf16 v[18:21], v[190:193], v[228:231], v[18:21]
	v_mfma_f32_16x16x32_bf16 v[82:85], v[170:173], v[202:205], v[82:85]
	v_mfma_f32_16x16x32_bf16 v[82:85], v[174:177], v[228:231], v[82:85]
	v_mfma_f32_16x16x32_bf16 v[86:89], v[142:145], v[202:205], v[86:89]
	v_mfma_f32_16x16x32_bf16 v[86:89], v[154:157], v[228:231], v[86:89]
	v_mfma_f32_16x16x32_bf16 v[78:81], v[142:145], v[232:235], v[78:81]
	v_mfma_f32_16x16x32_bf16 v[78:81], v[154:157], v[236:239], v[78:81]
	v_mfma_f32_16x16x32_bf16 v[74:77], v[170:173], v[232:235], v[74:77]
	v_mfma_f32_16x16x32_bf16 v[74:77], v[174:177], v[236:239], v[74:77]
	v_mfma_f32_16x16x32_bf16 v[10:13], v[186:189], v[232:235], v[10:13]
	v_mfma_f32_16x16x32_bf16 v[10:13], v[190:193], v[236:239], v[10:13]
	v_mfma_f32_16x16x32_bf16 v[14:17], v[178:181], v[232:235], v[14:17]
	v_mfma_f32_16x16x32_bf16 v[14:17], v[182:185], v[236:239], v[14:17]
	v_mfma_f32_16x16x32_bf16 v[6:9], v[178:181], v[240:243], v[6:9]
	v_mfma_f32_16x16x32_bf16 v[6:9], v[182:185], v[244:247], v[6:9]
	v_mfma_f32_16x16x32_bf16 v[2:5], v[186:189], v[240:243], v[2:5]
	v_mfma_f32_16x16x32_bf16 v[2:5], v[190:193], v[244:247], v[2:5]
	v_mfma_f32_16x16x32_bf16 v[66:69], v[170:173], v[240:243], v[66:69]
	v_mfma_f32_16x16x32_bf16 v[66:69], v[174:177], v[244:247], v[66:69]
	v_mfma_f32_16x16x32_bf16 v[70:73], v[142:145], v[240:243], v[70:73]
	v_mfma_f32_16x16x32_bf16 v[70:73], v[154:157], v[244:247], v[70:73]
	s_barrier
	s_add_i32 s72, s72, 2
	s_addk_i32 s30, 0x100
	s_addk_i32 s31, 0x100
	s_cmpk_gt_u32 s72, 0x7d
	s_cbranch_scc0 .LBB0_1193
	s_and_b64 vcc, exec, s[42:43]
	s_cbranch_vccz .LBB0_1196
	s_barrier

.LBB0_1222:
	s_lshl_b32 s14, s82, 22
	s_and_b64 s[8:9], s[44:45], exec
	s_cselect_b32 s8, s14, s19
	s_lshl_b32 s46, s84, 22
	s_and_b64 s[26:27], s[44:45], exec
	s_cselect_b32 s9, s46, s22
	s_add_i32 s19, s19, 0x200080
	s_addk_i32 s22, 0x100
	s_mov_b32 s26, -2
	v_add_u32_e32 v141, 0x10000, v139
	ds_read_b128 v[142:145], v141
	ds_read_b128 v[154:157], v141 offset:1024
	ds_read_b128 v[170:173], v141 offset:2048
	ds_read_b128 v[174:177], v141 offset:3072
	v_add_u32_e32 v141, 0x14000, v139
	ds_read_b128 v[178:181], v141
	ds_read_b128 v[182:185], v141 offset:1024
	ds_read_b128 v[186:189], v141 offset:2048
	ds_read_b128 v[190:193], v141 offset:3072
	s_add_i32 s27, s19, 0xffe00080
	s_cmpk_eq_i32 s26, 0x7c
	s_cselect_b32 s52, s8, s27
	s_cselect_b32 s47, s9, s22
	s_or_b32 s27, s52, 0x80
	s_mov_b32 m0, s71
	ds_read_b128 v[194:197], v140
	ds_read_b128 v[198:201], v140 offset:1024
	ds_read_b128 v[202:205], v140 offset:2048
	ds_read_b128 v[228:231], v140 offset:3072
	ds_read_b128 v[232:235], v140 offset:4096
	ds_read_b128 v[236:239], v140 offset:5120
	ds_read_b128 v[240:243], v140 offset:6144
	ds_read_b128 v[244:247], v140 offset:7168
	buffer_load_dwordx4 v131, s[60:63], s19 offen lds
	s_mov_b32 m0, s72
	s_nop 0
	buffer_load_dwordx4 v135, s[60:63], s19 offen lds
	s_waitcnt vmcnt(8)
	s_waitcnt lgkmcnt(0)
	s_barrier
	v_mfma_f32_16x16x32_bf16 v[126:129], v[142:145], v[194:197], 0
	v_mfma_f32_16x16x32_bf16 v[126:129], v[154:157], v[198:201], v[126:129]
	v_mfma_f32_16x16x32_bf16 v[122:125], v[170:173], v[194:197], 0
	v_mfma_f32_16x16x32_bf16 v[122:125], v[174:177], v[198:201], v[122:125]
	v_mfma_f32_16x16x32_bf16 v[58:61], v[186:189], v[194:197], 0
	v_mfma_f32_16x16x32_bf16 v[58:61], v[190:193], v[198:201], v[58:61]
	v_mfma_f32_16x16x32_bf16 v[62:65], v[178:181], v[194:197], 0
	v_mfma_f32_16x16x32_bf16 v[62:65], v[182:185], v[198:201], v[62:65]
	v_mfma_f32_16x16x32_bf16 v[54:57], v[178:181], v[202:205], 0
	v_mfma_f32_16x16x32_bf16 v[54:57], v[182:185], v[228:231], v[54:57]
	v_mfma_f32_16x16x32_bf16 v[50:53], v[186:189], v[202:205], 0
	v_mfma_f32_16x16x32_bf16 v[50:53], v[190:193], v[228:231], v[50:53]
	v_mfma_f32_16x16x32_bf16 v[114:117], v[170:173], v[202:205], 0
	v_mfma_f32_16x16x32_bf16 v[114:117], v[174:177], v[228:231], v[114:117]
	v_mfma_f32_16x16x32_bf16 v[118:121], v[142:145], v[202:205], 0
	v_mfma_f32_16x16x32_bf16 v[118:121], v[154:157], v[228:231], v[118:121]
	v_mfma_f32_16x16x32_bf16 v[110:113], v[142:145], v[232:235], 0
	v_mfma_f32_16x16x32_bf16 v[110:113], v[154:157], v[236:239], v[110:113]
	v_mfma_f32_16x16x32_bf16 v[106:109], v[170:173], v[232:235], 0
	v_mfma_f32_16x16x32_bf16 v[106:109], v[174:177], v[236:239], v[106:109]
	v_mfma_f32_16x16x32_bf16 v[42:45], v[186:189], v[232:235], 0
	v_mfma_f32_16x16x32_bf16 v[42:45], v[190:193], v[236:239], v[42:45]
	v_mfma_f32_16x16x32_bf16 v[46:49], v[178:181], v[232:235], 0
	v_mfma_f32_16x16x32_bf16 v[46:49], v[182:185], v[236:239], v[46:49]
	v_mfma_f32_16x16x32_bf16 v[38:41], v[178:181], v[240:243], 0
	v_mfma_f32_16x16x32_bf16 v[38:41], v[182:185], v[244:247], v[38:41]
	v_mfma_f32_16x16x32_bf16 v[34:37], v[186:189], v[240:243], 0
	v_mfma_f32_16x16x32_bf16 v[34:37], v[190:193], v[244:247], v[34:37]
	v_mfma_f32_16x16x32_bf16 v[98:101], v[170:173], v[240:243], 0
	v_mfma_f32_16x16x32_bf16 v[98:101], v[174:177], v[244:247], v[98:101]
	v_mfma_f32_16x16x32_bf16 v[102:105], v[142:145], v[240:243], 0
	v_mfma_f32_16x16x32_bf16 v[102:105], v[154:157], v[244:247], v[102:105]
	s_barrier
	s_mov_b32 s66, s62
	s_mov_b32 s67, s63
	s_mov_b32 m0, s2
	ds_read_b128 v[194:197], v140 offset:16384
	buffer_load_dwordx4 v134, s[64:67], s47 offen lds
	s_add_i32 s53, s47, 0x200000
	s_mov_b32 m0, s21
	ds_read_b128 v[198:201], v140 offset:17408
	buffer_load_dwordx4 v136, s[64:67], s47 offen lds
	s_mov_b32 m0, s23
	ds_read_b128 v[202:205], v140 offset:18432
	buffer_load_dwordx4 v134, s[64:67], s53 offen lds
	s_mov_b32 m0, s24
	ds_read_b128 v[228:231], v140 offset:19456
	buffer_load_dwordx4 v136, s[64:67], s53 offen lds
	s_mov_b32 m0, s16
	ds_read_b128 v[232:235], v140 offset:20480
	buffer_load_dwordx4 v131, s[60:63], s52 offen lds
	s_mov_b32 m0, s25
	ds_read_b128 v[236:239], v140 offset:21504
	buffer_load_dwordx4 v135, s[60:63], s52 offen lds
	ds_read_b128 v[240:243], v140 offset:22528
	ds_read_b128 v[244:247], v140 offset:23552
	s_waitcnt vmcnt(8)
	s_waitcnt lgkmcnt(0)
	s_barrier
	v_mfma_f32_16x16x32_bf16 v[94:97], v[142:145], v[194:197], 0
	v_mfma_f32_16x16x32_bf16 v[94:97], v[154:157], v[198:201], v[94:97]
	v_mfma_f32_16x16x32_bf16 v[90:93], v[170:173], v[194:197], 0
	v_mfma_f32_16x16x32_bf16 v[90:93], v[174:177], v[198:201], v[90:93]
	v_mfma_f32_16x16x32_bf16 v[26:29], v[186:189], v[194:197], 0
	v_mfma_f32_16x16x32_bf16 v[26:29], v[190:193], v[198:201], v[26:29]
	v_mfma_f32_16x16x32_bf16 v[30:33], v[178:181], v[194:197], 0
	v_mfma_f32_16x16x32_bf16 v[30:33], v[182:185], v[198:201], v[30:33]
	v_mfma_f32_16x16x32_bf16 v[22:25], v[178:181], v[202:205], 0
	v_mfma_f32_16x16x32_bf16 v[22:25], v[182:185], v[228:231], v[22:25]
	v_mfma_f32_16x16x32_bf16 v[18:21], v[186:189], v[202:205], 0
	v_mfma_f32_16x16x32_bf16 v[18:21], v[190:193], v[228:231], v[18:21]
	v_mfma_f32_16x16x32_bf16 v[82:85], v[170:173], v[202:205], 0
	v_mfma_f32_16x16x32_bf16 v[82:85], v[174:177], v[228:231], v[82:85]
	v_mfma_f32_16x16x32_bf16 v[86:89], v[142:145], v[202:205], 0
	v_mfma_f32_16x16x32_bf16 v[86:89], v[154:157], v[228:231], v[86:89]
	v_mfma_f32_16x16x32_bf16 v[78:81], v[142:145], v[232:235], 0
	v_mfma_f32_16x16x32_bf16 v[78:81], v[154:157], v[236:239], v[78:81]
	v_mfma_f32_16x16x32_bf16 v[74:77], v[170:173], v[232:235], 0
	v_mfma_f32_16x16x32_bf16 v[74:77], v[174:177], v[236:239], v[74:77]
	v_mfma_f32_16x16x32_bf16 v[10:13], v[186:189], v[232:235], 0
	v_mfma_f32_16x16x32_bf16 v[10:13], v[190:193], v[236:239], v[10:13]
	v_mfma_f32_16x16x32_bf16 v[14:17], v[178:181], v[232:235], 0
	v_mfma_f32_16x16x32_bf16 v[14:17], v[182:185], v[236:239], v[14:17]
	v_mfma_f32_16x16x32_bf16 v[6:9], v[178:181], v[240:243], 0
	v_mfma_f32_16x16x32_bf16 v[6:9], v[182:185], v[244:247], v[6:9]
	v_mfma_f32_16x16x32_bf16 v[2:5], v[186:189], v[240:243], 0
	v_mfma_f32_16x16x32_bf16 v[2:5], v[190:193], v[244:247], v[2:5]
	v_mfma_f32_16x16x32_bf16 v[66:69], v[170:173], v[240:243], 0
	v_mfma_f32_16x16x32_bf16 v[66:69], v[174:177], v[244:247], v[66:69]
	v_mfma_f32_16x16x32_bf16 v[70:73], v[142:145], v[240:243], 0
	v_mfma_f32_16x16x32_bf16 v[70:73], v[154:157], v[244:247], v[70:73]
	s_barrier
	v_add_u32_e32 v141, 0x18000, v139
	ds_read_b128 v[142:145], v141
	ds_read_b128 v[154:157], v141 offset:1024
	ds_read_b128 v[170:173], v141 offset:2048
	ds_read_b128 v[174:177], v141 offset:3072
	v_add_u32_e32 v141, 0x1c000, v139
	ds_read_b128 v[178:181], v141
	ds_read_b128 v[182:185], v141 offset:1024
	ds_read_b128 v[186:189], v141 offset:2048
	ds_read_b128 v[190:193], v141 offset:3072
	s_add_i32 s52, s52, 0x200000
	s_mov_b32 m0, s30
	ds_read_b128 v[194:197], v140 offset:32768
	ds_read_b128 v[198:201], v140 offset:33792
	ds_read_b128 v[202:205], v140 offset:34816
	ds_read_b128 v[228:231], v140 offset:35840
	ds_read_b128 v[232:235], v140 offset:36864
	ds_read_b128 v[236:239], v140 offset:37888
	ds_read_b128 v[240:243], v140 offset:38912
	ds_read_b128 v[244:247], v140 offset:39936
	buffer_load_dwordx4 v131, s[60:63], s52 offen lds
	s_mov_b32 m0, s31
	s_nop 0
	buffer_load_dwordx4 v135, s[60:63], s52 offen lds
	s_waitcnt vmcnt(8)
	s_waitcnt lgkmcnt(0)
	s_barrier
	v_mfma_f32_16x16x32_bf16 v[126:129], v[142:145], v[194:197], v[126:129]
	v_mfma_f32_16x16x32_bf16 v[126:129], v[154:157], v[198:201], v[126:129]
	v_mfma_f32_16x16x32_bf16 v[122:125], v[170:173], v[194:197], v[122:125]
	v_mfma_f32_16x16x32_bf16 v[122:125], v[174:177], v[198:201], v[122:125]
	v_mfma_f32_16x16x32_bf16 v[58:61], v[186:189], v[194:197], v[58:61]
	v_mfma_f32_16x16x32_bf16 v[58:61], v[190:193], v[198:201], v[58:61]
	v_mfma_f32_16x16x32_bf16 v[62:65], v[178:181], v[194:197], v[62:65]
	v_mfma_f32_16x16x32_bf16 v[62:65], v[182:185], v[198:201], v[62:65]
	v_mfma_f32_16x16x32_bf16 v[54:57], v[178:181], v[202:205], v[54:57]
	v_mfma_f32_16x16x32_bf16 v[54:57], v[182:185], v[228:231], v[54:57]
	v_mfma_f32_16x16x32_bf16 v[50:53], v[186:189], v[202:205], v[50:53]
	v_mfma_f32_16x16x32_bf16 v[50:53], v[190:193], v[228:231], v[50:53]
	v_mfma_f32_16x16x32_bf16 v[114:117], v[170:173], v[202:205], v[114:117]
	v_mfma_f32_16x16x32_bf16 v[114:117], v[174:177], v[228:231], v[114:117]
	v_mfma_f32_16x16x32_bf16 v[118:121], v[142:145], v[202:205], v[118:121]
	v_mfma_f32_16x16x32_bf16 v[118:121], v[154:157], v[228:231], v[118:121]
	v_mfma_f32_16x16x32_bf16 v[110:113], v[142:145], v[232:235], v[110:113]
	v_mfma_f32_16x16x32_bf16 v[110:113], v[154:157], v[236:239], v[110:113]
	v_mfma_f32_16x16x32_bf16 v[106:109], v[170:173], v[232:235], v[106:109]
	v_mfma_f32_16x16x32_bf16 v[106:109], v[174:177], v[236:239], v[106:109]
	v_mfma_f32_16x16x32_bf16 v[42:45], v[186:189], v[232:235], v[42:45]
	v_mfma_f32_16x16x32_bf16 v[42:45], v[190:193], v[236:239], v[42:45]
	v_mfma_f32_16x16x32_bf16 v[46:49], v[178:181], v[232:235], v[46:49]
	v_mfma_f32_16x16x32_bf16 v[46:49], v[182:185], v[236:239], v[46:49]
	v_mfma_f32_16x16x32_bf16 v[38:41], v[178:181], v[240:243], v[38:41]
	v_mfma_f32_16x16x32_bf16 v[38:41], v[182:185], v[244:247], v[38:41]
	v_mfma_f32_16x16x32_bf16 v[34:37], v[186:189], v[240:243], v[34:37]
	v_mfma_f32_16x16x32_bf16 v[34:37], v[190:193], v[244:247], v[34:37]
	v_mfma_f32_16x16x32_bf16 v[98:101], v[170:173], v[240:243], v[98:101]
	v_mfma_f32_16x16x32_bf16 v[98:101], v[174:177], v[244:247], v[98:101]
	v_mfma_f32_16x16x32_bf16 v[102:105], v[142:145], v[240:243], v[102:105]
	v_mfma_f32_16x16x32_bf16 v[102:105], v[154:157], v[244:247], v[102:105]
	s_barrier
	s_or_b32 s52, s47, 0x80
	s_mov_b32 m0, s33
	ds_read_b128 v[194:197], v140 offset:49152
	buffer_load_dwordx4 v134, s[64:67], s52 offen lds
	s_add_i32 s47, s47, 0x200080
	s_mov_b32 m0, s34
	ds_read_b128 v[198:201], v140 offset:50176
	buffer_load_dwordx4 v136, s[64:67], s52 offen lds
	s_mov_b32 m0, s37
	ds_read_b128 v[202:205], v140 offset:51200
	buffer_load_dwordx4 v134, s[64:67], s47 offen lds
	s_mov_b32 m0, s68
	ds_read_b128 v[228:231], v140 offset:52224
	buffer_load_dwordx4 v136, s[64:67], s47 offen lds
	s_mov_b32 m0, s35
	ds_read_b128 v[232:235], v140 offset:53248
	buffer_load_dwordx4 v131, s[60:63], s27 offen lds
	s_mov_b32 m0, s36
	ds_read_b128 v[236:239], v140 offset:54272
	buffer_load_dwordx4 v135, s[60:63], s27 offen lds
	ds_read_b128 v[240:243], v140 offset:55296
	ds_read_b128 v[244:247], v140 offset:56320
	s_waitcnt vmcnt(8)
	s_waitcnt lgkmcnt(0)
	s_barrier
	v_mfma_f32_16x16x32_bf16 v[94:97], v[142:145], v[194:197], v[94:97]
	v_mfma_f32_16x16x32_bf16 v[94:97], v[154:157], v[198:201], v[94:97]
	v_mfma_f32_16x16x32_bf16 v[90:93], v[170:173], v[194:197], v[90:93]
	v_mfma_f32_16x16x32_bf16 v[90:93], v[174:177], v[198:201], v[90:93]
	v_mfma_f32_16x16x32_bf16 v[26:29], v[186:189], v[194:197], v[26:29]
	v_mfma_f32_16x16x32_bf16 v[26:29], v[190:193], v[198:201], v[26:29]
	v_mfma_f32_16x16x32_bf16 v[30:33], v[178:181], v[194:197], v[30:33]
	v_mfma_f32_16x16x32_bf16 v[30:33], v[182:185], v[198:201], v[30:33]
	v_mfma_f32_16x16x32_bf16 v[22:25], v[178:181], v[202:205], v[22:25]
	v_mfma_f32_16x16x32_bf16 v[22:25], v[182:185], v[228:231], v[22:25]
	v_mfma_f32_16x16x32_bf16 v[18:21], v[186:189], v[202:205], v[18:21]
	v_mfma_f32_16x16x32_bf16 v[18:21], v[190:193], v[228:231], v[18:21]
	v_mfma_f32_16x16x32_bf16 v[82:85], v[170:173], v[202:205], v[82:85]
	v_mfma_f32_16x16x32_bf16 v[82:85], v[174:177], v[228:231], v[82:85]
	v_mfma_f32_16x16x32_bf16 v[86:89], v[142:145], v[202:205], v[86:89]
	v_mfma_f32_16x16x32_bf16 v[86:89], v[154:157], v[228:231], v[86:89]
	v_mfma_f32_16x16x32_bf16 v[78:81], v[142:145], v[232:235], v[78:81]
	v_mfma_f32_16x16x32_bf16 v[78:81], v[154:157], v[236:239], v[78:81]
	v_mfma_f32_16x16x32_bf16 v[74:77], v[170:173], v[232:235], v[74:77]
	v_mfma_f32_16x16x32_bf16 v[74:77], v[174:177], v[236:239], v[74:77]
	v_mfma_f32_16x16x32_bf16 v[10:13], v[186:189], v[232:235], v[10:13]
	v_mfma_f32_16x16x32_bf16 v[10:13], v[190:193], v[236:239], v[10:13]
	v_mfma_f32_16x16x32_bf16 v[14:17], v[178:181], v[232:235], v[14:17]
	v_mfma_f32_16x16x32_bf16 v[14:17], v[182:185], v[236:239], v[14:17]
	v_mfma_f32_16x16x32_bf16 v[6:9], v[178:181], v[240:243], v[6:9]
	v_mfma_f32_16x16x32_bf16 v[6:9], v[182:185], v[244:247], v[6:9]
	v_mfma_f32_16x16x32_bf16 v[2:5], v[186:189], v[240:243], v[2:5]
	v_mfma_f32_16x16x32_bf16 v[2:5], v[190:193], v[244:247], v[2:5]
	v_mfma_f32_16x16x32_bf16 v[66:69], v[170:173], v[240:243], v[66:69]
	v_mfma_f32_16x16x32_bf16 v[66:69], v[174:177], v[244:247], v[66:69]
	v_mfma_f32_16x16x32_bf16 v[70:73], v[142:145], v[240:243], v[70:73]
	v_mfma_f32_16x16x32_bf16 v[70:73], v[154:157], v[244:247], v[70:73]
	s_barrier
	s_add_i32 s26, s26, 2
	s_addk_i32 s19, 0x100
	s_addk_i32 s22, 0x100
	s_cmpk_gt_u32 s26, 0x7d
.LBB0_1223:
	v_add_u32_e32 v141, 0x10000, v139
	ds_read_b128 v[142:145], v141
	ds_read_b128 v[154:157], v141 offset:1024
	ds_read_b128 v[170:173], v141 offset:2048
	ds_read_b128 v[174:177], v141 offset:3072
	v_add_u32_e32 v141, 0x14000, v139
	ds_read_b128 v[178:181], v141
	ds_read_b128 v[182:185], v141 offset:1024
	ds_read_b128 v[186:189], v141 offset:2048
	ds_read_b128 v[190:193], v141 offset:3072
	s_add_i32 s27, s19, 0xffe00080
	s_cmpk_eq_i32 s26, 0x7c
	s_cselect_b32 s52, s8, s27
	s_cselect_b32 s47, s9, s22
	s_or_b32 s27, s52, 0x80
	s_mov_b32 m0, s71
	ds_read_b128 v[194:197], v140
	ds_read_b128 v[198:201], v140 offset:1024
	ds_read_b128 v[202:205], v140 offset:2048
	ds_read_b128 v[228:231], v140 offset:3072
	ds_read_b128 v[232:235], v140 offset:4096
	ds_read_b128 v[236:239], v140 offset:5120
	ds_read_b128 v[240:243], v140 offset:6144
	ds_read_b128 v[244:247], v140 offset:7168
	buffer_load_dwordx4 v131, s[60:63], s19 offen lds
	s_mov_b32 m0, s72
	s_nop 0
	buffer_load_dwordx4 v135, s[60:63], s19 offen lds
	s_waitcnt vmcnt(8)
	s_waitcnt lgkmcnt(0)
	s_barrier
	v_mfma_f32_16x16x32_bf16 v[126:129], v[142:145], v[194:197], v[126:129]
	v_mfma_f32_16x16x32_bf16 v[126:129], v[154:157], v[198:201], v[126:129]
	v_mfma_f32_16x16x32_bf16 v[122:125], v[170:173], v[194:197], v[122:125]
	v_mfma_f32_16x16x32_bf16 v[122:125], v[174:177], v[198:201], v[122:125]
	v_mfma_f32_16x16x32_bf16 v[58:61], v[186:189], v[194:197], v[58:61]
	v_mfma_f32_16x16x32_bf16 v[58:61], v[190:193], v[198:201], v[58:61]
	v_mfma_f32_16x16x32_bf16 v[62:65], v[178:181], v[194:197], v[62:65]
	v_mfma_f32_16x16x32_bf16 v[62:65], v[182:185], v[198:201], v[62:65]
	v_mfma_f32_16x16x32_bf16 v[54:57], v[178:181], v[202:205], v[54:57]
	v_mfma_f32_16x16x32_bf16 v[54:57], v[182:185], v[228:231], v[54:57]
	v_mfma_f32_16x16x32_bf16 v[50:53], v[186:189], v[202:205], v[50:53]
	v_mfma_f32_16x16x32_bf16 v[50:53], v[190:193], v[228:231], v[50:53]
	v_mfma_f32_16x16x32_bf16 v[114:117], v[170:173], v[202:205], v[114:117]
	v_mfma_f32_16x16x32_bf16 v[114:117], v[174:177], v[228:231], v[114:117]
	v_mfma_f32_16x16x32_bf16 v[118:121], v[142:145], v[202:205], v[118:121]
	v_mfma_f32_16x16x32_bf16 v[118:121], v[154:157], v[228:231], v[118:121]
	v_mfma_f32_16x16x32_bf16 v[110:113], v[142:145], v[232:235], v[110:113]
	v_mfma_f32_16x16x32_bf16 v[110:113], v[154:157], v[236:239], v[110:113]
	v_mfma_f32_16x16x32_bf16 v[106:109], v[170:173], v[232:235], v[106:109]
	v_mfma_f32_16x16x32_bf16 v[106:109], v[174:177], v[236:239], v[106:109]
	v_mfma_f32_16x16x32_bf16 v[42:45], v[186:189], v[232:235], v[42:45]
	v_mfma_f32_16x16x32_bf16 v[42:45], v[190:193], v[236:239], v[42:45]
	v_mfma_f32_16x16x32_bf16 v[46:49], v[178:181], v[232:235], v[46:49]
	v_mfma_f32_16x16x32_bf16 v[46:49], v[182:185], v[236:239], v[46:49]
	v_mfma_f32_16x16x32_bf16 v[38:41], v[178:181], v[240:243], v[38:41]
	v_mfma_f32_16x16x32_bf16 v[38:41], v[182:185], v[244:247], v[38:41]
	v_mfma_f32_16x16x32_bf16 v[34:37], v[186:189], v[240:243], v[34:37]
	v_mfma_f32_16x16x32_bf16 v[34:37], v[190:193], v[244:247], v[34:37]
	v_mfma_f32_16x16x32_bf16 v[98:101], v[170:173], v[240:243], v[98:101]
	v_mfma_f32_16x16x32_bf16 v[98:101], v[174:177], v[244:247], v[98:101]
	v_mfma_f32_16x16x32_bf16 v[102:105], v[142:145], v[240:243], v[102:105]
	v_mfma_f32_16x16x32_bf16 v[102:105], v[154:157], v[244:247], v[102:105]
	s_barrier
	s_mov_b32 s66, s62
	s_mov_b32 s67, s63
	s_mov_b32 m0, s2
	ds_read_b128 v[194:197], v140 offset:16384
	buffer_load_dwordx4 v134, s[64:67], s47 offen lds
	s_add_i32 s53, s47, 0x200000
	s_mov_b32 m0, s21
	ds_read_b128 v[198:201], v140 offset:17408
	buffer_load_dwordx4 v136, s[64:67], s47 offen lds
	s_mov_b32 m0, s23
	ds_read_b128 v[202:205], v140 offset:18432
	buffer_load_dwordx4 v134, s[64:67], s53 offen lds
	s_mov_b32 m0, s24
	ds_read_b128 v[228:231], v140 offset:19456
	buffer_load_dwordx4 v136, s[64:67], s53 offen lds
	s_mov_b32 m0, s16
	ds_read_b128 v[232:235], v140 offset:20480
	buffer_load_dwordx4 v131, s[60:63], s52 offen lds
	s_mov_b32 m0, s25
	ds_read_b128 v[236:239], v140 offset:21504
	buffer_load_dwordx4 v135, s[60:63], s52 offen lds
	ds_read_b128 v[240:243], v140 offset:22528
	ds_read_b128 v[244:247], v140 offset:23552
	s_waitcnt vmcnt(8)
	s_waitcnt lgkmcnt(0)
	s_barrier
	v_mfma_f32_16x16x32_bf16 v[94:97], v[142:145], v[194:197], v[94:97]
	v_mfma_f32_16x16x32_bf16 v[94:97], v[154:157], v[198:201], v[94:97]
	v_mfma_f32_16x16x32_bf16 v[90:93], v[170:173], v[194:197], v[90:93]
	v_mfma_f32_16x16x32_bf16 v[90:93], v[174:177], v[198:201], v[90:93]
	v_mfma_f32_16x16x32_bf16 v[26:29], v[186:189], v[194:197], v[26:29]
	v_mfma_f32_16x16x32_bf16 v[26:29], v[190:193], v[198:201], v[26:29]
	v_mfma_f32_16x16x32_bf16 v[30:33], v[178:181], v[194:197], v[30:33]
	v_mfma_f32_16x16x32_bf16 v[30:33], v[182:185], v[198:201], v[30:33]
	v_mfma_f32_16x16x32_bf16 v[22:25], v[178:181], v[202:205], v[22:25]
	v_mfma_f32_16x16x32_bf16 v[22:25], v[182:185], v[228:231], v[22:25]
	v_mfma_f32_16x16x32_bf16 v[18:21], v[186:189], v[202:205], v[18:21]
	v_mfma_f32_16x16x32_bf16 v[18:21], v[190:193], v[228:231], v[18:21]
	v_mfma_f32_16x16x32_bf16 v[82:85], v[170:173], v[202:205], v[82:85]
	v_mfma_f32_16x16x32_bf16 v[82:85], v[174:177], v[228:231], v[82:85]
	v_mfma_f32_16x16x32_bf16 v[86:89], v[142:145], v[202:205], v[86:89]
	v_mfma_f32_16x16x32_bf16 v[86:89], v[154:157], v[228:231], v[86:89]
	v_mfma_f32_16x16x32_bf16 v[78:81], v[142:145], v[232:235], v[78:81]
	v_mfma_f32_16x16x32_bf16 v[78:81], v[154:157], v[236:239], v[78:81]
	v_mfma_f32_16x16x32_bf16 v[74:77], v[170:173], v[232:235], v[74:77]
	v_mfma_f32_16x16x32_bf16 v[74:77], v[174:177], v[236:239], v[74:77]
	v_mfma_f32_16x16x32_bf16 v[10:13], v[186:189], v[232:235], v[10:13]
	v_mfma_f32_16x16x32_bf16 v[10:13], v[190:193], v[236:239], v[10:13]
	v_mfma_f32_16x16x32_bf16 v[14:17], v[178:181], v[232:235], v[14:17]
	v_mfma_f32_16x16x32_bf16 v[14:17], v[182:185], v[236:239], v[14:17]
	v_mfma_f32_16x16x32_bf16 v[6:9], v[178:181], v[240:243], v[6:9]
	v_mfma_f32_16x16x32_bf16 v[6:9], v[182:185], v[244:247], v[6:9]
	v_mfma_f32_16x16x32_bf16 v[2:5], v[186:189], v[240:243], v[2:5]
	v_mfma_f32_16x16x32_bf16 v[2:5], v[190:193], v[244:247], v[2:5]
	v_mfma_f32_16x16x32_bf16 v[66:69], v[170:173], v[240:243], v[66:69]
	v_mfma_f32_16x16x32_bf16 v[66:69], v[174:177], v[244:247], v[66:69]
	v_mfma_f32_16x16x32_bf16 v[70:73], v[142:145], v[240:243], v[70:73]
	v_mfma_f32_16x16x32_bf16 v[70:73], v[154:157], v[244:247], v[70:73]
	s_barrier
	v_add_u32_e32 v141, 0x18000, v139
	ds_read_b128 v[142:145], v141
	ds_read_b128 v[154:157], v141 offset:1024
	ds_read_b128 v[170:173], v141 offset:2048
	ds_read_b128 v[174:177], v141 offset:3072
	v_add_u32_e32 v141, 0x1c000, v139
	ds_read_b128 v[178:181], v141
	ds_read_b128 v[182:185], v141 offset:1024
	ds_read_b128 v[186:189], v141 offset:2048
	ds_read_b128 v[190:193], v141 offset:3072
	s_add_i32 s52, s52, 0x200000
	s_mov_b32 m0, s30
	ds_read_b128 v[194:197], v140 offset:32768
	ds_read_b128 v[198:201], v140 offset:33792
	ds_read_b128 v[202:205], v140 offset:34816
	ds_read_b128 v[228:231], v140 offset:35840
	ds_read_b128 v[232:235], v140 offset:36864
	ds_read_b128 v[236:239], v140 offset:37888
	ds_read_b128 v[240:243], v140 offset:38912
	ds_read_b128 v[244:247], v140 offset:39936
	buffer_load_dwordx4 v131, s[60:63], s52 offen lds
	s_mov_b32 m0, s31
	s_nop 0
	buffer_load_dwordx4 v135, s[60:63], s52 offen lds
	s_waitcnt vmcnt(8)
	s_waitcnt lgkmcnt(0)
	s_barrier
	v_mfma_f32_16x16x32_bf16 v[126:129], v[142:145], v[194:197], v[126:129]
	v_mfma_f32_16x16x32_bf16 v[126:129], v[154:157], v[198:201], v[126:129]
	v_mfma_f32_16x16x32_bf16 v[122:125], v[170:173], v[194:197], v[122:125]
	v_mfma_f32_16x16x32_bf16 v[122:125], v[174:177], v[198:201], v[122:125]
	v_mfma_f32_16x16x32_bf16 v[58:61], v[186:189], v[194:197], v[58:61]
	v_mfma_f32_16x16x32_bf16 v[58:61], v[190:193], v[198:201], v[58:61]
	v_mfma_f32_16x16x32_bf16 v[62:65], v[178:181], v[194:197], v[62:65]
	v_mfma_f32_16x16x32_bf16 v[62:65], v[182:185], v[198:201], v[62:65]
	v_mfma_f32_16x16x32_bf16 v[54:57], v[178:181], v[202:205], v[54:57]
	v_mfma_f32_16x16x32_bf16 v[54:57], v[182:185], v[228:231], v[54:57]
	v_mfma_f32_16x16x32_bf16 v[50:53], v[186:189], v[202:205], v[50:53]
	v_mfma_f32_16x16x32_bf16 v[50:53], v[190:193], v[228:231], v[50:53]
	v_mfma_f32_16x16x32_bf16 v[114:117], v[170:173], v[202:205], v[114:117]
	v_mfma_f32_16x16x32_bf16 v[114:117], v[174:177], v[228:231], v[114:117]
	v_mfma_f32_16x16x32_bf16 v[118:121], v[142:145], v[202:205], v[118:121]
	v_mfma_f32_16x16x32_bf16 v[118:121], v[154:157], v[228:231], v[118:121]
	v_mfma_f32_16x16x32_bf16 v[110:113], v[142:145], v[232:235], v[110:113]
	v_mfma_f32_16x16x32_bf16 v[110:113], v[154:157], v[236:239], v[110:113]
	v_mfma_f32_16x16x32_bf16 v[106:109], v[170:173], v[232:235], v[106:109]
	v_mfma_f32_16x16x32_bf16 v[106:109], v[174:177], v[236:239], v[106:109]
	v_mfma_f32_16x16x32_bf16 v[42:45], v[186:189], v[232:235], v[42:45]
	v_mfma_f32_16x16x32_bf16 v[42:45], v[190:193], v[236:239], v[42:45]
	v_mfma_f32_16x16x32_bf16 v[46:49], v[178:181], v[232:235], v[46:49]
	v_mfma_f32_16x16x32_bf16 v[46:49], v[182:185], v[236:239], v[46:49]
	v_mfma_f32_16x16x32_bf16 v[38:41], v[178:181], v[240:243], v[38:41]
	v_mfma_f32_16x16x32_bf16 v[38:41], v[182:185], v[244:247], v[38:41]
	v_mfma_f32_16x16x32_bf16 v[34:37], v[186:189], v[240:243], v[34:37]
	v_mfma_f32_16x16x32_bf16 v[34:37], v[190:193], v[244:247], v[34:37]
	v_mfma_f32_16x16x32_bf16 v[98:101], v[170:173], v[240:243], v[98:101]
	v_mfma_f32_16x16x32_bf16 v[98:101], v[174:177], v[244:247], v[98:101]
	v_mfma_f32_16x16x32_bf16 v[102:105], v[142:145], v[240:243], v[102:105]
	v_mfma_f32_16x16x32_bf16 v[102:105], v[154:157], v[244:247], v[102:105]
	s_barrier
	s_or_b32 s52, s47, 0x80
	s_mov_b32 m0, s33
	ds_read_b128 v[194:197], v140 offset:49152
	buffer_load_dwordx4 v134, s[64:67], s52 offen lds
	s_add_i32 s47, s47, 0x200080
	s_mov_b32 m0, s34
	ds_read_b128 v[198:201], v140 offset:50176
	buffer_load_dwordx4 v136, s[64:67], s52 offen lds
	s_mov_b32 m0, s37
	ds_read_b128 v[202:205], v140 offset:51200
	buffer_load_dwordx4 v134, s[64:67], s47 offen lds
	s_mov_b32 m0, s68
	ds_read_b128 v[228:231], v140 offset:52224
	buffer_load_dwordx4 v136, s[64:67], s47 offen lds
	s_mov_b32 m0, s35
	ds_read_b128 v[232:235], v140 offset:53248
	buffer_load_dwordx4 v131, s[60:63], s27 offen lds
	s_mov_b32 m0, s36
	ds_read_b128 v[236:239], v140 offset:54272
	buffer_load_dwordx4 v135, s[60:63], s27 offen lds
	ds_read_b128 v[240:243], v140 offset:55296
	ds_read_b128 v[244:247], v140 offset:56320
	s_waitcnt vmcnt(8)
	s_waitcnt lgkmcnt(0)
	s_barrier
	v_mfma_f32_16x16x32_bf16 v[94:97], v[142:145], v[194:197], v[94:97]
	v_mfma_f32_16x16x32_bf16 v[94:97], v[154:157], v[198:201], v[94:97]
	v_mfma_f32_16x16x32_bf16 v[90:93], v[170:173], v[194:197], v[90:93]
	v_mfma_f32_16x16x32_bf16 v[90:93], v[174:177], v[198:201], v[90:93]
	v_mfma_f32_16x16x32_bf16 v[26:29], v[186:189], v[194:197], v[26:29]
	v_mfma_f32_16x16x32_bf16 v[26:29], v[190:193], v[198:201], v[26:29]
	v_mfma_f32_16x16x32_bf16 v[30:33], v[178:181], v[194:197], v[30:33]
	v_mfma_f32_16x16x32_bf16 v[30:33], v[182:185], v[198:201], v[30:33]
	v_mfma_f32_16x16x32_bf16 v[22:25], v[178:181], v[202:205], v[22:25]
	v_mfma_f32_16x16x32_bf16 v[22:25], v[182:185], v[228:231], v[22:25]
	v_mfma_f32_16x16x32_bf16 v[18:21], v[186:189], v[202:205], v[18:21]
	v_mfma_f32_16x16x32_bf16 v[18:21], v[190:193], v[228:231], v[18:21]
	v_mfma_f32_16x16x32_bf16 v[82:85], v[170:173], v[202:205], v[82:85]
	v_mfma_f32_16x16x32_bf16 v[82:85], v[174:177], v[228:231], v[82:85]
	v_mfma_f32_16x16x32_bf16 v[86:89], v[142:145], v[202:205], v[86:89]
	v_mfma_f32_16x16x32_bf16 v[86:89], v[154:157], v[228:231], v[86:89]
	v_mfma_f32_16x16x32_bf16 v[78:81], v[142:145], v[232:235], v[78:81]
	v_mfma_f32_16x16x32_bf16 v[78:81], v[154:157], v[236:239], v[78:81]
	v_mfma_f32_16x16x32_bf16 v[74:77], v[170:173], v[232:235], v[74:77]
	v_mfma_f32_16x16x32_bf16 v[74:77], v[174:177], v[236:239], v[74:77]
	v_mfma_f32_16x16x32_bf16 v[10:13], v[186:189], v[232:235], v[10:13]
	v_mfma_f32_16x16x32_bf16 v[10:13], v[190:193], v[236:239], v[10:13]
	v_mfma_f32_16x16x32_bf16 v[14:17], v[178:181], v[232:235], v[14:17]
	v_mfma_f32_16x16x32_bf16 v[14:17], v[182:185], v[236:239], v[14:17]
	v_mfma_f32_16x16x32_bf16 v[6:9], v[178:181], v[240:243], v[6:9]
	v_mfma_f32_16x16x32_bf16 v[6:9], v[182:185], v[244:247], v[6:9]
	v_mfma_f32_16x16x32_bf16 v[2:5], v[186:189], v[240:243], v[2:5]
	v_mfma_f32_16x16x32_bf16 v[2:5], v[190:193], v[244:247], v[2:5]
	v_mfma_f32_16x16x32_bf16 v[66:69], v[170:173], v[240:243], v[66:69]
	v_mfma_f32_16x16x32_bf16 v[66:69], v[174:177], v[244:247], v[66:69]
	v_mfma_f32_16x16x32_bf16 v[70:73], v[142:145], v[240:243], v[70:73]
	v_mfma_f32_16x16x32_bf16 v[70:73], v[154:157], v[244:247], v[70:73]
	s_barrier
	s_add_i32 s26, s26, 2
	s_addk_i32 s19, 0x100
	s_addk_i32 s22, 0x100
	s_cmpk_gt_u32 s26, 0x7d
	s_cbranch_scc0 .LBB0_1223
	s_and_b64 vcc, exec, s[42:43]
	s_cbranch_vccz .LBB0_1226
	s_barrier

.LBB0_1252:
	s_lshl_b32 s12, s73, 20
	s_and_b64 s[8:9], s[40:41], exec
	s_cselect_b32 s8, s12, s26
	s_lshl_b32 s22, s82, 20
	s_and_b64 s[70:71], s[40:41], exec
	s_cselect_b32 s9, s22, s27
	s_add_i32 s26, s26, 0x80080
	s_addk_i32 s27, 0x100
	s_mov_b32 s83, -2
	v_add_u32_e32 v141, 0x10000, v139
	ds_read_b128 v[142:145], v141
	ds_read_b128 v[154:157], v141 offset:1024
	ds_read_b128 v[170:173], v141 offset:2048
	ds_read_b128 v[174:177], v141 offset:3072
	v_add_u32_e32 v141, 0x14000, v139
	ds_read_b128 v[178:181], v141
	ds_read_b128 v[182:185], v141 offset:1024
	ds_read_b128 v[186:189], v141 offset:2048
	ds_read_b128 v[190:193], v141 offset:3072
	s_add_i32 s52, s26, 0xfff80080
	s_cmp_eq_u32 s83, 28
	s_cselect_b32 s52, s8, s52
	s_cselect_b32 s85, s9, s27
	s_or_b32 s84, s52, 0x80
	s_mov_b32 m0, s72
	ds_read_b128 v[194:197], v140
	ds_read_b128 v[198:201], v140 offset:1024
	ds_read_b128 v[202:205], v140 offset:2048
	ds_read_b128 v[228:231], v140 offset:3072
	ds_read_b128 v[232:235], v140 offset:4096
	ds_read_b128 v[236:239], v140 offset:5120
	ds_read_b128 v[240:243], v140 offset:6144
	ds_read_b128 v[244:247], v140 offset:7168
	buffer_load_dwordx4 v131, s[60:63], s26 offen lds
	s_mov_b32 m0, s46
	s_nop 0
	buffer_load_dwordx4 v135, s[60:63], s26 offen lds
	s_waitcnt vmcnt(8)
	s_waitcnt lgkmcnt(0)
	s_barrier
	v_mfma_f32_16x16x32_bf16 v[126:129], v[142:145], v[194:197], 0
	v_mfma_f32_16x16x32_bf16 v[126:129], v[154:157], v[198:201], v[126:129]
	v_mfma_f32_16x16x32_bf16 v[122:125], v[170:173], v[194:197], 0
	v_mfma_f32_16x16x32_bf16 v[122:125], v[174:177], v[198:201], v[122:125]
	v_mfma_f32_16x16x32_bf16 v[58:61], v[186:189], v[194:197], 0
	v_mfma_f32_16x16x32_bf16 v[58:61], v[190:193], v[198:201], v[58:61]
	v_mfma_f32_16x16x32_bf16 v[62:65], v[178:181], v[194:197], 0
	v_mfma_f32_16x16x32_bf16 v[62:65], v[182:185], v[198:201], v[62:65]
	v_mfma_f32_16x16x32_bf16 v[54:57], v[178:181], v[202:205], 0
	v_mfma_f32_16x16x32_bf16 v[54:57], v[182:185], v[228:231], v[54:57]
	v_mfma_f32_16x16x32_bf16 v[50:53], v[186:189], v[202:205], 0
	v_mfma_f32_16x16x32_bf16 v[50:53], v[190:193], v[228:231], v[50:53]
	v_mfma_f32_16x16x32_bf16 v[114:117], v[170:173], v[202:205], 0
	v_mfma_f32_16x16x32_bf16 v[114:117], v[174:177], v[228:231], v[114:117]
	v_mfma_f32_16x16x32_bf16 v[118:121], v[142:145], v[202:205], 0
	v_mfma_f32_16x16x32_bf16 v[118:121], v[154:157], v[228:231], v[118:121]
	v_mfma_f32_16x16x32_bf16 v[110:113], v[142:145], v[232:235], 0
	v_mfma_f32_16x16x32_bf16 v[110:113], v[154:157], v[236:239], v[110:113]
	v_mfma_f32_16x16x32_bf16 v[106:109], v[170:173], v[232:235], 0
	v_mfma_f32_16x16x32_bf16 v[106:109], v[174:177], v[236:239], v[106:109]
	v_mfma_f32_16x16x32_bf16 v[42:45], v[186:189], v[232:235], 0
	v_mfma_f32_16x16x32_bf16 v[42:45], v[190:193], v[236:239], v[42:45]
	v_mfma_f32_16x16x32_bf16 v[46:49], v[178:181], v[232:235], 0
	v_mfma_f32_16x16x32_bf16 v[46:49], v[182:185], v[236:239], v[46:49]
	v_mfma_f32_16x16x32_bf16 v[38:41], v[178:181], v[240:243], 0
	v_mfma_f32_16x16x32_bf16 v[38:41], v[182:185], v[244:247], v[38:41]
	v_mfma_f32_16x16x32_bf16 v[34:37], v[186:189], v[240:243], 0
	v_mfma_f32_16x16x32_bf16 v[34:37], v[190:193], v[244:247], v[34:37]
	v_mfma_f32_16x16x32_bf16 v[98:101], v[170:173], v[240:243], 0
	v_mfma_f32_16x16x32_bf16 v[98:101], v[174:177], v[244:247], v[98:101]
	v_mfma_f32_16x16x32_bf16 v[102:105], v[142:145], v[240:243], 0
	v_mfma_f32_16x16x32_bf16 v[102:105], v[154:157], v[244:247], v[102:105]
	s_barrier
	s_mov_b32 s70, s62
	s_mov_b32 s71, s63
	s_mov_b32 m0, s21
	ds_read_b128 v[194:197], v140 offset:16384
	buffer_load_dwordx4 v134, s[68:71], s85 offen lds
	s_add_i32 s53, s85, 0x80000
	s_mov_b32 m0, s23
	ds_read_b128 v[198:201], v140 offset:17408
	buffer_load_dwordx4 v136, s[68:71], s85 offen lds
	s_mov_b32 m0, s24
	ds_read_b128 v[202:205], v140 offset:18432
	buffer_load_dwordx4 v134, s[68:71], s53 offen lds
	s_mov_b32 m0, s25
	ds_read_b128 v[228:231], v140 offset:19456
	buffer_load_dwordx4 v136, s[68:71], s53 offen lds
	s_mov_b32 m0, s16
	ds_read_b128 v[232:235], v140 offset:20480
	buffer_load_dwordx4 v131, s[60:63], s52 offen lds
	s_mov_b32 m0, s30
	ds_read_b128 v[236:239], v140 offset:21504
	buffer_load_dwordx4 v135, s[60:63], s52 offen lds
	ds_read_b128 v[240:243], v140 offset:22528
	ds_read_b128 v[244:247], v140 offset:23552
	s_waitcnt vmcnt(8)
	s_waitcnt lgkmcnt(0)
	s_barrier
	v_mfma_f32_16x16x32_bf16 v[94:97], v[142:145], v[194:197], 0
	v_mfma_f32_16x16x32_bf16 v[94:97], v[154:157], v[198:201], v[94:97]
	v_mfma_f32_16x16x32_bf16 v[90:93], v[170:173], v[194:197], 0
	v_mfma_f32_16x16x32_bf16 v[90:93], v[174:177], v[198:201], v[90:93]
	v_mfma_f32_16x16x32_bf16 v[26:29], v[186:189], v[194:197], 0
	v_mfma_f32_16x16x32_bf16 v[26:29], v[190:193], v[198:201], v[26:29]
	v_mfma_f32_16x16x32_bf16 v[30:33], v[178:181], v[194:197], 0
	v_mfma_f32_16x16x32_bf16 v[30:33], v[182:185], v[198:201], v[30:33]
	v_mfma_f32_16x16x32_bf16 v[22:25], v[178:181], v[202:205], 0
	v_mfma_f32_16x16x32_bf16 v[22:25], v[182:185], v[228:231], v[22:25]
	v_mfma_f32_16x16x32_bf16 v[18:21], v[186:189], v[202:205], 0
	v_mfma_f32_16x16x32_bf16 v[18:21], v[190:193], v[228:231], v[18:21]
	v_mfma_f32_16x16x32_bf16 v[82:85], v[170:173], v[202:205], 0
	v_mfma_f32_16x16x32_bf16 v[82:85], v[174:177], v[228:231], v[82:85]
	v_mfma_f32_16x16x32_bf16 v[86:89], v[142:145], v[202:205], 0
	v_mfma_f32_16x16x32_bf16 v[86:89], v[154:157], v[228:231], v[86:89]
	v_mfma_f32_16x16x32_bf16 v[78:81], v[142:145], v[232:235], 0
	v_mfma_f32_16x16x32_bf16 v[78:81], v[154:157], v[236:239], v[78:81]
	v_mfma_f32_16x16x32_bf16 v[74:77], v[170:173], v[232:235], 0
	v_mfma_f32_16x16x32_bf16 v[74:77], v[174:177], v[236:239], v[74:77]
	v_mfma_f32_16x16x32_bf16 v[10:13], v[186:189], v[232:235], 0
	v_mfma_f32_16x16x32_bf16 v[10:13], v[190:193], v[236:239], v[10:13]
	v_mfma_f32_16x16x32_bf16 v[14:17], v[178:181], v[232:235], 0
	v_mfma_f32_16x16x32_bf16 v[14:17], v[182:185], v[236:239], v[14:17]
	v_mfma_f32_16x16x32_bf16 v[6:9], v[178:181], v[240:243], 0
	v_mfma_f32_16x16x32_bf16 v[6:9], v[182:185], v[244:247], v[6:9]
	v_mfma_f32_16x16x32_bf16 v[2:5], v[186:189], v[240:243], 0
	v_mfma_f32_16x16x32_bf16 v[2:5], v[190:193], v[244:247], v[2:5]
	v_mfma_f32_16x16x32_bf16 v[66:69], v[170:173], v[240:243], 0
	v_mfma_f32_16x16x32_bf16 v[66:69], v[174:177], v[244:247], v[66:69]
	v_mfma_f32_16x16x32_bf16 v[70:73], v[142:145], v[240:243], 0
	v_mfma_f32_16x16x32_bf16 v[70:73], v[154:157], v[244:247], v[70:73]
	s_barrier
	v_add_u32_e32 v141, 0x18000, v139
	ds_read_b128 v[142:145], v141
	ds_read_b128 v[154:157], v141 offset:1024
	ds_read_b128 v[170:173], v141 offset:2048
	ds_read_b128 v[174:177], v141 offset:3072
	v_add_u32_e32 v141, 0x1c000, v139
	ds_read_b128 v[178:181], v141
	ds_read_b128 v[182:185], v141 offset:1024
	ds_read_b128 v[186:189], v141 offset:2048
	ds_read_b128 v[190:193], v141 offset:3072
	s_add_i32 s52, s52, 0x80000
	s_mov_b32 m0, s31
	ds_read_b128 v[194:197], v140 offset:32768
	ds_read_b128 v[198:201], v140 offset:33792
	ds_read_b128 v[202:205], v140 offset:34816
	ds_read_b128 v[228:231], v140 offset:35840
	ds_read_b128 v[232:235], v140 offset:36864
	ds_read_b128 v[236:239], v140 offset:37888
	ds_read_b128 v[240:243], v140 offset:38912
	ds_read_b128 v[244:247], v140 offset:39936
	buffer_load_dwordx4 v131, s[60:63], s52 offen lds
	s_mov_b32 m0, s33
	s_nop 0
	buffer_load_dwordx4 v135, s[60:63], s52 offen lds
	s_waitcnt vmcnt(8)
	s_waitcnt lgkmcnt(0)
	s_barrier
	v_mfma_f32_16x16x32_bf16 v[126:129], v[142:145], v[194:197], v[126:129]
	v_mfma_f32_16x16x32_bf16 v[126:129], v[154:157], v[198:201], v[126:129]
	v_mfma_f32_16x16x32_bf16 v[122:125], v[170:173], v[194:197], v[122:125]
	v_mfma_f32_16x16x32_bf16 v[122:125], v[174:177], v[198:201], v[122:125]
	v_mfma_f32_16x16x32_bf16 v[58:61], v[186:189], v[194:197], v[58:61]
	v_mfma_f32_16x16x32_bf16 v[58:61], v[190:193], v[198:201], v[58:61]
	v_mfma_f32_16x16x32_bf16 v[62:65], v[178:181], v[194:197], v[62:65]
	v_mfma_f32_16x16x32_bf16 v[62:65], v[182:185], v[198:201], v[62:65]
	v_mfma_f32_16x16x32_bf16 v[54:57], v[178:181], v[202:205], v[54:57]
	v_mfma_f32_16x16x32_bf16 v[54:57], v[182:185], v[228:231], v[54:57]
	v_mfma_f32_16x16x32_bf16 v[50:53], v[186:189], v[202:205], v[50:53]
	v_mfma_f32_16x16x32_bf16 v[50:53], v[190:193], v[228:231], v[50:53]
	v_mfma_f32_16x16x32_bf16 v[114:117], v[170:173], v[202:205], v[114:117]
	v_mfma_f32_16x16x32_bf16 v[114:117], v[174:177], v[228:231], v[114:117]
	v_mfma_f32_16x16x32_bf16 v[118:121], v[142:145], v[202:205], v[118:121]
	v_mfma_f32_16x16x32_bf16 v[118:121], v[154:157], v[228:231], v[118:121]
	v_mfma_f32_16x16x32_bf16 v[110:113], v[142:145], v[232:235], v[110:113]
	v_mfma_f32_16x16x32_bf16 v[110:113], v[154:157], v[236:239], v[110:113]
	v_mfma_f32_16x16x32_bf16 v[106:109], v[170:173], v[232:235], v[106:109]
	v_mfma_f32_16x16x32_bf16 v[106:109], v[174:177], v[236:239], v[106:109]
	v_mfma_f32_16x16x32_bf16 v[42:45], v[186:189], v[232:235], v[42:45]
	v_mfma_f32_16x16x32_bf16 v[42:45], v[190:193], v[236:239], v[42:45]
	v_mfma_f32_16x16x32_bf16 v[46:49], v[178:181], v[232:235], v[46:49]
	v_mfma_f32_16x16x32_bf16 v[46:49], v[182:185], v[236:239], v[46:49]
	v_mfma_f32_16x16x32_bf16 v[38:41], v[178:181], v[240:243], v[38:41]
	v_mfma_f32_16x16x32_bf16 v[38:41], v[182:185], v[244:247], v[38:41]
	v_mfma_f32_16x16x32_bf16 v[34:37], v[186:189], v[240:243], v[34:37]
	v_mfma_f32_16x16x32_bf16 v[34:37], v[190:193], v[244:247], v[34:37]
	v_mfma_f32_16x16x32_bf16 v[98:101], v[170:173], v[240:243], v[98:101]
	v_mfma_f32_16x16x32_bf16 v[98:101], v[174:177], v[244:247], v[98:101]
	v_mfma_f32_16x16x32_bf16 v[102:105], v[142:145], v[240:243], v[102:105]
	v_mfma_f32_16x16x32_bf16 v[102:105], v[154:157], v[244:247], v[102:105]
	s_barrier
	s_or_b32 s52, s85, 0x80
	s_mov_b32 m0, s34
	ds_read_b128 v[194:197], v140 offset:49152
	buffer_load_dwordx4 v134, s[68:71], s52 offen lds
	s_add_i32 s85, s85, 0x80080
	s_mov_b32 m0, s35
	ds_read_b128 v[198:201], v140 offset:50176
	buffer_load_dwordx4 v136, s[68:71], s52 offen lds
	s_mov_b32 m0, s37
	ds_read_b128 v[202:205], v140 offset:51200
	buffer_load_dwordx4 v134, s[68:71], s85 offen lds
	s_mov_b32 m0, s65
	ds_read_b128 v[228:231], v140 offset:52224
	buffer_load_dwordx4 v136, s[68:71], s85 offen lds
	s_mov_b32 m0, s14
	ds_read_b128 v[232:235], v140 offset:53248
	buffer_load_dwordx4 v131, s[60:63], s84 offen lds
	s_mov_b32 m0, s36
	ds_read_b128 v[236:239], v140 offset:54272
	buffer_load_dwordx4 v135, s[60:63], s84 offen lds
	ds_read_b128 v[240:243], v140 offset:55296
	ds_read_b128 v[244:247], v140 offset:56320
	s_waitcnt vmcnt(8)
	s_waitcnt lgkmcnt(0)
	s_barrier
	v_mfma_f32_16x16x32_bf16 v[94:97], v[142:145], v[194:197], v[94:97]
	v_mfma_f32_16x16x32_bf16 v[94:97], v[154:157], v[198:201], v[94:97]
	v_mfma_f32_16x16x32_bf16 v[90:93], v[170:173], v[194:197], v[90:93]
	v_mfma_f32_16x16x32_bf16 v[90:93], v[174:177], v[198:201], v[90:93]
	v_mfma_f32_16x16x32_bf16 v[26:29], v[186:189], v[194:197], v[26:29]
	v_mfma_f32_16x16x32_bf16 v[26:29], v[190:193], v[198:201], v[26:29]
	v_mfma_f32_16x16x32_bf16 v[30:33], v[178:181], v[194:197], v[30:33]
	v_mfma_f32_16x16x32_bf16 v[30:33], v[182:185], v[198:201], v[30:33]
	v_mfma_f32_16x16x32_bf16 v[22:25], v[178:181], v[202:205], v[22:25]
	v_mfma_f32_16x16x32_bf16 v[22:25], v[182:185], v[228:231], v[22:25]
	v_mfma_f32_16x16x32_bf16 v[18:21], v[186:189], v[202:205], v[18:21]
	v_mfma_f32_16x16x32_bf16 v[18:21], v[190:193], v[228:231], v[18:21]
	v_mfma_f32_16x16x32_bf16 v[82:85], v[170:173], v[202:205], v[82:85]
	v_mfma_f32_16x16x32_bf16 v[82:85], v[174:177], v[228:231], v[82:85]
	v_mfma_f32_16x16x32_bf16 v[86:89], v[142:145], v[202:205], v[86:89]
	v_mfma_f32_16x16x32_bf16 v[86:89], v[154:157], v[228:231], v[86:89]
	v_mfma_f32_16x16x32_bf16 v[78:81], v[142:145], v[232:235], v[78:81]
	v_mfma_f32_16x16x32_bf16 v[78:81], v[154:157], v[236:239], v[78:81]
	v_mfma_f32_16x16x32_bf16 v[74:77], v[170:173], v[232:235], v[74:77]
	v_mfma_f32_16x16x32_bf16 v[74:77], v[174:177], v[236:239], v[74:77]
	v_mfma_f32_16x16x32_bf16 v[10:13], v[186:189], v[232:235], v[10:13]
	v_mfma_f32_16x16x32_bf16 v[10:13], v[190:193], v[236:239], v[10:13]
	v_mfma_f32_16x16x32_bf16 v[14:17], v[178:181], v[232:235], v[14:17]
	v_mfma_f32_16x16x32_bf16 v[14:17], v[182:185], v[236:239], v[14:17]
	v_mfma_f32_16x16x32_bf16 v[6:9], v[178:181], v[240:243], v[6:9]
	v_mfma_f32_16x16x32_bf16 v[6:9], v[182:185], v[244:247], v[6:9]
	v_mfma_f32_16x16x32_bf16 v[2:5], v[186:189], v[240:243], v[2:5]
	v_mfma_f32_16x16x32_bf16 v[2:5], v[190:193], v[244:247], v[2:5]
	v_mfma_f32_16x16x32_bf16 v[66:69], v[170:173], v[240:243], v[66:69]
	v_mfma_f32_16x16x32_bf16 v[66:69], v[174:177], v[244:247], v[66:69]
	v_mfma_f32_16x16x32_bf16 v[70:73], v[142:145], v[240:243], v[70:73]
	v_mfma_f32_16x16x32_bf16 v[70:73], v[154:157], v[244:247], v[70:73]
	s_barrier
	s_add_i32 s83, s83, 2
	s_addk_i32 s26, 0x100
	s_addk_i32 s27, 0x100
	s_cmp_gt_u32 s83, 29
.LBB0_1253:
	v_add_u32_e32 v141, 0x10000, v139
	ds_read_b128 v[142:145], v141
	ds_read_b128 v[154:157], v141 offset:1024
	ds_read_b128 v[170:173], v141 offset:2048
	ds_read_b128 v[174:177], v141 offset:3072
	v_add_u32_e32 v141, 0x14000, v139
	ds_read_b128 v[178:181], v141
	ds_read_b128 v[182:185], v141 offset:1024
	ds_read_b128 v[186:189], v141 offset:2048
	ds_read_b128 v[190:193], v141 offset:3072
	s_add_i32 s52, s26, 0xfff80080
	s_cmp_eq_u32 s83, 28
	s_cselect_b32 s52, s8, s52
	s_cselect_b32 s85, s9, s27
	s_or_b32 s84, s52, 0x80
	s_mov_b32 m0, s72
	ds_read_b128 v[194:197], v140
	ds_read_b128 v[198:201], v140 offset:1024
	ds_read_b128 v[202:205], v140 offset:2048
	ds_read_b128 v[228:231], v140 offset:3072
	ds_read_b128 v[232:235], v140 offset:4096
	ds_read_b128 v[236:239], v140 offset:5120
	ds_read_b128 v[240:243], v140 offset:6144
	ds_read_b128 v[244:247], v140 offset:7168
	buffer_load_dwordx4 v131, s[60:63], s26 offen lds
	s_mov_b32 m0, s46
	s_nop 0
	buffer_load_dwordx4 v135, s[60:63], s26 offen lds
	s_waitcnt vmcnt(8)
	s_waitcnt lgkmcnt(0)
	s_barrier
	v_mfma_f32_16x16x32_bf16 v[126:129], v[142:145], v[194:197], v[126:129]
	v_mfma_f32_16x16x32_bf16 v[126:129], v[154:157], v[198:201], v[126:129]
	v_mfma_f32_16x16x32_bf16 v[122:125], v[170:173], v[194:197], v[122:125]
	v_mfma_f32_16x16x32_bf16 v[122:125], v[174:177], v[198:201], v[122:125]
	v_mfma_f32_16x16x32_bf16 v[58:61], v[186:189], v[194:197], v[58:61]
	v_mfma_f32_16x16x32_bf16 v[58:61], v[190:193], v[198:201], v[58:61]
	v_mfma_f32_16x16x32_bf16 v[62:65], v[178:181], v[194:197], v[62:65]
	v_mfma_f32_16x16x32_bf16 v[62:65], v[182:185], v[198:201], v[62:65]
	v_mfma_f32_16x16x32_bf16 v[54:57], v[178:181], v[202:205], v[54:57]
	v_mfma_f32_16x16x32_bf16 v[54:57], v[182:185], v[228:231], v[54:57]
	v_mfma_f32_16x16x32_bf16 v[50:53], v[186:189], v[202:205], v[50:53]
	v_mfma_f32_16x16x32_bf16 v[50:53], v[190:193], v[228:231], v[50:53]
	v_mfma_f32_16x16x32_bf16 v[114:117], v[170:173], v[202:205], v[114:117]
	v_mfma_f32_16x16x32_bf16 v[114:117], v[174:177], v[228:231], v[114:117]
	v_mfma_f32_16x16x32_bf16 v[118:121], v[142:145], v[202:205], v[118:121]
	v_mfma_f32_16x16x32_bf16 v[118:121], v[154:157], v[228:231], v[118:121]
	v_mfma_f32_16x16x32_bf16 v[110:113], v[142:145], v[232:235], v[110:113]
	v_mfma_f32_16x16x32_bf16 v[110:113], v[154:157], v[236:239], v[110:113]
	v_mfma_f32_16x16x32_bf16 v[106:109], v[170:173], v[232:235], v[106:109]
	v_mfma_f32_16x16x32_bf16 v[106:109], v[174:177], v[236:239], v[106:109]
	v_mfma_f32_16x16x32_bf16 v[42:45], v[186:189], v[232:235], v[42:45]
	v_mfma_f32_16x16x32_bf16 v[42:45], v[190:193], v[236:239], v[42:45]
	v_mfma_f32_16x16x32_bf16 v[46:49], v[178:181], v[232:235], v[46:49]
	v_mfma_f32_16x16x32_bf16 v[46:49], v[182:185], v[236:239], v[46:49]
	v_mfma_f32_16x16x32_bf16 v[38:41], v[178:181], v[240:243], v[38:41]
	v_mfma_f32_16x16x32_bf16 v[38:41], v[182:185], v[244:247], v[38:41]
	v_mfma_f32_16x16x32_bf16 v[34:37], v[186:189], v[240:243], v[34:37]
	v_mfma_f32_16x16x32_bf16 v[34:37], v[190:193], v[244:247], v[34:37]
	v_mfma_f32_16x16x32_bf16 v[98:101], v[170:173], v[240:243], v[98:101]
	v_mfma_f32_16x16x32_bf16 v[98:101], v[174:177], v[244:247], v[98:101]
	v_mfma_f32_16x16x32_bf16 v[102:105], v[142:145], v[240:243], v[102:105]
	v_mfma_f32_16x16x32_bf16 v[102:105], v[154:157], v[244:247], v[102:105]
	s_barrier
	s_mov_b32 s70, s62
	s_mov_b32 s71, s63
	s_mov_b32 m0, s21
	ds_read_b128 v[194:197], v140 offset:16384
	buffer_load_dwordx4 v134, s[68:71], s85 offen lds
	s_add_i32 s53, s85, 0x80000
	s_mov_b32 m0, s23
	ds_read_b128 v[198:201], v140 offset:17408
	buffer_load_dwordx4 v136, s[68:71], s85 offen lds
	s_mov_b32 m0, s24
	ds_read_b128 v[202:205], v140 offset:18432
	buffer_load_dwordx4 v134, s[68:71], s53 offen lds
	s_mov_b32 m0, s25
	ds_read_b128 v[228:231], v140 offset:19456
	buffer_load_dwordx4 v136, s[68:71], s53 offen lds
	s_mov_b32 m0, s16
	ds_read_b128 v[232:235], v140 offset:20480
	buffer_load_dwordx4 v131, s[60:63], s52 offen lds
	s_mov_b32 m0, s30
	ds_read_b128 v[236:239], v140 offset:21504
	buffer_load_dwordx4 v135, s[60:63], s52 offen lds
	ds_read_b128 v[240:243], v140 offset:22528
	ds_read_b128 v[244:247], v140 offset:23552
	s_waitcnt vmcnt(8)
	s_waitcnt lgkmcnt(0)
	s_barrier
	v_mfma_f32_16x16x32_bf16 v[94:97], v[142:145], v[194:197], v[94:97]
	v_mfma_f32_16x16x32_bf16 v[94:97], v[154:157], v[198:201], v[94:97]
	v_mfma_f32_16x16x32_bf16 v[90:93], v[170:173], v[194:197], v[90:93]
	v_mfma_f32_16x16x32_bf16 v[90:93], v[174:177], v[198:201], v[90:93]
	v_mfma_f32_16x16x32_bf16 v[26:29], v[186:189], v[194:197], v[26:29]
	v_mfma_f32_16x16x32_bf16 v[26:29], v[190:193], v[198:201], v[26:29]
	v_mfma_f32_16x16x32_bf16 v[30:33], v[178:181], v[194:197], v[30:33]
	v_mfma_f32_16x16x32_bf16 v[30:33], v[182:185], v[198:201], v[30:33]
	v_mfma_f32_16x16x32_bf16 v[22:25], v[178:181], v[202:205], v[22:25]
	v_mfma_f32_16x16x32_bf16 v[22:25], v[182:185], v[228:231], v[22:25]
	v_mfma_f32_16x16x32_bf16 v[18:21], v[186:189], v[202:205], v[18:21]
	v_mfma_f32_16x16x32_bf16 v[18:21], v[190:193], v[228:231], v[18:21]
	v_mfma_f32_16x16x32_bf16 v[82:85], v[170:173], v[202:205], v[82:85]
	v_mfma_f32_16x16x32_bf16 v[82:85], v[174:177], v[228:231], v[82:85]
	v_mfma_f32_16x16x32_bf16 v[86:89], v[142:145], v[202:205], v[86:89]
	v_mfma_f32_16x16x32_bf16 v[86:89], v[154:157], v[228:231], v[86:89]
	v_mfma_f32_16x16x32_bf16 v[78:81], v[142:145], v[232:235], v[78:81]
	v_mfma_f32_16x16x32_bf16 v[78:81], v[154:157], v[236:239], v[78:81]
	v_mfma_f32_16x16x32_bf16 v[74:77], v[170:173], v[232:235], v[74:77]
	v_mfma_f32_16x16x32_bf16 v[74:77], v[174:177], v[236:239], v[74:77]
	v_mfma_f32_16x16x32_bf16 v[10:13], v[186:189], v[232:235], v[10:13]
	v_mfma_f32_16x16x32_bf16 v[10:13], v[190:193], v[236:239], v[10:13]
	v_mfma_f32_16x16x32_bf16 v[14:17], v[178:181], v[232:235], v[14:17]
	v_mfma_f32_16x16x32_bf16 v[14:17], v[182:185], v[236:239], v[14:17]
	v_mfma_f32_16x16x32_bf16 v[6:9], v[178:181], v[240:243], v[6:9]
	v_mfma_f32_16x16x32_bf16 v[6:9], v[182:185], v[244:247], v[6:9]
	v_mfma_f32_16x16x32_bf16 v[2:5], v[186:189], v[240:243], v[2:5]
	v_mfma_f32_16x16x32_bf16 v[2:5], v[190:193], v[244:247], v[2:5]
	v_mfma_f32_16x16x32_bf16 v[66:69], v[170:173], v[240:243], v[66:69]
	v_mfma_f32_16x16x32_bf16 v[66:69], v[174:177], v[244:247], v[66:69]
	v_mfma_f32_16x16x32_bf16 v[70:73], v[142:145], v[240:243], v[70:73]
	v_mfma_f32_16x16x32_bf16 v[70:73], v[154:157], v[244:247], v[70:73]
	s_barrier
	v_add_u32_e32 v141, 0x18000, v139
	ds_read_b128 v[142:145], v141
	ds_read_b128 v[154:157], v141 offset:1024
	ds_read_b128 v[170:173], v141 offset:2048
	ds_read_b128 v[174:177], v141 offset:3072
	v_add_u32_e32 v141, 0x1c000, v139
	ds_read_b128 v[178:181], v141
	ds_read_b128 v[182:185], v141 offset:1024
	ds_read_b128 v[186:189], v141 offset:2048
	ds_read_b128 v[190:193], v141 offset:3072
	s_add_i32 s52, s52, 0x80000
	s_mov_b32 m0, s31
	ds_read_b128 v[194:197], v140 offset:32768
	ds_read_b128 v[198:201], v140 offset:33792
	ds_read_b128 v[202:205], v140 offset:34816
	ds_read_b128 v[228:231], v140 offset:35840
	ds_read_b128 v[232:235], v140 offset:36864
	ds_read_b128 v[236:239], v140 offset:37888
	ds_read_b128 v[240:243], v140 offset:38912
	ds_read_b128 v[244:247], v140 offset:39936
	buffer_load_dwordx4 v131, s[60:63], s52 offen lds
	s_mov_b32 m0, s33
	s_nop 0
	buffer_load_dwordx4 v135, s[60:63], s52 offen lds
	s_waitcnt vmcnt(8)
	s_waitcnt lgkmcnt(0)
	s_barrier
	v_mfma_f32_16x16x32_bf16 v[126:129], v[142:145], v[194:197], v[126:129]
	v_mfma_f32_16x16x32_bf16 v[126:129], v[154:157], v[198:201], v[126:129]
	v_mfma_f32_16x16x32_bf16 v[122:125], v[170:173], v[194:197], v[122:125]
	v_mfma_f32_16x16x32_bf16 v[122:125], v[174:177], v[198:201], v[122:125]
	v_mfma_f32_16x16x32_bf16 v[58:61], v[186:189], v[194:197], v[58:61]
	v_mfma_f32_16x16x32_bf16 v[58:61], v[190:193], v[198:201], v[58:61]
	v_mfma_f32_16x16x32_bf16 v[62:65], v[178:181], v[194:197], v[62:65]
	v_mfma_f32_16x16x32_bf16 v[62:65], v[182:185], v[198:201], v[62:65]
	v_mfma_f32_16x16x32_bf16 v[54:57], v[178:181], v[202:205], v[54:57]
	v_mfma_f32_16x16x32_bf16 v[54:57], v[182:185], v[228:231], v[54:57]
	v_mfma_f32_16x16x32_bf16 v[50:53], v[186:189], v[202:205], v[50:53]
	v_mfma_f32_16x16x32_bf16 v[50:53], v[190:193], v[228:231], v[50:53]
	v_mfma_f32_16x16x32_bf16 v[114:117], v[170:173], v[202:205], v[114:117]
	v_mfma_f32_16x16x32_bf16 v[114:117], v[174:177], v[228:231], v[114:117]
	v_mfma_f32_16x16x32_bf16 v[118:121], v[142:145], v[202:205], v[118:121]
	v_mfma_f32_16x16x32_bf16 v[118:121], v[154:157], v[228:231], v[118:121]
	v_mfma_f32_16x16x32_bf16 v[110:113], v[142:145], v[232:235], v[110:113]
	v_mfma_f32_16x16x32_bf16 v[110:113], v[154:157], v[236:239], v[110:113]
	v_mfma_f32_16x16x32_bf16 v[106:109], v[170:173], v[232:235], v[106:109]
	v_mfma_f32_16x16x32_bf16 v[106:109], v[174:177], v[236:239], v[106:109]
	v_mfma_f32_16x16x32_bf16 v[42:45], v[186:189], v[232:235], v[42:45]
	v_mfma_f32_16x16x32_bf16 v[42:45], v[190:193], v[236:239], v[42:45]
	v_mfma_f32_16x16x32_bf16 v[46:49], v[178:181], v[232:235], v[46:49]
	v_mfma_f32_16x16x32_bf16 v[46:49], v[182:185], v[236:239], v[46:49]
	v_mfma_f32_16x16x32_bf16 v[38:41], v[178:181], v[240:243], v[38:41]
	v_mfma_f32_16x16x32_bf16 v[38:41], v[182:185], v[244:247], v[38:41]
	v_mfma_f32_16x16x32_bf16 v[34:37], v[186:189], v[240:243], v[34:37]
	v_mfma_f32_16x16x32_bf16 v[34:37], v[190:193], v[244:247], v[34:37]
	v_mfma_f32_16x16x32_bf16 v[98:101], v[170:173], v[240:243], v[98:101]
	v_mfma_f32_16x16x32_bf16 v[98:101], v[174:177], v[244:247], v[98:101]
	v_mfma_f32_16x16x32_bf16 v[102:105], v[142:145], v[240:243], v[102:105]
	v_mfma_f32_16x16x32_bf16 v[102:105], v[154:157], v[244:247], v[102:105]
	s_barrier
	s_or_b32 s52, s85, 0x80
	s_mov_b32 m0, s34
	ds_read_b128 v[194:197], v140 offset:49152
	buffer_load_dwordx4 v134, s[68:71], s52 offen lds
	s_add_i32 s85, s85, 0x80080
	s_mov_b32 m0, s35
	ds_read_b128 v[198:201], v140 offset:50176
	buffer_load_dwordx4 v136, s[68:71], s52 offen lds
	s_mov_b32 m0, s37
	ds_read_b128 v[202:205], v140 offset:51200
	buffer_load_dwordx4 v134, s[68:71], s85 offen lds
	s_mov_b32 m0, s65
	ds_read_b128 v[228:231], v140 offset:52224
	buffer_load_dwordx4 v136, s[68:71], s85 offen lds
	s_mov_b32 m0, s14
	ds_read_b128 v[232:235], v140 offset:53248
	buffer_load_dwordx4 v131, s[60:63], s84 offen lds
	s_mov_b32 m0, s36
	ds_read_b128 v[236:239], v140 offset:54272
	buffer_load_dwordx4 v135, s[60:63], s84 offen lds
	ds_read_b128 v[240:243], v140 offset:55296
	ds_read_b128 v[244:247], v140 offset:56320
	s_waitcnt vmcnt(8)
	s_waitcnt lgkmcnt(0)
	s_barrier
	v_mfma_f32_16x16x32_bf16 v[94:97], v[142:145], v[194:197], v[94:97]
	v_mfma_f32_16x16x32_bf16 v[94:97], v[154:157], v[198:201], v[94:97]
	v_mfma_f32_16x16x32_bf16 v[90:93], v[170:173], v[194:197], v[90:93]
	v_mfma_f32_16x16x32_bf16 v[90:93], v[174:177], v[198:201], v[90:93]
	v_mfma_f32_16x16x32_bf16 v[26:29], v[186:189], v[194:197], v[26:29]
	v_mfma_f32_16x16x32_bf16 v[26:29], v[190:193], v[198:201], v[26:29]
	v_mfma_f32_16x16x32_bf16 v[30:33], v[178:181], v[194:197], v[30:33]
	v_mfma_f32_16x16x32_bf16 v[30:33], v[182:185], v[198:201], v[30:33]
	v_mfma_f32_16x16x32_bf16 v[22:25], v[178:181], v[202:205], v[22:25]
	v_mfma_f32_16x16x32_bf16 v[22:25], v[182:185], v[228:231], v[22:25]
	v_mfma_f32_16x16x32_bf16 v[18:21], v[186:189], v[202:205], v[18:21]
	v_mfma_f32_16x16x32_bf16 v[18:21], v[190:193], v[228:231], v[18:21]
	v_mfma_f32_16x16x32_bf16 v[82:85], v[170:173], v[202:205], v[82:85]
	v_mfma_f32_16x16x32_bf16 v[82:85], v[174:177], v[228:231], v[82:85]
	v_mfma_f32_16x16x32_bf16 v[86:89], v[142:145], v[202:205], v[86:89]
	v_mfma_f32_16x16x32_bf16 v[86:89], v[154:157], v[228:231], v[86:89]
	v_mfma_f32_16x16x32_bf16 v[78:81], v[142:145], v[232:235], v[78:81]
	v_mfma_f32_16x16x32_bf16 v[78:81], v[154:157], v[236:239], v[78:81]
	v_mfma_f32_16x16x32_bf16 v[74:77], v[170:173], v[232:235], v[74:77]
	v_mfma_f32_16x16x32_bf16 v[74:77], v[174:177], v[236:239], v[74:77]
	v_mfma_f32_16x16x32_bf16 v[10:13], v[186:189], v[232:235], v[10:13]
	v_mfma_f32_16x16x32_bf16 v[10:13], v[190:193], v[236:239], v[10:13]
	v_mfma_f32_16x16x32_bf16 v[14:17], v[178:181], v[232:235], v[14:17]
	v_mfma_f32_16x16x32_bf16 v[14:17], v[182:185], v[236:239], v[14:17]
	v_mfma_f32_16x16x32_bf16 v[6:9], v[178:181], v[240:243], v[6:9]
	v_mfma_f32_16x16x32_bf16 v[6:9], v[182:185], v[244:247], v[6:9]
	v_mfma_f32_16x16x32_bf16 v[2:5], v[186:189], v[240:243], v[2:5]
	v_mfma_f32_16x16x32_bf16 v[2:5], v[190:193], v[244:247], v[2:5]
	v_mfma_f32_16x16x32_bf16 v[66:69], v[170:173], v[240:243], v[66:69]
	v_mfma_f32_16x16x32_bf16 v[66:69], v[174:177], v[244:247], v[66:69]
	v_mfma_f32_16x16x32_bf16 v[70:73], v[142:145], v[240:243], v[70:73]
	v_mfma_f32_16x16x32_bf16 v[70:73], v[154:157], v[244:247], v[70:73]
	s_barrier
	s_add_i32 s83, s83, 2
	s_addk_i32 s26, 0x100
	s_addk_i32 s27, 0x100
	s_cmp_gt_u32 s83, 29
	s_cbranch_scc0 .LBB0_1253
	s_and_b64 vcc, exec, s[44:45]
	s_cbranch_vccz .LBB0_1256
	s_barrier

.LBB0_1282:
	s_lshl_b32 s46, s85, 20
	s_and_b64 s[8:9], s[40:41], exec
	s_cselect_b32 s8, s46, s19
	s_lshl_b32 s47, s14, 20
	s_and_b64 s[26:27], s[40:41], exec
	s_cselect_b32 s9, s47, s22
	s_add_i32 s19, s19, 0x80080
	s_addk_i32 s22, 0x100
	s_mov_b32 s26, -2
	v_add_u32_e32 v141, 0x10000, v139
	ds_read_b128 v[142:145], v141
	ds_read_b128 v[154:157], v141 offset:1024
	ds_read_b128 v[170:173], v141 offset:2048
	ds_read_b128 v[174:177], v141 offset:3072
	v_add_u32_e32 v141, 0x14000, v139
	ds_read_b128 v[178:181], v141
	ds_read_b128 v[182:185], v141 offset:1024
	ds_read_b128 v[186:189], v141 offset:2048
	ds_read_b128 v[190:193], v141 offset:3072
	s_add_i32 s27, s19, 0xfff80080
	s_cmp_eq_u32 s26, 28
	s_cselect_b32 s52, s8, s27
	s_cselect_b32 s83, s9, s22
	s_or_b32 s27, s52, 0x80
	s_mov_b32 m0, s73
	ds_read_b128 v[194:197], v140
	ds_read_b128 v[198:201], v140 offset:1024
	ds_read_b128 v[202:205], v140 offset:2048
	ds_read_b128 v[228:231], v140 offset:3072
	ds_read_b128 v[232:235], v140 offset:4096
	ds_read_b128 v[236:239], v140 offset:5120
	ds_read_b128 v[240:243], v140 offset:6144
	ds_read_b128 v[244:247], v140 offset:7168
	buffer_load_dwordx4 v131, s[60:63], s19 offen lds
	s_mov_b32 m0, s82
	s_nop 0
	buffer_load_dwordx4 v135, s[60:63], s19 offen lds
	s_waitcnt vmcnt(8)
	s_waitcnt lgkmcnt(0)
	s_barrier
	v_mfma_f32_16x16x32_bf16 v[126:129], v[142:145], v[194:197], 0
	v_mfma_f32_16x16x32_bf16 v[126:129], v[154:157], v[198:201], v[126:129]
	v_mfma_f32_16x16x32_bf16 v[122:125], v[170:173], v[194:197], 0
	v_mfma_f32_16x16x32_bf16 v[122:125], v[174:177], v[198:201], v[122:125]
	v_mfma_f32_16x16x32_bf16 v[58:61], v[186:189], v[194:197], 0
	v_mfma_f32_16x16x32_bf16 v[58:61], v[190:193], v[198:201], v[58:61]
	v_mfma_f32_16x16x32_bf16 v[62:65], v[178:181], v[194:197], 0
	v_mfma_f32_16x16x32_bf16 v[62:65], v[182:185], v[198:201], v[62:65]
	v_mfma_f32_16x16x32_bf16 v[54:57], v[178:181], v[202:205], 0
	v_mfma_f32_16x16x32_bf16 v[54:57], v[182:185], v[228:231], v[54:57]
	v_mfma_f32_16x16x32_bf16 v[50:53], v[186:189], v[202:205], 0
	v_mfma_f32_16x16x32_bf16 v[50:53], v[190:193], v[228:231], v[50:53]
	v_mfma_f32_16x16x32_bf16 v[114:117], v[170:173], v[202:205], 0
	v_mfma_f32_16x16x32_bf16 v[114:117], v[174:177], v[228:231], v[114:117]
	v_mfma_f32_16x16x32_bf16 v[118:121], v[142:145], v[202:205], 0
	v_mfma_f32_16x16x32_bf16 v[118:121], v[154:157], v[228:231], v[118:121]
	v_mfma_f32_16x16x32_bf16 v[110:113], v[142:145], v[232:235], 0
	v_mfma_f32_16x16x32_bf16 v[110:113], v[154:157], v[236:239], v[110:113]
	v_mfma_f32_16x16x32_bf16 v[106:109], v[170:173], v[232:235], 0
	v_mfma_f32_16x16x32_bf16 v[106:109], v[174:177], v[236:239], v[106:109]
	v_mfma_f32_16x16x32_bf16 v[42:45], v[186:189], v[232:235], 0
	v_mfma_f32_16x16x32_bf16 v[42:45], v[190:193], v[236:239], v[42:45]
	v_mfma_f32_16x16x32_bf16 v[46:49], v[178:181], v[232:235], 0
	v_mfma_f32_16x16x32_bf16 v[46:49], v[182:185], v[236:239], v[46:49]
	v_mfma_f32_16x16x32_bf16 v[38:41], v[178:181], v[240:243], 0
	v_mfma_f32_16x16x32_bf16 v[38:41], v[182:185], v[244:247], v[38:41]
	v_mfma_f32_16x16x32_bf16 v[34:37], v[186:189], v[240:243], 0
	v_mfma_f32_16x16x32_bf16 v[34:37], v[190:193], v[244:247], v[34:37]
	v_mfma_f32_16x16x32_bf16 v[98:101], v[170:173], v[240:243], 0
	v_mfma_f32_16x16x32_bf16 v[98:101], v[174:177], v[244:247], v[98:101]
	v_mfma_f32_16x16x32_bf16 v[102:105], v[142:145], v[240:243], 0
	v_mfma_f32_16x16x32_bf16 v[102:105], v[154:157], v[244:247], v[102:105]
	s_barrier
	s_mov_b32 s70, s62
	s_mov_b32 s71, s63
	s_mov_b32 m0, s21
	ds_read_b128 v[194:197], v140 offset:16384
	buffer_load_dwordx4 v134, s[68:71], s83 offen lds
	s_add_i32 s53, s83, 0x80000
	s_mov_b32 m0, s23
	ds_read_b128 v[198:201], v140 offset:17408
	buffer_load_dwordx4 v136, s[68:71], s83 offen lds
	s_mov_b32 m0, s24
	ds_read_b128 v[202:205], v140 offset:18432
	buffer_load_dwordx4 v134, s[68:71], s53 offen lds
	s_mov_b32 m0, s25
	ds_read_b128 v[228:231], v140 offset:19456
	buffer_load_dwordx4 v136, s[68:71], s53 offen lds
	s_mov_b32 m0, s2
	ds_read_b128 v[232:235], v140 offset:20480
	buffer_load_dwordx4 v131, s[60:63], s52 offen lds
	s_mov_b32 m0, s30
	ds_read_b128 v[236:239], v140 offset:21504
	buffer_load_dwordx4 v135, s[60:63], s52 offen lds
	ds_read_b128 v[240:243], v140 offset:22528
	ds_read_b128 v[244:247], v140 offset:23552
	s_waitcnt vmcnt(8)
	s_waitcnt lgkmcnt(0)
	s_barrier
	v_mfma_f32_16x16x32_bf16 v[94:97], v[142:145], v[194:197], 0
	v_mfma_f32_16x16x32_bf16 v[94:97], v[154:157], v[198:201], v[94:97]
	v_mfma_f32_16x16x32_bf16 v[90:93], v[170:173], v[194:197], 0
	v_mfma_f32_16x16x32_bf16 v[90:93], v[174:177], v[198:201], v[90:93]
	v_mfma_f32_16x16x32_bf16 v[26:29], v[186:189], v[194:197], 0
	v_mfma_f32_16x16x32_bf16 v[26:29], v[190:193], v[198:201], v[26:29]
	v_mfma_f32_16x16x32_bf16 v[30:33], v[178:181], v[194:197], 0
	v_mfma_f32_16x16x32_bf16 v[30:33], v[182:185], v[198:201], v[30:33]
	v_mfma_f32_16x16x32_bf16 v[22:25], v[178:181], v[202:205], 0
	v_mfma_f32_16x16x32_bf16 v[22:25], v[182:185], v[228:231], v[22:25]
	v_mfma_f32_16x16x32_bf16 v[18:21], v[186:189], v[202:205], 0
	v_mfma_f32_16x16x32_bf16 v[18:21], v[190:193], v[228:231], v[18:21]
	v_mfma_f32_16x16x32_bf16 v[82:85], v[170:173], v[202:205], 0
	v_mfma_f32_16x16x32_bf16 v[82:85], v[174:177], v[228:231], v[82:85]
	v_mfma_f32_16x16x32_bf16 v[86:89], v[142:145], v[202:205], 0
	v_mfma_f32_16x16x32_bf16 v[86:89], v[154:157], v[228:231], v[86:89]
	v_mfma_f32_16x16x32_bf16 v[78:81], v[142:145], v[232:235], 0
	v_mfma_f32_16x16x32_bf16 v[78:81], v[154:157], v[236:239], v[78:81]
	v_mfma_f32_16x16x32_bf16 v[74:77], v[170:173], v[232:235], 0
	v_mfma_f32_16x16x32_bf16 v[74:77], v[174:177], v[236:239], v[74:77]
	v_mfma_f32_16x16x32_bf16 v[10:13], v[186:189], v[232:235], 0
	v_mfma_f32_16x16x32_bf16 v[10:13], v[190:193], v[236:239], v[10:13]
	v_mfma_f32_16x16x32_bf16 v[14:17], v[178:181], v[232:235], 0
	v_mfma_f32_16x16x32_bf16 v[14:17], v[182:185], v[236:239], v[14:17]
	v_mfma_f32_16x16x32_bf16 v[6:9], v[178:181], v[240:243], 0
	v_mfma_f32_16x16x32_bf16 v[6:9], v[182:185], v[244:247], v[6:9]
	v_mfma_f32_16x16x32_bf16 v[2:5], v[186:189], v[240:243], 0
	v_mfma_f32_16x16x32_bf16 v[2:5], v[190:193], v[244:247], v[2:5]
	v_mfma_f32_16x16x32_bf16 v[66:69], v[170:173], v[240:243], 0
	v_mfma_f32_16x16x32_bf16 v[66:69], v[174:177], v[244:247], v[66:69]
	v_mfma_f32_16x16x32_bf16 v[70:73], v[142:145], v[240:243], 0
	v_mfma_f32_16x16x32_bf16 v[70:73], v[154:157], v[244:247], v[70:73]
	s_barrier
	v_add_u32_e32 v141, 0x18000, v139
	ds_read_b128 v[142:145], v141
	ds_read_b128 v[154:157], v141 offset:1024
	ds_read_b128 v[170:173], v141 offset:2048
	ds_read_b128 v[174:177], v141 offset:3072
	v_add_u32_e32 v141, 0x1c000, v139
	ds_read_b128 v[178:181], v141
	ds_read_b128 v[182:185], v141 offset:1024
	ds_read_b128 v[186:189], v141 offset:2048
	ds_read_b128 v[190:193], v141 offset:3072
	s_add_i32 s52, s52, 0x80000
	s_mov_b32 m0, s31
	ds_read_b128 v[194:197], v140 offset:32768
	ds_read_b128 v[198:201], v140 offset:33792
	ds_read_b128 v[202:205], v140 offset:34816
	ds_read_b128 v[228:231], v140 offset:35840
	ds_read_b128 v[232:235], v140 offset:36864
	ds_read_b128 v[236:239], v140 offset:37888
	ds_read_b128 v[240:243], v140 offset:38912
	ds_read_b128 v[244:247], v140 offset:39936
	buffer_load_dwordx4 v131, s[60:63], s52 offen lds
	s_mov_b32 m0, s33
	s_nop 0
	buffer_load_dwordx4 v135, s[60:63], s52 offen lds
	s_waitcnt vmcnt(8)
	s_waitcnt lgkmcnt(0)
	s_barrier
	v_mfma_f32_16x16x32_bf16 v[126:129], v[142:145], v[194:197], v[126:129]
	v_mfma_f32_16x16x32_bf16 v[126:129], v[154:157], v[198:201], v[126:129]
	v_mfma_f32_16x16x32_bf16 v[122:125], v[170:173], v[194:197], v[122:125]
	v_mfma_f32_16x16x32_bf16 v[122:125], v[174:177], v[198:201], v[122:125]
	v_mfma_f32_16x16x32_bf16 v[58:61], v[186:189], v[194:197], v[58:61]
	v_mfma_f32_16x16x32_bf16 v[58:61], v[190:193], v[198:201], v[58:61]
	v_mfma_f32_16x16x32_bf16 v[62:65], v[178:181], v[194:197], v[62:65]
	v_mfma_f32_16x16x32_bf16 v[62:65], v[182:185], v[198:201], v[62:65]
	v_mfma_f32_16x16x32_bf16 v[54:57], v[178:181], v[202:205], v[54:57]
	v_mfma_f32_16x16x32_bf16 v[54:57], v[182:185], v[228:231], v[54:57]
	v_mfma_f32_16x16x32_bf16 v[50:53], v[186:189], v[202:205], v[50:53]
	v_mfma_f32_16x16x32_bf16 v[50:53], v[190:193], v[228:231], v[50:53]
	v_mfma_f32_16x16x32_bf16 v[114:117], v[170:173], v[202:205], v[114:117]
	v_mfma_f32_16x16x32_bf16 v[114:117], v[174:177], v[228:231], v[114:117]
	v_mfma_f32_16x16x32_bf16 v[118:121], v[142:145], v[202:205], v[118:121]
	v_mfma_f32_16x16x32_bf16 v[118:121], v[154:157], v[228:231], v[118:121]
	v_mfma_f32_16x16x32_bf16 v[110:113], v[142:145], v[232:235], v[110:113]
	v_mfma_f32_16x16x32_bf16 v[110:113], v[154:157], v[236:239], v[110:113]
	v_mfma_f32_16x16x32_bf16 v[106:109], v[170:173], v[232:235], v[106:109]
	v_mfma_f32_16x16x32_bf16 v[106:109], v[174:177], v[236:239], v[106:109]
	v_mfma_f32_16x16x32_bf16 v[42:45], v[186:189], v[232:235], v[42:45]
	v_mfma_f32_16x16x32_bf16 v[42:45], v[190:193], v[236:239], v[42:45]
	v_mfma_f32_16x16x32_bf16 v[46:49], v[178:181], v[232:235], v[46:49]
	v_mfma_f32_16x16x32_bf16 v[46:49], v[182:185], v[236:239], v[46:49]
	v_mfma_f32_16x16x32_bf16 v[38:41], v[178:181], v[240:243], v[38:41]
	v_mfma_f32_16x16x32_bf16 v[38:41], v[182:185], v[244:247], v[38:41]
	v_mfma_f32_16x16x32_bf16 v[34:37], v[186:189], v[240:243], v[34:37]
	v_mfma_f32_16x16x32_bf16 v[34:37], v[190:193], v[244:247], v[34:37]
	v_mfma_f32_16x16x32_bf16 v[98:101], v[170:173], v[240:243], v[98:101]
	v_mfma_f32_16x16x32_bf16 v[98:101], v[174:177], v[244:247], v[98:101]
	v_mfma_f32_16x16x32_bf16 v[102:105], v[142:145], v[240:243], v[102:105]
	v_mfma_f32_16x16x32_bf16 v[102:105], v[154:157], v[244:247], v[102:105]
	s_barrier
	s_or_b32 s52, s83, 0x80
	s_mov_b32 m0, s34
	ds_read_b128 v[194:197], v140 offset:49152
	buffer_load_dwordx4 v134, s[68:71], s52 offen lds
	s_add_i32 s83, s83, 0x80080
	s_mov_b32 m0, s35
	ds_read_b128 v[198:201], v140 offset:50176
	buffer_load_dwordx4 v136, s[68:71], s52 offen lds
	s_mov_b32 m0, s65
	ds_read_b128 v[202:205], v140 offset:51200
	buffer_load_dwordx4 v134, s[68:71], s83 offen lds
	s_mov_b32 m0, s66
	ds_read_b128 v[228:231], v140 offset:52224
	buffer_load_dwordx4 v136, s[68:71], s83 offen lds
	s_mov_b32 m0, s36
	ds_read_b128 v[232:235], v140 offset:53248
	buffer_load_dwordx4 v131, s[60:63], s27 offen lds
	s_mov_b32 m0, s37
	ds_read_b128 v[236:239], v140 offset:54272
	buffer_load_dwordx4 v135, s[60:63], s27 offen lds
	ds_read_b128 v[240:243], v140 offset:55296
	ds_read_b128 v[244:247], v140 offset:56320
	s_waitcnt vmcnt(8)
	s_waitcnt lgkmcnt(0)
	s_barrier
	v_mfma_f32_16x16x32_bf16 v[94:97], v[142:145], v[194:197], v[94:97]
	v_mfma_f32_16x16x32_bf16 v[94:97], v[154:157], v[198:201], v[94:97]
	v_mfma_f32_16x16x32_bf16 v[90:93], v[170:173], v[194:197], v[90:93]
	v_mfma_f32_16x16x32_bf16 v[90:93], v[174:177], v[198:201], v[90:93]
	v_mfma_f32_16x16x32_bf16 v[26:29], v[186:189], v[194:197], v[26:29]
	v_mfma_f32_16x16x32_bf16 v[26:29], v[190:193], v[198:201], v[26:29]
	v_mfma_f32_16x16x32_bf16 v[30:33], v[178:181], v[194:197], v[30:33]
	v_mfma_f32_16x16x32_bf16 v[30:33], v[182:185], v[198:201], v[30:33]
	v_mfma_f32_16x16x32_bf16 v[22:25], v[178:181], v[202:205], v[22:25]
	v_mfma_f32_16x16x32_bf16 v[22:25], v[182:185], v[228:231], v[22:25]
	v_mfma_f32_16x16x32_bf16 v[18:21], v[186:189], v[202:205], v[18:21]
	v_mfma_f32_16x16x32_bf16 v[18:21], v[190:193], v[228:231], v[18:21]
	v_mfma_f32_16x16x32_bf16 v[82:85], v[170:173], v[202:205], v[82:85]
	v_mfma_f32_16x16x32_bf16 v[82:85], v[174:177], v[228:231], v[82:85]
	v_mfma_f32_16x16x32_bf16 v[86:89], v[142:145], v[202:205], v[86:89]
	v_mfma_f32_16x16x32_bf16 v[86:89], v[154:157], v[228:231], v[86:89]
	v_mfma_f32_16x16x32_bf16 v[78:81], v[142:145], v[232:235], v[78:81]
	v_mfma_f32_16x16x32_bf16 v[78:81], v[154:157], v[236:239], v[78:81]
	v_mfma_f32_16x16x32_bf16 v[74:77], v[170:173], v[232:235], v[74:77]
	v_mfma_f32_16x16x32_bf16 v[74:77], v[174:177], v[236:239], v[74:77]
	v_mfma_f32_16x16x32_bf16 v[10:13], v[186:189], v[232:235], v[10:13]
	v_mfma_f32_16x16x32_bf16 v[10:13], v[190:193], v[236:239], v[10:13]
	v_mfma_f32_16x16x32_bf16 v[14:17], v[178:181], v[232:235], v[14:17]
	v_mfma_f32_16x16x32_bf16 v[14:17], v[182:185], v[236:239], v[14:17]
	v_mfma_f32_16x16x32_bf16 v[6:9], v[178:181], v[240:243], v[6:9]
	v_mfma_f32_16x16x32_bf16 v[6:9], v[182:185], v[244:247], v[6:9]
	v_mfma_f32_16x16x32_bf16 v[2:5], v[186:189], v[240:243], v[2:5]
	v_mfma_f32_16x16x32_bf16 v[2:5], v[190:193], v[244:247], v[2:5]
	v_mfma_f32_16x16x32_bf16 v[66:69], v[170:173], v[240:243], v[66:69]
	v_mfma_f32_16x16x32_bf16 v[66:69], v[174:177], v[244:247], v[66:69]
	v_mfma_f32_16x16x32_bf16 v[70:73], v[142:145], v[240:243], v[70:73]
	v_mfma_f32_16x16x32_bf16 v[70:73], v[154:157], v[244:247], v[70:73]
	s_barrier
	s_add_i32 s26, s26, 2
	s_addk_i32 s19, 0x100
	s_addk_i32 s22, 0x100
	s_cmp_gt_u32 s26, 29
.LBB0_1283:
	v_add_u32_e32 v141, 0x10000, v139
	ds_read_b128 v[142:145], v141
	ds_read_b128 v[154:157], v141 offset:1024
	ds_read_b128 v[170:173], v141 offset:2048
	ds_read_b128 v[174:177], v141 offset:3072
	v_add_u32_e32 v141, 0x14000, v139
	ds_read_b128 v[178:181], v141
	ds_read_b128 v[182:185], v141 offset:1024
	ds_read_b128 v[186:189], v141 offset:2048
	ds_read_b128 v[190:193], v141 offset:3072
	s_add_i32 s27, s19, 0xfff80080
	s_cmp_eq_u32 s26, 28
	s_cselect_b32 s52, s8, s27
	s_cselect_b32 s83, s9, s22
	s_or_b32 s27, s52, 0x80
	s_mov_b32 m0, s73
	ds_read_b128 v[194:197], v140
	ds_read_b128 v[198:201], v140 offset:1024
	ds_read_b128 v[202:205], v140 offset:2048
	ds_read_b128 v[228:231], v140 offset:3072
	ds_read_b128 v[232:235], v140 offset:4096
	ds_read_b128 v[236:239], v140 offset:5120
	ds_read_b128 v[240:243], v140 offset:6144
	ds_read_b128 v[244:247], v140 offset:7168
	buffer_load_dwordx4 v131, s[60:63], s19 offen lds
	s_mov_b32 m0, s82
	s_nop 0
	buffer_load_dwordx4 v135, s[60:63], s19 offen lds
	s_waitcnt vmcnt(8)
	s_waitcnt lgkmcnt(0)
	s_barrier
	v_mfma_f32_16x16x32_bf16 v[126:129], v[142:145], v[194:197], v[126:129]
	v_mfma_f32_16x16x32_bf16 v[126:129], v[154:157], v[198:201], v[126:129]
	v_mfma_f32_16x16x32_bf16 v[122:125], v[170:173], v[194:197], v[122:125]
	v_mfma_f32_16x16x32_bf16 v[122:125], v[174:177], v[198:201], v[122:125]
	v_mfma_f32_16x16x32_bf16 v[58:61], v[186:189], v[194:197], v[58:61]
	v_mfma_f32_16x16x32_bf16 v[58:61], v[190:193], v[198:201], v[58:61]
	v_mfma_f32_16x16x32_bf16 v[62:65], v[178:181], v[194:197], v[62:65]
	v_mfma_f32_16x16x32_bf16 v[62:65], v[182:185], v[198:201], v[62:65]
	v_mfma_f32_16x16x32_bf16 v[54:57], v[178:181], v[202:205], v[54:57]
	v_mfma_f32_16x16x32_bf16 v[54:57], v[182:185], v[228:231], v[54:57]
	v_mfma_f32_16x16x32_bf16 v[50:53], v[186:189], v[202:205], v[50:53]
	v_mfma_f32_16x16x32_bf16 v[50:53], v[190:193], v[228:231], v[50:53]
	v_mfma_f32_16x16x32_bf16 v[114:117], v[170:173], v[202:205], v[114:117]
	v_mfma_f32_16x16x32_bf16 v[114:117], v[174:177], v[228:231], v[114:117]
	v_mfma_f32_16x16x32_bf16 v[118:121], v[142:145], v[202:205], v[118:121]
	v_mfma_f32_16x16x32_bf16 v[118:121], v[154:157], v[228:231], v[118:121]
	v_mfma_f32_16x16x32_bf16 v[110:113], v[142:145], v[232:235], v[110:113]
	v_mfma_f32_16x16x32_bf16 v[110:113], v[154:157], v[236:239], v[110:113]
	v_mfma_f32_16x16x32_bf16 v[106:109], v[170:173], v[232:235], v[106:109]
	v_mfma_f32_16x16x32_bf16 v[106:109], v[174:177], v[236:239], v[106:109]
	v_mfma_f32_16x16x32_bf16 v[42:45], v[186:189], v[232:235], v[42:45]
	v_mfma_f32_16x16x32_bf16 v[42:45], v[190:193], v[236:239], v[42:45]
	v_mfma_f32_16x16x32_bf16 v[46:49], v[178:181], v[232:235], v[46:49]
	v_mfma_f32_16x16x32_bf16 v[46:49], v[182:185], v[236:239], v[46:49]
	v_mfma_f32_16x16x32_bf16 v[38:41], v[178:181], v[240:243], v[38:41]
	v_mfma_f32_16x16x32_bf16 v[38:41], v[182:185], v[244:247], v[38:41]
	v_mfma_f32_16x16x32_bf16 v[34:37], v[186:189], v[240:243], v[34:37]
	v_mfma_f32_16x16x32_bf16 v[34:37], v[190:193], v[244:247], v[34:37]
	v_mfma_f32_16x16x32_bf16 v[98:101], v[170:173], v[240:243], v[98:101]
	v_mfma_f32_16x16x32_bf16 v[98:101], v[174:177], v[244:247], v[98:101]
	v_mfma_f32_16x16x32_bf16 v[102:105], v[142:145], v[240:243], v[102:105]
	v_mfma_f32_16x16x32_bf16 v[102:105], v[154:157], v[244:247], v[102:105]
	s_barrier
	s_mov_b32 s70, s62
	s_mov_b32 s71, s63
	s_mov_b32 m0, s21
	ds_read_b128 v[194:197], v140 offset:16384
	buffer_load_dwordx4 v134, s[68:71], s83 offen lds
	s_add_i32 s53, s83, 0x80000
	s_mov_b32 m0, s23
	ds_read_b128 v[198:201], v140 offset:17408
	buffer_load_dwordx4 v136, s[68:71], s83 offen lds
	s_mov_b32 m0, s24
	ds_read_b128 v[202:205], v140 offset:18432
	buffer_load_dwordx4 v134, s[68:71], s53 offen lds
	s_mov_b32 m0, s25
	ds_read_b128 v[228:231], v140 offset:19456
	buffer_load_dwordx4 v136, s[68:71], s53 offen lds
	s_mov_b32 m0, s2
	ds_read_b128 v[232:235], v140 offset:20480
	buffer_load_dwordx4 v131, s[60:63], s52 offen lds
	s_mov_b32 m0, s30
	ds_read_b128 v[236:239], v140 offset:21504
	buffer_load_dwordx4 v135, s[60:63], s52 offen lds
	ds_read_b128 v[240:243], v140 offset:22528
	ds_read_b128 v[244:247], v140 offset:23552
	s_waitcnt vmcnt(8)
	s_waitcnt lgkmcnt(0)
	s_barrier
	v_mfma_f32_16x16x32_bf16 v[94:97], v[142:145], v[194:197], v[94:97]
	v_mfma_f32_16x16x32_bf16 v[94:97], v[154:157], v[198:201], v[94:97]
	v_mfma_f32_16x16x32_bf16 v[90:93], v[170:173], v[194:197], v[90:93]
	v_mfma_f32_16x16x32_bf16 v[90:93], v[174:177], v[198:201], v[90:93]
	v_mfma_f32_16x16x32_bf16 v[26:29], v[186:189], v[194:197], v[26:29]
	v_mfma_f32_16x16x32_bf16 v[26:29], v[190:193], v[198:201], v[26:29]
	v_mfma_f32_16x16x32_bf16 v[30:33], v[178:181], v[194:197], v[30:33]
	v_mfma_f32_16x16x32_bf16 v[30:33], v[182:185], v[198:201], v[30:33]
	v_mfma_f32_16x16x32_bf16 v[22:25], v[178:181], v[202:205], v[22:25]
	v_mfma_f32_16x16x32_bf16 v[22:25], v[182:185], v[228:231], v[22:25]
	v_mfma_f32_16x16x32_bf16 v[18:21], v[186:189], v[202:205], v[18:21]
	v_mfma_f32_16x16x32_bf16 v[18:21], v[190:193], v[228:231], v[18:21]
	v_mfma_f32_16x16x32_bf16 v[82:85], v[170:173], v[202:205], v[82:85]
	v_mfma_f32_16x16x32_bf16 v[82:85], v[174:177], v[228:231], v[82:85]
	v_mfma_f32_16x16x32_bf16 v[86:89], v[142:145], v[202:205], v[86:89]
	v_mfma_f32_16x16x32_bf16 v[86:89], v[154:157], v[228:231], v[86:89]
	v_mfma_f32_16x16x32_bf16 v[78:81], v[142:145], v[232:235], v[78:81]
	v_mfma_f32_16x16x32_bf16 v[78:81], v[154:157], v[236:239], v[78:81]
	v_mfma_f32_16x16x32_bf16 v[74:77], v[170:173], v[232:235], v[74:77]
	v_mfma_f32_16x16x32_bf16 v[74:77], v[174:177], v[236:239], v[74:77]
	v_mfma_f32_16x16x32_bf16 v[10:13], v[186:189], v[232:235], v[10:13]
	v_mfma_f32_16x16x32_bf16 v[10:13], v[190:193], v[236:239], v[10:13]
	v_mfma_f32_16x16x32_bf16 v[14:17], v[178:181], v[232:235], v[14:17]
	v_mfma_f32_16x16x32_bf16 v[14:17], v[182:185], v[236:239], v[14:17]
	v_mfma_f32_16x16x32_bf16 v[6:9], v[178:181], v[240:243], v[6:9]
	v_mfma_f32_16x16x32_bf16 v[6:9], v[182:185], v[244:247], v[6:9]
	v_mfma_f32_16x16x32_bf16 v[2:5], v[186:189], v[240:243], v[2:5]
	v_mfma_f32_16x16x32_bf16 v[2:5], v[190:193], v[244:247], v[2:5]
	v_mfma_f32_16x16x32_bf16 v[66:69], v[170:173], v[240:243], v[66:69]
	v_mfma_f32_16x16x32_bf16 v[66:69], v[174:177], v[244:247], v[66:69]
	v_mfma_f32_16x16x32_bf16 v[70:73], v[142:145], v[240:243], v[70:73]
	v_mfma_f32_16x16x32_bf16 v[70:73], v[154:157], v[244:247], v[70:73]
	s_barrier
	v_add_u32_e32 v141, 0x18000, v139
	ds_read_b128 v[142:145], v141
	ds_read_b128 v[154:157], v141 offset:1024
	ds_read_b128 v[170:173], v141 offset:2048
	ds_read_b128 v[174:177], v141 offset:3072
	v_add_u32_e32 v141, 0x1c000, v139
	ds_read_b128 v[178:181], v141
	ds_read_b128 v[182:185], v141 offset:1024
	ds_read_b128 v[186:189], v141 offset:2048
	ds_read_b128 v[190:193], v141 offset:3072
	s_add_i32 s52, s52, 0x80000
	s_mov_b32 m0, s31
	ds_read_b128 v[194:197], v140 offset:32768
	ds_read_b128 v[198:201], v140 offset:33792
	ds_read_b128 v[202:205], v140 offset:34816
	ds_read_b128 v[228:231], v140 offset:35840
	ds_read_b128 v[232:235], v140 offset:36864
	ds_read_b128 v[236:239], v140 offset:37888
	ds_read_b128 v[240:243], v140 offset:38912
	ds_read_b128 v[244:247], v140 offset:39936
	buffer_load_dwordx4 v131, s[60:63], s52 offen lds
	s_mov_b32 m0, s33
	s_nop 0
	buffer_load_dwordx4 v135, s[60:63], s52 offen lds
	s_waitcnt vmcnt(8)
	s_waitcnt lgkmcnt(0)
	s_barrier
	v_mfma_f32_16x16x32_bf16 v[126:129], v[142:145], v[194:197], v[126:129]
	v_mfma_f32_16x16x32_bf16 v[126:129], v[154:157], v[198:201], v[126:129]
	v_mfma_f32_16x16x32_bf16 v[122:125], v[170:173], v[194:197], v[122:125]
	v_mfma_f32_16x16x32_bf16 v[122:125], v[174:177], v[198:201], v[122:125]
	v_mfma_f32_16x16x32_bf16 v[58:61], v[186:189], v[194:197], v[58:61]
	v_mfma_f32_16x16x32_bf16 v[58:61], v[190:193], v[198:201], v[58:61]
	v_mfma_f32_16x16x32_bf16 v[62:65], v[178:181], v[194:197], v[62:65]
	v_mfma_f32_16x16x32_bf16 v[62:65], v[182:185], v[198:201], v[62:65]
	v_mfma_f32_16x16x32_bf16 v[54:57], v[178:181], v[202:205], v[54:57]
	v_mfma_f32_16x16x32_bf16 v[54:57], v[182:185], v[228:231], v[54:57]
	v_mfma_f32_16x16x32_bf16 v[50:53], v[186:189], v[202:205], v[50:53]
	v_mfma_f32_16x16x32_bf16 v[50:53], v[190:193], v[228:231], v[50:53]
	v_mfma_f32_16x16x32_bf16 v[114:117], v[170:173], v[202:205], v[114:117]
	v_mfma_f32_16x16x32_bf16 v[114:117], v[174:177], v[228:231], v[114:117]
	v_mfma_f32_16x16x32_bf16 v[118:121], v[142:145], v[202:205], v[118:121]
	v_mfma_f32_16x16x32_bf16 v[118:121], v[154:157], v[228:231], v[118:121]
	v_mfma_f32_16x16x32_bf16 v[110:113], v[142:145], v[232:235], v[110:113]
	v_mfma_f32_16x16x32_bf16 v[110:113], v[154:157], v[236:239], v[110:113]
	v_mfma_f32_16x16x32_bf16 v[106:109], v[170:173], v[232:235], v[106:109]
	v_mfma_f32_16x16x32_bf16 v[106:109], v[174:177], v[236:239], v[106:109]
	v_mfma_f32_16x16x32_bf16 v[42:45], v[186:189], v[232:235], v[42:45]
	v_mfma_f32_16x16x32_bf16 v[42:45], v[190:193], v[236:239], v[42:45]
	v_mfma_f32_16x16x32_bf16 v[46:49], v[178:181], v[232:235], v[46:49]
	v_mfma_f32_16x16x32_bf16 v[46:49], v[182:185], v[236:239], v[46:49]
	v_mfma_f32_16x16x32_bf16 v[38:41], v[178:181], v[240:243], v[38:41]
	v_mfma_f32_16x16x32_bf16 v[38:41], v[182:185], v[244:247], v[38:41]
	v_mfma_f32_16x16x32_bf16 v[34:37], v[186:189], v[240:243], v[34:37]
	v_mfma_f32_16x16x32_bf16 v[34:37], v[190:193], v[244:247], v[34:37]
	v_mfma_f32_16x16x32_bf16 v[98:101], v[170:173], v[240:243], v[98:101]
	v_mfma_f32_16x16x32_bf16 v[98:101], v[174:177], v[244:247], v[98:101]
	v_mfma_f32_16x16x32_bf16 v[102:105], v[142:145], v[240:243], v[102:105]
	v_mfma_f32_16x16x32_bf16 v[102:105], v[154:157], v[244:247], v[102:105]
	s_barrier
	s_or_b32 s52, s83, 0x80
	s_mov_b32 m0, s34
	ds_read_b128 v[194:197], v140 offset:49152
	buffer_load_dwordx4 v134, s[68:71], s52 offen lds
	s_add_i32 s83, s83, 0x80080
	s_mov_b32 m0, s35
	ds_read_b128 v[198:201], v140 offset:50176
	buffer_load_dwordx4 v136, s[68:71], s52 offen lds
	s_mov_b32 m0, s65
	ds_read_b128 v[202:205], v140 offset:51200
	buffer_load_dwordx4 v134, s[68:71], s83 offen lds
	s_mov_b32 m0, s66
	ds_read_b128 v[228:231], v140 offset:52224
	buffer_load_dwordx4 v136, s[68:71], s83 offen lds
	s_mov_b32 m0, s36
	ds_read_b128 v[232:235], v140 offset:53248
	buffer_load_dwordx4 v131, s[60:63], s27 offen lds
	s_mov_b32 m0, s37
	ds_read_b128 v[236:239], v140 offset:54272
	buffer_load_dwordx4 v135, s[60:63], s27 offen lds
	ds_read_b128 v[240:243], v140 offset:55296
	ds_read_b128 v[244:247], v140 offset:56320
	s_waitcnt vmcnt(8)
	s_waitcnt lgkmcnt(0)
	s_barrier
	v_mfma_f32_16x16x32_bf16 v[94:97], v[142:145], v[194:197], v[94:97]
	v_mfma_f32_16x16x32_bf16 v[94:97], v[154:157], v[198:201], v[94:97]
	v_mfma_f32_16x16x32_bf16 v[90:93], v[170:173], v[194:197], v[90:93]
	v_mfma_f32_16x16x32_bf16 v[90:93], v[174:177], v[198:201], v[90:93]
	v_mfma_f32_16x16x32_bf16 v[26:29], v[186:189], v[194:197], v[26:29]
	v_mfma_f32_16x16x32_bf16 v[26:29], v[190:193], v[198:201], v[26:29]
	v_mfma_f32_16x16x32_bf16 v[30:33], v[178:181], v[194:197], v[30:33]
	v_mfma_f32_16x16x32_bf16 v[30:33], v[182:185], v[198:201], v[30:33]
	v_mfma_f32_16x16x32_bf16 v[22:25], v[178:181], v[202:205], v[22:25]
	v_mfma_f32_16x16x32_bf16 v[22:25], v[182:185], v[228:231], v[22:25]
	v_mfma_f32_16x16x32_bf16 v[18:21], v[186:189], v[202:205], v[18:21]
	v_mfma_f32_16x16x32_bf16 v[18:21], v[190:193], v[228:231], v[18:21]
	v_mfma_f32_16x16x32_bf16 v[82:85], v[170:173], v[202:205], v[82:85]
	v_mfma_f32_16x16x32_bf16 v[82:85], v[174:177], v[228:231], v[82:85]
	v_mfma_f32_16x16x32_bf16 v[86:89], v[142:145], v[202:205], v[86:89]
	v_mfma_f32_16x16x32_bf16 v[86:89], v[154:157], v[228:231], v[86:89]
	v_mfma_f32_16x16x32_bf16 v[78:81], v[142:145], v[232:235], v[78:81]
	v_mfma_f32_16x16x32_bf16 v[78:81], v[154:157], v[236:239], v[78:81]
	v_mfma_f32_16x16x32_bf16 v[74:77], v[170:173], v[232:235], v[74:77]
	v_mfma_f32_16x16x32_bf16 v[74:77], v[174:177], v[236:239], v[74:77]
	v_mfma_f32_16x16x32_bf16 v[10:13], v[186:189], v[232:235], v[10:13]
	v_mfma_f32_16x16x32_bf16 v[10:13], v[190:193], v[236:239], v[10:13]
	v_mfma_f32_16x16x32_bf16 v[14:17], v[178:181], v[232:235], v[14:17]
	v_mfma_f32_16x16x32_bf16 v[14:17], v[182:185], v[236:239], v[14:17]
	v_mfma_f32_16x16x32_bf16 v[6:9], v[178:181], v[240:243], v[6:9]
	v_mfma_f32_16x16x32_bf16 v[6:9], v[182:185], v[244:247], v[6:9]
	v_mfma_f32_16x16x32_bf16 v[2:5], v[186:189], v[240:243], v[2:5]
	v_mfma_f32_16x16x32_bf16 v[2:5], v[190:193], v[244:247], v[2:5]
	v_mfma_f32_16x16x32_bf16 v[66:69], v[170:173], v[240:243], v[66:69]
	v_mfma_f32_16x16x32_bf16 v[66:69], v[174:177], v[244:247], v[66:69]
	v_mfma_f32_16x16x32_bf16 v[70:73], v[142:145], v[240:243], v[70:73]
	v_mfma_f32_16x16x32_bf16 v[70:73], v[154:157], v[244:247], v[70:73]
	s_barrier
	s_add_i32 s26, s26, 2
	s_addk_i32 s19, 0x100
	s_addk_i32 s22, 0x100
	s_cmp_gt_u32 s26, 29
	s_cbranch_scc0 .LBB0_1283
	s_and_b64 vcc, exec, s[44:45]
	s_cbranch_vccz .LBB0_1286
	s_barrier

.LBB0_1588:
	s_lshl_b32 s85, s84, 20
	s_and_b64 s[8:9], s[42:43], exec
	s_cselect_b32 s8, s85, s13
	s_lshl_b32 s48, s73, 20
	s_and_b64 s[22:23], s[42:43], exec
	s_cselect_b32 s9, s48, s21
	s_add_i32 s13, s13, 0x80080
	s_addk_i32 s21, 0x100
	s_mov_b32 s22, -2
	s_waitcnt lgkmcnt(0)
	v_add_u32_e32 v170, 0x10000, v140
	v_add_u32_e32 v186, 0x14000, v140
	ds_read_b128 v[132:135], v170
	ds_read_b128 v[142:145], v170 offset:1024
	ds_read_b128 v[154:157], v170 offset:2048
	ds_read_b128 v[170:173], v170 offset:3072
	ds_read_b128 v[174:177], v186
	ds_read_b128 v[178:181], v186 offset:1024
	ds_read_b128 v[182:185], v186 offset:2048
	ds_read_b128 v[186:189], v186 offset:3072
	s_add_i32 s23, s13, 0xfff80080
	s_cmp_eq_u32 s22, 28
	s_cselect_b32 s27, s8, s23
	s_cselect_b32 s26, s9, s21
	s_or_b32 s23, s27, 0x80
	s_mov_b32 m0, s70
	ds_read_b128 v[190:193], v141
	ds_read_b128 v[194:197], v141 offset:1024
	ds_read_b128 v[198:201], v141 offset:2048
	ds_read_b128 v[202:205], v141 offset:3072
	ds_read_b128 v[228:231], v141 offset:4096
	ds_read_b128 v[232:235], v141 offset:5120
	ds_read_b128 v[236:239], v141 offset:6144
	ds_read_b128 v[240:243], v141 offset:7168
	buffer_load_dwordx4 v136, s[60:63], s13 offen lds
	s_mov_b32 m0, s72
	s_nop 0
	buffer_load_dwordx4 v138, s[60:63], s13 offen lds
	s_waitcnt vmcnt(8)
	s_waitcnt lgkmcnt(0)
	s_barrier
	v_mfma_f32_16x16x32_bf16 v[126:129], v[132:135], v[190:193], 0
	v_mfma_f32_16x16x32_bf16 v[126:129], v[142:145], v[194:197], v[126:129]
	v_mfma_f32_16x16x32_bf16 v[106:109], v[154:157], v[190:193], 0
	v_mfma_f32_16x16x32_bf16 v[106:109], v[170:173], v[194:197], v[106:109]
	v_mfma_f32_16x16x32_bf16 v[110:113], v[182:185], v[190:193], 0
	v_mfma_f32_16x16x32_bf16 v[110:113], v[186:189], v[194:197], v[110:113]
	v_mfma_f32_16x16x32_bf16 v[122:125], v[174:177], v[190:193], 0
	v_mfma_f32_16x16x32_bf16 v[122:125], v[178:181], v[194:197], v[122:125]
	v_mfma_f32_16x16x32_bf16 v[102:105], v[174:177], v[198:201], 0
	v_mfma_f32_16x16x32_bf16 v[102:105], v[178:181], v[202:205], v[102:105]
	v_mfma_f32_16x16x32_bf16 v[98:101], v[182:185], v[198:201], 0
	v_mfma_f32_16x16x32_bf16 v[98:101], v[186:189], v[202:205], v[98:101]
	v_mfma_f32_16x16x32_bf16 v[114:117], v[154:157], v[198:201], 0
	v_mfma_f32_16x16x32_bf16 v[114:117], v[170:173], v[202:205], v[114:117]
	v_mfma_f32_16x16x32_bf16 v[118:121], v[132:135], v[198:201], 0
	v_mfma_f32_16x16x32_bf16 v[118:121], v[142:145], v[202:205], v[118:121]
	v_mfma_f32_16x16x32_bf16 v[94:97], v[132:135], v[228:231], 0
	v_mfma_f32_16x16x32_bf16 v[94:97], v[142:145], v[232:235], v[94:97]
	v_mfma_f32_16x16x32_bf16 v[90:93], v[154:157], v[228:231], 0
	v_mfma_f32_16x16x32_bf16 v[90:93], v[170:173], v[232:235], v[90:93]
	v_mfma_f32_16x16x32_bf16 v[82:85], v[182:185], v[228:231], 0
	v_mfma_f32_16x16x32_bf16 v[82:85], v[186:189], v[232:235], v[82:85]
	v_mfma_f32_16x16x32_bf16 v[86:89], v[174:177], v[228:231], 0
	v_mfma_f32_16x16x32_bf16 v[86:89], v[178:181], v[232:235], v[86:89]
	v_mfma_f32_16x16x32_bf16 v[70:73], v[174:177], v[236:239], 0
	v_mfma_f32_16x16x32_bf16 v[70:73], v[178:181], v[240:243], v[70:73]
	v_mfma_f32_16x16x32_bf16 v[66:69], v[182:185], v[236:239], 0
	v_mfma_f32_16x16x32_bf16 v[66:69], v[186:189], v[240:243], v[66:69]
	v_mfma_f32_16x16x32_bf16 v[74:77], v[154:157], v[236:239], 0
	v_mfma_f32_16x16x32_bf16 v[74:77], v[170:173], v[240:243], v[74:77]
	v_mfma_f32_16x16x32_bf16 v[78:81], v[132:135], v[236:239], 0
	v_mfma_f32_16x16x32_bf16 v[78:81], v[142:145], v[240:243], v[78:81]
	s_barrier
	s_mov_b32 s46, s62
	s_mov_b32 s47, s63
	s_mov_b32 m0, s15
	ds_read_b128 v[190:193], v141 offset:16384
	buffer_load_dwordx4 v137, s[44:47], s26 offen lds
	s_add_i32 s49, s26, 0x80000
	s_mov_b32 m0, s16
	ds_read_b128 v[194:197], v141 offset:17408
	buffer_load_dwordx4 v139, s[44:47], s26 offen lds
	s_mov_b32 m0, s18
	ds_read_b128 v[198:201], v141 offset:18432
	buffer_load_dwordx4 v137, s[44:47], s49 offen lds
	s_mov_b32 m0, s19
	ds_read_b128 v[202:205], v141 offset:19456
	buffer_load_dwordx4 v139, s[44:47], s49 offen lds
	s_mov_b32 m0, s14
	ds_read_b128 v[228:231], v141 offset:20480
	buffer_load_dwordx4 v136, s[60:63], s27 offen lds
	s_mov_b32 m0, s24
	ds_read_b128 v[232:235], v141 offset:21504
	buffer_load_dwordx4 v138, s[60:63], s27 offen lds
	ds_read_b128 v[236:239], v141 offset:22528
	ds_read_b128 v[240:243], v141 offset:23552
	s_waitcnt vmcnt(8)
	s_waitcnt lgkmcnt(0)
	s_barrier
	v_mfma_f32_16x16x32_bf16 v[62:65], v[132:135], v[190:193], 0
	v_mfma_f32_16x16x32_bf16 v[62:65], v[142:145], v[194:197], v[62:65]
	v_mfma_f32_16x16x32_bf16 v[58:61], v[154:157], v[190:193], 0
	v_mfma_f32_16x16x32_bf16 v[58:61], v[170:173], v[194:197], v[58:61]
	v_mfma_f32_16x16x32_bf16 v[50:53], v[182:185], v[190:193], 0
	v_mfma_f32_16x16x32_bf16 v[50:53], v[186:189], v[194:197], v[50:53]
	v_mfma_f32_16x16x32_bf16 v[54:57], v[174:177], v[190:193], 0
	v_mfma_f32_16x16x32_bf16 v[54:57], v[178:181], v[194:197], v[54:57]
	v_mfma_f32_16x16x32_bf16 v[38:41], v[174:177], v[198:201], 0
	v_mfma_f32_16x16x32_bf16 v[38:41], v[178:181], v[202:205], v[38:41]
	v_mfma_f32_16x16x32_bf16 v[34:37], v[182:185], v[198:201], 0
	v_mfma_f32_16x16x32_bf16 v[34:37], v[186:189], v[202:205], v[34:37]
	v_mfma_f32_16x16x32_bf16 v[42:45], v[154:157], v[198:201], 0
	v_mfma_f32_16x16x32_bf16 v[42:45], v[170:173], v[202:205], v[42:45]
	v_mfma_f32_16x16x32_bf16 v[46:49], v[132:135], v[198:201], 0
	v_mfma_f32_16x16x32_bf16 v[46:49], v[142:145], v[202:205], v[46:49]
	v_mfma_f32_16x16x32_bf16 v[30:33], v[132:135], v[228:231], 0
	v_mfma_f32_16x16x32_bf16 v[30:33], v[142:145], v[232:235], v[30:33]
	v_mfma_f32_16x16x32_bf16 v[26:29], v[154:157], v[228:231], 0
	v_mfma_f32_16x16x32_bf16 v[26:29], v[170:173], v[232:235], v[26:29]
	v_mfma_f32_16x16x32_bf16 v[18:21], v[182:185], v[228:231], 0
	v_mfma_f32_16x16x32_bf16 v[18:21], v[186:189], v[232:235], v[18:21]
	v_mfma_f32_16x16x32_bf16 v[22:25], v[174:177], v[228:231], 0
	v_mfma_f32_16x16x32_bf16 v[22:25], v[178:181], v[232:235], v[22:25]
	v_mfma_f32_16x16x32_bf16 v[6:9], v[174:177], v[236:239], 0
	v_mfma_f32_16x16x32_bf16 v[6:9], v[178:181], v[240:243], v[6:9]
	v_mfma_f32_16x16x32_bf16 v[2:5], v[182:185], v[236:239], 0
	v_mfma_f32_16x16x32_bf16 v[2:5], v[186:189], v[240:243], v[2:5]
	v_mfma_f32_16x16x32_bf16 v[10:13], v[154:157], v[236:239], 0
	v_mfma_f32_16x16x32_bf16 v[10:13], v[170:173], v[240:243], v[10:13]
	v_mfma_f32_16x16x32_bf16 v[14:17], v[132:135], v[236:239], 0
	v_mfma_f32_16x16x32_bf16 v[14:17], v[142:145], v[240:243], v[14:17]
	s_barrier
	v_add_u32_e32 v170, 0x18000, v140
	v_add_u32_e32 v186, 0x1c000, v140
	ds_read_b128 v[132:135], v170
	ds_read_b128 v[142:145], v170 offset:1024
	ds_read_b128 v[154:157], v170 offset:2048
	ds_read_b128 v[170:173], v170 offset:3072
	ds_read_b128 v[174:177], v186
	ds_read_b128 v[178:181], v186 offset:1024
	ds_read_b128 v[182:185], v186 offset:2048
	ds_read_b128 v[186:189], v186 offset:3072
	s_add_i32 s27, s27, 0x80000
	s_mov_b32 m0, s25
	ds_read_b128 v[190:193], v141 offset:32768
	ds_read_b128 v[194:197], v141 offset:33792
	ds_read_b128 v[198:201], v141 offset:34816
	ds_read_b128 v[202:205], v141 offset:35840
	ds_read_b128 v[228:231], v141 offset:36864
	ds_read_b128 v[232:235], v141 offset:37888
	ds_read_b128 v[236:239], v141 offset:38912
	ds_read_b128 v[240:243], v141 offset:39936
	buffer_load_dwordx4 v136, s[60:63], s27 offen lds
	s_mov_b32 m0, s30
	s_nop 0
	buffer_load_dwordx4 v138, s[60:63], s27 offen lds
	s_waitcnt vmcnt(8)
	s_waitcnt lgkmcnt(0)
	s_barrier
	v_mfma_f32_16x16x32_bf16 v[126:129], v[132:135], v[190:193], v[126:129]
	v_mfma_f32_16x16x32_bf16 v[126:129], v[142:145], v[194:197], v[126:129]
	v_mfma_f32_16x16x32_bf16 v[106:109], v[154:157], v[190:193], v[106:109]
	v_mfma_f32_16x16x32_bf16 v[106:109], v[170:173], v[194:197], v[106:109]
	v_mfma_f32_16x16x32_bf16 v[110:113], v[182:185], v[190:193], v[110:113]
	v_mfma_f32_16x16x32_bf16 v[110:113], v[186:189], v[194:197], v[110:113]
	v_mfma_f32_16x16x32_bf16 v[122:125], v[174:177], v[190:193], v[122:125]
	v_mfma_f32_16x16x32_bf16 v[122:125], v[178:181], v[194:197], v[122:125]
	v_mfma_f32_16x16x32_bf16 v[102:105], v[174:177], v[198:201], v[102:105]
	v_mfma_f32_16x16x32_bf16 v[102:105], v[178:181], v[202:205], v[102:105]
	v_mfma_f32_16x16x32_bf16 v[98:101], v[182:185], v[198:201], v[98:101]
	v_mfma_f32_16x16x32_bf16 v[98:101], v[186:189], v[202:205], v[98:101]
	v_mfma_f32_16x16x32_bf16 v[114:117], v[154:157], v[198:201], v[114:117]
	v_mfma_f32_16x16x32_bf16 v[114:117], v[170:173], v[202:205], v[114:117]
	v_mfma_f32_16x16x32_bf16 v[118:121], v[132:135], v[198:201], v[118:121]
	v_mfma_f32_16x16x32_bf16 v[118:121], v[142:145], v[202:205], v[118:121]
	v_mfma_f32_16x16x32_bf16 v[94:97], v[132:135], v[228:231], v[94:97]
	v_mfma_f32_16x16x32_bf16 v[94:97], v[142:145], v[232:235], v[94:97]
	v_mfma_f32_16x16x32_bf16 v[90:93], v[154:157], v[228:231], v[90:93]
	v_mfma_f32_16x16x32_bf16 v[90:93], v[170:173], v[232:235], v[90:93]
	v_mfma_f32_16x16x32_bf16 v[82:85], v[182:185], v[228:231], v[82:85]
	v_mfma_f32_16x16x32_bf16 v[82:85], v[186:189], v[232:235], v[82:85]
	v_mfma_f32_16x16x32_bf16 v[86:89], v[174:177], v[228:231], v[86:89]
	v_mfma_f32_16x16x32_bf16 v[86:89], v[178:181], v[232:235], v[86:89]
	v_mfma_f32_16x16x32_bf16 v[70:73], v[174:177], v[236:239], v[70:73]
	v_mfma_f32_16x16x32_bf16 v[70:73], v[178:181], v[240:243], v[70:73]
	v_mfma_f32_16x16x32_bf16 v[66:69], v[182:185], v[236:239], v[66:69]
	v_mfma_f32_16x16x32_bf16 v[66:69], v[186:189], v[240:243], v[66:69]
	v_mfma_f32_16x16x32_bf16 v[74:77], v[154:157], v[236:239], v[74:77]
	v_mfma_f32_16x16x32_bf16 v[74:77], v[170:173], v[240:243], v[74:77]
	v_mfma_f32_16x16x32_bf16 v[78:81], v[132:135], v[236:239], v[78:81]
	v_mfma_f32_16x16x32_bf16 v[78:81], v[142:145], v[240:243], v[78:81]
	s_barrier
	s_or_b32 s27, s26, 0x80
	s_mov_b32 m0, s36
	ds_read_b128 v[190:193], v141 offset:49152
	buffer_load_dwordx4 v137, s[44:47], s27 offen lds
	s_add_i32 s26, s26, 0x80080
	s_mov_b32 m0, s37
	ds_read_b128 v[194:197], v141 offset:50176
	buffer_load_dwordx4 v139, s[44:47], s27 offen lds
	s_mov_b32 m0, s68
	ds_read_b128 v[198:201], v141 offset:51200
	buffer_load_dwordx4 v137, s[44:47], s26 offen lds
	s_mov_b32 m0, s69
	ds_read_b128 v[202:205], v141 offset:52224
	buffer_load_dwordx4 v139, s[44:47], s26 offen lds
	s_mov_b32 m0, s66
	ds_read_b128 v[228:231], v141 offset:53248
	buffer_load_dwordx4 v136, s[60:63], s23 offen lds
	s_mov_b32 m0, s67
	ds_read_b128 v[232:235], v141 offset:54272
	buffer_load_dwordx4 v138, s[60:63], s23 offen lds
	ds_read_b128 v[236:239], v141 offset:55296
	ds_read_b128 v[240:243], v141 offset:56320
	s_waitcnt vmcnt(8)
	s_waitcnt lgkmcnt(0)
	s_barrier
	v_mfma_f32_16x16x32_bf16 v[62:65], v[132:135], v[190:193], v[62:65]
	v_mfma_f32_16x16x32_bf16 v[62:65], v[142:145], v[194:197], v[62:65]
	v_mfma_f32_16x16x32_bf16 v[58:61], v[154:157], v[190:193], v[58:61]
	v_mfma_f32_16x16x32_bf16 v[58:61], v[170:173], v[194:197], v[58:61]
	v_mfma_f32_16x16x32_bf16 v[50:53], v[182:185], v[190:193], v[50:53]
	v_mfma_f32_16x16x32_bf16 v[50:53], v[186:189], v[194:197], v[50:53]
	v_mfma_f32_16x16x32_bf16 v[54:57], v[174:177], v[190:193], v[54:57]
	v_mfma_f32_16x16x32_bf16 v[54:57], v[178:181], v[194:197], v[54:57]
	v_mfma_f32_16x16x32_bf16 v[38:41], v[174:177], v[198:201], v[38:41]
	v_mfma_f32_16x16x32_bf16 v[38:41], v[178:181], v[202:205], v[38:41]
	v_mfma_f32_16x16x32_bf16 v[34:37], v[182:185], v[198:201], v[34:37]
	v_mfma_f32_16x16x32_bf16 v[34:37], v[186:189], v[202:205], v[34:37]
	v_mfma_f32_16x16x32_bf16 v[42:45], v[154:157], v[198:201], v[42:45]
	v_mfma_f32_16x16x32_bf16 v[42:45], v[170:173], v[202:205], v[42:45]
	v_mfma_f32_16x16x32_bf16 v[46:49], v[132:135], v[198:201], v[46:49]
	v_mfma_f32_16x16x32_bf16 v[46:49], v[142:145], v[202:205], v[46:49]
	v_mfma_f32_16x16x32_bf16 v[30:33], v[132:135], v[228:231], v[30:33]
	v_mfma_f32_16x16x32_bf16 v[30:33], v[142:145], v[232:235], v[30:33]
	v_mfma_f32_16x16x32_bf16 v[26:29], v[154:157], v[228:231], v[26:29]
	v_mfma_f32_16x16x32_bf16 v[26:29], v[170:173], v[232:235], v[26:29]
	v_mfma_f32_16x16x32_bf16 v[18:21], v[182:185], v[228:231], v[18:21]
	v_mfma_f32_16x16x32_bf16 v[18:21], v[186:189], v[232:235], v[18:21]
	v_mfma_f32_16x16x32_bf16 v[22:25], v[174:177], v[228:231], v[22:25]
	v_mfma_f32_16x16x32_bf16 v[22:25], v[178:181], v[232:235], v[22:25]
	v_mfma_f32_16x16x32_bf16 v[6:9], v[174:177], v[236:239], v[6:9]
	v_mfma_f32_16x16x32_bf16 v[6:9], v[178:181], v[240:243], v[6:9]
	v_mfma_f32_16x16x32_bf16 v[2:5], v[182:185], v[236:239], v[2:5]
	v_mfma_f32_16x16x32_bf16 v[2:5], v[186:189], v[240:243], v[2:5]
	v_mfma_f32_16x16x32_bf16 v[10:13], v[154:157], v[236:239], v[10:13]
	v_mfma_f32_16x16x32_bf16 v[10:13], v[170:173], v[240:243], v[10:13]
	v_mfma_f32_16x16x32_bf16 v[14:17], v[132:135], v[236:239], v[14:17]
	v_mfma_f32_16x16x32_bf16 v[14:17], v[142:145], v[240:243], v[14:17]
	s_barrier
	s_add_i32 s22, s22, 2
	s_addk_i32 s13, 0x100
	s_addk_i32 s21, 0x100
	s_cmp_gt_u32 s22, 29
.LBB0_1589:
	v_add_u32_e32 v170, 0x10000, v140
	v_add_u32_e32 v186, 0x14000, v140
	ds_read_b128 v[132:135], v170
	ds_read_b128 v[142:145], v170 offset:1024
	ds_read_b128 v[154:157], v170 offset:2048
	ds_read_b128 v[170:173], v170 offset:3072
	ds_read_b128 v[174:177], v186
	ds_read_b128 v[178:181], v186 offset:1024
	ds_read_b128 v[182:185], v186 offset:2048
	ds_read_b128 v[186:189], v186 offset:3072
	s_add_i32 s23, s13, 0xfff80080
	s_cmp_eq_u32 s22, 28
	s_cselect_b32 s27, s8, s23
	s_cselect_b32 s26, s9, s21
	s_or_b32 s23, s27, 0x80
	s_mov_b32 m0, s70
	ds_read_b128 v[190:193], v141
	ds_read_b128 v[194:197], v141 offset:1024
	ds_read_b128 v[198:201], v141 offset:2048
	ds_read_b128 v[202:205], v141 offset:3072
	ds_read_b128 v[228:231], v141 offset:4096
	ds_read_b128 v[232:235], v141 offset:5120
	ds_read_b128 v[236:239], v141 offset:6144
	ds_read_b128 v[240:243], v141 offset:7168
	buffer_load_dwordx4 v136, s[60:63], s13 offen lds
	s_mov_b32 m0, s72
	s_nop 0
	buffer_load_dwordx4 v138, s[60:63], s13 offen lds
	s_waitcnt vmcnt(8)
	s_waitcnt lgkmcnt(0)
	s_barrier
	v_mfma_f32_16x16x32_bf16 v[126:129], v[132:135], v[190:193], v[126:129]
	v_mfma_f32_16x16x32_bf16 v[126:129], v[142:145], v[194:197], v[126:129]
	v_mfma_f32_16x16x32_bf16 v[106:109], v[154:157], v[190:193], v[106:109]
	v_mfma_f32_16x16x32_bf16 v[106:109], v[170:173], v[194:197], v[106:109]
	v_mfma_f32_16x16x32_bf16 v[110:113], v[182:185], v[190:193], v[110:113]
	v_mfma_f32_16x16x32_bf16 v[110:113], v[186:189], v[194:197], v[110:113]
	v_mfma_f32_16x16x32_bf16 v[122:125], v[174:177], v[190:193], v[122:125]
	v_mfma_f32_16x16x32_bf16 v[122:125], v[178:181], v[194:197], v[122:125]
	v_mfma_f32_16x16x32_bf16 v[102:105], v[174:177], v[198:201], v[102:105]
	v_mfma_f32_16x16x32_bf16 v[102:105], v[178:181], v[202:205], v[102:105]
	v_mfma_f32_16x16x32_bf16 v[98:101], v[182:185], v[198:201], v[98:101]
	v_mfma_f32_16x16x32_bf16 v[98:101], v[186:189], v[202:205], v[98:101]
	v_mfma_f32_16x16x32_bf16 v[114:117], v[154:157], v[198:201], v[114:117]
	v_mfma_f32_16x16x32_bf16 v[114:117], v[170:173], v[202:205], v[114:117]
	v_mfma_f32_16x16x32_bf16 v[118:121], v[132:135], v[198:201], v[118:121]
	v_mfma_f32_16x16x32_bf16 v[118:121], v[142:145], v[202:205], v[118:121]
	v_mfma_f32_16x16x32_bf16 v[94:97], v[132:135], v[228:231], v[94:97]
	v_mfma_f32_16x16x32_bf16 v[94:97], v[142:145], v[232:235], v[94:97]
	v_mfma_f32_16x16x32_bf16 v[90:93], v[154:157], v[228:231], v[90:93]
	v_mfma_f32_16x16x32_bf16 v[90:93], v[170:173], v[232:235], v[90:93]
	v_mfma_f32_16x16x32_bf16 v[82:85], v[182:185], v[228:231], v[82:85]
	v_mfma_f32_16x16x32_bf16 v[82:85], v[186:189], v[232:235], v[82:85]
	v_mfma_f32_16x16x32_bf16 v[86:89], v[174:177], v[228:231], v[86:89]
	v_mfma_f32_16x16x32_bf16 v[86:89], v[178:181], v[232:235], v[86:89]
	v_mfma_f32_16x16x32_bf16 v[70:73], v[174:177], v[236:239], v[70:73]
	v_mfma_f32_16x16x32_bf16 v[70:73], v[178:181], v[240:243], v[70:73]
	v_mfma_f32_16x16x32_bf16 v[66:69], v[182:185], v[236:239], v[66:69]
	v_mfma_f32_16x16x32_bf16 v[66:69], v[186:189], v[240:243], v[66:69]
	v_mfma_f32_16x16x32_bf16 v[74:77], v[154:157], v[236:239], v[74:77]
	v_mfma_f32_16x16x32_bf16 v[74:77], v[170:173], v[240:243], v[74:77]
	v_mfma_f32_16x16x32_bf16 v[78:81], v[132:135], v[236:239], v[78:81]
	v_mfma_f32_16x16x32_bf16 v[78:81], v[142:145], v[240:243], v[78:81]
	s_barrier
	s_mov_b32 s46, s62
	s_mov_b32 s47, s63
	s_mov_b32 m0, s15
	ds_read_b128 v[190:193], v141 offset:16384
	buffer_load_dwordx4 v137, s[44:47], s26 offen lds
	s_add_i32 s49, s26, 0x80000
	s_mov_b32 m0, s16
	ds_read_b128 v[194:197], v141 offset:17408
	buffer_load_dwordx4 v139, s[44:47], s26 offen lds
	s_mov_b32 m0, s18
	ds_read_b128 v[198:201], v141 offset:18432
	buffer_load_dwordx4 v137, s[44:47], s49 offen lds
	s_mov_b32 m0, s19
	ds_read_b128 v[202:205], v141 offset:19456
	buffer_load_dwordx4 v139, s[44:47], s49 offen lds
	s_mov_b32 m0, s14
	ds_read_b128 v[228:231], v141 offset:20480
	buffer_load_dwordx4 v136, s[60:63], s27 offen lds
	s_mov_b32 m0, s24
	ds_read_b128 v[232:235], v141 offset:21504
	buffer_load_dwordx4 v138, s[60:63], s27 offen lds
	ds_read_b128 v[236:239], v141 offset:22528
	ds_read_b128 v[240:243], v141 offset:23552
	s_waitcnt vmcnt(8)
	s_waitcnt lgkmcnt(0)
	s_barrier
	v_mfma_f32_16x16x32_bf16 v[62:65], v[132:135], v[190:193], v[62:65]
	v_mfma_f32_16x16x32_bf16 v[62:65], v[142:145], v[194:197], v[62:65]
	v_mfma_f32_16x16x32_bf16 v[58:61], v[154:157], v[190:193], v[58:61]
	v_mfma_f32_16x16x32_bf16 v[58:61], v[170:173], v[194:197], v[58:61]
	v_mfma_f32_16x16x32_bf16 v[50:53], v[182:185], v[190:193], v[50:53]
	v_mfma_f32_16x16x32_bf16 v[50:53], v[186:189], v[194:197], v[50:53]
	v_mfma_f32_16x16x32_bf16 v[54:57], v[174:177], v[190:193], v[54:57]
	v_mfma_f32_16x16x32_bf16 v[54:57], v[178:181], v[194:197], v[54:57]
	v_mfma_f32_16x16x32_bf16 v[38:41], v[174:177], v[198:201], v[38:41]
	v_mfma_f32_16x16x32_bf16 v[38:41], v[178:181], v[202:205], v[38:41]
	v_mfma_f32_16x16x32_bf16 v[34:37], v[182:185], v[198:201], v[34:37]
	v_mfma_f32_16x16x32_bf16 v[34:37], v[186:189], v[202:205], v[34:37]
	v_mfma_f32_16x16x32_bf16 v[42:45], v[154:157], v[198:201], v[42:45]
	v_mfma_f32_16x16x32_bf16 v[42:45], v[170:173], v[202:205], v[42:45]
	v_mfma_f32_16x16x32_bf16 v[46:49], v[132:135], v[198:201], v[46:49]
	v_mfma_f32_16x16x32_bf16 v[46:49], v[142:145], v[202:205], v[46:49]
	v_mfma_f32_16x16x32_bf16 v[30:33], v[132:135], v[228:231], v[30:33]
	v_mfma_f32_16x16x32_bf16 v[30:33], v[142:145], v[232:235], v[30:33]
	v_mfma_f32_16x16x32_bf16 v[26:29], v[154:157], v[228:231], v[26:29]
	v_mfma_f32_16x16x32_bf16 v[26:29], v[170:173], v[232:235], v[26:29]
	v_mfma_f32_16x16x32_bf16 v[18:21], v[182:185], v[228:231], v[18:21]
	v_mfma_f32_16x16x32_bf16 v[18:21], v[186:189], v[232:235], v[18:21]
	v_mfma_f32_16x16x32_bf16 v[22:25], v[174:177], v[228:231], v[22:25]
	v_mfma_f32_16x16x32_bf16 v[22:25], v[178:181], v[232:235], v[22:25]
	v_mfma_f32_16x16x32_bf16 v[6:9], v[174:177], v[236:239], v[6:9]
	v_mfma_f32_16x16x32_bf16 v[6:9], v[178:181], v[240:243], v[6:9]
	v_mfma_f32_16x16x32_bf16 v[2:5], v[182:185], v[236:239], v[2:5]
	v_mfma_f32_16x16x32_bf16 v[2:5], v[186:189], v[240:243], v[2:5]
	v_mfma_f32_16x16x32_bf16 v[10:13], v[154:157], v[236:239], v[10:13]
	v_mfma_f32_16x16x32_bf16 v[10:13], v[170:173], v[240:243], v[10:13]
	v_mfma_f32_16x16x32_bf16 v[14:17], v[132:135], v[236:239], v[14:17]
	v_mfma_f32_16x16x32_bf16 v[14:17], v[142:145], v[240:243], v[14:17]
	s_barrier
	v_add_u32_e32 v170, 0x18000, v140
	v_add_u32_e32 v186, 0x1c000, v140
	ds_read_b128 v[132:135], v170
	ds_read_b128 v[142:145], v170 offset:1024
	ds_read_b128 v[154:157], v170 offset:2048
	ds_read_b128 v[170:173], v170 offset:3072
	ds_read_b128 v[174:177], v186
	ds_read_b128 v[178:181], v186 offset:1024
	ds_read_b128 v[182:185], v186 offset:2048
	ds_read_b128 v[186:189], v186 offset:3072
	s_add_i32 s27, s27, 0x80000
	s_mov_b32 m0, s25
	ds_read_b128 v[190:193], v141 offset:32768
	ds_read_b128 v[194:197], v141 offset:33792
	ds_read_b128 v[198:201], v141 offset:34816
	ds_read_b128 v[202:205], v141 offset:35840
	ds_read_b128 v[228:231], v141 offset:36864
	ds_read_b128 v[232:235], v141 offset:37888
	ds_read_b128 v[236:239], v141 offset:38912
	ds_read_b128 v[240:243], v141 offset:39936
	buffer_load_dwordx4 v136, s[60:63], s27 offen lds
	s_mov_b32 m0, s30
	s_nop 0
	buffer_load_dwordx4 v138, s[60:63], s27 offen lds
	s_waitcnt vmcnt(8)
	s_waitcnt lgkmcnt(0)
	s_barrier
	v_mfma_f32_16x16x32_bf16 v[126:129], v[132:135], v[190:193], v[126:129]
	v_mfma_f32_16x16x32_bf16 v[126:129], v[142:145], v[194:197], v[126:129]
	v_mfma_f32_16x16x32_bf16 v[106:109], v[154:157], v[190:193], v[106:109]
	v_mfma_f32_16x16x32_bf16 v[106:109], v[170:173], v[194:197], v[106:109]
	v_mfma_f32_16x16x32_bf16 v[110:113], v[182:185], v[190:193], v[110:113]
	v_mfma_f32_16x16x32_bf16 v[110:113], v[186:189], v[194:197], v[110:113]
	v_mfma_f32_16x16x32_bf16 v[122:125], v[174:177], v[190:193], v[122:125]
	v_mfma_f32_16x16x32_bf16 v[122:125], v[178:181], v[194:197], v[122:125]
	v_mfma_f32_16x16x32_bf16 v[102:105], v[174:177], v[198:201], v[102:105]
	v_mfma_f32_16x16x32_bf16 v[102:105], v[178:181], v[202:205], v[102:105]
	v_mfma_f32_16x16x32_bf16 v[98:101], v[182:185], v[198:201], v[98:101]
	v_mfma_f32_16x16x32_bf16 v[98:101], v[186:189], v[202:205], v[98:101]
	v_mfma_f32_16x16x32_bf16 v[114:117], v[154:157], v[198:201], v[114:117]
	v_mfma_f32_16x16x32_bf16 v[114:117], v[170:173], v[202:205], v[114:117]
	v_mfma_f32_16x16x32_bf16 v[118:121], v[132:135], v[198:201], v[118:121]
	v_mfma_f32_16x16x32_bf16 v[118:121], v[142:145], v[202:205], v[118:121]
	v_mfma_f32_16x16x32_bf16 v[94:97], v[132:135], v[228:231], v[94:97]
	v_mfma_f32_16x16x32_bf16 v[94:97], v[142:145], v[232:235], v[94:97]
	v_mfma_f32_16x16x32_bf16 v[90:93], v[154:157], v[228:231], v[90:93]
	v_mfma_f32_16x16x32_bf16 v[90:93], v[170:173], v[232:235], v[90:93]
	v_mfma_f32_16x16x32_bf16 v[82:85], v[182:185], v[228:231], v[82:85]
	v_mfma_f32_16x16x32_bf16 v[82:85], v[186:189], v[232:235], v[82:85]
	v_mfma_f32_16x16x32_bf16 v[86:89], v[174:177], v[228:231], v[86:89]
	v_mfma_f32_16x16x32_bf16 v[86:89], v[178:181], v[232:235], v[86:89]
	v_mfma_f32_16x16x32_bf16 v[70:73], v[174:177], v[236:239], v[70:73]
	v_mfma_f32_16x16x32_bf16 v[70:73], v[178:181], v[240:243], v[70:73]
	v_mfma_f32_16x16x32_bf16 v[66:69], v[182:185], v[236:239], v[66:69]
	v_mfma_f32_16x16x32_bf16 v[66:69], v[186:189], v[240:243], v[66:69]
	v_mfma_f32_16x16x32_bf16 v[74:77], v[154:157], v[236:239], v[74:77]
	v_mfma_f32_16x16x32_bf16 v[74:77], v[170:173], v[240:243], v[74:77]
	v_mfma_f32_16x16x32_bf16 v[78:81], v[132:135], v[236:239], v[78:81]
	v_mfma_f32_16x16x32_bf16 v[78:81], v[142:145], v[240:243], v[78:81]
	s_barrier
	s_or_b32 s27, s26, 0x80
	s_mov_b32 m0, s36
	ds_read_b128 v[190:193], v141 offset:49152
	buffer_load_dwordx4 v137, s[44:47], s27 offen lds
	s_add_i32 s26, s26, 0x80080
	s_mov_b32 m0, s37
	ds_read_b128 v[194:197], v141 offset:50176
	buffer_load_dwordx4 v139, s[44:47], s27 offen lds
	s_mov_b32 m0, s68
	ds_read_b128 v[198:201], v141 offset:51200
	buffer_load_dwordx4 v137, s[44:47], s26 offen lds
	s_mov_b32 m0, s69
	ds_read_b128 v[202:205], v141 offset:52224
	buffer_load_dwordx4 v139, s[44:47], s26 offen lds
	s_mov_b32 m0, s66
	ds_read_b128 v[228:231], v141 offset:53248
	buffer_load_dwordx4 v136, s[60:63], s23 offen lds
	s_mov_b32 m0, s67
	ds_read_b128 v[232:235], v141 offset:54272
	buffer_load_dwordx4 v138, s[60:63], s23 offen lds
	ds_read_b128 v[236:239], v141 offset:55296
	ds_read_b128 v[240:243], v141 offset:56320
	s_waitcnt vmcnt(8)
	s_waitcnt lgkmcnt(0)
	s_barrier
	v_mfma_f32_16x16x32_bf16 v[62:65], v[132:135], v[190:193], v[62:65]
	v_mfma_f32_16x16x32_bf16 v[62:65], v[142:145], v[194:197], v[62:65]
	v_mfma_f32_16x16x32_bf16 v[58:61], v[154:157], v[190:193], v[58:61]
	v_mfma_f32_16x16x32_bf16 v[58:61], v[170:173], v[194:197], v[58:61]
	v_mfma_f32_16x16x32_bf16 v[50:53], v[182:185], v[190:193], v[50:53]
	v_mfma_f32_16x16x32_bf16 v[50:53], v[186:189], v[194:197], v[50:53]
	v_mfma_f32_16x16x32_bf16 v[54:57], v[174:177], v[190:193], v[54:57]
	v_mfma_f32_16x16x32_bf16 v[54:57], v[178:181], v[194:197], v[54:57]
	v_mfma_f32_16x16x32_bf16 v[38:41], v[174:177], v[198:201], v[38:41]
	v_mfma_f32_16x16x32_bf16 v[38:41], v[178:181], v[202:205], v[38:41]
	v_mfma_f32_16x16x32_bf16 v[34:37], v[182:185], v[198:201], v[34:37]
	v_mfma_f32_16x16x32_bf16 v[34:37], v[186:189], v[202:205], v[34:37]
	v_mfma_f32_16x16x32_bf16 v[42:45], v[154:157], v[198:201], v[42:45]
	v_mfma_f32_16x16x32_bf16 v[42:45], v[170:173], v[202:205], v[42:45]
	v_mfma_f32_16x16x32_bf16 v[46:49], v[132:135], v[198:201], v[46:49]
	v_mfma_f32_16x16x32_bf16 v[46:49], v[142:145], v[202:205], v[46:49]
	v_mfma_f32_16x16x32_bf16 v[30:33], v[132:135], v[228:231], v[30:33]
	v_mfma_f32_16x16x32_bf16 v[30:33], v[142:145], v[232:235], v[30:33]
	v_mfma_f32_16x16x32_bf16 v[26:29], v[154:157], v[228:231], v[26:29]
	v_mfma_f32_16x16x32_bf16 v[26:29], v[170:173], v[232:235], v[26:29]
	v_mfma_f32_16x16x32_bf16 v[18:21], v[182:185], v[228:231], v[18:21]
	v_mfma_f32_16x16x32_bf16 v[18:21], v[186:189], v[232:235], v[18:21]
	v_mfma_f32_16x16x32_bf16 v[22:25], v[174:177], v[228:231], v[22:25]
	v_mfma_f32_16x16x32_bf16 v[22:25], v[178:181], v[232:235], v[22:25]
	v_mfma_f32_16x16x32_bf16 v[6:9], v[174:177], v[236:239], v[6:9]
	v_mfma_f32_16x16x32_bf16 v[6:9], v[178:181], v[240:243], v[6:9]
	v_mfma_f32_16x16x32_bf16 v[2:5], v[182:185], v[236:239], v[2:5]
	v_mfma_f32_16x16x32_bf16 v[2:5], v[186:189], v[240:243], v[2:5]
	v_mfma_f32_16x16x32_bf16 v[10:13], v[154:157], v[236:239], v[10:13]
	v_mfma_f32_16x16x32_bf16 v[10:13], v[170:173], v[240:243], v[10:13]
	v_mfma_f32_16x16x32_bf16 v[14:17], v[132:135], v[236:239], v[14:17]
	v_mfma_f32_16x16x32_bf16 v[14:17], v[142:145], v[240:243], v[14:17]
	s_barrier
	s_add_i32 s22, s22, 2
	s_addk_i32 s13, 0x100
	s_addk_i32 s21, 0x100
	s_cmp_gt_u32 s22, 29
	s_cbranch_scc0 .LBB0_1589
	s_and_b64 vcc, exec, s[64:65]
	s_cbranch_vccz .LBB0_1592
	s_barrier

.LBB0_1879:
	s_lshl_b32 s18, s91, 20
	s_and_b64 s[8:9], s[48:49], exec
	s_cselect_b32 s8, s18, s95
	s_lshl_b32 s19, s92, 20
	s_and_b64 s[42:43], s[48:49], exec
	s_cselect_b32 s9, s19, s94
	s_add_i32 vcc_lo, s95, 0x80080
	s_add_i32 vcc_hi, s94, 0x100
	s_mov_b32 s94, -2
	v_add_u32_e32 v139, 0x10000, v136
	ds_read_b128 v[140:143], v139
	ds_read_b128 v[154:157], v139 offset:1024
	ds_read_b128 v[170:173], v139 offset:2048
	ds_read_b128 v[174:177], v139 offset:3072
	v_add_u32_e32 v139, 0x14000, v136
	ds_read_b128 v[178:181], v139
	ds_read_b128 v[182:185], v139 offset:1024
	ds_read_b128 v[186:189], v139 offset:2048
	ds_read_b128 v[190:193], v139 offset:3072
	s_add_i32 s42, vcc_lo, 0xfff80080
	s_cmp_eq_u32 s94, 28
	s_cselect_b32 s52, s8, s42
	s_cselect_b32 s96, s9, vcc_hi
	s_or_b32 s95, s52, 0x80
	s_mov_b32 m0, s72
	ds_read_b128 v[194:197], v137
	ds_read_b128 v[198:201], v137 offset:1024
	ds_read_b128 v[202:205], v137 offset:2048
	ds_read_b128 v[228:231], v137 offset:3072
	ds_read_b128 v[232:235], v137 offset:4096
	ds_read_b128 v[236:239], v137 offset:5120
	ds_read_b128 v[240:243], v137 offset:6144
	ds_read_b128 v[244:247], v137 offset:7168
	buffer_load_dwordx4 v132, s[60:63], vcc_lo offen lds
	s_mov_b32 m0, s47
	s_nop 0
	buffer_load_dwordx4 v134, s[60:63], vcc_lo offen lds
	s_waitcnt vmcnt(8)
	s_waitcnt lgkmcnt(0)
	s_barrier
	v_mfma_f32_16x16x32_bf16 v[114:117], v[140:143], v[194:197], 0
	v_mfma_f32_16x16x32_bf16 v[114:117], v[154:157], v[198:201], v[114:117]
	v_mfma_f32_16x16x32_bf16 v[110:113], v[170:173], v[194:197], 0
	v_mfma_f32_16x16x32_bf16 v[110:113], v[174:177], v[198:201], v[110:113]
	v_mfma_f32_16x16x32_bf16 v[122:125], v[186:189], v[194:197], 0
	v_mfma_f32_16x16x32_bf16 v[122:125], v[190:193], v[198:201], v[122:125]
	v_mfma_f32_16x16x32_bf16 v[126:129], v[178:181], v[194:197], 0
	v_mfma_f32_16x16x32_bf16 v[126:129], v[182:185], v[198:201], v[126:129]
	v_mfma_f32_16x16x32_bf16 v[118:121], v[178:181], v[202:205], 0
	v_mfma_f32_16x16x32_bf16 v[118:121], v[182:185], v[228:231], v[118:121]
	v_mfma_f32_16x16x32_bf16 v[98:101], v[186:189], v[202:205], 0
	v_mfma_f32_16x16x32_bf16 v[98:101], v[190:193], v[228:231], v[98:101]
	v_mfma_f32_16x16x32_bf16 v[102:105], v[170:173], v[202:205], 0
	v_mfma_f32_16x16x32_bf16 v[102:105], v[174:177], v[228:231], v[102:105]
	v_mfma_f32_16x16x32_bf16 v[106:109], v[140:143], v[202:205], 0
	v_mfma_f32_16x16x32_bf16 v[106:109], v[154:157], v[228:231], v[106:109]
	v_mfma_f32_16x16x32_bf16 v[94:97], v[140:143], v[232:235], 0
	v_mfma_f32_16x16x32_bf16 v[94:97], v[154:157], v[236:239], v[94:97]
	v_mfma_f32_16x16x32_bf16 v[86:89], v[170:173], v[232:235], 0
	v_mfma_f32_16x16x32_bf16 v[86:89], v[174:177], v[236:239], v[86:89]
	v_mfma_f32_16x16x32_bf16 v[82:85], v[186:189], v[232:235], 0
	v_mfma_f32_16x16x32_bf16 v[82:85], v[190:193], v[236:239], v[82:85]
	v_mfma_f32_16x16x32_bf16 v[90:93], v[178:181], v[232:235], 0
	v_mfma_f32_16x16x32_bf16 v[90:93], v[182:185], v[236:239], v[90:93]
	v_mfma_f32_16x16x32_bf16 v[74:77], v[178:181], v[240:243], 0
	v_mfma_f32_16x16x32_bf16 v[74:77], v[182:185], v[244:247], v[74:77]
	v_mfma_f32_16x16x32_bf16 v[66:69], v[186:189], v[240:243], 0
	v_mfma_f32_16x16x32_bf16 v[66:69], v[190:193], v[244:247], v[66:69]
	v_mfma_f32_16x16x32_bf16 v[70:73], v[170:173], v[240:243], 0
	v_mfma_f32_16x16x32_bf16 v[70:73], v[174:177], v[244:247], v[70:73]
	v_mfma_f32_16x16x32_bf16 v[78:81], v[140:143], v[240:243], 0
	v_mfma_f32_16x16x32_bf16 v[78:81], v[154:157], v[244:247], v[78:81]
	s_barrier
	s_mov_b32 s42, s62
	s_mov_b32 s43, s63
	s_mov_b32 m0, s13
	ds_read_b128 v[194:197], v137 offset:16384
	buffer_load_dwordx4 v133, s[40:43], s96 offen lds
	s_add_i32 s53, s96, 0x80000
	s_mov_b32 m0, s14
	ds_read_b128 v[198:201], v137 offset:17408
	buffer_load_dwordx4 v135, s[40:43], s96 offen lds
	s_mov_b32 m0, s15
	ds_read_b128 v[202:205], v137 offset:18432
	buffer_load_dwordx4 v133, s[40:43], s53 offen lds
	s_mov_b32 m0, s16
	ds_read_b128 v[228:231], v137 offset:19456
	buffer_load_dwordx4 v135, s[40:43], s53 offen lds
	s_mov_b32 m0, s2
	ds_read_b128 v[232:235], v137 offset:20480
	buffer_load_dwordx4 v132, s[60:63], s52 offen lds
	s_mov_b32 m0, s21
	ds_read_b128 v[236:239], v137 offset:21504
	buffer_load_dwordx4 v134, s[60:63], s52 offen lds
	ds_read_b128 v[240:243], v137 offset:22528
	ds_read_b128 v[244:247], v137 offset:23552
	s_waitcnt vmcnt(8)
	s_waitcnt lgkmcnt(0)
	s_barrier
	v_mfma_f32_16x16x32_bf16 v[62:65], v[140:143], v[194:197], 0
	v_mfma_f32_16x16x32_bf16 v[62:65], v[154:157], v[198:201], v[62:65]
	v_mfma_f32_16x16x32_bf16 v[54:57], v[170:173], v[194:197], 0
	v_mfma_f32_16x16x32_bf16 v[54:57], v[174:177], v[198:201], v[54:57]
	v_mfma_f32_16x16x32_bf16 v[50:53], v[186:189], v[194:197], 0
	v_mfma_f32_16x16x32_bf16 v[50:53], v[190:193], v[198:201], v[50:53]
	v_mfma_f32_16x16x32_bf16 v[58:61], v[178:181], v[194:197], 0
	v_mfma_f32_16x16x32_bf16 v[58:61], v[182:185], v[198:201], v[58:61]
	v_mfma_f32_16x16x32_bf16 v[42:45], v[178:181], v[202:205], 0
	v_mfma_f32_16x16x32_bf16 v[42:45], v[182:185], v[228:231], v[42:45]
	v_mfma_f32_16x16x32_bf16 v[34:37], v[186:189], v[202:205], 0
	v_mfma_f32_16x16x32_bf16 v[34:37], v[190:193], v[228:231], v[34:37]
	v_mfma_f32_16x16x32_bf16 v[38:41], v[170:173], v[202:205], 0
	v_mfma_f32_16x16x32_bf16 v[38:41], v[174:177], v[228:231], v[38:41]
	v_mfma_f32_16x16x32_bf16 v[46:49], v[140:143], v[202:205], 0
	v_mfma_f32_16x16x32_bf16 v[46:49], v[154:157], v[228:231], v[46:49]
	v_mfma_f32_16x16x32_bf16 v[30:33], v[140:143], v[232:235], 0
	v_mfma_f32_16x16x32_bf16 v[30:33], v[154:157], v[236:239], v[30:33]
	v_mfma_f32_16x16x32_bf16 v[22:25], v[170:173], v[232:235], 0
	v_mfma_f32_16x16x32_bf16 v[22:25], v[174:177], v[236:239], v[22:25]
	v_mfma_f32_16x16x32_bf16 v[18:21], v[186:189], v[232:235], 0
	v_mfma_f32_16x16x32_bf16 v[18:21], v[190:193], v[236:239], v[18:21]
	v_mfma_f32_16x16x32_bf16 v[26:29], v[178:181], v[232:235], 0
	v_mfma_f32_16x16x32_bf16 v[26:29], v[182:185], v[236:239], v[26:29]
	v_mfma_f32_16x16x32_bf16 v[10:13], v[178:181], v[240:243], 0
	v_mfma_f32_16x16x32_bf16 v[10:13], v[182:185], v[244:247], v[10:13]
	v_mfma_f32_16x16x32_bf16 v[2:5], v[186:189], v[240:243], 0
	v_mfma_f32_16x16x32_bf16 v[2:5], v[190:193], v[244:247], v[2:5]
	v_mfma_f32_16x16x32_bf16 v[6:9], v[170:173], v[240:243], 0
	v_mfma_f32_16x16x32_bf16 v[6:9], v[174:177], v[244:247], v[6:9]
	v_mfma_f32_16x16x32_bf16 v[14:17], v[140:143], v[240:243], 0
	v_mfma_f32_16x16x32_bf16 v[14:17], v[154:157], v[244:247], v[14:17]
	s_barrier
	v_add_u32_e32 v139, 0x18000, v136
	ds_read_b128 v[140:143], v139
	ds_read_b128 v[154:157], v139 offset:1024
	ds_read_b128 v[170:173], v139 offset:2048
	ds_read_b128 v[174:177], v139 offset:3072
	v_add_u32_e32 v139, 0x1c000, v136
	ds_read_b128 v[178:181], v139
	ds_read_b128 v[182:185], v139 offset:1024
	ds_read_b128 v[186:189], v139 offset:2048
	ds_read_b128 v[190:193], v139 offset:3072
	s_add_i32 s52, s52, 0x80000
	s_mov_b32 m0, s23
	ds_read_b128 v[194:197], v137 offset:32768
	ds_read_b128 v[198:201], v137 offset:33792
	ds_read_b128 v[202:205], v137 offset:34816
	ds_read_b128 v[228:231], v137 offset:35840
	ds_read_b128 v[232:235], v137 offset:36864
	ds_read_b128 v[236:239], v137 offset:37888
	ds_read_b128 v[240:243], v137 offset:38912
	ds_read_b128 v[244:247], v137 offset:39936
	buffer_load_dwordx4 v132, s[60:63], s52 offen lds
	s_mov_b32 m0, s24
	s_nop 0
	buffer_load_dwordx4 v134, s[60:63], s52 offen lds
	s_waitcnt vmcnt(8)
	s_waitcnt lgkmcnt(0)
	s_barrier
	v_mfma_f32_16x16x32_bf16 v[114:117], v[140:143], v[194:197], v[114:117]
	v_mfma_f32_16x16x32_bf16 v[114:117], v[154:157], v[198:201], v[114:117]
	v_mfma_f32_16x16x32_bf16 v[110:113], v[170:173], v[194:197], v[110:113]
	v_mfma_f32_16x16x32_bf16 v[110:113], v[174:177], v[198:201], v[110:113]
	v_mfma_f32_16x16x32_bf16 v[122:125], v[186:189], v[194:197], v[122:125]
	v_mfma_f32_16x16x32_bf16 v[122:125], v[190:193], v[198:201], v[122:125]
	v_mfma_f32_16x16x32_bf16 v[126:129], v[178:181], v[194:197], v[126:129]
	v_mfma_f32_16x16x32_bf16 v[126:129], v[182:185], v[198:201], v[126:129]
	v_mfma_f32_16x16x32_bf16 v[118:121], v[178:181], v[202:205], v[118:121]
	v_mfma_f32_16x16x32_bf16 v[118:121], v[182:185], v[228:231], v[118:121]
	v_mfma_f32_16x16x32_bf16 v[98:101], v[186:189], v[202:205], v[98:101]
	v_mfma_f32_16x16x32_bf16 v[98:101], v[190:193], v[228:231], v[98:101]
	v_mfma_f32_16x16x32_bf16 v[102:105], v[170:173], v[202:205], v[102:105]
	v_mfma_f32_16x16x32_bf16 v[102:105], v[174:177], v[228:231], v[102:105]
	v_mfma_f32_16x16x32_bf16 v[106:109], v[140:143], v[202:205], v[106:109]
	v_mfma_f32_16x16x32_bf16 v[106:109], v[154:157], v[228:231], v[106:109]
	v_mfma_f32_16x16x32_bf16 v[94:97], v[140:143], v[232:235], v[94:97]
	v_mfma_f32_16x16x32_bf16 v[94:97], v[154:157], v[236:239], v[94:97]
	v_mfma_f32_16x16x32_bf16 v[86:89], v[170:173], v[232:235], v[86:89]
	v_mfma_f32_16x16x32_bf16 v[86:89], v[174:177], v[236:239], v[86:89]
	v_mfma_f32_16x16x32_bf16 v[82:85], v[186:189], v[232:235], v[82:85]
	v_mfma_f32_16x16x32_bf16 v[82:85], v[190:193], v[236:239], v[82:85]
	v_mfma_f32_16x16x32_bf16 v[90:93], v[178:181], v[232:235], v[90:93]
	v_mfma_f32_16x16x32_bf16 v[90:93], v[182:185], v[236:239], v[90:93]
	v_mfma_f32_16x16x32_bf16 v[74:77], v[178:181], v[240:243], v[74:77]
	v_mfma_f32_16x16x32_bf16 v[74:77], v[182:185], v[244:247], v[74:77]
	v_mfma_f32_16x16x32_bf16 v[66:69], v[186:189], v[240:243], v[66:69]
	v_mfma_f32_16x16x32_bf16 v[66:69], v[190:193], v[244:247], v[66:69]
	v_mfma_f32_16x16x32_bf16 v[70:73], v[170:173], v[240:243], v[70:73]
	v_mfma_f32_16x16x32_bf16 v[70:73], v[174:177], v[244:247], v[70:73]
	v_mfma_f32_16x16x32_bf16 v[78:81], v[140:143], v[240:243], v[78:81]
	v_mfma_f32_16x16x32_bf16 v[78:81], v[154:157], v[244:247], v[78:81]
	s_barrier
	s_or_b32 s52, s96, 0x80
	s_mov_b32 m0, s31
	ds_read_b128 v[194:197], v137 offset:49152
	buffer_load_dwordx4 v133, s[40:43], s52 offen lds
	s_add_i32 s96, s96, 0x80080
	s_mov_b32 m0, s33
	ds_read_b128 v[198:201], v137 offset:50176
	buffer_load_dwordx4 v135, s[40:43], s52 offen lds
	s_mov_b32 m0, s36
	ds_read_b128 v[202:205], v137 offset:51200
	buffer_load_dwordx4 v133, s[40:43], s96 offen lds
	s_mov_b32 m0, s37
	ds_read_b128 v[228:231], v137 offset:52224
	buffer_load_dwordx4 v135, s[40:43], s96 offen lds
	s_mov_b32 m0, s34
	ds_read_b128 v[232:235], v137 offset:53248
	buffer_load_dwordx4 v132, s[60:63], s95 offen lds
	s_mov_b32 m0, s35
	ds_read_b128 v[236:239], v137 offset:54272
	buffer_load_dwordx4 v134, s[60:63], s95 offen lds
	ds_read_b128 v[240:243], v137 offset:55296
	ds_read_b128 v[244:247], v137 offset:56320
	s_waitcnt vmcnt(8)
	s_waitcnt lgkmcnt(0)
	s_barrier
	v_mfma_f32_16x16x32_bf16 v[62:65], v[140:143], v[194:197], v[62:65]
	v_mfma_f32_16x16x32_bf16 v[62:65], v[154:157], v[198:201], v[62:65]
	v_mfma_f32_16x16x32_bf16 v[54:57], v[170:173], v[194:197], v[54:57]
	v_mfma_f32_16x16x32_bf16 v[54:57], v[174:177], v[198:201], v[54:57]
	v_mfma_f32_16x16x32_bf16 v[50:53], v[186:189], v[194:197], v[50:53]
	v_mfma_f32_16x16x32_bf16 v[50:53], v[190:193], v[198:201], v[50:53]
	v_mfma_f32_16x16x32_bf16 v[58:61], v[178:181], v[194:197], v[58:61]
	v_mfma_f32_16x16x32_bf16 v[58:61], v[182:185], v[198:201], v[58:61]
	v_mfma_f32_16x16x32_bf16 v[42:45], v[178:181], v[202:205], v[42:45]
	v_mfma_f32_16x16x32_bf16 v[42:45], v[182:185], v[228:231], v[42:45]
	v_mfma_f32_16x16x32_bf16 v[34:37], v[186:189], v[202:205], v[34:37]
	v_mfma_f32_16x16x32_bf16 v[34:37], v[190:193], v[228:231], v[34:37]
	v_mfma_f32_16x16x32_bf16 v[38:41], v[170:173], v[202:205], v[38:41]
	v_mfma_f32_16x16x32_bf16 v[38:41], v[174:177], v[228:231], v[38:41]
	v_mfma_f32_16x16x32_bf16 v[46:49], v[140:143], v[202:205], v[46:49]
	v_mfma_f32_16x16x32_bf16 v[46:49], v[154:157], v[228:231], v[46:49]
	v_mfma_f32_16x16x32_bf16 v[30:33], v[140:143], v[232:235], v[30:33]
	v_mfma_f32_16x16x32_bf16 v[30:33], v[154:157], v[236:239], v[30:33]
	v_mfma_f32_16x16x32_bf16 v[22:25], v[170:173], v[232:235], v[22:25]
	v_mfma_f32_16x16x32_bf16 v[22:25], v[174:177], v[236:239], v[22:25]
	v_mfma_f32_16x16x32_bf16 v[18:21], v[186:189], v[232:235], v[18:21]
	v_mfma_f32_16x16x32_bf16 v[18:21], v[190:193], v[236:239], v[18:21]
	v_mfma_f32_16x16x32_bf16 v[26:29], v[178:181], v[232:235], v[26:29]
	v_mfma_f32_16x16x32_bf16 v[26:29], v[182:185], v[236:239], v[26:29]
	v_mfma_f32_16x16x32_bf16 v[10:13], v[178:181], v[240:243], v[10:13]
	v_mfma_f32_16x16x32_bf16 v[10:13], v[182:185], v[244:247], v[10:13]
	v_mfma_f32_16x16x32_bf16 v[2:5], v[186:189], v[240:243], v[2:5]
	v_mfma_f32_16x16x32_bf16 v[2:5], v[190:193], v[244:247], v[2:5]
	v_mfma_f32_16x16x32_bf16 v[6:9], v[170:173], v[240:243], v[6:9]
	v_mfma_f32_16x16x32_bf16 v[6:9], v[174:177], v[244:247], v[6:9]
	v_mfma_f32_16x16x32_bf16 v[14:17], v[140:143], v[240:243], v[14:17]
	v_mfma_f32_16x16x32_bf16 v[14:17], v[154:157], v[244:247], v[14:17]
	s_barrier
	s_add_i32 s94, s94, 2
	s_addk_i32 vcc_lo, 0x100
	s_addk_i32 vcc_hi, 0x100
	s_cmp_gt_u32 s94, 29
.LBB0_1880:
	v_add_u32_e32 v139, 0x10000, v136
	ds_read_b128 v[140:143], v139
	ds_read_b128 v[154:157], v139 offset:1024
	ds_read_b128 v[170:173], v139 offset:2048
	ds_read_b128 v[174:177], v139 offset:3072
	v_add_u32_e32 v139, 0x14000, v136
	ds_read_b128 v[178:181], v139
	ds_read_b128 v[182:185], v139 offset:1024
	ds_read_b128 v[186:189], v139 offset:2048
	ds_read_b128 v[190:193], v139 offset:3072
	s_add_i32 s42, vcc_lo, 0xfff80080
	s_cmp_eq_u32 s94, 28
	s_cselect_b32 s52, s8, s42
	s_cselect_b32 s96, s9, vcc_hi
	s_or_b32 s95, s52, 0x80
	s_mov_b32 m0, s72
	ds_read_b128 v[194:197], v137
	ds_read_b128 v[198:201], v137 offset:1024
	ds_read_b128 v[202:205], v137 offset:2048
	ds_read_b128 v[228:231], v137 offset:3072
	ds_read_b128 v[232:235], v137 offset:4096
	ds_read_b128 v[236:239], v137 offset:5120
	ds_read_b128 v[240:243], v137 offset:6144
	ds_read_b128 v[244:247], v137 offset:7168
	buffer_load_dwordx4 v132, s[60:63], vcc_lo offen lds
	s_mov_b32 m0, s47
	s_nop 0
	buffer_load_dwordx4 v134, s[60:63], vcc_lo offen lds
	s_waitcnt vmcnt(8)
	s_waitcnt lgkmcnt(0)
	s_barrier
	v_mfma_f32_16x16x32_bf16 v[114:117], v[140:143], v[194:197], v[114:117]
	v_mfma_f32_16x16x32_bf16 v[114:117], v[154:157], v[198:201], v[114:117]
	v_mfma_f32_16x16x32_bf16 v[110:113], v[170:173], v[194:197], v[110:113]
	v_mfma_f32_16x16x32_bf16 v[110:113], v[174:177], v[198:201], v[110:113]
	v_mfma_f32_16x16x32_bf16 v[122:125], v[186:189], v[194:197], v[122:125]
	v_mfma_f32_16x16x32_bf16 v[122:125], v[190:193], v[198:201], v[122:125]
	v_mfma_f32_16x16x32_bf16 v[126:129], v[178:181], v[194:197], v[126:129]
	v_mfma_f32_16x16x32_bf16 v[126:129], v[182:185], v[198:201], v[126:129]
	v_mfma_f32_16x16x32_bf16 v[118:121], v[178:181], v[202:205], v[118:121]
	v_mfma_f32_16x16x32_bf16 v[118:121], v[182:185], v[228:231], v[118:121]
	v_mfma_f32_16x16x32_bf16 v[98:101], v[186:189], v[202:205], v[98:101]
	v_mfma_f32_16x16x32_bf16 v[98:101], v[190:193], v[228:231], v[98:101]
	v_mfma_f32_16x16x32_bf16 v[102:105], v[170:173], v[202:205], v[102:105]
	v_mfma_f32_16x16x32_bf16 v[102:105], v[174:177], v[228:231], v[102:105]
	v_mfma_f32_16x16x32_bf16 v[106:109], v[140:143], v[202:205], v[106:109]
	v_mfma_f32_16x16x32_bf16 v[106:109], v[154:157], v[228:231], v[106:109]
	v_mfma_f32_16x16x32_bf16 v[94:97], v[140:143], v[232:235], v[94:97]
	v_mfma_f32_16x16x32_bf16 v[94:97], v[154:157], v[236:239], v[94:97]
	v_mfma_f32_16x16x32_bf16 v[86:89], v[170:173], v[232:235], v[86:89]
	v_mfma_f32_16x16x32_bf16 v[86:89], v[174:177], v[236:239], v[86:89]
	v_mfma_f32_16x16x32_bf16 v[82:85], v[186:189], v[232:235], v[82:85]
	v_mfma_f32_16x16x32_bf16 v[82:85], v[190:193], v[236:239], v[82:85]
	v_mfma_f32_16x16x32_bf16 v[90:93], v[178:181], v[232:235], v[90:93]
	v_mfma_f32_16x16x32_bf16 v[90:93], v[182:185], v[236:239], v[90:93]
	v_mfma_f32_16x16x32_bf16 v[74:77], v[178:181], v[240:243], v[74:77]
	v_mfma_f32_16x16x32_bf16 v[74:77], v[182:185], v[244:247], v[74:77]
	v_mfma_f32_16x16x32_bf16 v[66:69], v[186:189], v[240:243], v[66:69]
	v_mfma_f32_16x16x32_bf16 v[66:69], v[190:193], v[244:247], v[66:69]
	v_mfma_f32_16x16x32_bf16 v[70:73], v[170:173], v[240:243], v[70:73]
	v_mfma_f32_16x16x32_bf16 v[70:73], v[174:177], v[244:247], v[70:73]
	v_mfma_f32_16x16x32_bf16 v[78:81], v[140:143], v[240:243], v[78:81]
	v_mfma_f32_16x16x32_bf16 v[78:81], v[154:157], v[244:247], v[78:81]
	s_barrier
	s_mov_b32 s42, s62
	s_mov_b32 s43, s63
	s_mov_b32 m0, s13
	ds_read_b128 v[194:197], v137 offset:16384
	buffer_load_dwordx4 v133, s[40:43], s96 offen lds
	s_add_i32 s53, s96, 0x80000
	s_mov_b32 m0, s14
	ds_read_b128 v[198:201], v137 offset:17408
	buffer_load_dwordx4 v135, s[40:43], s96 offen lds
	s_mov_b32 m0, s15
	ds_read_b128 v[202:205], v137 offset:18432
	buffer_load_dwordx4 v133, s[40:43], s53 offen lds
	s_mov_b32 m0, s16
	ds_read_b128 v[228:231], v137 offset:19456
	buffer_load_dwordx4 v135, s[40:43], s53 offen lds
	s_mov_b32 m0, s2
	ds_read_b128 v[232:235], v137 offset:20480
	buffer_load_dwordx4 v132, s[60:63], s52 offen lds
	s_mov_b32 m0, s21
	ds_read_b128 v[236:239], v137 offset:21504
	buffer_load_dwordx4 v134, s[60:63], s52 offen lds
	ds_read_b128 v[240:243], v137 offset:22528
	ds_read_b128 v[244:247], v137 offset:23552
	s_waitcnt vmcnt(8)
	s_waitcnt lgkmcnt(0)
	s_barrier
	v_mfma_f32_16x16x32_bf16 v[62:65], v[140:143], v[194:197], v[62:65]
	v_mfma_f32_16x16x32_bf16 v[62:65], v[154:157], v[198:201], v[62:65]
	v_mfma_f32_16x16x32_bf16 v[54:57], v[170:173], v[194:197], v[54:57]
	v_mfma_f32_16x16x32_bf16 v[54:57], v[174:177], v[198:201], v[54:57]
	v_mfma_f32_16x16x32_bf16 v[50:53], v[186:189], v[194:197], v[50:53]
	v_mfma_f32_16x16x32_bf16 v[50:53], v[190:193], v[198:201], v[50:53]
	v_mfma_f32_16x16x32_bf16 v[58:61], v[178:181], v[194:197], v[58:61]
	v_mfma_f32_16x16x32_bf16 v[58:61], v[182:185], v[198:201], v[58:61]
	v_mfma_f32_16x16x32_bf16 v[42:45], v[178:181], v[202:205], v[42:45]
	v_mfma_f32_16x16x32_bf16 v[42:45], v[182:185], v[228:231], v[42:45]
	v_mfma_f32_16x16x32_bf16 v[34:37], v[186:189], v[202:205], v[34:37]
	v_mfma_f32_16x16x32_bf16 v[34:37], v[190:193], v[228:231], v[34:37]
	v_mfma_f32_16x16x32_bf16 v[38:41], v[170:173], v[202:205], v[38:41]
	v_mfma_f32_16x16x32_bf16 v[38:41], v[174:177], v[228:231], v[38:41]
	v_mfma_f32_16x16x32_bf16 v[46:49], v[140:143], v[202:205], v[46:49]
	v_mfma_f32_16x16x32_bf16 v[46:49], v[154:157], v[228:231], v[46:49]
	v_mfma_f32_16x16x32_bf16 v[30:33], v[140:143], v[232:235], v[30:33]
	v_mfma_f32_16x16x32_bf16 v[30:33], v[154:157], v[236:239], v[30:33]
	v_mfma_f32_16x16x32_bf16 v[22:25], v[170:173], v[232:235], v[22:25]
	v_mfma_f32_16x16x32_bf16 v[22:25], v[174:177], v[236:239], v[22:25]
	v_mfma_f32_16x16x32_bf16 v[18:21], v[186:189], v[232:235], v[18:21]
	v_mfma_f32_16x16x32_bf16 v[18:21], v[190:193], v[236:239], v[18:21]
	v_mfma_f32_16x16x32_bf16 v[26:29], v[178:181], v[232:235], v[26:29]
	v_mfma_f32_16x16x32_bf16 v[26:29], v[182:185], v[236:239], v[26:29]
	v_mfma_f32_16x16x32_bf16 v[10:13], v[178:181], v[240:243], v[10:13]
	v_mfma_f32_16x16x32_bf16 v[10:13], v[182:185], v[244:247], v[10:13]
	v_mfma_f32_16x16x32_bf16 v[2:5], v[186:189], v[240:243], v[2:5]
	v_mfma_f32_16x16x32_bf16 v[2:5], v[190:193], v[244:247], v[2:5]
	v_mfma_f32_16x16x32_bf16 v[6:9], v[170:173], v[240:243], v[6:9]
	v_mfma_f32_16x16x32_bf16 v[6:9], v[174:177], v[244:247], v[6:9]
	v_mfma_f32_16x16x32_bf16 v[14:17], v[140:143], v[240:243], v[14:17]
	v_mfma_f32_16x16x32_bf16 v[14:17], v[154:157], v[244:247], v[14:17]
	s_barrier
	v_add_u32_e32 v139, 0x18000, v136
	ds_read_b128 v[140:143], v139
	ds_read_b128 v[154:157], v139 offset:1024
	ds_read_b128 v[170:173], v139 offset:2048
	ds_read_b128 v[174:177], v139 offset:3072
	v_add_u32_e32 v139, 0x1c000, v136
	ds_read_b128 v[178:181], v139
	ds_read_b128 v[182:185], v139 offset:1024
	ds_read_b128 v[186:189], v139 offset:2048
	ds_read_b128 v[190:193], v139 offset:3072
	s_add_i32 s52, s52, 0x80000
	s_mov_b32 m0, s23
	ds_read_b128 v[194:197], v137 offset:32768
	ds_read_b128 v[198:201], v137 offset:33792
	ds_read_b128 v[202:205], v137 offset:34816
	ds_read_b128 v[228:231], v137 offset:35840
	ds_read_b128 v[232:235], v137 offset:36864
	ds_read_b128 v[236:239], v137 offset:37888
	ds_read_b128 v[240:243], v137 offset:38912
	ds_read_b128 v[244:247], v137 offset:39936
	buffer_load_dwordx4 v132, s[60:63], s52 offen lds
	s_mov_b32 m0, s24
	s_nop 0
	buffer_load_dwordx4 v134, s[60:63], s52 offen lds
	s_waitcnt vmcnt(8)
	s_waitcnt lgkmcnt(0)
	s_barrier
	v_mfma_f32_16x16x32_bf16 v[114:117], v[140:143], v[194:197], v[114:117]
	v_mfma_f32_16x16x32_bf16 v[114:117], v[154:157], v[198:201], v[114:117]
	v_mfma_f32_16x16x32_bf16 v[110:113], v[170:173], v[194:197], v[110:113]
	v_mfma_f32_16x16x32_bf16 v[110:113], v[174:177], v[198:201], v[110:113]
	v_mfma_f32_16x16x32_bf16 v[122:125], v[186:189], v[194:197], v[122:125]
	v_mfma_f32_16x16x32_bf16 v[122:125], v[190:193], v[198:201], v[122:125]
	v_mfma_f32_16x16x32_bf16 v[126:129], v[178:181], v[194:197], v[126:129]
	v_mfma_f32_16x16x32_bf16 v[126:129], v[182:185], v[198:201], v[126:129]
	v_mfma_f32_16x16x32_bf16 v[118:121], v[178:181], v[202:205], v[118:121]
	v_mfma_f32_16x16x32_bf16 v[118:121], v[182:185], v[228:231], v[118:121]
	v_mfma_f32_16x16x32_bf16 v[98:101], v[186:189], v[202:205], v[98:101]
	v_mfma_f32_16x16x32_bf16 v[98:101], v[190:193], v[228:231], v[98:101]
	v_mfma_f32_16x16x32_bf16 v[102:105], v[170:173], v[202:205], v[102:105]
	v_mfma_f32_16x16x32_bf16 v[102:105], v[174:177], v[228:231], v[102:105]
	v_mfma_f32_16x16x32_bf16 v[106:109], v[140:143], v[202:205], v[106:109]
	v_mfma_f32_16x16x32_bf16 v[106:109], v[154:157], v[228:231], v[106:109]
	v_mfma_f32_16x16x32_bf16 v[94:97], v[140:143], v[232:235], v[94:97]
	v_mfma_f32_16x16x32_bf16 v[94:97], v[154:157], v[236:239], v[94:97]
	v_mfma_f32_16x16x32_bf16 v[86:89], v[170:173], v[232:235], v[86:89]
	v_mfma_f32_16x16x32_bf16 v[86:89], v[174:177], v[236:239], v[86:89]
	v_mfma_f32_16x16x32_bf16 v[82:85], v[186:189], v[232:235], v[82:85]
	v_mfma_f32_16x16x32_bf16 v[82:85], v[190:193], v[236:239], v[82:85]
	v_mfma_f32_16x16x32_bf16 v[90:93], v[178:181], v[232:235], v[90:93]
	v_mfma_f32_16x16x32_bf16 v[90:93], v[182:185], v[236:239], v[90:93]
	v_mfma_f32_16x16x32_bf16 v[74:77], v[178:181], v[240:243], v[74:77]
	v_mfma_f32_16x16x32_bf16 v[74:77], v[182:185], v[244:247], v[74:77]
	v_mfma_f32_16x16x32_bf16 v[66:69], v[186:189], v[240:243], v[66:69]
	v_mfma_f32_16x16x32_bf16 v[66:69], v[190:193], v[244:247], v[66:69]
	v_mfma_f32_16x16x32_bf16 v[70:73], v[170:173], v[240:243], v[70:73]
	v_mfma_f32_16x16x32_bf16 v[70:73], v[174:177], v[244:247], v[70:73]
	v_mfma_f32_16x16x32_bf16 v[78:81], v[140:143], v[240:243], v[78:81]
	v_mfma_f32_16x16x32_bf16 v[78:81], v[154:157], v[244:247], v[78:81]
	s_barrier
	s_or_b32 s52, s96, 0x80
	s_mov_b32 m0, s31
	ds_read_b128 v[194:197], v137 offset:49152
	buffer_load_dwordx4 v133, s[40:43], s52 offen lds
	s_add_i32 s96, s96, 0x80080
	s_mov_b32 m0, s33
	ds_read_b128 v[198:201], v137 offset:50176
	buffer_load_dwordx4 v135, s[40:43], s52 offen lds
	s_mov_b32 m0, s36
	ds_read_b128 v[202:205], v137 offset:51200
	buffer_load_dwordx4 v133, s[40:43], s96 offen lds
	s_mov_b32 m0, s37
	ds_read_b128 v[228:231], v137 offset:52224
	buffer_load_dwordx4 v135, s[40:43], s96 offen lds
	s_mov_b32 m0, s34
	ds_read_b128 v[232:235], v137 offset:53248
	buffer_load_dwordx4 v132, s[60:63], s95 offen lds
	s_mov_b32 m0, s35
	ds_read_b128 v[236:239], v137 offset:54272
	buffer_load_dwordx4 v134, s[60:63], s95 offen lds
	ds_read_b128 v[240:243], v137 offset:55296
	ds_read_b128 v[244:247], v137 offset:56320
	s_waitcnt vmcnt(8)
	s_waitcnt lgkmcnt(0)
	s_barrier
	v_mfma_f32_16x16x32_bf16 v[62:65], v[140:143], v[194:197], v[62:65]
	v_mfma_f32_16x16x32_bf16 v[62:65], v[154:157], v[198:201], v[62:65]
	v_mfma_f32_16x16x32_bf16 v[54:57], v[170:173], v[194:197], v[54:57]
	v_mfma_f32_16x16x32_bf16 v[54:57], v[174:177], v[198:201], v[54:57]
	v_mfma_f32_16x16x32_bf16 v[50:53], v[186:189], v[194:197], v[50:53]
	v_mfma_f32_16x16x32_bf16 v[50:53], v[190:193], v[198:201], v[50:53]
	v_mfma_f32_16x16x32_bf16 v[58:61], v[178:181], v[194:197], v[58:61]
	v_mfma_f32_16x16x32_bf16 v[58:61], v[182:185], v[198:201], v[58:61]
	v_mfma_f32_16x16x32_bf16 v[42:45], v[178:181], v[202:205], v[42:45]
	v_mfma_f32_16x16x32_bf16 v[42:45], v[182:185], v[228:231], v[42:45]
	v_mfma_f32_16x16x32_bf16 v[34:37], v[186:189], v[202:205], v[34:37]
	v_mfma_f32_16x16x32_bf16 v[34:37], v[190:193], v[228:231], v[34:37]
	v_mfma_f32_16x16x32_bf16 v[38:41], v[170:173], v[202:205], v[38:41]
	v_mfma_f32_16x16x32_bf16 v[38:41], v[174:177], v[228:231], v[38:41]
	v_mfma_f32_16x16x32_bf16 v[46:49], v[140:143], v[202:205], v[46:49]
	v_mfma_f32_16x16x32_bf16 v[46:49], v[154:157], v[228:231], v[46:49]
	v_mfma_f32_16x16x32_bf16 v[30:33], v[140:143], v[232:235], v[30:33]
	v_mfma_f32_16x16x32_bf16 v[30:33], v[154:157], v[236:239], v[30:33]
	v_mfma_f32_16x16x32_bf16 v[22:25], v[170:173], v[232:235], v[22:25]
	v_mfma_f32_16x16x32_bf16 v[22:25], v[174:177], v[236:239], v[22:25]
	v_mfma_f32_16x16x32_bf16 v[18:21], v[186:189], v[232:235], v[18:21]
	v_mfma_f32_16x16x32_bf16 v[18:21], v[190:193], v[236:239], v[18:21]
	v_mfma_f32_16x16x32_bf16 v[26:29], v[178:181], v[232:235], v[26:29]
	v_mfma_f32_16x16x32_bf16 v[26:29], v[182:185], v[236:239], v[26:29]
	v_mfma_f32_16x16x32_bf16 v[10:13], v[178:181], v[240:243], v[10:13]
	v_mfma_f32_16x16x32_bf16 v[10:13], v[182:185], v[244:247], v[10:13]
	v_mfma_f32_16x16x32_bf16 v[2:5], v[186:189], v[240:243], v[2:5]
	v_mfma_f32_16x16x32_bf16 v[2:5], v[190:193], v[244:247], v[2:5]
	v_mfma_f32_16x16x32_bf16 v[6:9], v[170:173], v[240:243], v[6:9]
	v_mfma_f32_16x16x32_bf16 v[6:9], v[174:177], v[244:247], v[6:9]
	v_mfma_f32_16x16x32_bf16 v[14:17], v[140:143], v[240:243], v[14:17]
	v_mfma_f32_16x16x32_bf16 v[14:17], v[154:157], v[244:247], v[14:17]
	s_barrier
	s_add_i32 s94, s94, 2
	s_addk_i32 vcc_lo, 0x100
	s_addk_i32 vcc_hi, 0x100
	s_cmp_gt_u32 s94, 29
	s_cbranch_scc0 .LBB0_1880
	s_and_b64 vcc, exec, s[64:65]
	s_cbranch_vccz .LBB0_1883
	s_barrier

.LBB0_2155:
	s_mul_i32 s49, s48, 0x2c0000
	s_and_b64 s[8:9], s[42:43], exec
	s_mul_i32 s23, s15, 0x2c0000
	s_cselect_b32 s8, s49, s21
	s_cselect_b32 s9, s23, s13
	s_addk_i32 s13, 0x100
	s_add_i32 s21, s21, 0xc000
	s_mov_b32 s22, -2
	s_waitcnt lgkmcnt(0)
	v_add_u32_e32 v170, 0x10000, v140
	v_add_u32_e32 v186, 0x14000, v140
	ds_read_b128 v[132:135], v170
	ds_read_b128 v[142:145], v170 offset:1024
	ds_read_b128 v[154:157], v170 offset:2048
	ds_read_b128 v[170:173], v170 offset:3072
	ds_read_b128 v[174:177], v186
	ds_read_b128 v[178:181], v186 offset:1024
	ds_read_b128 v[182:185], v186 offset:2048
	ds_read_b128 v[186:189], v186 offset:3072
	s_add_i32 s26, s21, 0x4000
	s_cmpk_eq_i32 s22, 0x54
	s_cselect_b32 s52, s8, s26
	s_cselect_b32 s27, s9, s13
	s_or_b32 s26, s52, 0x8000
	s_mov_b32 m0, s84
	ds_read_b128 v[190:193], v141
	ds_read_b128 v[194:197], v141 offset:1024
	ds_read_b128 v[198:201], v141 offset:2048
	ds_read_b128 v[202:205], v141 offset:3072
	ds_read_b128 v[228:231], v141 offset:4096
	ds_read_b128 v[232:235], v141 offset:5120
	ds_read_b128 v[236:239], v141 offset:6144
	ds_read_b128 v[240:243], v141 offset:7168
	buffer_load_dwordx4 v136, s[60:63], s21 offen lds
	s_mov_b32 m0, s16
	s_nop 0
	buffer_load_dwordx4 v138, s[60:63], s21 offen lds
	s_waitcnt vmcnt(8)
	s_waitcnt lgkmcnt(0)
	s_barrier
	v_mfma_f32_16x16x32_bf16 v[126:129], v[132:135], v[190:193], 0
	v_mfma_f32_16x16x32_bf16 v[126:129], v[142:145], v[194:197], v[126:129]
	v_mfma_f32_16x16x32_bf16 v[106:109], v[154:157], v[190:193], 0
	v_mfma_f32_16x16x32_bf16 v[106:109], v[170:173], v[194:197], v[106:109]
	v_mfma_f32_16x16x32_bf16 v[110:113], v[182:185], v[190:193], 0
	v_mfma_f32_16x16x32_bf16 v[110:113], v[186:189], v[194:197], v[110:113]
	v_mfma_f32_16x16x32_bf16 v[122:125], v[174:177], v[190:193], 0
	v_mfma_f32_16x16x32_bf16 v[122:125], v[178:181], v[194:197], v[122:125]
	v_mfma_f32_16x16x32_bf16 v[102:105], v[174:177], v[198:201], 0
	v_mfma_f32_16x16x32_bf16 v[102:105], v[178:181], v[202:205], v[102:105]
	v_mfma_f32_16x16x32_bf16 v[98:101], v[182:185], v[198:201], 0
	v_mfma_f32_16x16x32_bf16 v[98:101], v[186:189], v[202:205], v[98:101]
	v_mfma_f32_16x16x32_bf16 v[114:117], v[154:157], v[198:201], 0
	v_mfma_f32_16x16x32_bf16 v[114:117], v[170:173], v[202:205], v[114:117]
	v_mfma_f32_16x16x32_bf16 v[118:121], v[132:135], v[198:201], 0
	v_mfma_f32_16x16x32_bf16 v[118:121], v[142:145], v[202:205], v[118:121]
	v_mfma_f32_16x16x32_bf16 v[94:97], v[132:135], v[228:231], 0
	v_mfma_f32_16x16x32_bf16 v[94:97], v[142:145], v[232:235], v[94:97]
	v_mfma_f32_16x16x32_bf16 v[90:93], v[154:157], v[228:231], 0
	v_mfma_f32_16x16x32_bf16 v[90:93], v[170:173], v[232:235], v[90:93]
	v_mfma_f32_16x16x32_bf16 v[82:85], v[182:185], v[228:231], 0
	v_mfma_f32_16x16x32_bf16 v[82:85], v[186:189], v[232:235], v[82:85]
	v_mfma_f32_16x16x32_bf16 v[86:89], v[174:177], v[228:231], 0
	v_mfma_f32_16x16x32_bf16 v[86:89], v[178:181], v[232:235], v[86:89]
	v_mfma_f32_16x16x32_bf16 v[70:73], v[174:177], v[236:239], 0
	v_mfma_f32_16x16x32_bf16 v[70:73], v[178:181], v[240:243], v[70:73]
	v_mfma_f32_16x16x32_bf16 v[66:69], v[182:185], v[236:239], 0
	v_mfma_f32_16x16x32_bf16 v[66:69], v[186:189], v[240:243], v[66:69]
	v_mfma_f32_16x16x32_bf16 v[74:77], v[154:157], v[236:239], 0
	v_mfma_f32_16x16x32_bf16 v[74:77], v[170:173], v[240:243], v[74:77]
	v_mfma_f32_16x16x32_bf16 v[78:81], v[132:135], v[236:239], 0
	v_mfma_f32_16x16x32_bf16 v[78:81], v[142:145], v[240:243], v[78:81]
	s_barrier
	s_mov_b32 s46, s62
	s_mov_b32 s47, s63
	s_mov_b32 m0, s18
	ds_read_b128 v[190:193], v141 offset:16384
	buffer_load_dwordx4 v137, s[44:47], s27 offen lds
	s_add_i32 s53, s27, 0x160000
	s_mov_b32 m0, s19
	ds_read_b128 v[194:197], v141 offset:17408
	buffer_load_dwordx4 v139, s[44:47], s27 offen lds
	s_mov_b32 m0, s24
	ds_read_b128 v[198:201], v141 offset:18432
	buffer_load_dwordx4 v137, s[44:47], s53 offen lds
	s_mov_b32 m0, s25
	ds_read_b128 v[202:205], v141 offset:19456
	buffer_load_dwordx4 v139, s[44:47], s53 offen lds
	s_mov_b32 m0, s14
	ds_read_b128 v[228:231], v141 offset:20480
	buffer_load_dwordx4 v136, s[60:63], s52 offen lds
	s_mov_b32 m0, s30
	ds_read_b128 v[232:235], v141 offset:21504
	buffer_load_dwordx4 v138, s[60:63], s52 offen lds
	ds_read_b128 v[236:239], v141 offset:22528
	ds_read_b128 v[240:243], v141 offset:23552
	s_waitcnt vmcnt(8)
	s_waitcnt lgkmcnt(0)
	s_barrier
	v_mfma_f32_16x16x32_bf16 v[62:65], v[132:135], v[190:193], 0
	v_mfma_f32_16x16x32_bf16 v[62:65], v[142:145], v[194:197], v[62:65]
	v_mfma_f32_16x16x32_bf16 v[58:61], v[154:157], v[190:193], 0
	v_mfma_f32_16x16x32_bf16 v[58:61], v[170:173], v[194:197], v[58:61]
	v_mfma_f32_16x16x32_bf16 v[50:53], v[182:185], v[190:193], 0
	v_mfma_f32_16x16x32_bf16 v[50:53], v[186:189], v[194:197], v[50:53]
	v_mfma_f32_16x16x32_bf16 v[54:57], v[174:177], v[190:193], 0
	v_mfma_f32_16x16x32_bf16 v[54:57], v[178:181], v[194:197], v[54:57]
	v_mfma_f32_16x16x32_bf16 v[38:41], v[174:177], v[198:201], 0
	v_mfma_f32_16x16x32_bf16 v[38:41], v[178:181], v[202:205], v[38:41]
	v_mfma_f32_16x16x32_bf16 v[34:37], v[182:185], v[198:201], 0
	v_mfma_f32_16x16x32_bf16 v[34:37], v[186:189], v[202:205], v[34:37]
	v_mfma_f32_16x16x32_bf16 v[42:45], v[154:157], v[198:201], 0
	v_mfma_f32_16x16x32_bf16 v[42:45], v[170:173], v[202:205], v[42:45]
	v_mfma_f32_16x16x32_bf16 v[46:49], v[132:135], v[198:201], 0
	v_mfma_f32_16x16x32_bf16 v[46:49], v[142:145], v[202:205], v[46:49]
	v_mfma_f32_16x16x32_bf16 v[30:33], v[132:135], v[228:231], 0
	v_mfma_f32_16x16x32_bf16 v[30:33], v[142:145], v[232:235], v[30:33]
	v_mfma_f32_16x16x32_bf16 v[26:29], v[154:157], v[228:231], 0
	v_mfma_f32_16x16x32_bf16 v[26:29], v[170:173], v[232:235], v[26:29]
	v_mfma_f32_16x16x32_bf16 v[18:21], v[182:185], v[228:231], 0
	v_mfma_f32_16x16x32_bf16 v[18:21], v[186:189], v[232:235], v[18:21]
	v_mfma_f32_16x16x32_bf16 v[22:25], v[174:177], v[228:231], 0
	v_mfma_f32_16x16x32_bf16 v[22:25], v[178:181], v[232:235], v[22:25]
	v_mfma_f32_16x16x32_bf16 v[6:9], v[174:177], v[236:239], 0
	v_mfma_f32_16x16x32_bf16 v[6:9], v[178:181], v[240:243], v[6:9]
	v_mfma_f32_16x16x32_bf16 v[2:5], v[182:185], v[236:239], 0
	v_mfma_f32_16x16x32_bf16 v[2:5], v[186:189], v[240:243], v[2:5]
	v_mfma_f32_16x16x32_bf16 v[10:13], v[154:157], v[236:239], 0
	v_mfma_f32_16x16x32_bf16 v[10:13], v[170:173], v[240:243], v[10:13]
	v_mfma_f32_16x16x32_bf16 v[14:17], v[132:135], v[236:239], 0
	v_mfma_f32_16x16x32_bf16 v[14:17], v[142:145], v[240:243], v[14:17]
	s_barrier
	v_add_u32_e32 v170, 0x18000, v140
	v_add_u32_e32 v186, 0x1c000, v140
	ds_read_b128 v[132:135], v170
	ds_read_b128 v[142:145], v170 offset:1024
	ds_read_b128 v[154:157], v170 offset:2048
	ds_read_b128 v[170:173], v170 offset:3072
	ds_read_b128 v[174:177], v186
	ds_read_b128 v[178:181], v186 offset:1024
	ds_read_b128 v[182:185], v186 offset:2048
	ds_read_b128 v[186:189], v186 offset:3072
	s_bitset1_b32 s52, 14
	s_mov_b32 m0, s31
	ds_read_b128 v[190:193], v141 offset:32768
	ds_read_b128 v[194:197], v141 offset:33792
	ds_read_b128 v[198:201], v141 offset:34816
	ds_read_b128 v[202:205], v141 offset:35840
	ds_read_b128 v[228:231], v141 offset:36864
	ds_read_b128 v[232:235], v141 offset:37888
	ds_read_b128 v[236:239], v141 offset:38912
	ds_read_b128 v[240:243], v141 offset:39936
	buffer_load_dwordx4 v136, s[60:63], s52 offen lds
	s_mov_b32 m0, s33
	s_nop 0
	buffer_load_dwordx4 v138, s[60:63], s52 offen lds
	s_waitcnt vmcnt(8)
	s_waitcnt lgkmcnt(0)
	s_barrier
	v_mfma_f32_16x16x32_bf16 v[126:129], v[132:135], v[190:193], v[126:129]
	v_mfma_f32_16x16x32_bf16 v[126:129], v[142:145], v[194:197], v[126:129]
	v_mfma_f32_16x16x32_bf16 v[106:109], v[154:157], v[190:193], v[106:109]
	v_mfma_f32_16x16x32_bf16 v[106:109], v[170:173], v[194:197], v[106:109]
	v_mfma_f32_16x16x32_bf16 v[110:113], v[182:185], v[190:193], v[110:113]
	v_mfma_f32_16x16x32_bf16 v[110:113], v[186:189], v[194:197], v[110:113]
	v_mfma_f32_16x16x32_bf16 v[122:125], v[174:177], v[190:193], v[122:125]
	v_mfma_f32_16x16x32_bf16 v[122:125], v[178:181], v[194:197], v[122:125]
	v_mfma_f32_16x16x32_bf16 v[102:105], v[174:177], v[198:201], v[102:105]
	v_mfma_f32_16x16x32_bf16 v[102:105], v[178:181], v[202:205], v[102:105]
	v_mfma_f32_16x16x32_bf16 v[98:101], v[182:185], v[198:201], v[98:101]
	v_mfma_f32_16x16x32_bf16 v[98:101], v[186:189], v[202:205], v[98:101]
	v_mfma_f32_16x16x32_bf16 v[114:117], v[154:157], v[198:201], v[114:117]
	v_mfma_f32_16x16x32_bf16 v[114:117], v[170:173], v[202:205], v[114:117]
	v_mfma_f32_16x16x32_bf16 v[118:121], v[132:135], v[198:201], v[118:121]
	v_mfma_f32_16x16x32_bf16 v[118:121], v[142:145], v[202:205], v[118:121]
	v_mfma_f32_16x16x32_bf16 v[94:97], v[132:135], v[228:231], v[94:97]
	v_mfma_f32_16x16x32_bf16 v[94:97], v[142:145], v[232:235], v[94:97]
	v_mfma_f32_16x16x32_bf16 v[90:93], v[154:157], v[228:231], v[90:93]
	v_mfma_f32_16x16x32_bf16 v[90:93], v[170:173], v[232:235], v[90:93]
	v_mfma_f32_16x16x32_bf16 v[82:85], v[182:185], v[228:231], v[82:85]
	v_mfma_f32_16x16x32_bf16 v[82:85], v[186:189], v[232:235], v[82:85]
	v_mfma_f32_16x16x32_bf16 v[86:89], v[174:177], v[228:231], v[86:89]
	v_mfma_f32_16x16x32_bf16 v[86:89], v[178:181], v[232:235], v[86:89]
	v_mfma_f32_16x16x32_bf16 v[70:73], v[174:177], v[236:239], v[70:73]
	v_mfma_f32_16x16x32_bf16 v[70:73], v[178:181], v[240:243], v[70:73]
	v_mfma_f32_16x16x32_bf16 v[66:69], v[182:185], v[236:239], v[66:69]
	v_mfma_f32_16x16x32_bf16 v[66:69], v[186:189], v[240:243], v[66:69]
	v_mfma_f32_16x16x32_bf16 v[74:77], v[154:157], v[236:239], v[74:77]
	v_mfma_f32_16x16x32_bf16 v[74:77], v[170:173], v[240:243], v[74:77]
	v_mfma_f32_16x16x32_bf16 v[78:81], v[132:135], v[236:239], v[78:81]
	v_mfma_f32_16x16x32_bf16 v[78:81], v[142:145], v[240:243], v[78:81]
	s_barrier
	s_or_b32 s52, s27, 0x80
	s_mov_b32 m0, s68
	ds_read_b128 v[190:193], v141 offset:49152
	buffer_load_dwordx4 v137, s[44:47], s52 offen lds
	s_add_i32 s27, s27, 0x160080
	s_mov_b32 m0, s69
	ds_read_b128 v[194:197], v141 offset:50176
	buffer_load_dwordx4 v139, s[44:47], s52 offen lds
	s_mov_b32 m0, s72
	ds_read_b128 v[198:201], v141 offset:51200
	buffer_load_dwordx4 v137, s[44:47], s27 offen lds
	s_mov_b32 m0, s73
	ds_read_b128 v[202:205], v141 offset:52224
	buffer_load_dwordx4 v139, s[44:47], s27 offen lds
	s_mov_b32 m0, s70
	ds_read_b128 v[228:231], v141 offset:53248
	buffer_load_dwordx4 v136, s[60:63], s26 offen lds
	s_mov_b32 m0, s71
	ds_read_b128 v[232:235], v141 offset:54272
	buffer_load_dwordx4 v138, s[60:63], s26 offen lds
	ds_read_b128 v[236:239], v141 offset:55296
	ds_read_b128 v[240:243], v141 offset:56320
	s_waitcnt vmcnt(8)
	s_waitcnt lgkmcnt(0)
	s_barrier
	v_mfma_f32_16x16x32_bf16 v[62:65], v[132:135], v[190:193], v[62:65]
	v_mfma_f32_16x16x32_bf16 v[62:65], v[142:145], v[194:197], v[62:65]
	v_mfma_f32_16x16x32_bf16 v[58:61], v[154:157], v[190:193], v[58:61]
	v_mfma_f32_16x16x32_bf16 v[58:61], v[170:173], v[194:197], v[58:61]
	v_mfma_f32_16x16x32_bf16 v[50:53], v[182:185], v[190:193], v[50:53]
	v_mfma_f32_16x16x32_bf16 v[50:53], v[186:189], v[194:197], v[50:53]
	v_mfma_f32_16x16x32_bf16 v[54:57], v[174:177], v[190:193], v[54:57]
	v_mfma_f32_16x16x32_bf16 v[54:57], v[178:181], v[194:197], v[54:57]
	v_mfma_f32_16x16x32_bf16 v[38:41], v[174:177], v[198:201], v[38:41]
	v_mfma_f32_16x16x32_bf16 v[38:41], v[178:181], v[202:205], v[38:41]
	v_mfma_f32_16x16x32_bf16 v[34:37], v[182:185], v[198:201], v[34:37]
	v_mfma_f32_16x16x32_bf16 v[34:37], v[186:189], v[202:205], v[34:37]
	v_mfma_f32_16x16x32_bf16 v[42:45], v[154:157], v[198:201], v[42:45]
	v_mfma_f32_16x16x32_bf16 v[42:45], v[170:173], v[202:205], v[42:45]
	v_mfma_f32_16x16x32_bf16 v[46:49], v[132:135], v[198:201], v[46:49]
	v_mfma_f32_16x16x32_bf16 v[46:49], v[142:145], v[202:205], v[46:49]
	v_mfma_f32_16x16x32_bf16 v[30:33], v[132:135], v[228:231], v[30:33]
	v_mfma_f32_16x16x32_bf16 v[30:33], v[142:145], v[232:235], v[30:33]
	v_mfma_f32_16x16x32_bf16 v[26:29], v[154:157], v[228:231], v[26:29]
	v_mfma_f32_16x16x32_bf16 v[26:29], v[170:173], v[232:235], v[26:29]
	v_mfma_f32_16x16x32_bf16 v[18:21], v[182:185], v[228:231], v[18:21]
	v_mfma_f32_16x16x32_bf16 v[18:21], v[186:189], v[232:235], v[18:21]
	v_mfma_f32_16x16x32_bf16 v[22:25], v[174:177], v[228:231], v[22:25]
	v_mfma_f32_16x16x32_bf16 v[22:25], v[178:181], v[232:235], v[22:25]
	v_mfma_f32_16x16x32_bf16 v[6:9], v[174:177], v[236:239], v[6:9]
	v_mfma_f32_16x16x32_bf16 v[6:9], v[178:181], v[240:243], v[6:9]
	v_mfma_f32_16x16x32_bf16 v[2:5], v[182:185], v[236:239], v[2:5]
	v_mfma_f32_16x16x32_bf16 v[2:5], v[186:189], v[240:243], v[2:5]
	v_mfma_f32_16x16x32_bf16 v[10:13], v[154:157], v[236:239], v[10:13]
	v_mfma_f32_16x16x32_bf16 v[10:13], v[170:173], v[240:243], v[10:13]
	v_mfma_f32_16x16x32_bf16 v[14:17], v[132:135], v[236:239], v[14:17]
	v_mfma_f32_16x16x32_bf16 v[14:17], v[142:145], v[240:243], v[14:17]
	s_barrier
	s_addk_i32 s13, 0x100
	s_add_i32 s22, s22, 2
	s_add_i32 s21, s21, 0x10000
	s_cmpk_gt_u32 s22, 0x55
.LBB0_2156:
	v_add_u32_e32 v170, 0x10000, v140
	v_add_u32_e32 v186, 0x14000, v140
	ds_read_b128 v[132:135], v170
	ds_read_b128 v[142:145], v170 offset:1024
	ds_read_b128 v[154:157], v170 offset:2048
	ds_read_b128 v[170:173], v170 offset:3072
	ds_read_b128 v[174:177], v186
	ds_read_b128 v[178:181], v186 offset:1024
	ds_read_b128 v[182:185], v186 offset:2048
	ds_read_b128 v[186:189], v186 offset:3072
	s_add_i32 s26, s21, 0x4000
	s_cmpk_eq_i32 s22, 0x54
	s_cselect_b32 s52, s8, s26
	s_cselect_b32 s27, s9, s13
	s_or_b32 s26, s52, 0x8000
	s_mov_b32 m0, s84
	ds_read_b128 v[190:193], v141
	ds_read_b128 v[194:197], v141 offset:1024
	ds_read_b128 v[198:201], v141 offset:2048
	ds_read_b128 v[202:205], v141 offset:3072
	ds_read_b128 v[228:231], v141 offset:4096
	ds_read_b128 v[232:235], v141 offset:5120
	ds_read_b128 v[236:239], v141 offset:6144
	ds_read_b128 v[240:243], v141 offset:7168
	buffer_load_dwordx4 v136, s[60:63], s21 offen lds
	s_mov_b32 m0, s16
	s_nop 0
	buffer_load_dwordx4 v138, s[60:63], s21 offen lds
	s_waitcnt vmcnt(8)
	s_waitcnt lgkmcnt(0)
	s_barrier
	v_mfma_f32_16x16x32_bf16 v[126:129], v[132:135], v[190:193], v[126:129]
	v_mfma_f32_16x16x32_bf16 v[126:129], v[142:145], v[194:197], v[126:129]
	v_mfma_f32_16x16x32_bf16 v[106:109], v[154:157], v[190:193], v[106:109]
	v_mfma_f32_16x16x32_bf16 v[106:109], v[170:173], v[194:197], v[106:109]
	v_mfma_f32_16x16x32_bf16 v[110:113], v[182:185], v[190:193], v[110:113]
	v_mfma_f32_16x16x32_bf16 v[110:113], v[186:189], v[194:197], v[110:113]
	v_mfma_f32_16x16x32_bf16 v[122:125], v[174:177], v[190:193], v[122:125]
	v_mfma_f32_16x16x32_bf16 v[122:125], v[178:181], v[194:197], v[122:125]
	v_mfma_f32_16x16x32_bf16 v[102:105], v[174:177], v[198:201], v[102:105]
	v_mfma_f32_16x16x32_bf16 v[102:105], v[178:181], v[202:205], v[102:105]
	v_mfma_f32_16x16x32_bf16 v[98:101], v[182:185], v[198:201], v[98:101]
	v_mfma_f32_16x16x32_bf16 v[98:101], v[186:189], v[202:205], v[98:101]
	v_mfma_f32_16x16x32_bf16 v[114:117], v[154:157], v[198:201], v[114:117]
	v_mfma_f32_16x16x32_bf16 v[114:117], v[170:173], v[202:205], v[114:117]
	v_mfma_f32_16x16x32_bf16 v[118:121], v[132:135], v[198:201], v[118:121]
	v_mfma_f32_16x16x32_bf16 v[118:121], v[142:145], v[202:205], v[118:121]
	v_mfma_f32_16x16x32_bf16 v[94:97], v[132:135], v[228:231], v[94:97]
	v_mfma_f32_16x16x32_bf16 v[94:97], v[142:145], v[232:235], v[94:97]
	v_mfma_f32_16x16x32_bf16 v[90:93], v[154:157], v[228:231], v[90:93]
	v_mfma_f32_16x16x32_bf16 v[90:93], v[170:173], v[232:235], v[90:93]
	v_mfma_f32_16x16x32_bf16 v[82:85], v[182:185], v[228:231], v[82:85]
	v_mfma_f32_16x16x32_bf16 v[82:85], v[186:189], v[232:235], v[82:85]
	v_mfma_f32_16x16x32_bf16 v[86:89], v[174:177], v[228:231], v[86:89]
	v_mfma_f32_16x16x32_bf16 v[86:89], v[178:181], v[232:235], v[86:89]
	v_mfma_f32_16x16x32_bf16 v[70:73], v[174:177], v[236:239], v[70:73]
	v_mfma_f32_16x16x32_bf16 v[70:73], v[178:181], v[240:243], v[70:73]
	v_mfma_f32_16x16x32_bf16 v[66:69], v[182:185], v[236:239], v[66:69]
	v_mfma_f32_16x16x32_bf16 v[66:69], v[186:189], v[240:243], v[66:69]
	v_mfma_f32_16x16x32_bf16 v[74:77], v[154:157], v[236:239], v[74:77]
	v_mfma_f32_16x16x32_bf16 v[74:77], v[170:173], v[240:243], v[74:77]
	v_mfma_f32_16x16x32_bf16 v[78:81], v[132:135], v[236:239], v[78:81]
	v_mfma_f32_16x16x32_bf16 v[78:81], v[142:145], v[240:243], v[78:81]
	s_barrier
	s_mov_b32 s46, s62
	s_mov_b32 s47, s63
	s_mov_b32 m0, s18
	ds_read_b128 v[190:193], v141 offset:16384
	buffer_load_dwordx4 v137, s[44:47], s27 offen lds
	s_add_i32 s53, s27, 0x160000
	s_mov_b32 m0, s19
	ds_read_b128 v[194:197], v141 offset:17408
	buffer_load_dwordx4 v139, s[44:47], s27 offen lds
	s_mov_b32 m0, s24
	ds_read_b128 v[198:201], v141 offset:18432
	buffer_load_dwordx4 v137, s[44:47], s53 offen lds
	s_mov_b32 m0, s25
	ds_read_b128 v[202:205], v141 offset:19456
	buffer_load_dwordx4 v139, s[44:47], s53 offen lds
	s_mov_b32 m0, s14
	ds_read_b128 v[228:231], v141 offset:20480
	buffer_load_dwordx4 v136, s[60:63], s52 offen lds
	s_mov_b32 m0, s30
	ds_read_b128 v[232:235], v141 offset:21504
	buffer_load_dwordx4 v138, s[60:63], s52 offen lds
	ds_read_b128 v[236:239], v141 offset:22528
	ds_read_b128 v[240:243], v141 offset:23552
	s_waitcnt vmcnt(8)
	s_waitcnt lgkmcnt(0)
	s_barrier
	v_mfma_f32_16x16x32_bf16 v[62:65], v[132:135], v[190:193], v[62:65]
	v_mfma_f32_16x16x32_bf16 v[62:65], v[142:145], v[194:197], v[62:65]
	v_mfma_f32_16x16x32_bf16 v[58:61], v[154:157], v[190:193], v[58:61]
	v_mfma_f32_16x16x32_bf16 v[58:61], v[170:173], v[194:197], v[58:61]
	v_mfma_f32_16x16x32_bf16 v[50:53], v[182:185], v[190:193], v[50:53]
	v_mfma_f32_16x16x32_bf16 v[50:53], v[186:189], v[194:197], v[50:53]
	v_mfma_f32_16x16x32_bf16 v[54:57], v[174:177], v[190:193], v[54:57]
	v_mfma_f32_16x16x32_bf16 v[54:57], v[178:181], v[194:197], v[54:57]
	v_mfma_f32_16x16x32_bf16 v[38:41], v[174:177], v[198:201], v[38:41]
	v_mfma_f32_16x16x32_bf16 v[38:41], v[178:181], v[202:205], v[38:41]
	v_mfma_f32_16x16x32_bf16 v[34:37], v[182:185], v[198:201], v[34:37]
	v_mfma_f32_16x16x32_bf16 v[34:37], v[186:189], v[202:205], v[34:37]
	v_mfma_f32_16x16x32_bf16 v[42:45], v[154:157], v[198:201], v[42:45]
	v_mfma_f32_16x16x32_bf16 v[42:45], v[170:173], v[202:205], v[42:45]
	v_mfma_f32_16x16x32_bf16 v[46:49], v[132:135], v[198:201], v[46:49]
	v_mfma_f32_16x16x32_bf16 v[46:49], v[142:145], v[202:205], v[46:49]
	v_mfma_f32_16x16x32_bf16 v[30:33], v[132:135], v[228:231], v[30:33]
	v_mfma_f32_16x16x32_bf16 v[30:33], v[142:145], v[232:235], v[30:33]
	v_mfma_f32_16x16x32_bf16 v[26:29], v[154:157], v[228:231], v[26:29]
	v_mfma_f32_16x16x32_bf16 v[26:29], v[170:173], v[232:235], v[26:29]
	v_mfma_f32_16x16x32_bf16 v[18:21], v[182:185], v[228:231], v[18:21]
	v_mfma_f32_16x16x32_bf16 v[18:21], v[186:189], v[232:235], v[18:21]
	v_mfma_f32_16x16x32_bf16 v[22:25], v[174:177], v[228:231], v[22:25]
	v_mfma_f32_16x16x32_bf16 v[22:25], v[178:181], v[232:235], v[22:25]
	v_mfma_f32_16x16x32_bf16 v[6:9], v[174:177], v[236:239], v[6:9]
	v_mfma_f32_16x16x32_bf16 v[6:9], v[178:181], v[240:243], v[6:9]
	v_mfma_f32_16x16x32_bf16 v[2:5], v[182:185], v[236:239], v[2:5]
	v_mfma_f32_16x16x32_bf16 v[2:5], v[186:189], v[240:243], v[2:5]
	v_mfma_f32_16x16x32_bf16 v[10:13], v[154:157], v[236:239], v[10:13]
	v_mfma_f32_16x16x32_bf16 v[10:13], v[170:173], v[240:243], v[10:13]
	v_mfma_f32_16x16x32_bf16 v[14:17], v[132:135], v[236:239], v[14:17]
	v_mfma_f32_16x16x32_bf16 v[14:17], v[142:145], v[240:243], v[14:17]
	s_barrier
	v_add_u32_e32 v170, 0x18000, v140
	v_add_u32_e32 v186, 0x1c000, v140
	ds_read_b128 v[132:135], v170
	ds_read_b128 v[142:145], v170 offset:1024
	ds_read_b128 v[154:157], v170 offset:2048
	ds_read_b128 v[170:173], v170 offset:3072
	ds_read_b128 v[174:177], v186
	ds_read_b128 v[178:181], v186 offset:1024
	ds_read_b128 v[182:185], v186 offset:2048
	ds_read_b128 v[186:189], v186 offset:3072
	s_bitset1_b32 s52, 14
	s_mov_b32 m0, s31
	ds_read_b128 v[190:193], v141 offset:32768
	ds_read_b128 v[194:197], v141 offset:33792
	ds_read_b128 v[198:201], v141 offset:34816
	ds_read_b128 v[202:205], v141 offset:35840
	ds_read_b128 v[228:231], v141 offset:36864
	ds_read_b128 v[232:235], v141 offset:37888
	ds_read_b128 v[236:239], v141 offset:38912
	ds_read_b128 v[240:243], v141 offset:39936
	buffer_load_dwordx4 v136, s[60:63], s52 offen lds
	s_mov_b32 m0, s33
	s_nop 0
	buffer_load_dwordx4 v138, s[60:63], s52 offen lds
	s_waitcnt vmcnt(8)
	s_waitcnt lgkmcnt(0)
	s_barrier
	v_mfma_f32_16x16x32_bf16 v[126:129], v[132:135], v[190:193], v[126:129]
	v_mfma_f32_16x16x32_bf16 v[126:129], v[142:145], v[194:197], v[126:129]
	v_mfma_f32_16x16x32_bf16 v[106:109], v[154:157], v[190:193], v[106:109]
	v_mfma_f32_16x16x32_bf16 v[106:109], v[170:173], v[194:197], v[106:109]
	v_mfma_f32_16x16x32_bf16 v[110:113], v[182:185], v[190:193], v[110:113]
	v_mfma_f32_16x16x32_bf16 v[110:113], v[186:189], v[194:197], v[110:113]
	v_mfma_f32_16x16x32_bf16 v[122:125], v[174:177], v[190:193], v[122:125]
	v_mfma_f32_16x16x32_bf16 v[122:125], v[178:181], v[194:197], v[122:125]
	v_mfma_f32_16x16x32_bf16 v[102:105], v[174:177], v[198:201], v[102:105]
	v_mfma_f32_16x16x32_bf16 v[102:105], v[178:181], v[202:205], v[102:105]
	v_mfma_f32_16x16x32_bf16 v[98:101], v[182:185], v[198:201], v[98:101]
	v_mfma_f32_16x16x32_bf16 v[98:101], v[186:189], v[202:205], v[98:101]
	v_mfma_f32_16x16x32_bf16 v[114:117], v[154:157], v[198:201], v[114:117]
	v_mfma_f32_16x16x32_bf16 v[114:117], v[170:173], v[202:205], v[114:117]
	v_mfma_f32_16x16x32_bf16 v[118:121], v[132:135], v[198:201], v[118:121]
	v_mfma_f32_16x16x32_bf16 v[118:121], v[142:145], v[202:205], v[118:121]
	v_mfma_f32_16x16x32_bf16 v[94:97], v[132:135], v[228:231], v[94:97]
	v_mfma_f32_16x16x32_bf16 v[94:97], v[142:145], v[232:235], v[94:97]
	v_mfma_f32_16x16x32_bf16 v[90:93], v[154:157], v[228:231], v[90:93]
	v_mfma_f32_16x16x32_bf16 v[90:93], v[170:173], v[232:235], v[90:93]
	v_mfma_f32_16x16x32_bf16 v[82:85], v[182:185], v[228:231], v[82:85]
	v_mfma_f32_16x16x32_bf16 v[82:85], v[186:189], v[232:235], v[82:85]
	v_mfma_f32_16x16x32_bf16 v[86:89], v[174:177], v[228:231], v[86:89]
	v_mfma_f32_16x16x32_bf16 v[86:89], v[178:181], v[232:235], v[86:89]
	v_mfma_f32_16x16x32_bf16 v[70:73], v[174:177], v[236:239], v[70:73]
	v_mfma_f32_16x16x32_bf16 v[70:73], v[178:181], v[240:243], v[70:73]
	v_mfma_f32_16x16x32_bf16 v[66:69], v[182:185], v[236:239], v[66:69]
	v_mfma_f32_16x16x32_bf16 v[66:69], v[186:189], v[240:243], v[66:69]
	v_mfma_f32_16x16x32_bf16 v[74:77], v[154:157], v[236:239], v[74:77]
	v_mfma_f32_16x16x32_bf16 v[74:77], v[170:173], v[240:243], v[74:77]
	v_mfma_f32_16x16x32_bf16 v[78:81], v[132:135], v[236:239], v[78:81]
	v_mfma_f32_16x16x32_bf16 v[78:81], v[142:145], v[240:243], v[78:81]
	s_barrier
	s_or_b32 s52, s27, 0x80
	s_mov_b32 m0, s68
	ds_read_b128 v[190:193], v141 offset:49152
	buffer_load_dwordx4 v137, s[44:47], s52 offen lds
	s_add_i32 s27, s27, 0x160080
	s_mov_b32 m0, s69
	ds_read_b128 v[194:197], v141 offset:50176
	buffer_load_dwordx4 v139, s[44:47], s52 offen lds
	s_mov_b32 m0, s72
	ds_read_b128 v[198:201], v141 offset:51200
	buffer_load_dwordx4 v137, s[44:47], s27 offen lds
	s_mov_b32 m0, s73
	ds_read_b128 v[202:205], v141 offset:52224
	buffer_load_dwordx4 v139, s[44:47], s27 offen lds
	s_mov_b32 m0, s70
	ds_read_b128 v[228:231], v141 offset:53248
	buffer_load_dwordx4 v136, s[60:63], s26 offen lds
	s_mov_b32 m0, s71
	ds_read_b128 v[232:235], v141 offset:54272
	buffer_load_dwordx4 v138, s[60:63], s26 offen lds
	ds_read_b128 v[236:239], v141 offset:55296
	ds_read_b128 v[240:243], v141 offset:56320
	s_waitcnt vmcnt(8)
	s_waitcnt lgkmcnt(0)
	s_barrier
	v_mfma_f32_16x16x32_bf16 v[62:65], v[132:135], v[190:193], v[62:65]
	v_mfma_f32_16x16x32_bf16 v[62:65], v[142:145], v[194:197], v[62:65]
	v_mfma_f32_16x16x32_bf16 v[58:61], v[154:157], v[190:193], v[58:61]
	v_mfma_f32_16x16x32_bf16 v[58:61], v[170:173], v[194:197], v[58:61]
	v_mfma_f32_16x16x32_bf16 v[50:53], v[182:185], v[190:193], v[50:53]
	v_mfma_f32_16x16x32_bf16 v[50:53], v[186:189], v[194:197], v[50:53]
	v_mfma_f32_16x16x32_bf16 v[54:57], v[174:177], v[190:193], v[54:57]
	v_mfma_f32_16x16x32_bf16 v[54:57], v[178:181], v[194:197], v[54:57]
	v_mfma_f32_16x16x32_bf16 v[38:41], v[174:177], v[198:201], v[38:41]
	v_mfma_f32_16x16x32_bf16 v[38:41], v[178:181], v[202:205], v[38:41]
	v_mfma_f32_16x16x32_bf16 v[34:37], v[182:185], v[198:201], v[34:37]
	v_mfma_f32_16x16x32_bf16 v[34:37], v[186:189], v[202:205], v[34:37]
	v_mfma_f32_16x16x32_bf16 v[42:45], v[154:157], v[198:201], v[42:45]
	v_mfma_f32_16x16x32_bf16 v[42:45], v[170:173], v[202:205], v[42:45]
	v_mfma_f32_16x16x32_bf16 v[46:49], v[132:135], v[198:201], v[46:49]
	v_mfma_f32_16x16x32_bf16 v[46:49], v[142:145], v[202:205], v[46:49]
	v_mfma_f32_16x16x32_bf16 v[30:33], v[132:135], v[228:231], v[30:33]
	v_mfma_f32_16x16x32_bf16 v[30:33], v[142:145], v[232:235], v[30:33]
	v_mfma_f32_16x16x32_bf16 v[26:29], v[154:157], v[228:231], v[26:29]
	v_mfma_f32_16x16x32_bf16 v[26:29], v[170:173], v[232:235], v[26:29]
	v_mfma_f32_16x16x32_bf16 v[18:21], v[182:185], v[228:231], v[18:21]
	v_mfma_f32_16x16x32_bf16 v[18:21], v[186:189], v[232:235], v[18:21]
	v_mfma_f32_16x16x32_bf16 v[22:25], v[174:177], v[228:231], v[22:25]
	v_mfma_f32_16x16x32_bf16 v[22:25], v[178:181], v[232:235], v[22:25]
	v_mfma_f32_16x16x32_bf16 v[6:9], v[174:177], v[236:239], v[6:9]
	v_mfma_f32_16x16x32_bf16 v[6:9], v[178:181], v[240:243], v[6:9]
	v_mfma_f32_16x16x32_bf16 v[2:5], v[182:185], v[236:239], v[2:5]
	v_mfma_f32_16x16x32_bf16 v[2:5], v[186:189], v[240:243], v[2:5]
	v_mfma_f32_16x16x32_bf16 v[10:13], v[154:157], v[236:239], v[10:13]
	v_mfma_f32_16x16x32_bf16 v[10:13], v[170:173], v[240:243], v[10:13]
	v_mfma_f32_16x16x32_bf16 v[14:17], v[132:135], v[236:239], v[14:17]
	v_mfma_f32_16x16x32_bf16 v[14:17], v[142:145], v[240:243], v[14:17]
	s_barrier
	s_addk_i32 s13, 0x100
	s_add_i32 s22, s22, 2
	s_add_i32 s21, s21, 0x10000
	s_cmpk_gt_u32 s22, 0x55
	s_cbranch_scc0 .LBB0_2156
	s_and_b64 vcc, exec, s[66:67]
	s_cbranch_vccz .LBB0_2159
	s_barrier

.LBB0_2173:
	v_mov_b32_e32 v125, 0
	s_mul_i32 s69, s68, s12
	s_mul_i32 s70, s67, s12
	s_andn2_b64 vcc, exec, s[34:35]
	v_mov_b32_e32 v124, v125
	v_mov_b32_e32 v123, v125
	v_mov_b32_e32 v122, v125
	v_mov_b32_e32 v129, v125
	v_mov_b32_e32 v128, v125
	v_mov_b32_e32 v127, v125
	v_mov_b32_e32 v126, v125
	v_mov_b32_e32 v113, v125
	v_mov_b32_e32 v112, v125
	v_mov_b32_e32 v111, v125
	v_mov_b32_e32 v110, v125
	v_mov_b32_e32 v109, v125
	v_mov_b32_e32 v108, v125
	v_mov_b32_e32 v107, v125
	v_mov_b32_e32 v106, v125
	v_mov_b32_e32 v97, v125
	v_mov_b32_e32 v96, v125
	v_mov_b32_e32 v95, v125
	v_mov_b32_e32 v94, v125
	v_mov_b32_e32 v93, v125
	v_mov_b32_e32 v92, v125
	v_mov_b32_e32 v91, v125
	v_mov_b32_e32 v90, v125
	v_mov_b32_e32 v81, v125
	v_mov_b32_e32 v80, v125
	v_mov_b32_e32 v79, v125
	v_mov_b32_e32 v78, v125
	v_mov_b32_e32 v77, v125
	v_mov_b32_e32 v76, v125
	v_mov_b32_e32 v75, v125
	v_mov_b32_e32 v74, v125
	v_mov_b32_e32 v121, v125
	v_mov_b32_e32 v120, v125
	v_mov_b32_e32 v119, v125
	v_mov_b32_e32 v118, v125
	v_mov_b32_e32 v117, v125
	v_mov_b32_e32 v116, v125
	v_mov_b32_e32 v115, v125
	v_mov_b32_e32 v114, v125
	v_mov_b32_e32 v105, v125
	v_mov_b32_e32 v104, v125
	v_mov_b32_e32 v103, v125
	v_mov_b32_e32 v102, v125
	v_mov_b32_e32 v101, v125
	v_mov_b32_e32 v100, v125
	v_mov_b32_e32 v99, v125
	v_mov_b32_e32 v98, v125
	v_mov_b32_e32 v89, v125
	v_mov_b32_e32 v88, v125
	v_mov_b32_e32 v87, v125
	v_mov_b32_e32 v86, v125
	v_mov_b32_e32 v85, v125
	v_mov_b32_e32 v84, v125
	v_mov_b32_e32 v83, v125
	v_mov_b32_e32 v82, v125
	v_mov_b32_e32 v73, v125
	v_mov_b32_e32 v72, v125
	v_mov_b32_e32 v71, v125
	v_mov_b32_e32 v70, v125
	v_mov_b32_e32 v69, v125
	v_mov_b32_e32 v68, v125
	v_mov_b32_e32 v67, v125
	v_mov_b32_e32 v66, v125
	v_mov_b32_e32 v65, v125
	v_mov_b32_e32 v64, v125
	v_mov_b32_e32 v63, v125
	v_mov_b32_e32 v62, v125
	v_mov_b32_e32 v61, v125
	v_mov_b32_e32 v60, v125
	v_mov_b32_e32 v59, v125
	v_mov_b32_e32 v58, v125
	v_mov_b32_e32 v49, v125
	v_mov_b32_e32 v48, v125
	v_mov_b32_e32 v47, v125
	v_mov_b32_e32 v46, v125
	v_mov_b32_e32 v45, v125
	v_mov_b32_e32 v44, v125
	v_mov_b32_e32 v43, v125
	v_mov_b32_e32 v42, v125
	v_mov_b32_e32 v33, v125
	v_mov_b32_e32 v32, v125
	v_mov_b32_e32 v31, v125
	v_mov_b32_e32 v30, v125
	v_mov_b32_e32 v29, v125
	v_mov_b32_e32 v28, v125
	v_mov_b32_e32 v27, v125
	v_mov_b32_e32 v26, v125
	v_mov_b32_e32 v17, v125
	v_mov_b32_e32 v16, v125
	v_mov_b32_e32 v15, v125
	v_mov_b32_e32 v14, v125
	v_mov_b32_e32 v13, v125
	v_mov_b32_e32 v12, v125
	v_mov_b32_e32 v11, v125
	v_mov_b32_e32 v10, v125
	v_mov_b32_e32 v57, v125
	v_mov_b32_e32 v56, v125
	v_mov_b32_e32 v55, v125
	v_mov_b32_e32 v54, v125
	v_mov_b32_e32 v53, v125
	v_mov_b32_e32 v52, v125
	v_mov_b32_e32 v51, v125
	v_mov_b32_e32 v50, v125
	v_mov_b32_e32 v41, v125
	v_mov_b32_e32 v40, v125
	v_mov_b32_e32 v39, v125
	v_mov_b32_e32 v38, v125
	v_mov_b32_e32 v37, v125
	v_mov_b32_e32 v36, v125
	v_mov_b32_e32 v35, v125
	v_mov_b32_e32 v34, v125
	v_mov_b32_e32 v25, v125
	v_mov_b32_e32 v24, v125
	v_mov_b32_e32 v23, v125
	v_mov_b32_e32 v22, v125
	v_mov_b32_e32 v21, v125
	v_mov_b32_e32 v20, v125
	v_mov_b32_e32 v19, v125
	v_mov_b32_e32 v18, v125
	v_mov_b32_e32 v9, v125
	v_mov_b32_e32 v8, v125
	v_mov_b32_e32 v7, v125
	v_mov_b32_e32 v6, v125
	v_mov_b32_e32 v5, v125
	v_mov_b32_e32 v4, v125
	v_mov_b32_e32 v3, v125
	v_mov_b32_e32 v2, v125
	s_cbranch_vccnz .LBB0_2177
	s_and_b64 s[8:9], s[40:41], exec
	s_cselect_b32 s8, s69, s73
	s_cselect_b32 s9, s70, s82
	s_addk_i32 s73, 0x80
	s_addk_i32 s82, 0x100
	s_mov_b32 s83, 0
	v_add_u32_e32 v144, 0x10000, v134
	ds_read_b128 v[136:139], v144
	ds_read_b128 v[140:143], v144 offset:1024
	ds_read_b128 v[154:157], v144 offset:2048
	ds_read_b128 v[170:173], v144 offset:3072
	v_add_u32_e32 v144, 0x14000, v134
	ds_read_b128 v[174:177], v144
	ds_read_b128 v[178:181], v144 offset:1024
	ds_read_b128 v[182:185], v144 offset:2048
	ds_read_b128 v[186:189], v144 offset:3072
	s_add_i32 s46, s73, 0x80
	s_cmp_eq_u32 s49, s83
	s_cselect_b32 s52, s8, s46
	s_cselect_b32 s85, s9, s82
	s_add_i32 s84, s52, 0x80
	s_add_i32 s46, s2, s73
	s_mov_b32 m0, s64
	ds_read_b128 v[190:193], v135
	ds_read_b128 v[194:197], v135 offset:1024
	ds_read_b128 v[198:201], v135 offset:2048
	ds_read_b128 v[202:205], v135 offset:3072
	ds_read_b128 v[228:231], v135 offset:4096
	ds_read_b128 v[232:235], v135 offset:5120
	ds_read_b128 v[236:239], v135 offset:6144
	ds_read_b128 v[240:243], v135 offset:7168
	buffer_load_dwordx4 v130, s[60:63], s46 offen lds
	s_mov_b32 m0, s65
	s_nop 0
	buffer_load_dwordx4 v132, s[60:63], s46 offen lds
	s_waitcnt vmcnt(8)
	s_waitcnt lgkmcnt(0)
	s_barrier
	v_mfma_f32_16x16x32_bf16 v[122:125], v[136:139], v[190:193], 0
	v_mfma_f32_16x16x32_bf16 v[122:125], v[140:143], v[194:197], v[122:125]
	v_mfma_f32_16x16x32_bf16 v[126:129], v[154:157], v[190:193], 0
	v_mfma_f32_16x16x32_bf16 v[126:129], v[170:173], v[194:197], v[126:129]
	v_mfma_f32_16x16x32_bf16 v[114:117], v[182:185], v[190:193], 0
	v_mfma_f32_16x16x32_bf16 v[114:117], v[186:189], v[194:197], v[114:117]
	v_mfma_f32_16x16x32_bf16 v[118:121], v[174:177], v[190:193], 0
	v_mfma_f32_16x16x32_bf16 v[118:121], v[178:181], v[194:197], v[118:121]
	v_mfma_f32_16x16x32_bf16 v[102:105], v[174:177], v[198:201], 0
	v_mfma_f32_16x16x32_bf16 v[102:105], v[178:181], v[202:205], v[102:105]
	v_mfma_f32_16x16x32_bf16 v[98:101], v[182:185], v[198:201], 0
	v_mfma_f32_16x16x32_bf16 v[98:101], v[186:189], v[202:205], v[98:101]
	v_mfma_f32_16x16x32_bf16 v[106:109], v[154:157], v[198:201], 0
	v_mfma_f32_16x16x32_bf16 v[106:109], v[170:173], v[202:205], v[106:109]
	v_mfma_f32_16x16x32_bf16 v[110:113], v[136:139], v[198:201], 0
	v_mfma_f32_16x16x32_bf16 v[110:113], v[140:143], v[202:205], v[110:113]
	v_mfma_f32_16x16x32_bf16 v[94:97], v[136:139], v[228:231], 0
	v_mfma_f32_16x16x32_bf16 v[94:97], v[140:143], v[232:235], v[94:97]
	v_mfma_f32_16x16x32_bf16 v[90:93], v[154:157], v[228:231], 0
	v_mfma_f32_16x16x32_bf16 v[90:93], v[170:173], v[232:235], v[90:93]
	v_mfma_f32_16x16x32_bf16 v[82:85], v[182:185], v[228:231], 0
	v_mfma_f32_16x16x32_bf16 v[82:85], v[186:189], v[232:235], v[82:85]
	v_mfma_f32_16x16x32_bf16 v[86:89], v[174:177], v[228:231], 0
	v_mfma_f32_16x16x32_bf16 v[86:89], v[178:181], v[232:235], v[86:89]
	v_mfma_f32_16x16x32_bf16 v[70:73], v[174:177], v[236:239], 0
	v_mfma_f32_16x16x32_bf16 v[70:73], v[178:181], v[240:243], v[70:73]
	v_mfma_f32_16x16x32_bf16 v[66:69], v[182:185], v[236:239], 0
	v_mfma_f32_16x16x32_bf16 v[66:69], v[186:189], v[240:243], v[66:69]
	v_mfma_f32_16x16x32_bf16 v[74:77], v[154:157], v[236:239], 0
	v_mfma_f32_16x16x32_bf16 v[74:77], v[170:173], v[240:243], v[74:77]
	v_mfma_f32_16x16x32_bf16 v[78:81], v[136:139], v[236:239], 0
	v_mfma_f32_16x16x32_bf16 v[78:81], v[140:143], v[240:243], v[78:81]
	s_barrier
	s_mov_b32 s46, s62
	s_mov_b32 s47, s63
	s_mov_b32 m0, s14
	ds_read_b128 v[190:193], v135 offset:16384
	buffer_load_dwordx4 v131, s[44:47], s85 offen lds
	s_add_i32 s53, s85, s2
	s_mov_b32 m0, s15
	ds_read_b128 v[194:197], v135 offset:17408
	buffer_load_dwordx4 v133, s[44:47], s85 offen lds
	s_mov_b32 m0, s16
	ds_read_b128 v[198:201], v135 offset:18432
	buffer_load_dwordx4 v131, s[44:47], s53 offen lds
	s_mov_b32 m0, s18
	ds_read_b128 v[202:205], v135 offset:19456
	buffer_load_dwordx4 v133, s[44:47], s53 offen lds
	s_mov_b32 m0, s13
	ds_read_b128 v[228:231], v135 offset:20480
	buffer_load_dwordx4 v130, s[60:63], s52 offen lds
	s_mov_b32 m0, s19
	ds_read_b128 v[232:235], v135 offset:21504
	buffer_load_dwordx4 v132, s[60:63], s52 offen lds
	ds_read_b128 v[236:239], v135 offset:22528
	ds_read_b128 v[240:243], v135 offset:23552
	s_waitcnt vmcnt(8)
	s_waitcnt lgkmcnt(0)
	s_barrier
	v_mfma_f32_16x16x32_bf16 v[62:65], v[136:139], v[190:193], 0
	v_mfma_f32_16x16x32_bf16 v[62:65], v[140:143], v[194:197], v[62:65]
	v_mfma_f32_16x16x32_bf16 v[58:61], v[154:157], v[190:193], 0
	v_mfma_f32_16x16x32_bf16 v[58:61], v[170:173], v[194:197], v[58:61]
	v_mfma_f32_16x16x32_bf16 v[50:53], v[182:185], v[190:193], 0
	v_mfma_f32_16x16x32_bf16 v[50:53], v[186:189], v[194:197], v[50:53]
	v_mfma_f32_16x16x32_bf16 v[54:57], v[174:177], v[190:193], 0
	v_mfma_f32_16x16x32_bf16 v[54:57], v[178:181], v[194:197], v[54:57]
	v_mfma_f32_16x16x32_bf16 v[38:41], v[174:177], v[198:201], 0
	v_mfma_f32_16x16x32_bf16 v[38:41], v[178:181], v[202:205], v[38:41]
	v_mfma_f32_16x16x32_bf16 v[34:37], v[182:185], v[198:201], 0
	v_mfma_f32_16x16x32_bf16 v[34:37], v[186:189], v[202:205], v[34:37]
	v_mfma_f32_16x16x32_bf16 v[42:45], v[154:157], v[198:201], 0
	v_mfma_f32_16x16x32_bf16 v[42:45], v[170:173], v[202:205], v[42:45]
	v_mfma_f32_16x16x32_bf16 v[46:49], v[136:139], v[198:201], 0
	v_mfma_f32_16x16x32_bf16 v[46:49], v[140:143], v[202:205], v[46:49]
	v_mfma_f32_16x16x32_bf16 v[30:33], v[136:139], v[228:231], 0
	v_mfma_f32_16x16x32_bf16 v[30:33], v[140:143], v[232:235], v[30:33]
	v_mfma_f32_16x16x32_bf16 v[26:29], v[154:157], v[228:231], 0
	v_mfma_f32_16x16x32_bf16 v[26:29], v[170:173], v[232:235], v[26:29]
	v_mfma_f32_16x16x32_bf16 v[18:21], v[182:185], v[228:231], 0
	v_mfma_f32_16x16x32_bf16 v[18:21], v[186:189], v[232:235], v[18:21]
	v_mfma_f32_16x16x32_bf16 v[22:25], v[174:177], v[228:231], 0
	v_mfma_f32_16x16x32_bf16 v[22:25], v[178:181], v[232:235], v[22:25]
	v_mfma_f32_16x16x32_bf16 v[6:9], v[174:177], v[236:239], 0
	v_mfma_f32_16x16x32_bf16 v[6:9], v[178:181], v[240:243], v[6:9]
	v_mfma_f32_16x16x32_bf16 v[2:5], v[182:185], v[236:239], 0
	v_mfma_f32_16x16x32_bf16 v[2:5], v[186:189], v[240:243], v[2:5]
	v_mfma_f32_16x16x32_bf16 v[10:13], v[154:157], v[236:239], 0
	v_mfma_f32_16x16x32_bf16 v[10:13], v[170:173], v[240:243], v[10:13]
	v_mfma_f32_16x16x32_bf16 v[14:17], v[136:139], v[236:239], 0
	v_mfma_f32_16x16x32_bf16 v[14:17], v[140:143], v[240:243], v[14:17]
	s_barrier
	v_add_u32_e32 v144, 0x18000, v134
	ds_read_b128 v[136:139], v144
	ds_read_b128 v[140:143], v144 offset:1024
	ds_read_b128 v[154:157], v144 offset:2048
	ds_read_b128 v[170:173], v144 offset:3072
	v_add_u32_e32 v144, 0x1c000, v134
	ds_read_b128 v[174:177], v144
	ds_read_b128 v[178:181], v144 offset:1024
	ds_read_b128 v[182:185], v144 offset:2048
	ds_read_b128 v[186:189], v144 offset:3072
	s_add_i32 s52, s52, s2
	s_mov_b32 m0, s21
	ds_read_b128 v[190:193], v135 offset:32768
	ds_read_b128 v[194:197], v135 offset:33792
	ds_read_b128 v[198:201], v135 offset:34816
	ds_read_b128 v[202:205], v135 offset:35840
	ds_read_b128 v[228:231], v135 offset:36864
	ds_read_b128 v[232:235], v135 offset:37888
	ds_read_b128 v[236:239], v135 offset:38912
	ds_read_b128 v[240:243], v135 offset:39936
	buffer_load_dwordx4 v130, s[60:63], s52 offen lds
	s_mov_b32 m0, s22
	s_nop 0
	buffer_load_dwordx4 v132, s[60:63], s52 offen lds
	s_waitcnt vmcnt(8)
	s_waitcnt lgkmcnt(0)
	s_barrier
	v_mfma_f32_16x16x32_bf16 v[122:125], v[136:139], v[190:193], v[122:125]
	v_mfma_f32_16x16x32_bf16 v[122:125], v[140:143], v[194:197], v[122:125]
	v_mfma_f32_16x16x32_bf16 v[126:129], v[154:157], v[190:193], v[126:129]
	v_mfma_f32_16x16x32_bf16 v[126:129], v[170:173], v[194:197], v[126:129]
	v_mfma_f32_16x16x32_bf16 v[114:117], v[182:185], v[190:193], v[114:117]
	v_mfma_f32_16x16x32_bf16 v[114:117], v[186:189], v[194:197], v[114:117]
	v_mfma_f32_16x16x32_bf16 v[118:121], v[174:177], v[190:193], v[118:121]
	v_mfma_f32_16x16x32_bf16 v[118:121], v[178:181], v[194:197], v[118:121]
	v_mfma_f32_16x16x32_bf16 v[102:105], v[174:177], v[198:201], v[102:105]
	v_mfma_f32_16x16x32_bf16 v[102:105], v[178:181], v[202:205], v[102:105]
	v_mfma_f32_16x16x32_bf16 v[98:101], v[182:185], v[198:201], v[98:101]
	v_mfma_f32_16x16x32_bf16 v[98:101], v[186:189], v[202:205], v[98:101]
	v_mfma_f32_16x16x32_bf16 v[106:109], v[154:157], v[198:201], v[106:109]
	v_mfma_f32_16x16x32_bf16 v[106:109], v[170:173], v[202:205], v[106:109]
	v_mfma_f32_16x16x32_bf16 v[110:113], v[136:139], v[198:201], v[110:113]
	v_mfma_f32_16x16x32_bf16 v[110:113], v[140:143], v[202:205], v[110:113]
	v_mfma_f32_16x16x32_bf16 v[94:97], v[136:139], v[228:231], v[94:97]
	v_mfma_f32_16x16x32_bf16 v[94:97], v[140:143], v[232:235], v[94:97]
	v_mfma_f32_16x16x32_bf16 v[90:93], v[154:157], v[228:231], v[90:93]
	v_mfma_f32_16x16x32_bf16 v[90:93], v[170:173], v[232:235], v[90:93]
	v_mfma_f32_16x16x32_bf16 v[82:85], v[182:185], v[228:231], v[82:85]
	v_mfma_f32_16x16x32_bf16 v[82:85], v[186:189], v[232:235], v[82:85]
	v_mfma_f32_16x16x32_bf16 v[86:89], v[174:177], v[228:231], v[86:89]
	v_mfma_f32_16x16x32_bf16 v[86:89], v[178:181], v[232:235], v[86:89]
	v_mfma_f32_16x16x32_bf16 v[70:73], v[174:177], v[236:239], v[70:73]
	v_mfma_f32_16x16x32_bf16 v[70:73], v[178:181], v[240:243], v[70:73]
	v_mfma_f32_16x16x32_bf16 v[66:69], v[182:185], v[236:239], v[66:69]
	v_mfma_f32_16x16x32_bf16 v[66:69], v[186:189], v[240:243], v[66:69]
	v_mfma_f32_16x16x32_bf16 v[74:77], v[154:157], v[236:239], v[74:77]
	v_mfma_f32_16x16x32_bf16 v[74:77], v[170:173], v[240:243], v[74:77]
	v_mfma_f32_16x16x32_bf16 v[78:81], v[136:139], v[236:239], v[78:81]
	v_mfma_f32_16x16x32_bf16 v[78:81], v[140:143], v[240:243], v[78:81]
	s_barrier
	s_add_i32 s52, s85, 0x80
	s_mov_b32 m0, s33
	ds_read_b128 v[190:193], v135 offset:49152
	buffer_load_dwordx4 v131, s[44:47], s52 offen lds
	s_mov_b32 m0, s36
	ds_read_b128 v[194:197], v135 offset:50176
	buffer_load_dwordx4 v133, s[44:47], s52 offen lds
	s_add_i32 s52, s52, s2
	s_mov_b32 m0, s43
	ds_read_b128 v[198:201], v135 offset:51200
	buffer_load_dwordx4 v131, s[44:47], s52 offen lds
	s_mov_b32 m0, s48
	ds_read_b128 v[202:205], v135 offset:52224
	buffer_load_dwordx4 v133, s[44:47], s52 offen lds
	s_mov_b32 m0, s37
	ds_read_b128 v[228:231], v135 offset:53248
	buffer_load_dwordx4 v130, s[60:63], s84 offen lds
	s_mov_b32 m0, s42
	ds_read_b128 v[232:235], v135 offset:54272
	buffer_load_dwordx4 v132, s[60:63], s84 offen lds
	ds_read_b128 v[236:239], v135 offset:55296
	ds_read_b128 v[240:243], v135 offset:56320
	s_waitcnt vmcnt(8)
	s_waitcnt lgkmcnt(0)
	s_barrier
	v_mfma_f32_16x16x32_bf16 v[62:65], v[136:139], v[190:193], v[62:65]
	v_mfma_f32_16x16x32_bf16 v[62:65], v[140:143], v[194:197], v[62:65]
	v_mfma_f32_16x16x32_bf16 v[58:61], v[154:157], v[190:193], v[58:61]
	v_mfma_f32_16x16x32_bf16 v[58:61], v[170:173], v[194:197], v[58:61]
	v_mfma_f32_16x16x32_bf16 v[50:53], v[182:185], v[190:193], v[50:53]
	v_mfma_f32_16x16x32_bf16 v[50:53], v[186:189], v[194:197], v[50:53]
	v_mfma_f32_16x16x32_bf16 v[54:57], v[174:177], v[190:193], v[54:57]
	v_mfma_f32_16x16x32_bf16 v[54:57], v[178:181], v[194:197], v[54:57]
	v_mfma_f32_16x16x32_bf16 v[38:41], v[174:177], v[198:201], v[38:41]
	v_mfma_f32_16x16x32_bf16 v[38:41], v[178:181], v[202:205], v[38:41]
	v_mfma_f32_16x16x32_bf16 v[34:37], v[182:185], v[198:201], v[34:37]
	v_mfma_f32_16x16x32_bf16 v[34:37], v[186:189], v[202:205], v[34:37]
	v_mfma_f32_16x16x32_bf16 v[42:45], v[154:157], v[198:201], v[42:45]
	v_mfma_f32_16x16x32_bf16 v[42:45], v[170:173], v[202:205], v[42:45]
	v_mfma_f32_16x16x32_bf16 v[46:49], v[136:139], v[198:201], v[46:49]
	v_mfma_f32_16x16x32_bf16 v[46:49], v[140:143], v[202:205], v[46:49]
	v_mfma_f32_16x16x32_bf16 v[30:33], v[136:139], v[228:231], v[30:33]
	v_mfma_f32_16x16x32_bf16 v[30:33], v[140:143], v[232:235], v[30:33]
	v_mfma_f32_16x16x32_bf16 v[26:29], v[154:157], v[228:231], v[26:29]
	v_mfma_f32_16x16x32_bf16 v[26:29], v[170:173], v[232:235], v[26:29]
	v_mfma_f32_16x16x32_bf16 v[18:21], v[182:185], v[228:231], v[18:21]
	v_mfma_f32_16x16x32_bf16 v[18:21], v[186:189], v[232:235], v[18:21]
	v_mfma_f32_16x16x32_bf16 v[22:25], v[174:177], v[228:231], v[22:25]
	v_mfma_f32_16x16x32_bf16 v[22:25], v[178:181], v[232:235], v[22:25]
	v_mfma_f32_16x16x32_bf16 v[6:9], v[174:177], v[236:239], v[6:9]
	v_mfma_f32_16x16x32_bf16 v[6:9], v[178:181], v[240:243], v[6:9]
	v_mfma_f32_16x16x32_bf16 v[2:5], v[182:185], v[236:239], v[2:5]
	v_mfma_f32_16x16x32_bf16 v[2:5], v[186:189], v[240:243], v[2:5]
	v_mfma_f32_16x16x32_bf16 v[10:13], v[154:157], v[236:239], v[10:13]
	v_mfma_f32_16x16x32_bf16 v[10:13], v[170:173], v[240:243], v[10:13]
	v_mfma_f32_16x16x32_bf16 v[14:17], v[136:139], v[236:239], v[14:17]
	v_mfma_f32_16x16x32_bf16 v[14:17], v[140:143], v[240:243], v[14:17]
	s_barrier
	s_add_i32 s83, s83, 2
	s_addk_i32 s73, 0x100
	s_addk_i32 s82, 0x100
	s_cmp_ge_i32 s83, s23
.LBB0_2175:
	v_add_u32_e32 v144, 0x10000, v134
	ds_read_b128 v[136:139], v144
	ds_read_b128 v[140:143], v144 offset:1024
	ds_read_b128 v[154:157], v144 offset:2048
	ds_read_b128 v[170:173], v144 offset:3072
	v_add_u32_e32 v144, 0x14000, v134
	ds_read_b128 v[174:177], v144
	ds_read_b128 v[178:181], v144 offset:1024
	ds_read_b128 v[182:185], v144 offset:2048
	ds_read_b128 v[186:189], v144 offset:3072
	s_add_i32 s46, s73, 0x80
	s_cmp_eq_u32 s49, s83
	s_cselect_b32 s52, s8, s46
	s_cselect_b32 s85, s9, s82
	s_add_i32 s84, s52, 0x80
	s_add_i32 s46, s2, s73
	s_mov_b32 m0, s64
	ds_read_b128 v[190:193], v135
	ds_read_b128 v[194:197], v135 offset:1024
	ds_read_b128 v[198:201], v135 offset:2048
	ds_read_b128 v[202:205], v135 offset:3072
	ds_read_b128 v[228:231], v135 offset:4096
	ds_read_b128 v[232:235], v135 offset:5120
	ds_read_b128 v[236:239], v135 offset:6144
	ds_read_b128 v[240:243], v135 offset:7168
	buffer_load_dwordx4 v130, s[60:63], s46 offen lds
	s_mov_b32 m0, s65
	s_nop 0
	buffer_load_dwordx4 v132, s[60:63], s46 offen lds
	s_waitcnt vmcnt(8)
	s_waitcnt lgkmcnt(0)
	s_barrier
	v_mfma_f32_16x16x32_bf16 v[122:125], v[136:139], v[190:193], v[122:125]
	v_mfma_f32_16x16x32_bf16 v[122:125], v[140:143], v[194:197], v[122:125]
	v_mfma_f32_16x16x32_bf16 v[126:129], v[154:157], v[190:193], v[126:129]
	v_mfma_f32_16x16x32_bf16 v[126:129], v[170:173], v[194:197], v[126:129]
	v_mfma_f32_16x16x32_bf16 v[114:117], v[182:185], v[190:193], v[114:117]
	v_mfma_f32_16x16x32_bf16 v[114:117], v[186:189], v[194:197], v[114:117]
	v_mfma_f32_16x16x32_bf16 v[118:121], v[174:177], v[190:193], v[118:121]
	v_mfma_f32_16x16x32_bf16 v[118:121], v[178:181], v[194:197], v[118:121]
	v_mfma_f32_16x16x32_bf16 v[102:105], v[174:177], v[198:201], v[102:105]
	v_mfma_f32_16x16x32_bf16 v[102:105], v[178:181], v[202:205], v[102:105]
	v_mfma_f32_16x16x32_bf16 v[98:101], v[182:185], v[198:201], v[98:101]
	v_mfma_f32_16x16x32_bf16 v[98:101], v[186:189], v[202:205], v[98:101]
	v_mfma_f32_16x16x32_bf16 v[106:109], v[154:157], v[198:201], v[106:109]
	v_mfma_f32_16x16x32_bf16 v[106:109], v[170:173], v[202:205], v[106:109]
	v_mfma_f32_16x16x32_bf16 v[110:113], v[136:139], v[198:201], v[110:113]
	v_mfma_f32_16x16x32_bf16 v[110:113], v[140:143], v[202:205], v[110:113]
	v_mfma_f32_16x16x32_bf16 v[94:97], v[136:139], v[228:231], v[94:97]
	v_mfma_f32_16x16x32_bf16 v[94:97], v[140:143], v[232:235], v[94:97]
	v_mfma_f32_16x16x32_bf16 v[90:93], v[154:157], v[228:231], v[90:93]
	v_mfma_f32_16x16x32_bf16 v[90:93], v[170:173], v[232:235], v[90:93]
	v_mfma_f32_16x16x32_bf16 v[82:85], v[182:185], v[228:231], v[82:85]
	v_mfma_f32_16x16x32_bf16 v[82:85], v[186:189], v[232:235], v[82:85]
	v_mfma_f32_16x16x32_bf16 v[86:89], v[174:177], v[228:231], v[86:89]
	v_mfma_f32_16x16x32_bf16 v[86:89], v[178:181], v[232:235], v[86:89]
	v_mfma_f32_16x16x32_bf16 v[70:73], v[174:177], v[236:239], v[70:73]
	v_mfma_f32_16x16x32_bf16 v[70:73], v[178:181], v[240:243], v[70:73]
	v_mfma_f32_16x16x32_bf16 v[66:69], v[182:185], v[236:239], v[66:69]
	v_mfma_f32_16x16x32_bf16 v[66:69], v[186:189], v[240:243], v[66:69]
	v_mfma_f32_16x16x32_bf16 v[74:77], v[154:157], v[236:239], v[74:77]
	v_mfma_f32_16x16x32_bf16 v[74:77], v[170:173], v[240:243], v[74:77]
	v_mfma_f32_16x16x32_bf16 v[78:81], v[136:139], v[236:239], v[78:81]
	v_mfma_f32_16x16x32_bf16 v[78:81], v[140:143], v[240:243], v[78:81]
	s_barrier
	s_mov_b32 s46, s62
	s_mov_b32 s47, s63
	s_mov_b32 m0, s14
	ds_read_b128 v[190:193], v135 offset:16384
	buffer_load_dwordx4 v131, s[44:47], s85 offen lds
	s_add_i32 s53, s85, s2
	s_mov_b32 m0, s15
	ds_read_b128 v[194:197], v135 offset:17408
	buffer_load_dwordx4 v133, s[44:47], s85 offen lds
	s_mov_b32 m0, s16
	ds_read_b128 v[198:201], v135 offset:18432
	buffer_load_dwordx4 v131, s[44:47], s53 offen lds
	s_mov_b32 m0, s18
	ds_read_b128 v[202:205], v135 offset:19456
	buffer_load_dwordx4 v133, s[44:47], s53 offen lds
	s_mov_b32 m0, s13
	ds_read_b128 v[228:231], v135 offset:20480
	buffer_load_dwordx4 v130, s[60:63], s52 offen lds
	s_mov_b32 m0, s19
	ds_read_b128 v[232:235], v135 offset:21504
	buffer_load_dwordx4 v132, s[60:63], s52 offen lds
	ds_read_b128 v[236:239], v135 offset:22528
	ds_read_b128 v[240:243], v135 offset:23552
	s_waitcnt vmcnt(8)
	s_waitcnt lgkmcnt(0)
	s_barrier
	v_mfma_f32_16x16x32_bf16 v[62:65], v[136:139], v[190:193], v[62:65]
	v_mfma_f32_16x16x32_bf16 v[62:65], v[140:143], v[194:197], v[62:65]
	v_mfma_f32_16x16x32_bf16 v[58:61], v[154:157], v[190:193], v[58:61]
	v_mfma_f32_16x16x32_bf16 v[58:61], v[170:173], v[194:197], v[58:61]
	v_mfma_f32_16x16x32_bf16 v[50:53], v[182:185], v[190:193], v[50:53]
	v_mfma_f32_16x16x32_bf16 v[50:53], v[186:189], v[194:197], v[50:53]
	v_mfma_f32_16x16x32_bf16 v[54:57], v[174:177], v[190:193], v[54:57]
	v_mfma_f32_16x16x32_bf16 v[54:57], v[178:181], v[194:197], v[54:57]
	v_mfma_f32_16x16x32_bf16 v[38:41], v[174:177], v[198:201], v[38:41]
	v_mfma_f32_16x16x32_bf16 v[38:41], v[178:181], v[202:205], v[38:41]
	v_mfma_f32_16x16x32_bf16 v[34:37], v[182:185], v[198:201], v[34:37]
	v_mfma_f32_16x16x32_bf16 v[34:37], v[186:189], v[202:205], v[34:37]
	v_mfma_f32_16x16x32_bf16 v[42:45], v[154:157], v[198:201], v[42:45]
	v_mfma_f32_16x16x32_bf16 v[42:45], v[170:173], v[202:205], v[42:45]
	v_mfma_f32_16x16x32_bf16 v[46:49], v[136:139], v[198:201], v[46:49]
	v_mfma_f32_16x16x32_bf16 v[46:49], v[140:143], v[202:205], v[46:49]
	v_mfma_f32_16x16x32_bf16 v[30:33], v[136:139], v[228:231], v[30:33]
	v_mfma_f32_16x16x32_bf16 v[30:33], v[140:143], v[232:235], v[30:33]
	v_mfma_f32_16x16x32_bf16 v[26:29], v[154:157], v[228:231], v[26:29]
	v_mfma_f32_16x16x32_bf16 v[26:29], v[170:173], v[232:235], v[26:29]
	v_mfma_f32_16x16x32_bf16 v[18:21], v[182:185], v[228:231], v[18:21]
	v_mfma_f32_16x16x32_bf16 v[18:21], v[186:189], v[232:235], v[18:21]
	v_mfma_f32_16x16x32_bf16 v[22:25], v[174:177], v[228:231], v[22:25]
	v_mfma_f32_16x16x32_bf16 v[22:25], v[178:181], v[232:235], v[22:25]
	v_mfma_f32_16x16x32_bf16 v[6:9], v[174:177], v[236:239], v[6:9]
	v_mfma_f32_16x16x32_bf16 v[6:9], v[178:181], v[240:243], v[6:9]
	v_mfma_f32_16x16x32_bf16 v[2:5], v[182:185], v[236:239], v[2:5]
	v_mfma_f32_16x16x32_bf16 v[2:5], v[186:189], v[240:243], v[2:5]
	v_mfma_f32_16x16x32_bf16 v[10:13], v[154:157], v[236:239], v[10:13]
	v_mfma_f32_16x16x32_bf16 v[10:13], v[170:173], v[240:243], v[10:13]
	v_mfma_f32_16x16x32_bf16 v[14:17], v[136:139], v[236:239], v[14:17]
	v_mfma_f32_16x16x32_bf16 v[14:17], v[140:143], v[240:243], v[14:17]
	s_barrier
	v_add_u32_e32 v144, 0x18000, v134
	ds_read_b128 v[136:139], v144
	ds_read_b128 v[140:143], v144 offset:1024
	ds_read_b128 v[154:157], v144 offset:2048
	ds_read_b128 v[170:173], v144 offset:3072
	v_add_u32_e32 v144, 0x1c000, v134
	ds_read_b128 v[174:177], v144
	ds_read_b128 v[178:181], v144 offset:1024
	ds_read_b128 v[182:185], v144 offset:2048
	ds_read_b128 v[186:189], v144 offset:3072
	s_add_i32 s52, s52, s2
	s_mov_b32 m0, s21
	ds_read_b128 v[190:193], v135 offset:32768
	ds_read_b128 v[194:197], v135 offset:33792
	ds_read_b128 v[198:201], v135 offset:34816
	ds_read_b128 v[202:205], v135 offset:35840
	ds_read_b128 v[228:231], v135 offset:36864
	ds_read_b128 v[232:235], v135 offset:37888
	ds_read_b128 v[236:239], v135 offset:38912
	ds_read_b128 v[240:243], v135 offset:39936
	buffer_load_dwordx4 v130, s[60:63], s52 offen lds
	s_mov_b32 m0, s22
	s_nop 0
	buffer_load_dwordx4 v132, s[60:63], s52 offen lds
	s_waitcnt vmcnt(8)
	s_waitcnt lgkmcnt(0)
	s_barrier
	v_mfma_f32_16x16x32_bf16 v[122:125], v[136:139], v[190:193], v[122:125]
	v_mfma_f32_16x16x32_bf16 v[122:125], v[140:143], v[194:197], v[122:125]
	v_mfma_f32_16x16x32_bf16 v[126:129], v[154:157], v[190:193], v[126:129]
	v_mfma_f32_16x16x32_bf16 v[126:129], v[170:173], v[194:197], v[126:129]
	v_mfma_f32_16x16x32_bf16 v[114:117], v[182:185], v[190:193], v[114:117]
	v_mfma_f32_16x16x32_bf16 v[114:117], v[186:189], v[194:197], v[114:117]
	v_mfma_f32_16x16x32_bf16 v[118:121], v[174:177], v[190:193], v[118:121]
	v_mfma_f32_16x16x32_bf16 v[118:121], v[178:181], v[194:197], v[118:121]
	v_mfma_f32_16x16x32_bf16 v[102:105], v[174:177], v[198:201], v[102:105]
	v_mfma_f32_16x16x32_bf16 v[102:105], v[178:181], v[202:205], v[102:105]
	v_mfma_f32_16x16x32_bf16 v[98:101], v[182:185], v[198:201], v[98:101]
	v_mfma_f32_16x16x32_bf16 v[98:101], v[186:189], v[202:205], v[98:101]
	v_mfma_f32_16x16x32_bf16 v[106:109], v[154:157], v[198:201], v[106:109]
	v_mfma_f32_16x16x32_bf16 v[106:109], v[170:173], v[202:205], v[106:109]
	v_mfma_f32_16x16x32_bf16 v[110:113], v[136:139], v[198:201], v[110:113]
	v_mfma_f32_16x16x32_bf16 v[110:113], v[140:143], v[202:205], v[110:113]
	v_mfma_f32_16x16x32_bf16 v[94:97], v[136:139], v[228:231], v[94:97]
	v_mfma_f32_16x16x32_bf16 v[94:97], v[140:143], v[232:235], v[94:97]
	v_mfma_f32_16x16x32_bf16 v[90:93], v[154:157], v[228:231], v[90:93]
	v_mfma_f32_16x16x32_bf16 v[90:93], v[170:173], v[232:235], v[90:93]
	v_mfma_f32_16x16x32_bf16 v[82:85], v[182:185], v[228:231], v[82:85]
	v_mfma_f32_16x16x32_bf16 v[82:85], v[186:189], v[232:235], v[82:85]
	v_mfma_f32_16x16x32_bf16 v[86:89], v[174:177], v[228:231], v[86:89]
	v_mfma_f32_16x16x32_bf16 v[86:89], v[178:181], v[232:235], v[86:89]
	v_mfma_f32_16x16x32_bf16 v[70:73], v[174:177], v[236:239], v[70:73]
	v_mfma_f32_16x16x32_bf16 v[70:73], v[178:181], v[240:243], v[70:73]
	v_mfma_f32_16x16x32_bf16 v[66:69], v[182:185], v[236:239], v[66:69]
	v_mfma_f32_16x16x32_bf16 v[66:69], v[186:189], v[240:243], v[66:69]
	v_mfma_f32_16x16x32_bf16 v[74:77], v[154:157], v[236:239], v[74:77]
	v_mfma_f32_16x16x32_bf16 v[74:77], v[170:173], v[240:243], v[74:77]
	v_mfma_f32_16x16x32_bf16 v[78:81], v[136:139], v[236:239], v[78:81]
	v_mfma_f32_16x16x32_bf16 v[78:81], v[140:143], v[240:243], v[78:81]
	s_barrier
	s_add_i32 s52, s85, 0x80
	s_mov_b32 m0, s33
	ds_read_b128 v[190:193], v135 offset:49152
	buffer_load_dwordx4 v131, s[44:47], s52 offen lds
	s_mov_b32 m0, s36
	ds_read_b128 v[194:197], v135 offset:50176
	buffer_load_dwordx4 v133, s[44:47], s52 offen lds
	s_add_i32 s52, s52, s2
	s_mov_b32 m0, s43
	ds_read_b128 v[198:201], v135 offset:51200
	buffer_load_dwordx4 v131, s[44:47], s52 offen lds
	s_mov_b32 m0, s48
	ds_read_b128 v[202:205], v135 offset:52224
	buffer_load_dwordx4 v133, s[44:47], s52 offen lds
	s_mov_b32 m0, s37
	ds_read_b128 v[228:231], v135 offset:53248
	buffer_load_dwordx4 v130, s[60:63], s84 offen lds
	s_mov_b32 m0, s42
	ds_read_b128 v[232:235], v135 offset:54272
	buffer_load_dwordx4 v132, s[60:63], s84 offen lds
	ds_read_b128 v[236:239], v135 offset:55296
	ds_read_b128 v[240:243], v135 offset:56320
	s_waitcnt vmcnt(8)
	s_waitcnt lgkmcnt(0)
	s_barrier
	v_mfma_f32_16x16x32_bf16 v[62:65], v[136:139], v[190:193], v[62:65]
	v_mfma_f32_16x16x32_bf16 v[62:65], v[140:143], v[194:197], v[62:65]
	v_mfma_f32_16x16x32_bf16 v[58:61], v[154:157], v[190:193], v[58:61]
	v_mfma_f32_16x16x32_bf16 v[58:61], v[170:173], v[194:197], v[58:61]
	v_mfma_f32_16x16x32_bf16 v[50:53], v[182:185], v[190:193], v[50:53]
	v_mfma_f32_16x16x32_bf16 v[50:53], v[186:189], v[194:197], v[50:53]
	v_mfma_f32_16x16x32_bf16 v[54:57], v[174:177], v[190:193], v[54:57]
	v_mfma_f32_16x16x32_bf16 v[54:57], v[178:181], v[194:197], v[54:57]
	v_mfma_f32_16x16x32_bf16 v[38:41], v[174:177], v[198:201], v[38:41]
	v_mfma_f32_16x16x32_bf16 v[38:41], v[178:181], v[202:205], v[38:41]
	v_mfma_f32_16x16x32_bf16 v[34:37], v[182:185], v[198:201], v[34:37]
	v_mfma_f32_16x16x32_bf16 v[34:37], v[186:189], v[202:205], v[34:37]
	v_mfma_f32_16x16x32_bf16 v[42:45], v[154:157], v[198:201], v[42:45]
	v_mfma_f32_16x16x32_bf16 v[42:45], v[170:173], v[202:205], v[42:45]
	v_mfma_f32_16x16x32_bf16 v[46:49], v[136:139], v[198:201], v[46:49]
	v_mfma_f32_16x16x32_bf16 v[46:49], v[140:143], v[202:205], v[46:49]
	v_mfma_f32_16x16x32_bf16 v[30:33], v[136:139], v[228:231], v[30:33]
	v_mfma_f32_16x16x32_bf16 v[30:33], v[140:143], v[232:235], v[30:33]
	v_mfma_f32_16x16x32_bf16 v[26:29], v[154:157], v[228:231], v[26:29]
	v_mfma_f32_16x16x32_bf16 v[26:29], v[170:173], v[232:235], v[26:29]
	v_mfma_f32_16x16x32_bf16 v[18:21], v[182:185], v[228:231], v[18:21]
	v_mfma_f32_16x16x32_bf16 v[18:21], v[186:189], v[232:235], v[18:21]
	v_mfma_f32_16x16x32_bf16 v[22:25], v[174:177], v[228:231], v[22:25]
	v_mfma_f32_16x16x32_bf16 v[22:25], v[178:181], v[232:235], v[22:25]
	v_mfma_f32_16x16x32_bf16 v[6:9], v[174:177], v[236:239], v[6:9]
	v_mfma_f32_16x16x32_bf16 v[6:9], v[178:181], v[240:243], v[6:9]
	v_mfma_f32_16x16x32_bf16 v[2:5], v[182:185], v[236:239], v[2:5]
	v_mfma_f32_16x16x32_bf16 v[2:5], v[186:189], v[240:243], v[2:5]
	v_mfma_f32_16x16x32_bf16 v[10:13], v[154:157], v[236:239], v[10:13]
	v_mfma_f32_16x16x32_bf16 v[10:13], v[170:173], v[240:243], v[10:13]
	v_mfma_f32_16x16x32_bf16 v[14:17], v[136:139], v[236:239], v[14:17]
	v_mfma_f32_16x16x32_bf16 v[14:17], v[140:143], v[240:243], v[14:17]
	s_barrier
	s_add_i32 s83, s83, 2
	s_addk_i32 s73, 0x100
	s_addk_i32 s82, 0x100
	s_cmp_ge_i32 s83, s23
	s_cbranch_scc0 .LBB0_2175
	v_readlane_b32 s83, v252, 30

.LBB0_2449:
	s_lshl_b32 s73, s72, 20
	s_and_b64 s[8:9], s[40:41], exec
	s_cselect_b32 s8, s73, s13
	s_lshl_b32 s84, s71, 20
	s_and_b64 s[24:25], s[40:41], exec
	s_cselect_b32 s9, s84, s21
	s_add_i32 s13, s13, 0x80080
	s_addk_i32 s21, 0x100
	s_mov_b32 s22, -2
	s_waitcnt lgkmcnt(0)
	v_add_u32_e32 v142, 0x10000, v188
	v_add_u32_e32 v182, 0x14000, v188
	ds_read_b128 v[130:133], v142
	ds_read_b128 v[134:137], v142 offset:1024
	ds_read_b128 v[138:141], v142 offset:2048
	ds_read_b128 v[142:145], v142 offset:3072
	ds_read_b128 v[154:157], v182
	ds_read_b128 v[174:177], v182 offset:1024
	ds_read_b128 v[178:181], v182 offset:2048
	ds_read_b128 v[190:193], v182 offset:3072
	s_add_i32 s24, s13, 0xfff80080
	s_cmp_eq_u32 s22, 28
	s_cselect_b32 s52, s8, s24
	s_cselect_b32 s25, s9, s21
	s_or_b32 s24, s52, 0x80
	s_mov_b32 m0, s68
	ds_read_b128 v[194:197], v189
	ds_read_b128 v[198:201], v189 offset:1024
	ds_read_b128 v[202:205], v189 offset:2048
	ds_read_b128 v[228:231], v189 offset:3072
	ds_read_b128 v[232:235], v189 offset:4096
	ds_read_b128 v[236:239], v189 offset:5120
	ds_read_b128 v[240:243], v189 offset:6144
	ds_read_b128 v[244:247], v189 offset:7168
	buffer_load_dwordx4 v184, s[60:63], s13 offen lds
	s_mov_b32 m0, s70
	s_nop 0
	buffer_load_dwordx4 v186, s[60:63], s13 offen lds
	s_waitcnt vmcnt(8)
	s_waitcnt lgkmcnt(0)
	s_barrier
	v_mfma_f32_16x16x32_bf16 v[126:129], v[130:133], v[194:197], 0
	v_mfma_f32_16x16x32_bf16 v[126:129], v[134:137], v[198:201], v[126:129]
	v_mfma_f32_16x16x32_bf16 v[122:125], v[138:141], v[194:197], 0
	v_mfma_f32_16x16x32_bf16 v[122:125], v[142:145], v[198:201], v[122:125]
	v_mfma_f32_16x16x32_bf16 v[114:117], v[178:181], v[194:197], 0
	v_mfma_f32_16x16x32_bf16 v[114:117], v[190:193], v[198:201], v[114:117]
	v_mfma_f32_16x16x32_bf16 v[118:121], v[154:157], v[194:197], 0
	v_mfma_f32_16x16x32_bf16 v[118:121], v[174:177], v[198:201], v[118:121]
	v_mfma_f32_16x16x32_bf16 v[102:105], v[154:157], v[202:205], 0
	v_mfma_f32_16x16x32_bf16 v[102:105], v[174:177], v[228:231], v[102:105]
	v_mfma_f32_16x16x32_bf16 v[98:101], v[178:181], v[202:205], 0
	v_mfma_f32_16x16x32_bf16 v[98:101], v[190:193], v[228:231], v[98:101]
	v_mfma_f32_16x16x32_bf16 v[106:109], v[138:141], v[202:205], 0
	v_mfma_f32_16x16x32_bf16 v[106:109], v[142:145], v[228:231], v[106:109]
	v_mfma_f32_16x16x32_bf16 v[110:113], v[130:133], v[202:205], 0
	v_mfma_f32_16x16x32_bf16 v[110:113], v[134:137], v[228:231], v[110:113]
	v_mfma_f32_16x16x32_bf16 v[94:97], v[130:133], v[232:235], 0
	v_mfma_f32_16x16x32_bf16 v[94:97], v[134:137], v[236:239], v[94:97]
	v_mfma_f32_16x16x32_bf16 v[90:93], v[138:141], v[232:235], 0
	v_mfma_f32_16x16x32_bf16 v[90:93], v[142:145], v[236:239], v[90:93]
	v_mfma_f32_16x16x32_bf16 v[82:85], v[178:181], v[232:235], 0
	v_mfma_f32_16x16x32_bf16 v[82:85], v[190:193], v[236:239], v[82:85]
	v_mfma_f32_16x16x32_bf16 v[86:89], v[154:157], v[232:235], 0
	v_mfma_f32_16x16x32_bf16 v[86:89], v[174:177], v[236:239], v[86:89]
	v_mfma_f32_16x16x32_bf16 v[70:73], v[154:157], v[240:243], 0
	v_mfma_f32_16x16x32_bf16 v[70:73], v[174:177], v[244:247], v[70:73]
	v_mfma_f32_16x16x32_bf16 v[66:69], v[178:181], v[240:243], 0
	v_mfma_f32_16x16x32_bf16 v[66:69], v[190:193], v[244:247], v[66:69]
	v_mfma_f32_16x16x32_bf16 v[74:77], v[138:141], v[240:243], 0
	v_mfma_f32_16x16x32_bf16 v[74:77], v[142:145], v[244:247], v[74:77]
	v_mfma_f32_16x16x32_bf16 v[78:81], v[130:133], v[240:243], 0
	v_mfma_f32_16x16x32_bf16 v[78:81], v[134:137], v[244:247], v[78:81]
	s_barrier
	s_mov_b32 s46, s62
	s_mov_b32 s47, s63
	s_mov_b32 m0, s16
	ds_read_b128 v[194:197], v189 offset:16384
	buffer_load_dwordx4 v185, s[44:47], s25 offen lds
	s_add_i32 s53, s25, 0x80000
	s_mov_b32 m0, s18
	ds_read_b128 v[198:201], v189 offset:17408
	buffer_load_dwordx4 v187, s[44:47], s25 offen lds
	s_mov_b32 m0, s19
	ds_read_b128 v[202:205], v189 offset:18432
	buffer_load_dwordx4 v185, s[44:47], s53 offen lds
	s_mov_b32 m0, s23
	ds_read_b128 v[228:231], v189 offset:19456
	buffer_load_dwordx4 v187, s[44:47], s53 offen lds
	s_mov_b32 m0, s15
	ds_read_b128 v[232:235], v189 offset:20480
	buffer_load_dwordx4 v184, s[60:63], s52 offen lds
	s_mov_b32 m0, s26
	ds_read_b128 v[236:239], v189 offset:21504
	buffer_load_dwordx4 v186, s[60:63], s52 offen lds
	ds_read_b128 v[240:243], v189 offset:22528
	ds_read_b128 v[244:247], v189 offset:23552
	s_waitcnt vmcnt(8)
	s_waitcnt lgkmcnt(0)
	s_barrier
	v_mfma_f32_16x16x32_bf16 v[62:65], v[130:133], v[194:197], 0
	v_mfma_f32_16x16x32_bf16 v[62:65], v[134:137], v[198:201], v[62:65]
	v_mfma_f32_16x16x32_bf16 v[58:61], v[138:141], v[194:197], 0
	v_mfma_f32_16x16x32_bf16 v[58:61], v[142:145], v[198:201], v[58:61]
	v_mfma_f32_16x16x32_bf16 v[50:53], v[178:181], v[194:197], 0
	v_mfma_f32_16x16x32_bf16 v[50:53], v[190:193], v[198:201], v[50:53]
	v_mfma_f32_16x16x32_bf16 v[54:57], v[154:157], v[194:197], 0
	v_mfma_f32_16x16x32_bf16 v[54:57], v[174:177], v[198:201], v[54:57]
	v_mfma_f32_16x16x32_bf16 v[38:41], v[154:157], v[202:205], 0
	v_mfma_f32_16x16x32_bf16 v[38:41], v[174:177], v[228:231], v[38:41]
	v_mfma_f32_16x16x32_bf16 v[34:37], v[178:181], v[202:205], 0
	v_mfma_f32_16x16x32_bf16 v[34:37], v[190:193], v[228:231], v[34:37]
	v_mfma_f32_16x16x32_bf16 v[42:45], v[138:141], v[202:205], 0
	v_mfma_f32_16x16x32_bf16 v[42:45], v[142:145], v[228:231], v[42:45]
	v_mfma_f32_16x16x32_bf16 v[46:49], v[130:133], v[202:205], 0
	v_mfma_f32_16x16x32_bf16 v[46:49], v[134:137], v[228:231], v[46:49]
	v_mfma_f32_16x16x32_bf16 v[30:33], v[130:133], v[232:235], 0
	v_mfma_f32_16x16x32_bf16 v[30:33], v[134:137], v[236:239], v[30:33]
	v_mfma_f32_16x16x32_bf16 v[26:29], v[138:141], v[232:235], 0
	v_mfma_f32_16x16x32_bf16 v[26:29], v[142:145], v[236:239], v[26:29]
	v_mfma_f32_16x16x32_bf16 v[18:21], v[178:181], v[232:235], 0
	v_mfma_f32_16x16x32_bf16 v[18:21], v[190:193], v[236:239], v[18:21]
	v_mfma_f32_16x16x32_bf16 v[22:25], v[154:157], v[232:235], 0
	v_mfma_f32_16x16x32_bf16 v[22:25], v[174:177], v[236:239], v[22:25]
	v_mfma_f32_16x16x32_bf16 v[6:9], v[154:157], v[240:243], 0
	v_mfma_f32_16x16x32_bf16 v[6:9], v[174:177], v[244:247], v[6:9]
	v_mfma_f32_16x16x32_bf16 v[2:5], v[178:181], v[240:243], 0
	v_mfma_f32_16x16x32_bf16 v[2:5], v[190:193], v[244:247], v[2:5]
	v_mfma_f32_16x16x32_bf16 v[10:13], v[138:141], v[240:243], 0
	v_mfma_f32_16x16x32_bf16 v[10:13], v[142:145], v[244:247], v[10:13]
	v_mfma_f32_16x16x32_bf16 v[14:17], v[130:133], v[240:243], 0
	v_mfma_f32_16x16x32_bf16 v[14:17], v[134:137], v[244:247], v[14:17]
	s_barrier
	v_add_u32_e32 v142, 0x18000, v188
	v_add_u32_e32 v182, 0x1c000, v188
	ds_read_b128 v[130:133], v142
	ds_read_b128 v[134:137], v142 offset:1024
	ds_read_b128 v[138:141], v142 offset:2048
	ds_read_b128 v[142:145], v142 offset:3072
	ds_read_b128 v[154:157], v182
	ds_read_b128 v[174:177], v182 offset:1024
	ds_read_b128 v[178:181], v182 offset:2048
	ds_read_b128 v[190:193], v182 offset:3072
	s_add_i32 s52, s52, 0x80000
	s_mov_b32 m0, s27
	ds_read_b128 v[194:197], v189 offset:32768
	ds_read_b128 v[198:201], v189 offset:33792
	ds_read_b128 v[202:205], v189 offset:34816
	ds_read_b128 v[228:231], v189 offset:35840
	ds_read_b128 v[232:235], v189 offset:36864
	ds_read_b128 v[236:239], v189 offset:37888
	ds_read_b128 v[240:243], v189 offset:38912
	ds_read_b128 v[244:247], v189 offset:39936
	buffer_load_dwordx4 v184, s[60:63], s52 offen lds
	s_mov_b32 m0, s30
	s_nop 0
	buffer_load_dwordx4 v186, s[60:63], s52 offen lds
	s_waitcnt vmcnt(8)
	s_waitcnt lgkmcnt(0)
	s_barrier
	v_mfma_f32_16x16x32_bf16 v[126:129], v[130:133], v[194:197], v[126:129]
	v_mfma_f32_16x16x32_bf16 v[126:129], v[134:137], v[198:201], v[126:129]
	v_mfma_f32_16x16x32_bf16 v[122:125], v[138:141], v[194:197], v[122:125]
	v_mfma_f32_16x16x32_bf16 v[122:125], v[142:145], v[198:201], v[122:125]
	v_mfma_f32_16x16x32_bf16 v[114:117], v[178:181], v[194:197], v[114:117]
	v_mfma_f32_16x16x32_bf16 v[114:117], v[190:193], v[198:201], v[114:117]
	v_mfma_f32_16x16x32_bf16 v[118:121], v[154:157], v[194:197], v[118:121]
	v_mfma_f32_16x16x32_bf16 v[118:121], v[174:177], v[198:201], v[118:121]
	v_mfma_f32_16x16x32_bf16 v[102:105], v[154:157], v[202:205], v[102:105]
	v_mfma_f32_16x16x32_bf16 v[102:105], v[174:177], v[228:231], v[102:105]
	v_mfma_f32_16x16x32_bf16 v[98:101], v[178:181], v[202:205], v[98:101]
	v_mfma_f32_16x16x32_bf16 v[98:101], v[190:193], v[228:231], v[98:101]
	v_mfma_f32_16x16x32_bf16 v[106:109], v[138:141], v[202:205], v[106:109]
	v_mfma_f32_16x16x32_bf16 v[106:109], v[142:145], v[228:231], v[106:109]
	v_mfma_f32_16x16x32_bf16 v[110:113], v[130:133], v[202:205], v[110:113]
	v_mfma_f32_16x16x32_bf16 v[110:113], v[134:137], v[228:231], v[110:113]
	v_mfma_f32_16x16x32_bf16 v[94:97], v[130:133], v[232:235], v[94:97]
	v_mfma_f32_16x16x32_bf16 v[94:97], v[134:137], v[236:239], v[94:97]
	v_mfma_f32_16x16x32_bf16 v[90:93], v[138:141], v[232:235], v[90:93]
	v_mfma_f32_16x16x32_bf16 v[90:93], v[142:145], v[236:239], v[90:93]
	v_mfma_f32_16x16x32_bf16 v[82:85], v[178:181], v[232:235], v[82:85]
	v_mfma_f32_16x16x32_bf16 v[82:85], v[190:193], v[236:239], v[82:85]
	v_mfma_f32_16x16x32_bf16 v[86:89], v[154:157], v[232:235], v[86:89]
	v_mfma_f32_16x16x32_bf16 v[86:89], v[174:177], v[236:239], v[86:89]
	v_mfma_f32_16x16x32_bf16 v[70:73], v[154:157], v[240:243], v[70:73]
	v_mfma_f32_16x16x32_bf16 v[70:73], v[174:177], v[244:247], v[70:73]
	v_mfma_f32_16x16x32_bf16 v[66:69], v[178:181], v[240:243], v[66:69]
	v_mfma_f32_16x16x32_bf16 v[66:69], v[190:193], v[244:247], v[66:69]
	v_mfma_f32_16x16x32_bf16 v[74:77], v[138:141], v[240:243], v[74:77]
	v_mfma_f32_16x16x32_bf16 v[74:77], v[142:145], v[244:247], v[74:77]
	v_mfma_f32_16x16x32_bf16 v[78:81], v[130:133], v[240:243], v[78:81]
	v_mfma_f32_16x16x32_bf16 v[78:81], v[134:137], v[244:247], v[78:81]
	s_barrier
	s_or_b32 s52, s25, 0x80
	s_mov_b32 m0, s36
	ds_read_b128 v[194:197], v189 offset:49152
	buffer_load_dwordx4 v185, s[44:47], s52 offen lds
	s_add_i32 s25, s25, 0x80080
	s_mov_b32 m0, s37
	ds_read_b128 v[198:201], v189 offset:50176
	buffer_load_dwordx4 v187, s[44:47], s52 offen lds
	s_mov_b32 m0, s66
	ds_read_b128 v[202:205], v189 offset:51200
	buffer_load_dwordx4 v185, s[44:47], s25 offen lds
	s_mov_b32 m0, s67
	ds_read_b128 v[228:231], v189 offset:52224
	buffer_load_dwordx4 v187, s[44:47], s25 offen lds
	s_mov_b32 m0, s48
	ds_read_b128 v[232:235], v189 offset:53248
	buffer_load_dwordx4 v184, s[60:63], s24 offen lds
	s_mov_b32 m0, s49
	ds_read_b128 v[236:239], v189 offset:54272
	buffer_load_dwordx4 v186, s[60:63], s24 offen lds
	ds_read_b128 v[240:243], v189 offset:55296
	ds_read_b128 v[244:247], v189 offset:56320
	s_waitcnt vmcnt(8)
	s_waitcnt lgkmcnt(0)
	s_barrier
	v_mfma_f32_16x16x32_bf16 v[62:65], v[130:133], v[194:197], v[62:65]
	v_mfma_f32_16x16x32_bf16 v[62:65], v[134:137], v[198:201], v[62:65]
	v_mfma_f32_16x16x32_bf16 v[58:61], v[138:141], v[194:197], v[58:61]
	v_mfma_f32_16x16x32_bf16 v[58:61], v[142:145], v[198:201], v[58:61]
	v_mfma_f32_16x16x32_bf16 v[50:53], v[178:181], v[194:197], v[50:53]
	v_mfma_f32_16x16x32_bf16 v[50:53], v[190:193], v[198:201], v[50:53]
	v_mfma_f32_16x16x32_bf16 v[54:57], v[154:157], v[194:197], v[54:57]
	v_mfma_f32_16x16x32_bf16 v[54:57], v[174:177], v[198:201], v[54:57]
	v_mfma_f32_16x16x32_bf16 v[38:41], v[154:157], v[202:205], v[38:41]
	v_mfma_f32_16x16x32_bf16 v[38:41], v[174:177], v[228:231], v[38:41]
	v_mfma_f32_16x16x32_bf16 v[34:37], v[178:181], v[202:205], v[34:37]
	v_mfma_f32_16x16x32_bf16 v[34:37], v[190:193], v[228:231], v[34:37]
	v_mfma_f32_16x16x32_bf16 v[42:45], v[138:141], v[202:205], v[42:45]
	v_mfma_f32_16x16x32_bf16 v[42:45], v[142:145], v[228:231], v[42:45]
	v_mfma_f32_16x16x32_bf16 v[46:49], v[130:133], v[202:205], v[46:49]
	v_mfma_f32_16x16x32_bf16 v[46:49], v[134:137], v[228:231], v[46:49]
	v_mfma_f32_16x16x32_bf16 v[30:33], v[130:133], v[232:235], v[30:33]
	v_mfma_f32_16x16x32_bf16 v[30:33], v[134:137], v[236:239], v[30:33]
	v_mfma_f32_16x16x32_bf16 v[26:29], v[138:141], v[232:235], v[26:29]
	v_mfma_f32_16x16x32_bf16 v[26:29], v[142:145], v[236:239], v[26:29]
	v_mfma_f32_16x16x32_bf16 v[18:21], v[178:181], v[232:235], v[18:21]
	v_mfma_f32_16x16x32_bf16 v[18:21], v[190:193], v[236:239], v[18:21]
	v_mfma_f32_16x16x32_bf16 v[22:25], v[154:157], v[232:235], v[22:25]
	v_mfma_f32_16x16x32_bf16 v[22:25], v[174:177], v[236:239], v[22:25]
	v_mfma_f32_16x16x32_bf16 v[6:9], v[154:157], v[240:243], v[6:9]
	v_mfma_f32_16x16x32_bf16 v[6:9], v[174:177], v[244:247], v[6:9]
	v_mfma_f32_16x16x32_bf16 v[2:5], v[178:181], v[240:243], v[2:5]
	v_mfma_f32_16x16x32_bf16 v[2:5], v[190:193], v[244:247], v[2:5]
	v_mfma_f32_16x16x32_bf16 v[10:13], v[138:141], v[240:243], v[10:13]
	v_mfma_f32_16x16x32_bf16 v[10:13], v[142:145], v[244:247], v[10:13]
	v_mfma_f32_16x16x32_bf16 v[14:17], v[130:133], v[240:243], v[14:17]
	v_mfma_f32_16x16x32_bf16 v[14:17], v[134:137], v[244:247], v[14:17]
	s_barrier
	s_add_i32 s22, s22, 2
	s_addk_i32 s13, 0x100
	s_addk_i32 s21, 0x100
	s_cmp_gt_u32 s22, 29
.LBB0_2450:
	v_add_u32_e32 v142, 0x10000, v188
	v_add_u32_e32 v182, 0x14000, v188
	ds_read_b128 v[130:133], v142
	ds_read_b128 v[134:137], v142 offset:1024
	ds_read_b128 v[138:141], v142 offset:2048
	ds_read_b128 v[142:145], v142 offset:3072
	ds_read_b128 v[154:157], v182
	ds_read_b128 v[174:177], v182 offset:1024
	ds_read_b128 v[178:181], v182 offset:2048
	ds_read_b128 v[190:193], v182 offset:3072
	s_add_i32 s24, s13, 0xfff80080
	s_cmp_eq_u32 s22, 28
	s_cselect_b32 s52, s8, s24
	s_cselect_b32 s25, s9, s21
	s_or_b32 s24, s52, 0x80
	s_mov_b32 m0, s68
	ds_read_b128 v[194:197], v189
	ds_read_b128 v[198:201], v189 offset:1024
	ds_read_b128 v[202:205], v189 offset:2048
	ds_read_b128 v[228:231], v189 offset:3072
	ds_read_b128 v[232:235], v189 offset:4096
	ds_read_b128 v[236:239], v189 offset:5120
	ds_read_b128 v[240:243], v189 offset:6144
	ds_read_b128 v[244:247], v189 offset:7168
	buffer_load_dwordx4 v184, s[60:63], s13 offen lds
	s_mov_b32 m0, s70
	s_nop 0
	buffer_load_dwordx4 v186, s[60:63], s13 offen lds
	s_waitcnt vmcnt(8)
	s_waitcnt lgkmcnt(0)
	s_barrier
	v_mfma_f32_16x16x32_bf16 v[126:129], v[130:133], v[194:197], v[126:129]
	v_mfma_f32_16x16x32_bf16 v[126:129], v[134:137], v[198:201], v[126:129]
	v_mfma_f32_16x16x32_bf16 v[122:125], v[138:141], v[194:197], v[122:125]
	v_mfma_f32_16x16x32_bf16 v[122:125], v[142:145], v[198:201], v[122:125]
	v_mfma_f32_16x16x32_bf16 v[114:117], v[178:181], v[194:197], v[114:117]
	v_mfma_f32_16x16x32_bf16 v[114:117], v[190:193], v[198:201], v[114:117]
	v_mfma_f32_16x16x32_bf16 v[118:121], v[154:157], v[194:197], v[118:121]
	v_mfma_f32_16x16x32_bf16 v[118:121], v[174:177], v[198:201], v[118:121]
	v_mfma_f32_16x16x32_bf16 v[102:105], v[154:157], v[202:205], v[102:105]
	v_mfma_f32_16x16x32_bf16 v[102:105], v[174:177], v[228:231], v[102:105]
	v_mfma_f32_16x16x32_bf16 v[98:101], v[178:181], v[202:205], v[98:101]
	v_mfma_f32_16x16x32_bf16 v[98:101], v[190:193], v[228:231], v[98:101]
	v_mfma_f32_16x16x32_bf16 v[106:109], v[138:141], v[202:205], v[106:109]
	v_mfma_f32_16x16x32_bf16 v[106:109], v[142:145], v[228:231], v[106:109]
	v_mfma_f32_16x16x32_bf16 v[110:113], v[130:133], v[202:205], v[110:113]
	v_mfma_f32_16x16x32_bf16 v[110:113], v[134:137], v[228:231], v[110:113]
	v_mfma_f32_16x16x32_bf16 v[94:97], v[130:133], v[232:235], v[94:97]
	v_mfma_f32_16x16x32_bf16 v[94:97], v[134:137], v[236:239], v[94:97]
	v_mfma_f32_16x16x32_bf16 v[90:93], v[138:141], v[232:235], v[90:93]
	v_mfma_f32_16x16x32_bf16 v[90:93], v[142:145], v[236:239], v[90:93]
	v_mfma_f32_16x16x32_bf16 v[82:85], v[178:181], v[232:235], v[82:85]
	v_mfma_f32_16x16x32_bf16 v[82:85], v[190:193], v[236:239], v[82:85]
	v_mfma_f32_16x16x32_bf16 v[86:89], v[154:157], v[232:235], v[86:89]
	v_mfma_f32_16x16x32_bf16 v[86:89], v[174:177], v[236:239], v[86:89]
	v_mfma_f32_16x16x32_bf16 v[70:73], v[154:157], v[240:243], v[70:73]
	v_mfma_f32_16x16x32_bf16 v[70:73], v[174:177], v[244:247], v[70:73]
	v_mfma_f32_16x16x32_bf16 v[66:69], v[178:181], v[240:243], v[66:69]
	v_mfma_f32_16x16x32_bf16 v[66:69], v[190:193], v[244:247], v[66:69]
	v_mfma_f32_16x16x32_bf16 v[74:77], v[138:141], v[240:243], v[74:77]
	v_mfma_f32_16x16x32_bf16 v[74:77], v[142:145], v[244:247], v[74:77]
	v_mfma_f32_16x16x32_bf16 v[78:81], v[130:133], v[240:243], v[78:81]
	v_mfma_f32_16x16x32_bf16 v[78:81], v[134:137], v[244:247], v[78:81]
	s_barrier
	s_mov_b32 s46, s62
	s_mov_b32 s47, s63
	s_mov_b32 m0, s16
	ds_read_b128 v[194:197], v189 offset:16384
	buffer_load_dwordx4 v185, s[44:47], s25 offen lds
	s_add_i32 s53, s25, 0x80000
	s_mov_b32 m0, s18
	ds_read_b128 v[198:201], v189 offset:17408
	buffer_load_dwordx4 v187, s[44:47], s25 offen lds
	s_mov_b32 m0, s19
	ds_read_b128 v[202:205], v189 offset:18432
	buffer_load_dwordx4 v185, s[44:47], s53 offen lds
	s_mov_b32 m0, s23
	ds_read_b128 v[228:231], v189 offset:19456
	buffer_load_dwordx4 v187, s[44:47], s53 offen lds
	s_mov_b32 m0, s15
	ds_read_b128 v[232:235], v189 offset:20480
	buffer_load_dwordx4 v184, s[60:63], s52 offen lds
	s_mov_b32 m0, s26
	ds_read_b128 v[236:239], v189 offset:21504
	buffer_load_dwordx4 v186, s[60:63], s52 offen lds
	ds_read_b128 v[240:243], v189 offset:22528
	ds_read_b128 v[244:247], v189 offset:23552
	s_waitcnt vmcnt(8)
	s_waitcnt lgkmcnt(0)
	s_barrier
	v_mfma_f32_16x16x32_bf16 v[62:65], v[130:133], v[194:197], v[62:65]
	v_mfma_f32_16x16x32_bf16 v[62:65], v[134:137], v[198:201], v[62:65]
	v_mfma_f32_16x16x32_bf16 v[58:61], v[138:141], v[194:197], v[58:61]
	v_mfma_f32_16x16x32_bf16 v[58:61], v[142:145], v[198:201], v[58:61]
	v_mfma_f32_16x16x32_bf16 v[50:53], v[178:181], v[194:197], v[50:53]
	v_mfma_f32_16x16x32_bf16 v[50:53], v[190:193], v[198:201], v[50:53]
	v_mfma_f32_16x16x32_bf16 v[54:57], v[154:157], v[194:197], v[54:57]
	v_mfma_f32_16x16x32_bf16 v[54:57], v[174:177], v[198:201], v[54:57]
	v_mfma_f32_16x16x32_bf16 v[38:41], v[154:157], v[202:205], v[38:41]
	v_mfma_f32_16x16x32_bf16 v[38:41], v[174:177], v[228:231], v[38:41]
	v_mfma_f32_16x16x32_bf16 v[34:37], v[178:181], v[202:205], v[34:37]
	v_mfma_f32_16x16x32_bf16 v[34:37], v[190:193], v[228:231], v[34:37]
	v_mfma_f32_16x16x32_bf16 v[42:45], v[138:141], v[202:205], v[42:45]
	v_mfma_f32_16x16x32_bf16 v[42:45], v[142:145], v[228:231], v[42:45]
	v_mfma_f32_16x16x32_bf16 v[46:49], v[130:133], v[202:205], v[46:49]
	v_mfma_f32_16x16x32_bf16 v[46:49], v[134:137], v[228:231], v[46:49]
	v_mfma_f32_16x16x32_bf16 v[30:33], v[130:133], v[232:235], v[30:33]
	v_mfma_f32_16x16x32_bf16 v[30:33], v[134:137], v[236:239], v[30:33]
	v_mfma_f32_16x16x32_bf16 v[26:29], v[138:141], v[232:235], v[26:29]
	v_mfma_f32_16x16x32_bf16 v[26:29], v[142:145], v[236:239], v[26:29]
	v_mfma_f32_16x16x32_bf16 v[18:21], v[178:181], v[232:235], v[18:21]
	v_mfma_f32_16x16x32_bf16 v[18:21], v[190:193], v[236:239], v[18:21]
	v_mfma_f32_16x16x32_bf16 v[22:25], v[154:157], v[232:235], v[22:25]
	v_mfma_f32_16x16x32_bf16 v[22:25], v[174:177], v[236:239], v[22:25]
	v_mfma_f32_16x16x32_bf16 v[6:9], v[154:157], v[240:243], v[6:9]
	v_mfma_f32_16x16x32_bf16 v[6:9], v[174:177], v[244:247], v[6:9]
	v_mfma_f32_16x16x32_bf16 v[2:5], v[178:181], v[240:243], v[2:5]
	v_mfma_f32_16x16x32_bf16 v[2:5], v[190:193], v[244:247], v[2:5]
	v_mfma_f32_16x16x32_bf16 v[10:13], v[138:141], v[240:243], v[10:13]
	v_mfma_f32_16x16x32_bf16 v[10:13], v[142:145], v[244:247], v[10:13]
	v_mfma_f32_16x16x32_bf16 v[14:17], v[130:133], v[240:243], v[14:17]
	v_mfma_f32_16x16x32_bf16 v[14:17], v[134:137], v[244:247], v[14:17]
	s_barrier
	v_add_u32_e32 v142, 0x18000, v188
	v_add_u32_e32 v182, 0x1c000, v188
	ds_read_b128 v[130:133], v142
	ds_read_b128 v[134:137], v142 offset:1024
	ds_read_b128 v[138:141], v142 offset:2048
	ds_read_b128 v[142:145], v142 offset:3072
	ds_read_b128 v[154:157], v182
	ds_read_b128 v[174:177], v182 offset:1024
	ds_read_b128 v[178:181], v182 offset:2048
	ds_read_b128 v[190:193], v182 offset:3072
	s_add_i32 s52, s52, 0x80000
	s_mov_b32 m0, s27
	ds_read_b128 v[194:197], v189 offset:32768
	ds_read_b128 v[198:201], v189 offset:33792
	ds_read_b128 v[202:205], v189 offset:34816
	ds_read_b128 v[228:231], v189 offset:35840
	ds_read_b128 v[232:235], v189 offset:36864
	ds_read_b128 v[236:239], v189 offset:37888
	ds_read_b128 v[240:243], v189 offset:38912
	ds_read_b128 v[244:247], v189 offset:39936
	buffer_load_dwordx4 v184, s[60:63], s52 offen lds
	s_mov_b32 m0, s30
	s_nop 0
	buffer_load_dwordx4 v186, s[60:63], s52 offen lds
	s_waitcnt vmcnt(8)
	s_waitcnt lgkmcnt(0)
	s_barrier
	v_mfma_f32_16x16x32_bf16 v[126:129], v[130:133], v[194:197], v[126:129]
	v_mfma_f32_16x16x32_bf16 v[126:129], v[134:137], v[198:201], v[126:129]
	v_mfma_f32_16x16x32_bf16 v[122:125], v[138:141], v[194:197], v[122:125]
	v_mfma_f32_16x16x32_bf16 v[122:125], v[142:145], v[198:201], v[122:125]
	v_mfma_f32_16x16x32_bf16 v[114:117], v[178:181], v[194:197], v[114:117]
	v_mfma_f32_16x16x32_bf16 v[114:117], v[190:193], v[198:201], v[114:117]
	v_mfma_f32_16x16x32_bf16 v[118:121], v[154:157], v[194:197], v[118:121]
	v_mfma_f32_16x16x32_bf16 v[118:121], v[174:177], v[198:201], v[118:121]
	v_mfma_f32_16x16x32_bf16 v[102:105], v[154:157], v[202:205], v[102:105]
	v_mfma_f32_16x16x32_bf16 v[102:105], v[174:177], v[228:231], v[102:105]
	v_mfma_f32_16x16x32_bf16 v[98:101], v[178:181], v[202:205], v[98:101]
	v_mfma_f32_16x16x32_bf16 v[98:101], v[190:193], v[228:231], v[98:101]
	v_mfma_f32_16x16x32_bf16 v[106:109], v[138:141], v[202:205], v[106:109]
	v_mfma_f32_16x16x32_bf16 v[106:109], v[142:145], v[228:231], v[106:109]
	v_mfma_f32_16x16x32_bf16 v[110:113], v[130:133], v[202:205], v[110:113]
	v_mfma_f32_16x16x32_bf16 v[110:113], v[134:137], v[228:231], v[110:113]
	v_mfma_f32_16x16x32_bf16 v[94:97], v[130:133], v[232:235], v[94:97]
	v_mfma_f32_16x16x32_bf16 v[94:97], v[134:137], v[236:239], v[94:97]
	v_mfma_f32_16x16x32_bf16 v[90:93], v[138:141], v[232:235], v[90:93]
	v_mfma_f32_16x16x32_bf16 v[90:93], v[142:145], v[236:239], v[90:93]
	v_mfma_f32_16x16x32_bf16 v[82:85], v[178:181], v[232:235], v[82:85]
	v_mfma_f32_16x16x32_bf16 v[82:85], v[190:193], v[236:239], v[82:85]
	v_mfma_f32_16x16x32_bf16 v[86:89], v[154:157], v[232:235], v[86:89]
	v_mfma_f32_16x16x32_bf16 v[86:89], v[174:177], v[236:239], v[86:89]
	v_mfma_f32_16x16x32_bf16 v[70:73], v[154:157], v[240:243], v[70:73]
	v_mfma_f32_16x16x32_bf16 v[70:73], v[174:177], v[244:247], v[70:73]
	v_mfma_f32_16x16x32_bf16 v[66:69], v[178:181], v[240:243], v[66:69]
	v_mfma_f32_16x16x32_bf16 v[66:69], v[190:193], v[244:247], v[66:69]
	v_mfma_f32_16x16x32_bf16 v[74:77], v[138:141], v[240:243], v[74:77]
	v_mfma_f32_16x16x32_bf16 v[74:77], v[142:145], v[244:247], v[74:77]
	v_mfma_f32_16x16x32_bf16 v[78:81], v[130:133], v[240:243], v[78:81]
	v_mfma_f32_16x16x32_bf16 v[78:81], v[134:137], v[244:247], v[78:81]
	s_barrier
	s_or_b32 s52, s25, 0x80
	s_mov_b32 m0, s36
	ds_read_b128 v[194:197], v189 offset:49152
	buffer_load_dwordx4 v185, s[44:47], s52 offen lds
	s_add_i32 s25, s25, 0x80080
	s_mov_b32 m0, s37
	ds_read_b128 v[198:201], v189 offset:50176
	buffer_load_dwordx4 v187, s[44:47], s52 offen lds
	s_mov_b32 m0, s66
	ds_read_b128 v[202:205], v189 offset:51200
	buffer_load_dwordx4 v185, s[44:47], s25 offen lds
	s_mov_b32 m0, s67
	ds_read_b128 v[228:231], v189 offset:52224
	buffer_load_dwordx4 v187, s[44:47], s25 offen lds
	s_mov_b32 m0, s48
	ds_read_b128 v[232:235], v189 offset:53248
	buffer_load_dwordx4 v184, s[60:63], s24 offen lds
	s_mov_b32 m0, s49
	ds_read_b128 v[236:239], v189 offset:54272
	buffer_load_dwordx4 v186, s[60:63], s24 offen lds
	ds_read_b128 v[240:243], v189 offset:55296
	ds_read_b128 v[244:247], v189 offset:56320
	s_waitcnt vmcnt(8)
	s_waitcnt lgkmcnt(0)
	s_barrier
	v_mfma_f32_16x16x32_bf16 v[62:65], v[130:133], v[194:197], v[62:65]
	v_mfma_f32_16x16x32_bf16 v[62:65], v[134:137], v[198:201], v[62:65]
	v_mfma_f32_16x16x32_bf16 v[58:61], v[138:141], v[194:197], v[58:61]
	v_mfma_f32_16x16x32_bf16 v[58:61], v[142:145], v[198:201], v[58:61]
	v_mfma_f32_16x16x32_bf16 v[50:53], v[178:181], v[194:197], v[50:53]
	v_mfma_f32_16x16x32_bf16 v[50:53], v[190:193], v[198:201], v[50:53]
	v_mfma_f32_16x16x32_bf16 v[54:57], v[154:157], v[194:197], v[54:57]
	v_mfma_f32_16x16x32_bf16 v[54:57], v[174:177], v[198:201], v[54:57]
	v_mfma_f32_16x16x32_bf16 v[38:41], v[154:157], v[202:205], v[38:41]
	v_mfma_f32_16x16x32_bf16 v[38:41], v[174:177], v[228:231], v[38:41]
	v_mfma_f32_16x16x32_bf16 v[34:37], v[178:181], v[202:205], v[34:37]
	v_mfma_f32_16x16x32_bf16 v[34:37], v[190:193], v[228:231], v[34:37]
	v_mfma_f32_16x16x32_bf16 v[42:45], v[138:141], v[202:205], v[42:45]
	v_mfma_f32_16x16x32_bf16 v[42:45], v[142:145], v[228:231], v[42:45]
	v_mfma_f32_16x16x32_bf16 v[46:49], v[130:133], v[202:205], v[46:49]
	v_mfma_f32_16x16x32_bf16 v[46:49], v[134:137], v[228:231], v[46:49]
	v_mfma_f32_16x16x32_bf16 v[30:33], v[130:133], v[232:235], v[30:33]
	v_mfma_f32_16x16x32_bf16 v[30:33], v[134:137], v[236:239], v[30:33]
	v_mfma_f32_16x16x32_bf16 v[26:29], v[138:141], v[232:235], v[26:29]
	v_mfma_f32_16x16x32_bf16 v[26:29], v[142:145], v[236:239], v[26:29]
	v_mfma_f32_16x16x32_bf16 v[18:21], v[178:181], v[232:235], v[18:21]
	v_mfma_f32_16x16x32_bf16 v[18:21], v[190:193], v[236:239], v[18:21]
	v_mfma_f32_16x16x32_bf16 v[22:25], v[154:157], v[232:235], v[22:25]
	v_mfma_f32_16x16x32_bf16 v[22:25], v[174:177], v[236:239], v[22:25]
	v_mfma_f32_16x16x32_bf16 v[6:9], v[154:157], v[240:243], v[6:9]
	v_mfma_f32_16x16x32_bf16 v[6:9], v[174:177], v[244:247], v[6:9]
	v_mfma_f32_16x16x32_bf16 v[2:5], v[178:181], v[240:243], v[2:5]
	v_mfma_f32_16x16x32_bf16 v[2:5], v[190:193], v[244:247], v[2:5]
	v_mfma_f32_16x16x32_bf16 v[10:13], v[138:141], v[240:243], v[10:13]
	v_mfma_f32_16x16x32_bf16 v[10:13], v[142:145], v[244:247], v[10:13]
	v_mfma_f32_16x16x32_bf16 v[14:17], v[130:133], v[240:243], v[14:17]
	v_mfma_f32_16x16x32_bf16 v[14:17], v[134:137], v[244:247], v[14:17]
	s_barrier
	s_add_i32 s22, s22, 2
	s_addk_i32 s13, 0x100
	s_addk_i32 s21, 0x100
	s_cmp_gt_u32 s22, 29
	s_cbranch_scc0 .LBB0_2450
	s_and_b64 vcc, exec, s[64:65]
	s_cbranch_vccz .LBB0_2453
	s_barrier
